# GEMM MFMA blocks: mid-block priority drop/raise pair removed (one continuous prio-1 block of 32 MFMAs)
# baseline (speedup 1.0000x reference)
; #define PG8_WAIT_V(n) asm volatile("s_waitcnt vmcnt(" #n ")" ::: "memory")
;     __host__ __device__ bool next(int i, Unit& u) const {
;         const long L = (long)i * G + c; if (L >= nwg) return false;
;         int wgid = (int)L; { const int q = nwg / NXCD, r = nwg % NXCD, xcd = wgid % NXCD, off = wgid / NXCD; wgid = (xcd < r ? xcd * (q + 1) : r * (q + 1) + (xcd - r) * q) + off; }
;         const int nig = wgm * nN, gid = wgid / nig, fm = gid * wgm, gsz = (nM - fm) < wgm ? (nM - fm) : wgm;
;         u.pm = fm + ((wgid % nig) % gsz); u.pn = (wgid % nig) / gsz; if (rev) u.pm = nM - 1 - u.pm; return true;
; template <class Epi, class Sched, bool ALIGN_EPI = false, bool SP2 = false>
; __device__ __forceinline__ void gemm_phase(PG8_LAS unsigned char* lds, const Gemm g, const Sched& S, const Epi& E) {
;     ...
;     const int tid = tid_, wid = __builtin_amdgcn_readfirstlane(tid >> 6), lane = tid & 63, wr = wid >> 2, wc = wid & 3, fr = lane & 15, fq = lane >> 4;
;     const int K = g.K, nt = K / BK;
;     unsigned voffA[2], voffB[2];
; #pragma unroll
;     for (int i = 0; i < 2; ++i) { int R, C; stage_rc(tid * 16 + i * 8192, R, C); const int Rb = Epi::PERM ? ((R & ~31) + perm32(R & 31)) : R;
;         voffA[i] = (unsigned)(R * K + C) * 2u; voffB[i] = (unsigned)(Rb * K + C) * 2u; }
;     const size_t kstep = (size_t)(BK * 2);
;     const size_t hstep = (size_t)HALF * K * 2;
;     const size_t tstep = 2 * hstep;
;     const unsigned ldsw = (unsigned)wid * 1024u;
;     const int aoff = lds_byte(wr * 64 + fr, fq * 8), boff = lds_byte(wc * 32 + fr, fq * 8);
;     ...
;     Unit cur, nxt; int ui = 0;
;     if (!S.next(0, cur)) return;
;     f32x4 acc[2][2][4][2];
; #pragma unroll
;     for (int a = 0; a < 2; ++a)
; #pragma unroll
;         for (int b = 0; b < 2; ++b)
; #pragma unroll
;             for (int m = 0; m < 4; ++m)
; #pragma unroll
;                 for (int n = 0; n < 2; ++n) acc[a][b][m][n] = (f32x4){0.f, 0.f, 0.f, 0.f};
;     bf16x8 At[4][2], B0[2][2], B1[2][2];
;     const char* cA = (const char*)g.A + (size_t)cur.pm * tstep; const char* cB = (const char*)g.Bt + (size_t)cur.pn * tstep;
;     S.a_ready(cur);
;     if constexpr (SP2) {
;         PG8_STAGE(PG8_SB(0, 0), cB, voffB); PG8_STAGE(PG8_SB(0, 1), cB + hstep, voffB); PG8_STAGE(PG8_SA(0, 0), cA, voffA); PG8_STAGE(PG8_SA(0, 1), cA + hstep, voffA);
;         if (wr == 1) PG8_BAR;
;         PG8_WAIT_V(2); PG8_BAR;
.LBB0_162:
	s_or_b64 exec, exec, s[14:15]
	s_nop 0
	s_nop 0
	s_nop 0
	s_nop 0
	s_nop 0
	s_nop 0
	s_nop 0
	s_nop 0
	s_nop 0
	s_nop 0
	s_nop 0
	s_nop 0
	v_writelane_b32 v254, s34, 49
	s_ashr_i32 s3, s46, 31
	s_ashr_i32 s33, s2, 31
	s_mov_b64 s[24:25], s[0:1]
	s_mov_b64 s[26:27], s[0:1]
	s_mov_b64 s[14:15], s[0:1]
	s_mov_b64 s[16:17], s[0:1]
	s_mov_b64 s[18:19], s[0:1]
	s_mov_b64 s[20:21], s[0:1]
	s_mov_b64 s[22:23], s[0:1]
	v_mov_b32_e32 v14, v216
	v_writelane_b32 v254, s35, 50
	s_waitcnt lgkmcnt(0)
	s_barrier
	s_cmpk_gt_i32 s2, 0x11ff
	v_writelane_b32 v254, s60, 51
	v_readfirstlane_b32 s30, v14
	s_nop 0
	v_writelane_b32 v254, s61, 52
	s_cbranch_scc1 .LBB0_186
	v_lshlrev_b32_e32 v0, 4, v14
	v_add_u32_e32 v1, 0x2000, v0
	v_ashrrev_i32_e32 v2, 31, v1
	v_lshrrev_b32_e32 v2, 22, v2
	v_add_u32_e32 v2, v1, v2
	v_ashrrev_i32_e32 v8, 10, v2
	v_mul_i32_i24_e32 v2, 0x400, v8
	v_sub_u32_e32 v1, v1, v2
	v_lshrrev_b32_e32 v2, 4, v1
	v_bitop3_b32 v1, v2, v1, 32 bitop3:0x6c
	v_ashrrev_i32_e32 v2, 31, v1
	s_load_dwordx2 s[24:25], s[24:25], 0xc8
	s_nop 0
	s_load_dwordx2 s[26:27], s[26:27], 0xc8
	v_lshrrev_b32_e32 v2, 26, v2
	v_add_u32_e32 v2, v1, v2
	v_lshlrev_b32_e32 v3, 3, v8
	v_ashrrev_i32_e32 v9, 6, v2
	v_and_b32_e32 v3, -16, v3
	v_add_u32_e32 v3, v9, v3
	s_waitcnt lgkmcnt(0)
	s_add_u32 s13, s24, 0x7800000
	v_and_b32_e32 v4, 3, v9
	s_mov_b32 s24, 0xfffe0
	v_lshrrev_b32_e32 v5, 2, v3
	v_lshlrev_b32_e32 v6, 1, v3
	v_and_b32_e32 v2, 0xc0, v2
	v_and_or_b32 v4, v3, s24, v4
	v_and_b32_e32 v5, 4, v5
	v_and_b32_e32 v6, 24, v6
	v_sub_u32_e32 v1, v1, v2
	v_mov_b32_e32 v2, 1
	v_or3_b32 v4, v4, v5, v6
	v_lshlrev_b32_e32 v5, 5, v8
	v_ashrrev_i16_sdwa v1, v2, sext(v1) dst_sel:DWORD dst_unused:UNUSED_PAD src0_sel:DWORD src1_sel:BYTE_0
	v_and_b32_e32 v5, 32, v5
	v_bfe_i32 v10, v1, 0, 16
	v_add_lshl_u32 v1, v5, v10, 1
	v_lshl_add_u32 v144, v4, 12, v1
	v_lshl_add_u32 v146, v3, 12, v1
	v_bfe_i32 v1, v14, 27, 1
	v_lshrrev_b32_e32 v1, 22, v1
	v_add_u32_e32 v1, v0, v1
	v_and_b32_e32 v1, 0xfffffc00, v1
	v_sub_u32_e32 v0, v0, v1
	v_lshrrev_b32_e32 v1, 4, v0
	v_ashrrev_i32_e32 v3, 31, v14
	v_bitop3_b32 v0, v1, v0, 32 bitop3:0x6c
	v_lshrrev_b32_e32 v3, 26, v3
	v_ashrrev_i32_e32 v1, 31, v0
	v_add_u32_e32 v3, v14, v3
	v_lshrrev_b32_e32 v1, 26, v1
	v_ashrrev_i32_e32 v12, 6, v3
	v_add_u32_e32 v1, v0, v1
	v_lshlrev_b32_e32 v3, 3, v12
	s_addc_u32 s47, s25, 0
	v_ashrrev_i32_e32 v11, 6, v1
	v_and_b32_e32 v3, -16, v3
	s_add_u32 s48, s26, 0x200000
	v_add_u32_e32 v3, v11, v3
	v_and_b32_e32 v4, 3, v11
	s_addc_u32 s49, s27, 0
	v_and_or_b32 v4, v3, s24, v4
	s_lshr_b32 s24, s33, 29
	s_add_i32 s24, s2, s24
	s_ashr_i32 s25, s30, 6
	s_ashr_i32 s26, s24, 3
	s_and_b32 s24, s24, -8
	s_ashr_i32 s31, s30, 8
	s_lshl_b32 s50, s25, 10
	s_sub_i32 s24, s2, s24
	s_cmp_lt_i32 s24, 0
	s_movk_i32 s51, 0x241
	s_cselect_b32 s27, s51, 0x240
	s_mul_i32 s24, s24, s27
	s_add_i32 s24, s24, s26
	s_mul_hi_i32 s26, s24, 0x38e38e39
	s_lshr_b32 s27, s26, 31
	s_ashr_i32 s26, s26, 5
	s_add_i32 s26, s26, s27
	s_lshl_b32 s27, s26, 2
	s_mulk_i32 s26, 0x90
	s_sub_i32 s26, s24, s26
	s_sext_i32_i16 s24, s26
	s_bfe_u32 s24, s24, 0x2001d
	s_add_i32 s28, s26, s24
	s_sext_i32_i16 s24, s28
	s_and_b32 s28, s28, 0xfffc
	s_sub_i32 s26, s26, s28
	s_sext_i32_i16 s26, s26
	v_lshrrev_b32_e32 v5, 2, v3
	v_lshlrev_b32_e32 v6, 1, v3
	v_and_b32_e32 v1, 0xc0, v1
	s_lshr_b32 s24, s24, 2
	s_add_i32 s36, s27, s26
	v_and_b32_e32 v5, 4, v5
	v_and_b32_e32 v6, 24, v6
	v_sub_u32_e32 v0, v0, v1
	s_ashr_i32 s37, s36, 31
	s_bfe_i64 s[28:29], s[24:25], 0x100000
	v_or3_b32 v4, v4, v5, v6
	v_lshlrev_b32_e32 v5, 5, v12
	v_ashrrev_i16_sdwa v0, v2, sext(v0) dst_sel:DWORD dst_unused:UNUSED_PAD src0_sel:DWORD src1_sel:BYTE_0
	s_lshl_b64 s[26:27], s[36:37], 20
	s_lshl_b64 s[28:29], s[28:29], 20
	v_and_b32_e32 v5, 32, v5
	v_bfe_i32 v13, v0, 0, 16
	s_add_u32 s42, s48, s28
	v_add_lshl_u32 v0, v5, v13, 1
	s_addc_u32 s43, s49, s29
	s_add_i32 s52, s50, 0
	v_lshl_add_u32 v148, v4, 12, v0
	s_add_i32 m0, s52, 0x10000
	v_lshl_add_u32 v150, v3, 12, v0
	global_load_lds_dwordx4 v148, s[42:43]
	s_add_i32 m0, s52, 0x12000
	s_add_u32 s28, s42, 0x80000
	global_load_lds_dwordx4 v144, s[42:43]
	s_addc_u32 s29, s43, 0
	s_add_i32 m0, s52, 0x14000
	v_mov_b32_e32 v153, 0
	global_load_lds_dwordx4 v148, s[28:29]
	s_add_i32 m0, s52, 0x16000
	s_add_u32 s40, s13, s26
	s_addc_u32 s41, s47, s27
	s_add_i32 s53, s52, 0x2000
	global_load_lds_dwordx4 v144, s[28:29]
	s_mov_b32 m0, s52
	s_add_u32 s26, s40, 0x80000
	global_load_lds_dwordx4 v150, s[40:41]
	s_mov_b32 m0, s53
	s_addc_u32 s27, s41, 0
	s_add_i32 s54, s52, 0x4000
	global_load_lds_dwordx4 v146, s[40:41]
	s_mov_b32 m0, s54
	s_add_i32 s55, s52, 0x6000
	global_load_lds_dwordx4 v150, s[26:27]
	s_mov_b32 m0, s55
	v_mov_b32_e32 v149, v153
	global_load_lds_dwordx4 v146, s[26:27]
	s_load_dwordx2 s[28:29], s[14:15], 0xc8
	s_nop 0
	s_load_dwordx2 s[14:15], s[16:17], 0xc8
	s_load_dwordx2 s[26:27], s[18:19], 0xc8
	s_nop 0
	s_load_dwordx2 s[20:21], s[20:21], 0xc8
	s_nop 0
	s_load_dwordx2 s[16:17], s[22:23], 0x98
	v_mov_b32_e32 v145, v153
	v_mov_b32_e32 v151, v153
	v_mov_b32_e32 v147, v153
	s_cmp_eq_u32 s31, 1
	v_lshl_add_u64 v[6:7], s[42:43], 0, v[148:149]
	v_lshl_add_u64 v[2:3], s[42:43], 0, v[144:145]
	v_lshl_add_u64 v[0:1], s[40:41], 0, v[150:151]
	s_cselect_b64 s[18:19], -1, 0
	s_cmp_lg_u32 s31, 1
	v_lshl_add_u64 v[4:5], s[40:41], 0, v[146:147]
	s_cbranch_scc1 .LBB0_165
	s_barrier

; #define PG8_STAGE(bufoff, gbase, voff) do { _Pragma("unroll") for (int _i = 0; _i < 2; ++_i) \
;         __builtin_amdgcn_global_load_lds((const unsigned*)((const char*)(gbase) + (voff)[_i]), (PG8_LAS unsigned*)(lds + (bufoff) + ldsw + _i * 8192), 16, 0, 0); } while (0)
; #define PG8_LDA(dst, b, h) do { _Pragma("unroll") for (int m = 0; m < 4; ++m) _Pragma("unroll") for (int k = 0; k < 2; ++k) dst[m][k] = *(const PG8_LAS bf16x8*)(lds + PG8_SA(b, h) + aoff + m * 2048 + k * 1024); } while (0)
; #define PG8_LDB(dst, b, h) do { _Pragma("unroll") for (int n = 0; n < 2; ++n) _Pragma("unroll") for (int k = 0; k < 2; ++k) dst[n][k] = *(const PG8_LAS bf16x8*)(lds + PG8_SB(b, h) + boff + n * 2048 + k * 1024); } while (0)
; #define PG8_WAIT_V(n) asm volatile("s_waitcnt vmcnt(" #n ")" ::: "memory")
; #define PG8_WAIT_L(n) asm volatile("s_waitcnt lgkmcnt(" #n ")" ::: "memory")
; #define PG8_BAR __builtin_amdgcn_s_barrier()
; #define PG8_SCHED __builtin_amdgcn_sched_barrier(0)
; template <class Epi, class Sched, bool ALIGN_EPI = false, bool SP2 = false>
; __device__ __forceinline__ void gemm_phase(PG8_LAS unsigned char* lds, const Gemm g, const Sched& S, const Epi& E) {
;     ...
;         const bool has_next = S.next(ui + 1, nxt);
;         const char* nA = has_next ? (const char*)g.A + (size_t)nxt.pm * tstep : cA; const char* nB = has_next ? (const char*)g.Bt + (size_t)nxt.pn * tstep : cB;
;         for (int t = 0; t < nt; t += 2) {
;             const bool last = (t == nt - 2);
;             const char* a1 = cA + (size_t)(t + 1) * kstep;
;             const char* a2 = last ? nA : cA + (size_t)(t + 2) * kstep; const char* b2 = last ? nB : cB + (size_t)(t + 2) * kstep;
;             const char* a3 = a2 + kstep; const char* b3 = b2 + kstep;
;             if (last && has_next) S.a_ready(nxt);
;             if constexpr (SP2) {
;             PG8_LDB(B0, 0, 0); PG8_LDB(B1, 0, 1); PG8_SCHED; PG8_LDA(At, 0, 0); PG8_STAGE(PG8_SA(1, 1), a1 + hstep, voffA);
;             PG8_WAIT_V(8); PG8_WAIT_L(0); PG8_BAR; PG8_MMA(0, 0, At, B0); PG8_MMA(0, 1, At, B1); PG8_BAR; PG8_SCHED;
;             PG8_LDA(At, 0, 1); PG8_STAGE(PG8_SB(0, 0), b2, voffB); PG8_STAGE(PG8_SB(0, 1), b2 + hstep, voffB); PG8_STAGE(PG8_SA(0, 0), a2, voffA);
;             PG8_WAIT_V(8); PG8_WAIT_L(0); PG8_BAR; PG8_MMA(1, 0, At, B0); PG8_MMA(1, 1, At, B1); PG8_BAR; PG8_SCHED;
.LBB0_170:
	s_ashr_i32 s29, s28, 31
	s_lshl_b64 s[30:31], s[28:29], 20
	s_add_u32 s30, s13, s30
	s_addc_u32 s31, s47, s31
	s_and_b64 s[34:35], s[38:39], exec
	s_cselect_b32 s29, s31, s41
	s_cselect_b32 s37, s30, s40
	s_ashr_i32 s27, s26, 31
	s_lshl_b64 s[34:35], s[26:27], 20
	s_add_u32 s34, s48, s34
	s_addc_u32 s35, s49, s35
	s_and_b64 s[44:45], s[38:39], exec
	s_cselect_b32 s27, s35, s43
	s_cselect_b32 s65, s34, s42
	s_add_u32 s40, s40, 0x80080
	s_addc_u32 s41, s41, 0
	s_add_u32 s67, s42, 0x100
	s_addc_u32 s68, s43, 0
	s_mov_b32 s69, -2
	ds_read_b128 v[128:131], v175
	ds_read_b128 v[132:135], v175 offset:1024
	ds_read_b128 v[136:139], v175 offset:2048
	ds_read_b128 v[140:143], v175 offset:3072
	ds_read_b128 v[164:167], v176
	ds_read_b128 v[168:171], v176 offset:1024
	ds_read_b128 v[178:181], v176 offset:2048
	ds_read_b128 v[182:185], v176 offset:3072
	s_add_u32 s42, s40, 0xfff80080
	s_addc_u32 s43, s41, -1
	s_cmp_eq_u32 s69, 28
	s_cselect_b32 s45, s29, s43
	s_cselect_b32 s44, s37, s42
	s_cselect_b32 s43, s27, s68
	s_cselect_b32 s42, s65, s67
	v_lshl_add_u64 v[190:191], s[40:41], 0, v[156:157]
	s_add_i32 m0, s52, 0xc000
	ds_read_b128 v[186:189], v177
	ds_read_b128 v[194:197], v177 offset:1024
	ds_read_b128 v[198:201], v177 offset:2048
	ds_read_b128 v[202:205], v177 offset:3072
	ds_read_b128 v[206:209], v177 offset:4096
	ds_read_b128 v[210:213], v177 offset:5120
	ds_read_b128 v[218:221], v177 offset:6144
	ds_read_b128 v[222:225], v177 offset:7168
	global_load_lds_dwordx4 v[190:191], off
	v_lshl_add_u64 v[190:191], s[40:41], 0, v[158:159]
	s_add_i32 m0, s52, 0xe000
	s_nop 0
	global_load_lds_dwordx4 v[190:191], off
	s_waitcnt vmcnt(8)
	s_waitcnt lgkmcnt(0)
	s_barrier
	s_setprio 1
	s_waitcnt lgkmcnt(0)
	v_mfma_f32_16x16x32_bf16 v[124:127], v[128:131], v[186:189], 0
	v_mfma_f32_16x16x32_bf16 v[120:123], v[136:139], v[186:189], 0
	v_mfma_f32_16x16x32_bf16 v[116:119], v[128:131], v[198:201], 0
	v_mfma_f32_16x16x32_bf16 v[112:115], v[136:139], v[198:201], 0
	v_mfma_f32_16x16x32_bf16 v[100:103], v[128:131], v[206:209], 0
	v_mfma_f32_16x16x32_bf16 v[96:99], v[136:139], v[206:209], 0
	v_mfma_f32_16x16x32_bf16 v[84:87], v[128:131], v[218:221], 0
	v_mfma_f32_16x16x32_bf16 v[80:83], v[136:139], v[218:221], 0
	v_mfma_f32_16x16x32_bf16 v[124:127], v[132:135], v[194:197], v[124:127]
	v_mfma_f32_16x16x32_bf16 v[120:123], v[140:143], v[194:197], v[120:123]
	v_mfma_f32_16x16x32_bf16 v[116:119], v[132:135], v[202:205], v[116:119]
	v_mfma_f32_16x16x32_bf16 v[112:115], v[140:143], v[202:205], v[112:115]
	v_mfma_f32_16x16x32_bf16 v[100:103], v[132:135], v[210:213], v[100:103]
	v_mfma_f32_16x16x32_bf16 v[96:99], v[140:143], v[210:213], v[96:99]
	v_mfma_f32_16x16x32_bf16 v[84:87], v[132:135], v[222:225], v[84:87]
	v_mfma_f32_16x16x32_bf16 v[80:83], v[140:143], v[222:225], v[80:83]
	v_mfma_f32_16x16x32_bf16 v[108:111], v[164:167], v[186:189], 0
	v_mfma_f32_16x16x32_bf16 v[104:107], v[178:181], v[186:189], 0
	v_mfma_f32_16x16x32_bf16 v[92:95], v[164:167], v[198:201], 0
	v_mfma_f32_16x16x32_bf16 v[88:91], v[178:181], v[198:201], 0
	v_mfma_f32_16x16x32_bf16 v[76:79], v[164:167], v[206:209], 0
	v_mfma_f32_16x16x32_bf16 v[72:75], v[178:181], v[206:209], 0
	v_mfma_f32_16x16x32_bf16 v[68:71], v[164:167], v[218:221], 0
	v_mfma_f32_16x16x32_bf16 v[64:67], v[178:181], v[218:221], 0
	v_mfma_f32_16x16x32_bf16 v[108:111], v[168:171], v[194:197], v[108:111]
	v_mfma_f32_16x16x32_bf16 v[104:107], v[182:185], v[194:197], v[104:107]
	v_mfma_f32_16x16x32_bf16 v[92:95], v[168:171], v[202:205], v[92:95]
	v_mfma_f32_16x16x32_bf16 v[88:91], v[182:185], v[202:205], v[88:91]
	v_mfma_f32_16x16x32_bf16 v[76:79], v[168:171], v[210:213], v[76:79]
	v_mfma_f32_16x16x32_bf16 v[72:75], v[182:185], v[210:213], v[72:75]
	v_mfma_f32_16x16x32_bf16 v[68:71], v[168:171], v[222:225], v[68:71]
	v_mfma_f32_16x16x32_bf16 v[64:67], v[182:185], v[222:225], v[64:67]
	s_setprio 0
	s_barrier
	s_add_i32 s70, s61, s50
	v_lshl_add_u64 v[190:191], s[42:43], 0, v[148:149]
	s_mov_b32 m0, s70
	ds_read_b128 v[186:189], v177 offset:16384
	ds_read_b128 v[194:197], v177 offset:17408
	ds_read_b128 v[198:201], v177 offset:18432
	ds_read_b128 v[202:205], v177 offset:19456
	ds_read_b128 v[206:209], v177 offset:20480
	ds_read_b128 v[210:213], v177 offset:21504
	ds_read_b128 v[218:221], v177 offset:22528
	ds_read_b128 v[222:225], v177 offset:23552
	global_load_lds_dwordx4 v[190:191], off
	s_add_i32 m0, s70, 0x2000
	s_add_u32 s70, s42, 0x80000
	v_lshl_add_u64 v[214:215], s[42:43], 0, v[144:145]
	s_addc_u32 s71, s43, 0
	s_add_i32 s72, s62, s50
	global_load_lds_dwordx4 v[214:215], off
	v_lshl_add_u64 v[226:227], s[70:71], 0, v[148:149]
	s_mov_b32 m0, s72
	v_lshl_add_u64 v[228:229], s[44:45], 0, v[146:147]
	global_load_lds_dwordx4 v[226:227], off
	v_lshl_add_u64 v[226:227], s[70:71], 0, v[144:145]
	s_add_i32 m0, s72, 0x2000
	s_nop 0
	global_load_lds_dwordx4 v[226:227], off
	v_lshl_add_u64 v[226:227], s[44:45], 0, v[150:151]
	s_mov_b32 m0, s52
	s_nop 0
	global_load_lds_dwordx4 v[226:227], off
	s_mov_b32 m0, s53
	s_nop 0
	global_load_lds_dwordx4 v[228:229], off
	s_waitcnt vmcnt(8)
	s_waitcnt lgkmcnt(0)
	s_barrier
; #define PG8_STAGE(bufoff, gbase, voff) do { _Pragma("unroll") for (int _i = 0; _i < 2; ++_i) \
;         __builtin_amdgcn_global_load_lds((const unsigned*)((const char*)(gbase) + (voff)[_i]), (PG8_LAS unsigned*)(lds + (bufoff) + ldsw + _i * 8192), 16, 0, 0); } while (0)
; #define PG8_LDA(dst, b, h) do { _Pragma("unroll") for (int m = 0; m < 4; ++m) _Pragma("unroll") for (int k = 0; k < 2; ++k) dst[m][k] = *(const PG8_LAS bf16x8*)(lds + PG8_SA(b, h) + aoff + m * 2048 + k * 1024); } while (0)
; #define PG8_LDB(dst, b, h) do { _Pragma("unroll") for (int n = 0; n < 2; ++n) _Pragma("unroll") for (int k = 0; k < 2; ++k) dst[n][k] = *(const PG8_LAS bf16x8*)(lds + PG8_SB(b, h) + boff + n * 2048 + k * 1024); } while (0)
; #define PG8_MMA(ai, bj, At, Bt) do { __builtin_amdgcn_s_setprio(1); _Pragma("unroll") for (int m = 0; m < 4; ++m) _Pragma("unroll") for (int n = 0; n < 2; ++n) _Pragma("unroll") for (int k = 0; k < 2; ++k) \
;         acc[ai][bj][m][n] = __builtin_amdgcn_mfma_f32_16x16x32_bf16(Bt[n][k], At[m][k], acc[ai][bj][m][n], 0, 0, 0); __builtin_amdgcn_s_setprio(0); } while (0)
; #define PG8_WAIT_V(n) asm volatile("s_waitcnt vmcnt(" #n ")" ::: "memory")
; #define PG8_WAIT_L(n) asm volatile("s_waitcnt lgkmcnt(" #n ")" ::: "memory")
; #define PG8_BAR __builtin_amdgcn_s_barrier()
; #define PG8_SCHED __builtin_amdgcn_sched_barrier(0)
; template <class Epi, class Sched, bool ALIGN_EPI = false, bool SP2 = false>
; __device__ __forceinline__ void gemm_phase(PG8_LAS unsigned char* lds, const Gemm g, const Sched& S, const Epi& E) {
;     ...
;             PG8_WAIT_V(8); PG8_WAIT_L(0); PG8_BAR; PG8_MMA(1, 0, At, B0); PG8_MMA(1, 1, At, B1); PG8_BAR; PG8_SCHED;
;             PG8_LDB(B0, 1, 0); PG8_LDB(B1, 1, 1); PG8_SCHED; PG8_LDA(At, 1, 0); PG8_STAGE(PG8_SA(0, 1), a2 + hstep, voffA);
;             PG8_WAIT_V(8); PG8_WAIT_L(0); PG8_BAR; PG8_MMA(0, 0, At, B0); PG8_MMA(0, 1, At, B1); PG8_BAR; PG8_SCHED;
	s_setprio 1
	s_waitcnt lgkmcnt(0)
	v_mfma_f32_16x16x32_bf16 v[60:63], v[128:131], v[186:189], 0
	v_mfma_f32_16x16x32_bf16 v[56:59], v[136:139], v[186:189], 0
	v_mfma_f32_16x16x32_bf16 v[52:55], v[128:131], v[198:201], 0
	v_mfma_f32_16x16x32_bf16 v[48:51], v[136:139], v[198:201], 0
	v_mfma_f32_16x16x32_bf16 v[36:39], v[128:131], v[206:209], 0
	v_mfma_f32_16x16x32_bf16 v[32:35], v[136:139], v[206:209], 0
	v_mfma_f32_16x16x32_bf16 v[20:23], v[128:131], v[218:221], 0
	v_mfma_f32_16x16x32_bf16 v[16:19], v[136:139], v[218:221], 0
	v_mfma_f32_16x16x32_bf16 v[60:63], v[132:135], v[194:197], v[60:63]
	v_mfma_f32_16x16x32_bf16 v[56:59], v[140:143], v[194:197], v[56:59]
	v_mfma_f32_16x16x32_bf16 v[52:55], v[132:135], v[202:205], v[52:55]
	v_mfma_f32_16x16x32_bf16 v[48:51], v[140:143], v[202:205], v[48:51]
	v_mfma_f32_16x16x32_bf16 v[36:39], v[132:135], v[210:213], v[36:39]
	v_mfma_f32_16x16x32_bf16 v[32:35], v[140:143], v[210:213], v[32:35]
	v_mfma_f32_16x16x32_bf16 v[20:23], v[132:135], v[222:225], v[20:23]
	v_mfma_f32_16x16x32_bf16 v[16:19], v[140:143], v[222:225], v[16:19]
	v_mfma_f32_16x16x32_bf16 v[44:47], v[164:167], v[186:189], 0
	v_mfma_f32_16x16x32_bf16 v[40:43], v[178:181], v[186:189], 0
	v_mfma_f32_16x16x32_bf16 v[28:31], v[164:167], v[198:201], 0
	v_mfma_f32_16x16x32_bf16 v[24:27], v[178:181], v[198:201], 0
	v_mfma_f32_16x16x32_bf16 v[12:15], v[164:167], v[206:209], 0
	v_mfma_f32_16x16x32_bf16 v[8:11], v[178:181], v[206:209], 0
	v_mfma_f32_16x16x32_bf16 v[4:7], v[164:167], v[218:221], 0
	v_mfma_f32_16x16x32_bf16 v[0:3], v[178:181], v[218:221], 0
	v_mfma_f32_16x16x32_bf16 v[44:47], v[168:171], v[194:197], v[44:47]
	v_mfma_f32_16x16x32_bf16 v[40:43], v[182:185], v[194:197], v[40:43]
	v_mfma_f32_16x16x32_bf16 v[28:31], v[168:171], v[202:205], v[28:31]
	v_mfma_f32_16x16x32_bf16 v[24:27], v[182:185], v[202:205], v[24:27]
	v_mfma_f32_16x16x32_bf16 v[12:15], v[168:171], v[210:213], v[12:15]
	v_mfma_f32_16x16x32_bf16 v[8:11], v[182:185], v[210:213], v[8:11]
	v_mfma_f32_16x16x32_bf16 v[4:7], v[168:171], v[222:225], v[4:7]
	v_mfma_f32_16x16x32_bf16 v[0:3], v[182:185], v[222:225], v[0:3]
	s_setprio 0
	s_barrier
	s_add_i32 s70, 0, 0x18000
	s_add_i32 s71, 0, 0x1c000
	v_add_u32_e32 v140, s70, v173
	v_add_u32_e32 v182, s71, v173
	ds_read_b128 v[128:131], v140
	ds_read_b128 v[132:135], v140 offset:1024
	ds_read_b128 v[136:139], v140 offset:2048
	ds_read_b128 v[140:143], v140 offset:3072
	ds_read_b128 v[164:167], v182
	ds_read_b128 v[168:171], v182 offset:1024
	ds_read_b128 v[178:181], v182 offset:2048
	ds_read_b128 v[182:185], v182 offset:3072
	s_add_u32 s44, s44, 0x80000
	s_addc_u32 s45, s45, 0
	s_mov_b32 m0, s54
	v_lshl_add_u64 v[230:231], s[44:45], 0, v[150:151]
	ds_read_b128 v[186:189], v177 offset:32768
	ds_read_b128 v[194:197], v177 offset:33792
	ds_read_b128 v[198:201], v177 offset:34816
	ds_read_b128 v[202:205], v177 offset:35840
	ds_read_b128 v[206:209], v177 offset:36864
	ds_read_b128 v[210:213], v177 offset:37888
	ds_read_b128 v[218:221], v177 offset:38912
	ds_read_b128 v[222:225], v177 offset:39936
	global_load_lds_dwordx4 v[230:231], off
	v_lshl_add_u64 v[230:231], s[44:45], 0, v[146:147]
	s_mov_b32 m0, s55
	s_nop 0
	global_load_lds_dwordx4 v[230:231], off
	s_waitcnt vmcnt(8)
	s_waitcnt lgkmcnt(0)
	s_barrier
	s_setprio 1
	s_waitcnt lgkmcnt(0)
	v_mfma_f32_16x16x32_bf16 v[124:127], v[128:131], v[186:189], v[124:127]
	v_mfma_f32_16x16x32_bf16 v[120:123], v[136:139], v[186:189], v[120:123]
	v_mfma_f32_16x16x32_bf16 v[116:119], v[128:131], v[198:201], v[116:119]
	v_mfma_f32_16x16x32_bf16 v[112:115], v[136:139], v[198:201], v[112:115]
	v_mfma_f32_16x16x32_bf16 v[100:103], v[128:131], v[206:209], v[100:103]
	v_mfma_f32_16x16x32_bf16 v[96:99], v[136:139], v[206:209], v[96:99]
	v_mfma_f32_16x16x32_bf16 v[84:87], v[128:131], v[218:221], v[84:87]
	v_mfma_f32_16x16x32_bf16 v[80:83], v[136:139], v[218:221], v[80:83]
	v_mfma_f32_16x16x32_bf16 v[124:127], v[132:135], v[194:197], v[124:127]
	v_mfma_f32_16x16x32_bf16 v[120:123], v[140:143], v[194:197], v[120:123]
	v_mfma_f32_16x16x32_bf16 v[116:119], v[132:135], v[202:205], v[116:119]
	v_mfma_f32_16x16x32_bf16 v[112:115], v[140:143], v[202:205], v[112:115]
	v_mfma_f32_16x16x32_bf16 v[100:103], v[132:135], v[210:213], v[100:103]
	v_mfma_f32_16x16x32_bf16 v[96:99], v[140:143], v[210:213], v[96:99]
	v_mfma_f32_16x16x32_bf16 v[84:87], v[132:135], v[222:225], v[84:87]
	v_mfma_f32_16x16x32_bf16 v[80:83], v[140:143], v[222:225], v[80:83]
	v_mfma_f32_16x16x32_bf16 v[108:111], v[164:167], v[186:189], v[108:111]
	v_mfma_f32_16x16x32_bf16 v[104:107], v[178:181], v[186:189], v[104:107]
	v_mfma_f32_16x16x32_bf16 v[92:95], v[164:167], v[198:201], v[92:95]
	v_mfma_f32_16x16x32_bf16 v[88:91], v[178:181], v[198:201], v[88:91]
	v_mfma_f32_16x16x32_bf16 v[76:79], v[164:167], v[206:209], v[76:79]
	v_mfma_f32_16x16x32_bf16 v[72:75], v[178:181], v[206:209], v[72:75]
	v_mfma_f32_16x16x32_bf16 v[68:71], v[164:167], v[218:221], v[68:71]
	v_mfma_f32_16x16x32_bf16 v[64:67], v[178:181], v[218:221], v[64:67]
	v_mfma_f32_16x16x32_bf16 v[108:111], v[168:171], v[194:197], v[108:111]
	v_mfma_f32_16x16x32_bf16 v[104:107], v[182:185], v[194:197], v[104:107]
	v_mfma_f32_16x16x32_bf16 v[92:95], v[168:171], v[202:205], v[92:95]
	v_mfma_f32_16x16x32_bf16 v[88:91], v[182:185], v[202:205], v[88:91]
	v_mfma_f32_16x16x32_bf16 v[76:79], v[168:171], v[210:213], v[76:79]
	v_mfma_f32_16x16x32_bf16 v[72:75], v[182:185], v[210:213], v[72:75]
	v_mfma_f32_16x16x32_bf16 v[68:71], v[168:171], v[222:225], v[68:71]
	v_mfma_f32_16x16x32_bf16 v[64:67], v[182:185], v[222:225], v[64:67]
	s_setprio 0
	s_barrier
; #define PG8_STAGE(bufoff, gbase, voff) do { _Pragma("unroll") for (int _i = 0; _i < 2; ++_i) \
;         __builtin_amdgcn_global_load_lds((const unsigned*)((const char*)(gbase) + (voff)[_i]), (PG8_LAS unsigned*)(lds + (bufoff) + ldsw + _i * 8192), 16, 0, 0); } while (0)
; #define PG8_LDA(dst, b, h) do { _Pragma("unroll") for (int m = 0; m < 4; ++m) _Pragma("unroll") for (int k = 0; k < 2; ++k) dst[m][k] = *(const PG8_LAS bf16x8*)(lds + PG8_SA(b, h) + aoff + m * 2048 + k * 1024); } while (0)
; #define PG8_LDB(dst, b, h) do { _Pragma("unroll") for (int n = 0; n < 2; ++n) _Pragma("unroll") for (int k = 0; k < 2; ++k) dst[n][k] = *(const PG8_LAS bf16x8*)(lds + PG8_SB(b, h) + boff + n * 2048 + k * 1024); } while (0)
; #define PG8_MMA(ai, bj, At, Bt) do { __builtin_amdgcn_s_setprio(1); _Pragma("unroll") for (int m = 0; m < 4; ++m) _Pragma("unroll") for (int n = 0; n < 2; ++n) _Pragma("unroll") for (int k = 0; k < 2; ++k) \
;         acc[ai][bj][m][n] = __builtin_amdgcn_mfma_f32_16x16x32_bf16(Bt[n][k], At[m][k], acc[ai][bj][m][n], 0, 0, 0); __builtin_amdgcn_s_setprio(0); } while (0)
; #define PG8_WAIT_V(n) asm volatile("s_waitcnt vmcnt(" #n ")" ::: "memory")
; template <class Epi, class Sched, bool ALIGN_EPI = false, bool SP2 = false>
; __device__ __forceinline__ void gemm_phase(PG8_LAS unsigned char* lds, const Gemm g, const Sched& S, const Epi& E) {
;     ...
;             PG8_LDB(B0, 0, 0); PG8_LDB(B1, 0, 1); PG8_SCHED; PG8_LDA(At, 0, 0); PG8_STAGE(PG8_SA(1, 1), a1 + hstep, voffA);
;             PG8_WAIT_V(8); PG8_WAIT_L(0); PG8_BAR; PG8_MMA(0, 0, At, B0); PG8_MMA(0, 1, At, B1); PG8_BAR; PG8_SCHED;
;             PG8_LDA(At, 0, 1); PG8_STAGE(PG8_SB(0, 0), b2, voffB); PG8_STAGE(PG8_SB(0, 1), b2 + hstep, voffB); PG8_STAGE(PG8_SA(0, 0), a2, voffA);
;             PG8_WAIT_V(8); PG8_WAIT_L(0); PG8_BAR; PG8_MMA(1, 0, At, B0); PG8_MMA(1, 1, At, B1); PG8_BAR; PG8_SCHED;
;             PG8_LDB(B0, 1, 0); PG8_LDB(B1, 1, 1); PG8_SCHED; PG8_LDA(At, 1, 0); PG8_STAGE(PG8_SA(0, 1), a2 + hstep, voffA);
;             PG8_WAIT_V(8); PG8_WAIT_L(0); PG8_BAR; PG8_MMA(0, 0, At, B0); PG8_MMA(0, 1, At, B1); PG8_BAR; PG8_SCHED;
;             PG8_LDA(At, 1, 1); PG8_STAGE(PG8_SB(1, 0), b3, voffB); PG8_STAGE(PG8_SB(1, 1), b3 + hstep, voffB); PG8_STAGE(PG8_SA(1, 0), a3, voffA);
;             PG8_WAIT_V(8); PG8_WAIT_L(0); PG8_BAR; PG8_MMA(1, 0, At, B0); PG8_MMA(1, 1, At, B1); PG8_BAR; PG8_SCHED;
	s_add_i32 s44, s70, s50
	v_lshl_add_u64 v[190:191], v[190:191], 0, s[22:23]
	s_mov_b32 m0, s44
	ds_read_b128 v[186:189], v177 offset:49152
	ds_read_b128 v[194:197], v177 offset:50176
	ds_read_b128 v[198:201], v177 offset:51200
	ds_read_b128 v[202:205], v177 offset:52224
	ds_read_b128 v[206:209], v177 offset:53248
	ds_read_b128 v[210:213], v177 offset:54272
	ds_read_b128 v[218:221], v177 offset:55296
	ds_read_b128 v[222:225], v177 offset:56320
	global_load_lds_dwordx4 v[190:191], off
	s_add_i32 m0, s44, 0x2000
	s_add_u32 s42, s42, 0x80080
	v_lshl_add_u64 v[190:191], v[214:215], 0, s[22:23]
	s_addc_u32 s43, s43, 0
	s_add_i32 s44, s71, s50
	global_load_lds_dwordx4 v[190:191], off
	v_lshl_add_u64 v[190:191], s[42:43], 0, v[148:149]
	s_mov_b32 m0, s44
	s_nop 0
	global_load_lds_dwordx4 v[190:191], off
	v_lshl_add_u64 v[190:191], s[42:43], 0, v[144:145]
	s_add_i32 m0, s44, 0x2000
	s_nop 0
	global_load_lds_dwordx4 v[190:191], off
	v_lshl_add_u64 v[190:191], v[226:227], 0, s[22:23]
	s_mov_b32 m0, s59
	s_nop 0
	global_load_lds_dwordx4 v[190:191], off
	v_lshl_add_u64 v[190:191], v[228:229], 0, s[22:23]
	s_mov_b32 m0, s60
	s_nop 0
	global_load_lds_dwordx4 v[190:191], off
	s_waitcnt vmcnt(8)
	s_waitcnt lgkmcnt(0)
	s_barrier
	s_setprio 1
	s_waitcnt lgkmcnt(0)
	v_mfma_f32_16x16x32_bf16 v[60:63], v[128:131], v[186:189], v[60:63]
	v_mfma_f32_16x16x32_bf16 v[56:59], v[136:139], v[186:189], v[56:59]
	v_mfma_f32_16x16x32_bf16 v[52:55], v[128:131], v[198:201], v[52:55]
	v_mfma_f32_16x16x32_bf16 v[48:51], v[136:139], v[198:201], v[48:51]
	v_mfma_f32_16x16x32_bf16 v[36:39], v[128:131], v[206:209], v[36:39]
	v_mfma_f32_16x16x32_bf16 v[32:35], v[136:139], v[206:209], v[32:35]
	v_mfma_f32_16x16x32_bf16 v[20:23], v[128:131], v[218:221], v[20:23]
	v_mfma_f32_16x16x32_bf16 v[16:19], v[136:139], v[218:221], v[16:19]
	v_mfma_f32_16x16x32_bf16 v[60:63], v[132:135], v[194:197], v[60:63]
	v_mfma_f32_16x16x32_bf16 v[56:59], v[140:143], v[194:197], v[56:59]
	v_mfma_f32_16x16x32_bf16 v[52:55], v[132:135], v[202:205], v[52:55]
	v_mfma_f32_16x16x32_bf16 v[48:51], v[140:143], v[202:205], v[48:51]
	v_mfma_f32_16x16x32_bf16 v[36:39], v[132:135], v[210:213], v[36:39]
	v_mfma_f32_16x16x32_bf16 v[32:35], v[140:143], v[210:213], v[32:35]
	v_mfma_f32_16x16x32_bf16 v[20:23], v[132:135], v[222:225], v[20:23]
	v_mfma_f32_16x16x32_bf16 v[16:19], v[140:143], v[222:225], v[16:19]
	v_mfma_f32_16x16x32_bf16 v[44:47], v[164:167], v[186:189], v[44:47]
	v_mfma_f32_16x16x32_bf16 v[40:43], v[178:181], v[186:189], v[40:43]
	v_mfma_f32_16x16x32_bf16 v[28:31], v[164:167], v[198:201], v[28:31]
	v_mfma_f32_16x16x32_bf16 v[24:27], v[178:181], v[198:201], v[24:27]
	v_mfma_f32_16x16x32_bf16 v[12:15], v[164:167], v[206:209], v[12:15]
	v_mfma_f32_16x16x32_bf16 v[8:11], v[178:181], v[206:209], v[8:11]
	v_mfma_f32_16x16x32_bf16 v[4:7], v[164:167], v[218:221], v[4:7]
	v_mfma_f32_16x16x32_bf16 v[0:3], v[178:181], v[218:221], v[0:3]
	v_mfma_f32_16x16x32_bf16 v[44:47], v[168:171], v[194:197], v[44:47]
	v_mfma_f32_16x16x32_bf16 v[40:43], v[182:185], v[194:197], v[40:43]
	v_mfma_f32_16x16x32_bf16 v[28:31], v[168:171], v[202:205], v[28:31]
	v_mfma_f32_16x16x32_bf16 v[24:27], v[182:185], v[202:205], v[24:27]
	v_mfma_f32_16x16x32_bf16 v[12:15], v[168:171], v[210:213], v[12:15]
	v_mfma_f32_16x16x32_bf16 v[8:11], v[182:185], v[210:213], v[8:11]
	v_mfma_f32_16x16x32_bf16 v[4:7], v[168:171], v[222:225], v[4:7]
	v_mfma_f32_16x16x32_bf16 v[0:3], v[182:185], v[222:225], v[0:3]
	s_setprio 0
	s_barrier
	s_add_i32 s69, s69, 2
	s_add_u32 s40, s40, 0x100
	s_addc_u32 s41, s41, 0
	s_add_u32 s67, s67, 0x100
	s_addc_u32 s68, s68, 0
	s_cmp_gt_u32 s69, 29
.LBB0_171:
	ds_read_b128 v[128:131], v175
	ds_read_b128 v[132:135], v175 offset:1024
	ds_read_b128 v[136:139], v175 offset:2048
	ds_read_b128 v[140:143], v175 offset:3072
	ds_read_b128 v[164:167], v176
	ds_read_b128 v[168:171], v176 offset:1024
	ds_read_b128 v[178:181], v176 offset:2048
	ds_read_b128 v[182:185], v176 offset:3072
	s_add_u32 s42, s40, 0xfff80080
	s_addc_u32 s43, s41, -1
	s_cmp_eq_u32 s69, 28
	s_cselect_b32 s45, s29, s43
	s_cselect_b32 s44, s37, s42
	s_cselect_b32 s43, s27, s68
	s_cselect_b32 s42, s65, s67
	v_lshl_add_u64 v[190:191], s[40:41], 0, v[156:157]
	s_add_i32 m0, s52, 0xc000
	ds_read_b128 v[186:189], v177
	ds_read_b128 v[194:197], v177 offset:1024
	ds_read_b128 v[198:201], v177 offset:2048
	ds_read_b128 v[202:205], v177 offset:3072
	ds_read_b128 v[206:209], v177 offset:4096
	ds_read_b128 v[210:213], v177 offset:5120
	ds_read_b128 v[218:221], v177 offset:6144
	ds_read_b128 v[222:225], v177 offset:7168
	global_load_lds_dwordx4 v[190:191], off
	v_lshl_add_u64 v[190:191], s[40:41], 0, v[158:159]
	s_add_i32 m0, s52, 0xe000
	s_nop 0
	global_load_lds_dwordx4 v[190:191], off
	s_waitcnt vmcnt(8)
	s_waitcnt lgkmcnt(0)
	s_barrier
; #define PG8_STAGE(bufoff, gbase, voff) do { _Pragma("unroll") for (int _i = 0; _i < 2; ++_i) \
;         __builtin_amdgcn_global_load_lds((const unsigned*)((const char*)(gbase) + (voff)[_i]), (PG8_LAS unsigned*)(lds + (bufoff) + ldsw + _i * 8192), 16, 0, 0); } while (0)
; #define PG8_LDA(dst, b, h) do { _Pragma("unroll") for (int m = 0; m < 4; ++m) _Pragma("unroll") for (int k = 0; k < 2; ++k) dst[m][k] = *(const PG8_LAS bf16x8*)(lds + PG8_SA(b, h) + aoff + m * 2048 + k * 1024); } while (0)
; #define PG8_MMA(ai, bj, At, Bt) do { __builtin_amdgcn_s_setprio(1); _Pragma("unroll") for (int m = 0; m < 4; ++m) _Pragma("unroll") for (int n = 0; n < 2; ++n) _Pragma("unroll") for (int k = 0; k < 2; ++k) \
;         acc[ai][bj][m][n] = __builtin_amdgcn_mfma_f32_16x16x32_bf16(Bt[n][k], At[m][k], acc[ai][bj][m][n], 0, 0, 0); __builtin_amdgcn_s_setprio(0); } while (0)
; #define PG8_WAIT_V(n) asm volatile("s_waitcnt vmcnt(" #n ")" ::: "memory")
; #define PG8_WAIT_L(n) asm volatile("s_waitcnt lgkmcnt(" #n ")" ::: "memory")
; #define PG8_BAR __builtin_amdgcn_s_barrier()
; #define PG8_SCHED __builtin_amdgcn_sched_barrier(0)
; template <class Epi, class Sched, bool ALIGN_EPI = false, bool SP2 = false>
; __device__ __forceinline__ void gemm_phase(PG8_LAS unsigned char* lds, const Gemm g, const Sched& S, const Epi& E) {
;     ...
;             PG8_WAIT_V(8); PG8_WAIT_L(0); PG8_BAR; PG8_MMA(0, 0, At, B0); PG8_MMA(0, 1, At, B1); PG8_BAR; PG8_SCHED;
;             PG8_LDA(At, 0, 1); PG8_STAGE(PG8_SB(0, 0), b2, voffB); PG8_STAGE(PG8_SB(0, 1), b2 + hstep, voffB); PG8_STAGE(PG8_SA(0, 0), a2, voffA);
;             PG8_WAIT_V(8); PG8_WAIT_L(0); PG8_BAR; PG8_MMA(1, 0, At, B0); PG8_MMA(1, 1, At, B1); PG8_BAR; PG8_SCHED;
	s_setprio 1
	s_waitcnt lgkmcnt(0)
	v_mfma_f32_16x16x32_bf16 v[124:127], v[128:131], v[186:189], v[124:127]
	v_mfma_f32_16x16x32_bf16 v[120:123], v[136:139], v[186:189], v[120:123]
	v_mfma_f32_16x16x32_bf16 v[116:119], v[128:131], v[198:201], v[116:119]
	v_mfma_f32_16x16x32_bf16 v[112:115], v[136:139], v[198:201], v[112:115]
	v_mfma_f32_16x16x32_bf16 v[100:103], v[128:131], v[206:209], v[100:103]
	v_mfma_f32_16x16x32_bf16 v[96:99], v[136:139], v[206:209], v[96:99]
	v_mfma_f32_16x16x32_bf16 v[84:87], v[128:131], v[218:221], v[84:87]
	v_mfma_f32_16x16x32_bf16 v[80:83], v[136:139], v[218:221], v[80:83]
	v_mfma_f32_16x16x32_bf16 v[124:127], v[132:135], v[194:197], v[124:127]
	v_mfma_f32_16x16x32_bf16 v[120:123], v[140:143], v[194:197], v[120:123]
	v_mfma_f32_16x16x32_bf16 v[116:119], v[132:135], v[202:205], v[116:119]
	v_mfma_f32_16x16x32_bf16 v[112:115], v[140:143], v[202:205], v[112:115]
	v_mfma_f32_16x16x32_bf16 v[100:103], v[132:135], v[210:213], v[100:103]
	v_mfma_f32_16x16x32_bf16 v[96:99], v[140:143], v[210:213], v[96:99]
	v_mfma_f32_16x16x32_bf16 v[84:87], v[132:135], v[222:225], v[84:87]
	v_mfma_f32_16x16x32_bf16 v[80:83], v[140:143], v[222:225], v[80:83]
	v_mfma_f32_16x16x32_bf16 v[108:111], v[164:167], v[186:189], v[108:111]
	v_mfma_f32_16x16x32_bf16 v[104:107], v[178:181], v[186:189], v[104:107]
	v_mfma_f32_16x16x32_bf16 v[92:95], v[164:167], v[198:201], v[92:95]
	v_mfma_f32_16x16x32_bf16 v[88:91], v[178:181], v[198:201], v[88:91]
	v_mfma_f32_16x16x32_bf16 v[76:79], v[164:167], v[206:209], v[76:79]
	v_mfma_f32_16x16x32_bf16 v[72:75], v[178:181], v[206:209], v[72:75]
	v_mfma_f32_16x16x32_bf16 v[68:71], v[164:167], v[218:221], v[68:71]
	v_mfma_f32_16x16x32_bf16 v[64:67], v[178:181], v[218:221], v[64:67]
	v_mfma_f32_16x16x32_bf16 v[108:111], v[168:171], v[194:197], v[108:111]
	v_mfma_f32_16x16x32_bf16 v[104:107], v[182:185], v[194:197], v[104:107]
	v_mfma_f32_16x16x32_bf16 v[92:95], v[168:171], v[202:205], v[92:95]
	v_mfma_f32_16x16x32_bf16 v[88:91], v[182:185], v[202:205], v[88:91]
	v_mfma_f32_16x16x32_bf16 v[76:79], v[168:171], v[210:213], v[76:79]
	v_mfma_f32_16x16x32_bf16 v[72:75], v[182:185], v[210:213], v[72:75]
	v_mfma_f32_16x16x32_bf16 v[68:71], v[168:171], v[222:225], v[68:71]
	v_mfma_f32_16x16x32_bf16 v[64:67], v[182:185], v[222:225], v[64:67]
	s_setprio 0
	s_barrier
	s_add_i32 s70, s61, s50
	v_lshl_add_u64 v[190:191], s[42:43], 0, v[148:149]
	s_mov_b32 m0, s70
	ds_read_b128 v[186:189], v177 offset:16384
	ds_read_b128 v[194:197], v177 offset:17408
	ds_read_b128 v[198:201], v177 offset:18432
	ds_read_b128 v[202:205], v177 offset:19456
	ds_read_b128 v[206:209], v177 offset:20480
	ds_read_b128 v[210:213], v177 offset:21504
	ds_read_b128 v[218:221], v177 offset:22528
	ds_read_b128 v[222:225], v177 offset:23552
	global_load_lds_dwordx4 v[190:191], off
	s_add_i32 m0, s70, 0x2000
	s_add_u32 s70, s42, 0x80000
	v_lshl_add_u64 v[214:215], s[42:43], 0, v[144:145]
	s_addc_u32 s71, s43, 0
	s_add_i32 s72, s62, s50
	global_load_lds_dwordx4 v[214:215], off
	v_lshl_add_u64 v[226:227], s[70:71], 0, v[148:149]
	s_mov_b32 m0, s72
	v_lshl_add_u64 v[228:229], s[44:45], 0, v[146:147]
	global_load_lds_dwordx4 v[226:227], off
	v_lshl_add_u64 v[226:227], s[70:71], 0, v[144:145]
	s_add_i32 m0, s72, 0x2000
	s_nop 0
	global_load_lds_dwordx4 v[226:227], off
	v_lshl_add_u64 v[226:227], s[44:45], 0, v[150:151]
	s_mov_b32 m0, s52
	s_nop 0
	global_load_lds_dwordx4 v[226:227], off
	s_mov_b32 m0, s53
	s_nop 0
	global_load_lds_dwordx4 v[228:229], off
	s_waitcnt vmcnt(8)
	s_waitcnt lgkmcnt(0)
	s_barrier
	s_setprio 1
	s_waitcnt lgkmcnt(0)
	v_mfma_f32_16x16x32_bf16 v[60:63], v[128:131], v[186:189], v[60:63]
	v_mfma_f32_16x16x32_bf16 v[56:59], v[136:139], v[186:189], v[56:59]
	v_mfma_f32_16x16x32_bf16 v[52:55], v[128:131], v[198:201], v[52:55]
	v_mfma_f32_16x16x32_bf16 v[48:51], v[136:139], v[198:201], v[48:51]
	v_mfma_f32_16x16x32_bf16 v[36:39], v[128:131], v[206:209], v[36:39]
	v_mfma_f32_16x16x32_bf16 v[32:35], v[136:139], v[206:209], v[32:35]
	v_mfma_f32_16x16x32_bf16 v[20:23], v[128:131], v[218:221], v[20:23]
	v_mfma_f32_16x16x32_bf16 v[16:19], v[136:139], v[218:221], v[16:19]
	v_mfma_f32_16x16x32_bf16 v[60:63], v[132:135], v[194:197], v[60:63]
	v_mfma_f32_16x16x32_bf16 v[56:59], v[140:143], v[194:197], v[56:59]
	v_mfma_f32_16x16x32_bf16 v[52:55], v[132:135], v[202:205], v[52:55]
	v_mfma_f32_16x16x32_bf16 v[48:51], v[140:143], v[202:205], v[48:51]
	v_mfma_f32_16x16x32_bf16 v[36:39], v[132:135], v[210:213], v[36:39]
	v_mfma_f32_16x16x32_bf16 v[32:35], v[140:143], v[210:213], v[32:35]
	v_mfma_f32_16x16x32_bf16 v[20:23], v[132:135], v[222:225], v[20:23]
	v_mfma_f32_16x16x32_bf16 v[16:19], v[140:143], v[222:225], v[16:19]
	v_mfma_f32_16x16x32_bf16 v[44:47], v[164:167], v[186:189], v[44:47]
	v_mfma_f32_16x16x32_bf16 v[40:43], v[178:181], v[186:189], v[40:43]
	v_mfma_f32_16x16x32_bf16 v[28:31], v[164:167], v[198:201], v[28:31]
	v_mfma_f32_16x16x32_bf16 v[24:27], v[178:181], v[198:201], v[24:27]
	v_mfma_f32_16x16x32_bf16 v[12:15], v[164:167], v[206:209], v[12:15]
	v_mfma_f32_16x16x32_bf16 v[8:11], v[178:181], v[206:209], v[8:11]
	v_mfma_f32_16x16x32_bf16 v[4:7], v[164:167], v[218:221], v[4:7]
	v_mfma_f32_16x16x32_bf16 v[0:3], v[178:181], v[218:221], v[0:3]
	v_mfma_f32_16x16x32_bf16 v[44:47], v[168:171], v[194:197], v[44:47]
	v_mfma_f32_16x16x32_bf16 v[40:43], v[182:185], v[194:197], v[40:43]
	v_mfma_f32_16x16x32_bf16 v[28:31], v[168:171], v[202:205], v[28:31]
	v_mfma_f32_16x16x32_bf16 v[24:27], v[182:185], v[202:205], v[24:27]
	v_mfma_f32_16x16x32_bf16 v[12:15], v[168:171], v[210:213], v[12:15]
	v_mfma_f32_16x16x32_bf16 v[8:11], v[182:185], v[210:213], v[8:11]
	v_mfma_f32_16x16x32_bf16 v[4:7], v[168:171], v[222:225], v[4:7]
	v_mfma_f32_16x16x32_bf16 v[0:3], v[182:185], v[222:225], v[0:3]
	s_setprio 0
	s_barrier
; #define PG8_STAGE(bufoff, gbase, voff) do { _Pragma("unroll") for (int _i = 0; _i < 2; ++_i) \
;         __builtin_amdgcn_global_load_lds((const unsigned*)((const char*)(gbase) + (voff)[_i]), (PG8_LAS unsigned*)(lds + (bufoff) + ldsw + _i * 8192), 16, 0, 0); } while (0)
; #define PG8_LDA(dst, b, h) do { _Pragma("unroll") for (int m = 0; m < 4; ++m) _Pragma("unroll") for (int k = 0; k < 2; ++k) dst[m][k] = *(const PG8_LAS bf16x8*)(lds + PG8_SA(b, h) + aoff + m * 2048 + k * 1024); } while (0)
; #define PG8_LDB(dst, b, h) do { _Pragma("unroll") for (int n = 0; n < 2; ++n) _Pragma("unroll") for (int k = 0; k < 2; ++k) dst[n][k] = *(const PG8_LAS bf16x8*)(lds + PG8_SB(b, h) + boff + n * 2048 + k * 1024); } while (0)
; #define PG8_MMA(ai, bj, At, Bt) do { __builtin_amdgcn_s_setprio(1); _Pragma("unroll") for (int m = 0; m < 4; ++m) _Pragma("unroll") for (int n = 0; n < 2; ++n) _Pragma("unroll") for (int k = 0; k < 2; ++k) \
;         acc[ai][bj][m][n] = __builtin_amdgcn_mfma_f32_16x16x32_bf16(Bt[n][k], At[m][k], acc[ai][bj][m][n], 0, 0, 0); __builtin_amdgcn_s_setprio(0); } while (0)
; #define PG8_WAIT_V(n) asm volatile("s_waitcnt vmcnt(" #n ")" ::: "memory")
; #define PG8_WAIT_L(n) asm volatile("s_waitcnt lgkmcnt(" #n ")" ::: "memory")
; #define PG8_BAR __builtin_amdgcn_s_barrier()
; #define PG8_SCHED __builtin_amdgcn_sched_barrier(0)
; template <class Epi, class Sched, bool ALIGN_EPI = false, bool SP2 = false>
; __device__ __forceinline__ void gemm_phase(PG8_LAS unsigned char* lds, const Gemm g, const Sched& S, const Epi& E) {
;     ...
;             PG8_LDB(B0, 1, 0); PG8_LDB(B1, 1, 1); PG8_SCHED; PG8_LDA(At, 1, 0); PG8_STAGE(PG8_SA(0, 1), a2 + hstep, voffA);
;             PG8_WAIT_V(8); PG8_WAIT_L(0); PG8_BAR; PG8_MMA(0, 0, At, B0); PG8_MMA(0, 1, At, B1); PG8_BAR; PG8_SCHED;
	s_add_i32 s70, 0, 0x18000
	s_add_i32 s71, 0, 0x1c000
	v_add_u32_e32 v140, s70, v173
	v_add_u32_e32 v182, s71, v173
	ds_read_b128 v[128:131], v140
	ds_read_b128 v[132:135], v140 offset:1024
	ds_read_b128 v[136:139], v140 offset:2048
	ds_read_b128 v[140:143], v140 offset:3072
	ds_read_b128 v[164:167], v182
	ds_read_b128 v[168:171], v182 offset:1024
	ds_read_b128 v[178:181], v182 offset:2048
	ds_read_b128 v[182:185], v182 offset:3072
	s_add_u32 s44, s44, 0x80000
	s_addc_u32 s45, s45, 0
	s_mov_b32 m0, s54
	v_lshl_add_u64 v[230:231], s[44:45], 0, v[150:151]
	ds_read_b128 v[186:189], v177 offset:32768
	ds_read_b128 v[194:197], v177 offset:33792
	ds_read_b128 v[198:201], v177 offset:34816
	ds_read_b128 v[202:205], v177 offset:35840
	ds_read_b128 v[206:209], v177 offset:36864
	ds_read_b128 v[210:213], v177 offset:37888
	ds_read_b128 v[218:221], v177 offset:38912
	ds_read_b128 v[222:225], v177 offset:39936
	global_load_lds_dwordx4 v[230:231], off
	v_lshl_add_u64 v[230:231], s[44:45], 0, v[146:147]
	s_mov_b32 m0, s55
	s_nop 0
	global_load_lds_dwordx4 v[230:231], off
	s_waitcnt vmcnt(8)
	s_waitcnt lgkmcnt(0)
	s_barrier
	s_setprio 1
	s_waitcnt lgkmcnt(0)
	v_mfma_f32_16x16x32_bf16 v[124:127], v[128:131], v[186:189], v[124:127]
	v_mfma_f32_16x16x32_bf16 v[120:123], v[136:139], v[186:189], v[120:123]
	v_mfma_f32_16x16x32_bf16 v[116:119], v[128:131], v[198:201], v[116:119]
	v_mfma_f32_16x16x32_bf16 v[112:115], v[136:139], v[198:201], v[112:115]
	v_mfma_f32_16x16x32_bf16 v[100:103], v[128:131], v[206:209], v[100:103]
	v_mfma_f32_16x16x32_bf16 v[96:99], v[136:139], v[206:209], v[96:99]
	v_mfma_f32_16x16x32_bf16 v[84:87], v[128:131], v[218:221], v[84:87]
	v_mfma_f32_16x16x32_bf16 v[80:83], v[136:139], v[218:221], v[80:83]
	v_mfma_f32_16x16x32_bf16 v[124:127], v[132:135], v[194:197], v[124:127]
	v_mfma_f32_16x16x32_bf16 v[120:123], v[140:143], v[194:197], v[120:123]
	v_mfma_f32_16x16x32_bf16 v[116:119], v[132:135], v[202:205], v[116:119]
	v_mfma_f32_16x16x32_bf16 v[112:115], v[140:143], v[202:205], v[112:115]
	v_mfma_f32_16x16x32_bf16 v[100:103], v[132:135], v[210:213], v[100:103]
	v_mfma_f32_16x16x32_bf16 v[96:99], v[140:143], v[210:213], v[96:99]
	v_mfma_f32_16x16x32_bf16 v[84:87], v[132:135], v[222:225], v[84:87]
	v_mfma_f32_16x16x32_bf16 v[80:83], v[140:143], v[222:225], v[80:83]
	v_mfma_f32_16x16x32_bf16 v[108:111], v[164:167], v[186:189], v[108:111]
	v_mfma_f32_16x16x32_bf16 v[104:107], v[178:181], v[186:189], v[104:107]
	v_mfma_f32_16x16x32_bf16 v[92:95], v[164:167], v[198:201], v[92:95]
	v_mfma_f32_16x16x32_bf16 v[88:91], v[178:181], v[198:201], v[88:91]
	v_mfma_f32_16x16x32_bf16 v[76:79], v[164:167], v[206:209], v[76:79]
	v_mfma_f32_16x16x32_bf16 v[72:75], v[178:181], v[206:209], v[72:75]
	v_mfma_f32_16x16x32_bf16 v[68:71], v[164:167], v[218:221], v[68:71]
	v_mfma_f32_16x16x32_bf16 v[64:67], v[178:181], v[218:221], v[64:67]
	v_mfma_f32_16x16x32_bf16 v[108:111], v[168:171], v[194:197], v[108:111]
	v_mfma_f32_16x16x32_bf16 v[104:107], v[182:185], v[194:197], v[104:107]
	v_mfma_f32_16x16x32_bf16 v[92:95], v[168:171], v[202:205], v[92:95]
	v_mfma_f32_16x16x32_bf16 v[88:91], v[182:185], v[202:205], v[88:91]
	v_mfma_f32_16x16x32_bf16 v[76:79], v[168:171], v[210:213], v[76:79]
	v_mfma_f32_16x16x32_bf16 v[72:75], v[182:185], v[210:213], v[72:75]
	v_mfma_f32_16x16x32_bf16 v[68:71], v[168:171], v[222:225], v[68:71]
	v_mfma_f32_16x16x32_bf16 v[64:67], v[182:185], v[222:225], v[64:67]
	s_setprio 0
	s_barrier
; #define PG8_STAGE(bufoff, gbase, voff) do { _Pragma("unroll") for (int _i = 0; _i < 2; ++_i) \
;         __builtin_amdgcn_global_load_lds((const unsigned*)((const char*)(gbase) + (voff)[_i]), (PG8_LAS unsigned*)(lds + (bufoff) + ldsw + _i * 8192), 16, 0, 0); } while (0)
; #define PG8_LDA(dst, b, h) do { _Pragma("unroll") for (int m = 0; m < 4; ++m) _Pragma("unroll") for (int k = 0; k < 2; ++k) dst[m][k] = *(const PG8_LAS bf16x8*)(lds + PG8_SA(b, h) + aoff + m * 2048 + k * 1024); } while (0)
; #define PG8_MMA(ai, bj, At, Bt) do { __builtin_amdgcn_s_setprio(1); _Pragma("unroll") for (int m = 0; m < 4; ++m) _Pragma("unroll") for (int n = 0; n < 2; ++n) _Pragma("unroll") for (int k = 0; k < 2; ++k) \
;         acc[ai][bj][m][n] = __builtin_amdgcn_mfma_f32_16x16x32_bf16(Bt[n][k], At[m][k], acc[ai][bj][m][n], 0, 0, 0); __builtin_amdgcn_s_setprio(0); } while (0)
; #define PG8_WAIT_V(n) asm volatile("s_waitcnt vmcnt(" #n ")" ::: "memory")
; #define PG8_WAIT_L(n) asm volatile("s_waitcnt lgkmcnt(" #n ")" ::: "memory")
; #define PG8_BAR __builtin_amdgcn_s_barrier()
; #define PG8_SCHED __builtin_amdgcn_sched_barrier(0)
; template <class Epi, class Sched, bool ALIGN_EPI = false, bool SP2 = false>
; __device__ __forceinline__ void gemm_phase(PG8_LAS unsigned char* lds, const Gemm g, const Sched& S, const Epi& E) {
;     ...
;             PG8_LDA(At, 1, 1); PG8_STAGE(PG8_SB(1, 0), b3, voffB); PG8_STAGE(PG8_SB(1, 1), b3 + hstep, voffB); PG8_STAGE(PG8_SA(1, 0), a3, voffA);
;             PG8_WAIT_V(8); PG8_WAIT_L(0); PG8_BAR; PG8_MMA(1, 0, At, B0); PG8_MMA(1, 1, At, B1); PG8_BAR; PG8_SCHED;
;     ...
;         if constexpr (ALIGN_EPI) { if (wr == 0) PG8_BAR; }
	s_add_i32 s44, s70, s50
	v_lshl_add_u64 v[190:191], v[190:191], 0, s[22:23]
	s_mov_b32 m0, s44
	ds_read_b128 v[186:189], v177 offset:49152
	ds_read_b128 v[194:197], v177 offset:50176
	ds_read_b128 v[198:201], v177 offset:51200
	ds_read_b128 v[202:205], v177 offset:52224
	ds_read_b128 v[206:209], v177 offset:53248
	ds_read_b128 v[210:213], v177 offset:54272
	ds_read_b128 v[218:221], v177 offset:55296
	ds_read_b128 v[222:225], v177 offset:56320
	global_load_lds_dwordx4 v[190:191], off
	s_add_i32 m0, s44, 0x2000
	s_add_u32 s42, s42, 0x80080
	v_lshl_add_u64 v[190:191], v[214:215], 0, s[22:23]
	s_addc_u32 s43, s43, 0
	s_add_i32 s44, s71, s50
	global_load_lds_dwordx4 v[190:191], off
	v_lshl_add_u64 v[190:191], s[42:43], 0, v[148:149]
	s_mov_b32 m0, s44
	s_nop 0
	global_load_lds_dwordx4 v[190:191], off
	v_lshl_add_u64 v[190:191], s[42:43], 0, v[144:145]
	s_add_i32 m0, s44, 0x2000
	s_nop 0
	global_load_lds_dwordx4 v[190:191], off
	v_lshl_add_u64 v[190:191], v[226:227], 0, s[22:23]
	s_mov_b32 m0, s59
	s_nop 0
	global_load_lds_dwordx4 v[190:191], off
	v_lshl_add_u64 v[190:191], v[228:229], 0, s[22:23]
	s_mov_b32 m0, s60
	s_nop 0
	global_load_lds_dwordx4 v[190:191], off
	s_waitcnt vmcnt(8)
	s_waitcnt lgkmcnt(0)
	s_barrier
	s_setprio 1
	s_waitcnt lgkmcnt(0)
	v_mfma_f32_16x16x32_bf16 v[60:63], v[128:131], v[186:189], v[60:63]
	v_mfma_f32_16x16x32_bf16 v[56:59], v[136:139], v[186:189], v[56:59]
	v_mfma_f32_16x16x32_bf16 v[52:55], v[128:131], v[198:201], v[52:55]
	v_mfma_f32_16x16x32_bf16 v[48:51], v[136:139], v[198:201], v[48:51]
	v_mfma_f32_16x16x32_bf16 v[36:39], v[128:131], v[206:209], v[36:39]
	v_mfma_f32_16x16x32_bf16 v[32:35], v[136:139], v[206:209], v[32:35]
	v_mfma_f32_16x16x32_bf16 v[20:23], v[128:131], v[218:221], v[20:23]
	v_mfma_f32_16x16x32_bf16 v[16:19], v[136:139], v[218:221], v[16:19]
	v_mfma_f32_16x16x32_bf16 v[60:63], v[132:135], v[194:197], v[60:63]
	v_mfma_f32_16x16x32_bf16 v[56:59], v[140:143], v[194:197], v[56:59]
	v_mfma_f32_16x16x32_bf16 v[52:55], v[132:135], v[202:205], v[52:55]
	v_mfma_f32_16x16x32_bf16 v[48:51], v[140:143], v[202:205], v[48:51]
	v_mfma_f32_16x16x32_bf16 v[36:39], v[132:135], v[210:213], v[36:39]
	v_mfma_f32_16x16x32_bf16 v[32:35], v[140:143], v[210:213], v[32:35]
	v_mfma_f32_16x16x32_bf16 v[20:23], v[132:135], v[222:225], v[20:23]
	v_mfma_f32_16x16x32_bf16 v[16:19], v[140:143], v[222:225], v[16:19]
	v_mfma_f32_16x16x32_bf16 v[44:47], v[164:167], v[186:189], v[44:47]
	v_mfma_f32_16x16x32_bf16 v[40:43], v[178:181], v[186:189], v[40:43]
	v_mfma_f32_16x16x32_bf16 v[28:31], v[164:167], v[198:201], v[28:31]
	v_mfma_f32_16x16x32_bf16 v[24:27], v[178:181], v[198:201], v[24:27]
	v_mfma_f32_16x16x32_bf16 v[12:15], v[164:167], v[206:209], v[12:15]
	v_mfma_f32_16x16x32_bf16 v[8:11], v[178:181], v[206:209], v[8:11]
	v_mfma_f32_16x16x32_bf16 v[4:7], v[164:167], v[218:221], v[4:7]
	v_mfma_f32_16x16x32_bf16 v[0:3], v[178:181], v[218:221], v[0:3]
	v_mfma_f32_16x16x32_bf16 v[44:47], v[168:171], v[194:197], v[44:47]
	v_mfma_f32_16x16x32_bf16 v[40:43], v[182:185], v[194:197], v[40:43]
	v_mfma_f32_16x16x32_bf16 v[28:31], v[168:171], v[202:205], v[28:31]
	v_mfma_f32_16x16x32_bf16 v[24:27], v[182:185], v[202:205], v[24:27]
	v_mfma_f32_16x16x32_bf16 v[12:15], v[168:171], v[210:213], v[12:15]
	v_mfma_f32_16x16x32_bf16 v[8:11], v[182:185], v[210:213], v[8:11]
	v_mfma_f32_16x16x32_bf16 v[4:7], v[168:171], v[222:225], v[4:7]
	v_mfma_f32_16x16x32_bf16 v[0:3], v[182:185], v[222:225], v[0:3]
	s_setprio 0
	s_barrier
	s_add_i32 s69, s69, 2
	s_add_u32 s40, s40, 0x100
	s_addc_u32 s41, s41, 0
	s_add_u32 s67, s67, 0x100
	s_addc_u32 s68, s68, 0
	s_cmp_gt_u32 s69, 29
	s_cbranch_scc0 .LBB0_171
	s_and_b64 vcc, exec, s[24:25]
	s_cbranch_vccz .LBB0_174
	s_barrier

; #define VMW() asm volatile("s_waitcnt vmcnt(0)" ::: "memory")
; #define SLOAD_H(Kp, Vp, k0) do { S.st_v0 = load8(ROW(Vp, k0, sr)); S.st_v1 = load8(ROW(Vp, k0, 32 + sr)); S.st_k0 = load8(ROW(Kp, k0, sr)); S.st_k1 = load8(ROW(Kp, k0, 32 + sr)); } while (0)
; #define SWRITE_HK(bf) do { *(bf16x8*)(K_lds + (bf) * SHM_K + kws) = S.st_k0; *(bf16x8*)(K_lds + (bf) * SHM_K + kws + 32 * 256) = S.st_k1; } while (0)
; __device__ __forceinline__ void attn_prime(const BlockRef& cur, char* lds, Seam& S) {
;     int tid_ = threadIdx.x; asm volatile("" : "+v"(tid_));
;     const int tid = tid_, wid = __builtin_amdgcn_readfirstlane(tid >> 6), lane = tid & 63, r32 = lane & 31, hi = lane >> 5;
;     const int sr = tid >> 4, sc = (tid & 15) * 8, kws = KSWZ(sr, sc * 2); char* K_lds = lds + 2 * SHM_V;
;     for (int d0 = 0; d0 < 8; ++d0) S.qr[d0] = load8(cur.Q + (size_t)(wid * QBLK + r32) * D + d0 * 16 + hi * 8);
;     SLOAD_H(cur.K, cur.V, 0); VMW(); SWRITE_HK(0);
;     __syncthreads();
; __global__ void __launch_bounds__(NTHR, 2) mega_fwd(Args args) {
;     ...
;         const int NSI = BATCH * 4 * 16;
;         if (vcu < NSI) {
;             int si = vcu, sub = 0;
;     ...
;             att::BlockRef cur, nxt; MKREF(cur, si, sub);
;             att::attn_prime(cur, (char*)lds, S);
.LBB0_314:
	s_or_b64 exec, exec, s[14:15]
	s_nop 0
	s_nop 0
	s_nop 0
	s_nop 0
	s_waitcnt lgkmcnt(0)
	s_barrier
	s_movk_i32 s13, 0x100
	s_cmpk_lt_i32 s66, 0x100
	s_mov_b64 s[22:23], s[0:1]
	v_readfirstlane_b32 s24, v192
	s_mov_b64 s[20:21], s[0:1]
	s_mov_b64 s[18:19], s[0:1]
	s_mov_b64 s[14:15], s[0:1]
	s_mov_b64 s[16:17], s[0:1]
	s_cbranch_scc0 .LBB0_488
	s_load_dwordx2 s[22:23], s[22:23], 0xc8
	v_mov_b32_e32 v1, v216
	s_load_dwordx2 s[20:21], s[20:21], 0xc8
	v_mov_b32_e32 v195, 0
	s_load_dwordx2 s[18:19], s[18:19], 0xc8
	s_waitcnt lgkmcnt(0)
	s_add_u32 s25, s22, 0x2f800000
	s_addc_u32 s26, s23, 0
	s_load_dwordx2 s[14:15], s[14:15], 0xc8
	s_add_u32 s27, s20, 0x33800000
	s_addc_u32 s28, s21, 0
	s_add_u32 s30, s18, 0x37800000
	s_addc_u32 s31, s19, 0
	s_waitcnt lgkmcnt(0)
	s_add_u32 s14, s14, 0xf800000
	s_addc_u32 s15, s15, 0
	s_bfe_u32 s20, s66, 0x20004
	s_ashr_i32 s21, s66, 6
	s_lshl_b32 s18, s20, 15
	s_lshl_b32 s19, s21, 17
	s_or_b32 s18, s18, s19
	s_lshl_b32 s19, s66, 8
	s_and_b32 s19, s19, 0xf00
	s_lshl_b32 s20, s20, 14
	s_lshl_b32 s21, s21, 16
	s_xor_b32 s29, s19, 0x1f00
	s_or_b32 s20, s20, s21
	s_or_b32 s18, s18, s29
	s_or_b32 s22, s20, s29
	s_ashr_i32 s19, s18, 31
	s_ashr_i32 s23, s22, 31
	s_lshl_b64 s[18:19], s[18:19], 8
	s_ashr_i32 s21, s20, 31
	s_lshl_b64 s[22:23], s[22:23], 8
	s_add_u32 s36, s25, s22
	s_addc_u32 s37, s26, s23
	s_lshl_b64 s[20:21], s[20:21], 8
	s_add_u32 s70, s27, s20
	s_addc_u32 s71, s28, s21
	s_add_u32 s72, s30, s20
	s_addc_u32 s73, s31, s21
	s_load_dwordx2 s[16:17], s[16:17], 0xc8
	s_add_u32 s22, s14, s18
	s_addc_u32 s23, s15, s19
	v_readfirstlane_b32 s18, v1
	s_ashr_i32 s18, s18, 1
	s_movk_i32 s19, 0xffe0
	v_mov_b32_e32 v2, s18
	v_bfi_b32 v2, s19, v2, v1
	v_ashrrev_i32_e32 v3, 31, v2
	v_lshlrev_b64 v[2:3], 8, v[2:3]
	s_waitcnt vmcnt(32)
	v_lshrrev_b32_e32 v4, 1, v1
	v_lshl_add_u64 v[2:3], s[36:37], 0, v[2:3]
	v_and_b32_e32 v194, 16, v4
	v_lshl_add_u64 v[2:3], v[2:3], 0, v[194:195]
	global_load_dwordx4 v[156:159], v[2:3], off
	global_load_dwordx4 v[152:155], v[2:3], off offset:32
	global_load_dwordx4 v[148:151], v[2:3], off offset:64
	global_load_dwordx4 v[144:147], v[2:3], off offset:96
	global_load_dwordx4 v[140:143], v[2:3], off offset:128
	global_load_dwordx4 v[136:139], v[2:3], off offset:160
	global_load_dwordx4 v[132:135], v[2:3], off offset:192
	global_load_dwordx4 v[128:131], v[2:3], off offset:224
	v_ashrrev_i32_e32 v2, 4, v1
	v_lshlrev_b32_e32 v3, 4, v1
	s_movk_i32 s18, 0xf0
	v_and_b32_e32 v1, 0x70, v1
	v_and_b32_e32 v194, 0xf0, v3
	v_bitop3_b32 v1, v3, v1, s18 bitop3:0x6c
	v_ashrrev_i32_e32 v3, 31, v2
	s_waitcnt vmcnt(37)
	v_lshlrev_b32_e32 v10, 8, v2
	v_lshlrev_b64 v[2:3], 8, v[2:3]
	v_lshl_add_u64 v[4:5], s[72:73], 0, v[2:3]
	s_mov_b64 s[18:19], 0x2000
	v_lshl_add_u64 v[4:5], v[4:5], 0, v[194:195]
	v_lshl_add_u64 v[6:7], v[2:3], 0, s[18:19]
	global_load_dwordx4 v[96:99], v[4:5], off
	v_lshl_add_u64 v[4:5], s[72:73], 0, v[6:7]
	v_lshl_add_u64 v[2:3], s[70:71], 0, v[2:3]
	v_lshl_add_u64 v[4:5], v[4:5], 0, v[194:195]
	v_lshl_add_u64 v[2:3], v[2:3], 0, v[194:195]
	v_lshl_add_u64 v[6:7], s[70:71], 0, v[6:7]
	global_load_dwordx4 v[100:103], v[4:5], off
	v_lshl_add_u64 v[6:7], v[6:7], 0, v[194:195]
	global_load_dwordx4 v[2:5], v[2:3], off
	v_writelane_b32 v254, s25, 53
	global_load_dwordx4 v[6:9], v[6:7], off
	v_add3_u32 v1, 0, v10, v1
	v_and_b32_e32 v255, 0x800, v10
	v_lshrrev_b32_e32 v255, 4, v255
	v_xor_b32_e32 v1, v1, v255
	v_writelane_b32 v254, s26, 54
	s_waitcnt vmcnt(0)
	v_writelane_b32 v254, s27, 55
	s_ashr_i32 s18, s24, 3
	v_writelane_b32 v254, s28, 56
	s_and_b32 s18, s18, -8
	v_and_b32_e32 v0, 63, v192
	v_writelane_b32 v254, s30, 57
	s_cmpk_lt_i32 s18, 0x200
	v_writelane_b32 v254, s31, 58
	s_mov_b32 s48, 0
	v_bfe_u32 v193, v192, 4, 2
	s_cselect_b64 s[24:25], -1, 0
	s_mov_b32 s67, 0x41000000
	s_mov_b32 s26, 0x3e0293ee
	v_mbcnt_hi_u32_b32 v205, -1, v217
	v_lshlrev_b32_e32 v214, 2, v0
	s_mov_b32 s28, 0x3f4ccccd
	s_mov_b32 s64, 0x200000
	s_mov_b32 s65, 0x400000
	s_mov_b32 s27, 0x600000
	v_mov_b32_e32 v218, 0x358637bd
	s_mov_b32 s47, 0xf800000
	v_mov_b32_e32 v219, 0x260
	v_mov_b32_e32 v220, 0xff800000
	v_mov_b32_e32 v221, 0xf149f2ca
	s_mov_b32 s77, 0
	v_writelane_b32 v254, s18, 59
	s_waitcnt vmcnt(1)
	ds_write_b128 v1, v[2:5] offset:32768
	s_waitcnt vmcnt(0)
	ds_write_b128 v1, v[6:9] offset:40960
	v_lshlrev_b32_e32 v1, 3, v192
	v_and_b32_e32 v2, 0x78, v1
	v_lshlrev_b32_e32 v194, 1, v2
	s_waitcnt lgkmcnt(0)
	v_lshl_add_u64 v[4:5], s[16:17], 0, v[194:195]
	s_mov_b64 s[16:17], 0x17800000
	v_lshl_add_u64 v[196:197], s[14:15], 0, v[194:195]
	v_lshl_add_u64 v[198:199], v[4:5], 0, s[16:17]
	v_lshlrev_b32_e32 v215, 2, v2
	s_barrier
	s_branch .LBB0_317

; #define PG8_WAIT_V(n) asm volatile("s_waitcnt vmcnt(" #n ")" ::: "memory")
;     __host__ __device__ bool next(int i, Unit& u) const {
;         const long L = (long)i * G + c; if (L >= nwg) return false;
;         int wgid = (int)L; { const int q = nwg / NXCD, r = nwg % NXCD, xcd = wgid % NXCD, off = wgid / NXCD; wgid = (xcd < r ? xcd * (q + 1) : r * (q + 1) + (xcd - r) * q) + off; }
;         const int nig = wgm * nN, gid = wgid / nig, fm = gid * wgm, gsz = (nM - fm) < wgm ? (nM - fm) : wgm;
;         u.pm = fm + ((wgid % nig) % gsz); u.pn = (wgid % nig) / gsz; if (rev) u.pm = nM - 1 - u.pm; return true;
; template <class Epi, class Sched, bool ALIGN_EPI = false, bool SP2 = false>
; __device__ __forceinline__ void gemm_phase(PG8_LAS unsigned char* lds, const Gemm g, const Sched& S, const Epi& E) {
;     ...
;     const int tid = tid_, wid = __builtin_amdgcn_readfirstlane(tid >> 6), lane = tid & 63, wr = wid >> 2, wc = wid & 3, fr = lane & 15, fq = lane >> 4;
;     const int K = g.K, nt = K / BK;
;     unsigned voffA[2], voffB[2];
; #pragma unroll
;     for (int i = 0; i < 2; ++i) { int R, C; stage_rc(tid * 16 + i * 8192, R, C); const int Rb = Epi::PERM ? ((R & ~31) + perm32(R & 31)) : R;
;         voffA[i] = (unsigned)(R * K + C) * 2u; voffB[i] = (unsigned)(Rb * K + C) * 2u; }
;     const size_t kstep = (size_t)(BK * 2);
;     const size_t hstep = (size_t)HALF * K * 2;
;     const size_t tstep = 2 * hstep;
;     const unsigned ldsw = (unsigned)wid * 1024u;
;     const int aoff = lds_byte(wr * 64 + fr, fq * 8), boff = lds_byte(wc * 32 + fr, fq * 8);
;     ...
;     Unit cur, nxt; int ui = 0;
;     if (!S.next(0, cur)) return;
;     f32x4 acc[2][2][4][2];
; #pragma unroll
;     for (int a = 0; a < 2; ++a)
; #pragma unroll
;         for (int b = 0; b < 2; ++b)
; #pragma unroll
;             for (int m = 0; m < 4; ++m)
; #pragma unroll
;                 for (int n = 0; n < 2; ++n) acc[a][b][m][n] = (f32x4){0.f, 0.f, 0.f, 0.f};
;     bf16x8 At[4][2], B0[2][2], B1[2][2];
;     const char* cA = (const char*)g.A + (size_t)cur.pm * tstep; const char* cB = (const char*)g.Bt + (size_t)cur.pn * tstep;
;     S.a_ready(cur);
;     if constexpr (SP2) {
;         PG8_STAGE(PG8_SB(0, 0), cB, voffB); PG8_STAGE(PG8_SB(0, 1), cB + hstep, voffB); PG8_STAGE(PG8_SA(0, 0), cA, voffA); PG8_STAGE(PG8_SA(0, 1), cA + hstep, voffA);
;         if (wr == 1) PG8_BAR;
;         PG8_WAIT_V(2); PG8_BAR;
.LBB0_540:
	s_or_b64 exec, exec, s[14:15]
	s_nop 0
	s_nop 0
	s_nop 0
	s_nop 0
	s_nop 0
	s_nop 0
	s_nop 0
	s_nop 0
	s_cmpk_lt_i32 s2, 0x400
	s_mov_b64 s[22:23], s[0:1]
	s_mov_b64 s[16:17], s[0:1]
	s_mov_b64 s[24:25], s[0:1]
	s_mov_b64 s[18:19], s[0:1]
	s_mov_b64 s[14:15], s[0:1]
	s_waitcnt lgkmcnt(0)
	s_barrier
	s_cselect_b64 s[48:49], -1, 0
	s_lshr_b32 s13, s33, 29
	s_add_i32 s13, s2, s13
	s_load_dwordx2 s[14:15], s[14:15], 0xc8
	s_ashr_i32 s56, s13, 3
	s_and_b32 s13, s13, -8
	s_load_dwordx2 s[20:21], s[16:17], 0xc8
	s_nop 0
	s_load_dwordx2 s[18:19], s[18:19], 0xc8
	s_mov_b64 s[16:17], s[0:1]
	s_sub_i32 s59, s2, s13
	s_cmp_lt_i32 s59, 0
	s_load_dwordx2 s[16:17], s[16:17], 0xc8
	s_cselect_b64 s[42:43], -1, 0
	s_lshl_b32 s57, s59, 7
	s_waitcnt lgkmcnt(0)
	s_add_u32 s14, s14, 0x2f800000
	s_addc_u32 s15, s15, 0
	s_waitcnt vmcnt(27)
	v_mov_b32_e32 v14, v216
	s_cmpk_gt_i32 s2, 0x3ff
	s_mul_i32 s58, s59, 0x81
	s_nop 0
	v_readfirstlane_b32 s28, v14
	s_cbranch_scc1 .LBB0_560
	v_lshlrev_b32_e32 v0, 4, v14
	v_add_u32_e32 v1, 0x2000, v0
	v_ashrrev_i32_e32 v2, 31, v1
	v_lshrrev_b32_e32 v2, 22, v2
	v_add_u32_e32 v2, v1, v2
	v_ashrrev_i32_e32 v8, 10, v2
	v_mul_i32_i24_e32 v2, 0x400, v8
	v_sub_u32_e32 v1, v1, v2
	v_lshrrev_b32_e32 v2, 4, v1
	v_bitop3_b32 v1, v2, v1, 32 bitop3:0x6c
	v_ashrrev_i32_e32 v2, 31, v1
	s_load_dwordx2 s[22:23], s[22:23], 0xc8
	s_nop 0
	s_load_dwordx2 s[24:25], s[24:25], 0xc8
	v_lshrrev_b32_e32 v2, 26, v2
	v_add_u32_e32 v2, v1, v2
	v_lshlrev_b32_e32 v3, 3, v8
	v_ashrrev_i32_e32 v9, 6, v2
	v_and_b32_e32 v3, -16, v3
	v_add_u32_e32 v3, v9, v3
	s_waitcnt lgkmcnt(0)
	s_add_u32 s13, s22, 0x3b800000
	v_and_b32_e32 v4, 3, v9
	s_mov_b32 s22, 0x1fffe0
	v_lshrrev_b32_e32 v5, 2, v3
	v_lshlrev_b32_e32 v6, 1, v3
	v_and_b32_e32 v2, 0xc0, v2
	v_and_or_b32 v4, v3, s22, v4
	v_and_b32_e32 v5, 4, v5
	v_and_b32_e32 v6, 24, v6
	v_sub_u32_e32 v1, v1, v2
	v_mov_b32_e32 v2, 1
	v_or3_b32 v4, v4, v5, v6
	v_lshlrev_b32_e32 v5, 5, v8
	v_ashrrev_i16_sdwa v1, v2, sext(v1) dst_sel:DWORD dst_unused:UNUSED_PAD src0_sel:DWORD src1_sel:BYTE_0
	v_and_b32_e32 v5, 32, v5
	v_bfe_i32 v10, v1, 0, 16
	v_add_lshl_u32 v1, v5, v10, 1
	s_waitcnt vmcnt(6)
	v_lshl_add_u32 v152, v4, 11, v1
	v_lshl_add_u32 v154, v3, 11, v1
	v_bfe_i32 v1, v14, 27, 1
	v_lshrrev_b32_e32 v1, 22, v1
	v_add_u32_e32 v1, v0, v1
	v_and_b32_e32 v1, 0xfffffc00, v1
	v_sub_u32_e32 v0, v0, v1
	v_lshrrev_b32_e32 v1, 4, v0
	v_ashrrev_i32_e32 v3, 31, v14
	v_bitop3_b32 v0, v1, v0, 32 bitop3:0x6c
	v_lshrrev_b32_e32 v3, 26, v3
	v_ashrrev_i32_e32 v1, 31, v0
	v_add_u32_e32 v3, v14, v3
	s_addc_u32 s47, s23, 0
	v_lshrrev_b32_e32 v1, 26, v1
	v_ashrrev_i32_e32 v12, 6, v3
	s_add_u32 s60, s24, 0x2600000
	v_add_u32_e32 v1, v0, v1
	v_lshlrev_b32_e32 v3, 3, v12
	s_addc_u32 s61, s25, 0
	s_ashr_i32 s26, s28, 6
	v_ashrrev_i32_e32 v11, 6, v1
	v_and_b32_e32 v3, -16, v3
	s_ashr_i32 s27, s28, 8
	s_lshl_b32 s62, s26, 10
	v_add_u32_e32 v3, v11, v3
	v_and_b32_e32 v4, 3, v11
	v_and_or_b32 v4, v3, s22, v4
	s_and_b64 s[22:23], s[42:43], exec
	s_cselect_b32 s22, s58, s57
	s_add_i32 s22, s22, s56
	s_ashr_i32 s23, s22, 31
	s_lshr_b32 s23, s23, 27
	s_add_i32 s23, s22, s23
	s_ashr_i32 s24, s23, 5
	s_and_b32 s23, s23, 0xffe0
	s_sub_i32 s22, s22, s23
	s_bfe_i32 s23, s22, 0x80000
	s_bfe_u32 s23, s23, 0x2000d
	s_add_i32 s23, s22, s23
	s_lshl_b32 s25, s24, 2
	s_bfe_i32 s24, s23, 0x80000
	s_and_b32 s23, s23, 0xfc
	s_sub_i32 s22, s22, s23
	s_sext_i32_i16 s24, s24
	s_sext_i32_i8 s22, s22
	v_lshrrev_b32_e32 v5, 2, v3
	v_lshlrev_b32_e32 v6, 1, v3
	v_and_b32_e32 v1, 0xc0, v1
	s_lshr_b32 s24, s24, 2
	s_add_i32 s44, s25, s22
	v_and_b32_e32 v5, 4, v5
	v_and_b32_e32 v6, 24, v6
	v_sub_u32_e32 v0, v0, v1
	s_ashr_i32 s45, s44, 31
	s_bfe_i64 s[30:31], s[24:25], 0x100000
	v_or3_b32 v4, v4, v5, v6
	v_lshlrev_b32_e32 v5, 5, v12
	v_ashrrev_i16_sdwa v0, v2, sext(v0) dst_sel:DWORD dst_unused:UNUSED_PAD src0_sel:DWORD src1_sel:BYTE_0
	s_lshl_b64 s[22:23], s[44:45], 19
	s_lshl_b64 s[30:31], s[30:31], 19
	v_and_b32_e32 v5, 32, v5
	v_bfe_i32 v13, v0, 0, 16
	s_add_u32 s52, s60, s30
	v_add_lshl_u32 v0, v5, v13, 1
	s_addc_u32 s53, s61, s31
	s_add_i32 s63, s62, 0
	v_lshl_add_u32 v156, v4, 11, v0
	s_add_i32 m0, s63, 0x10000
	v_lshl_add_u32 v158, v3, 11, v0
	global_load_lds_dwordx4 v156, s[52:53]
	s_add_i32 m0, s63, 0x12000
	s_add_u32 s30, s52, 0x40000
	global_load_lds_dwordx4 v152, s[52:53]
	s_addc_u32 s31, s53, 0
	s_add_i32 m0, s63, 0x14000
	v_mov_b32_e32 v157, 0
	global_load_lds_dwordx4 v156, s[30:31]
	s_add_i32 m0, s63, 0x16000
	s_add_u32 s50, s13, s22
	s_addc_u32 s51, s47, s23
	s_add_i32 s64, s63, 0x2000
	global_load_lds_dwordx4 v152, s[30:31]
	s_mov_b32 m0, s63
	s_add_u32 s22, s50, 0x40000
	global_load_lds_dwordx4 v158, s[50:51]
	s_mov_b32 m0, s64
	s_addc_u32 s23, s51, 0
	s_add_i32 s65, s63, 0x4000
	global_load_lds_dwordx4 v154, s[50:51]
	s_mov_b32 m0, s65
	s_add_i32 s66, s63, 0x6000
	global_load_lds_dwordx4 v158, s[22:23]
	s_mov_b32 m0, s66
	v_mov_b32_e32 v153, v157
	global_load_lds_dwordx4 v154, s[22:23]
	v_mov_b32_e32 v159, v157
	v_mov_b32_e32 v155, v157
	s_cmp_eq_u32 s27, 1
	v_lshl_add_u64 v[6:7], s[52:53], 0, v[156:157]
	v_lshl_add_u64 v[4:5], s[52:53], 0, v[152:153]
	v_lshl_add_u64 v[0:1], s[50:51], 0, v[158:159]
	s_cselect_b64 s[22:23], -1, 0
	s_cmp_lg_u32 s27, 1
	v_lshl_add_u64 v[2:3], s[50:51], 0, v[154:155]
	s_cbranch_scc1 .LBB0_543
	s_barrier

; #define PG8_STAGE(bufoff, gbase, voff) do { _Pragma("unroll") for (int _i = 0; _i < 2; ++_i) \
;         __builtin_amdgcn_global_load_lds((const unsigned*)((const char*)(gbase) + (voff)[_i]), (PG8_LAS unsigned*)(lds + (bufoff) + ldsw + _i * 8192), 16, 0, 0); } while (0)
; #define PG8_LDA(dst, b, h) do { _Pragma("unroll") for (int m = 0; m < 4; ++m) _Pragma("unroll") for (int k = 0; k < 2; ++k) dst[m][k] = *(const PG8_LAS bf16x8*)(lds + PG8_SA(b, h) + aoff + m * 2048 + k * 1024); } while (0)
; #define PG8_LDB(dst, b, h) do { _Pragma("unroll") for (int n = 0; n < 2; ++n) _Pragma("unroll") for (int k = 0; k < 2; ++k) dst[n][k] = *(const PG8_LAS bf16x8*)(lds + PG8_SB(b, h) + boff + n * 2048 + k * 1024); } while (0)
; #define PG8_WAIT_V(n) asm volatile("s_waitcnt vmcnt(" #n ")" ::: "memory")
; #define PG8_WAIT_L(n) asm volatile("s_waitcnt lgkmcnt(" #n ")" ::: "memory")
; #define PG8_BAR __builtin_amdgcn_s_barrier()
; #define PG8_SCHED __builtin_amdgcn_sched_barrier(0)
; template <class Epi, class Sched, bool ALIGN_EPI = false, bool SP2 = false>
; __device__ __forceinline__ void gemm_phase(PG8_LAS unsigned char* lds, const Gemm g, const Sched& S, const Epi& E) {
;     ...
;         const bool has_next = S.next(ui + 1, nxt);
;         const char* nA = has_next ? (const char*)g.A + (size_t)nxt.pm * tstep : cA; const char* nB = has_next ? (const char*)g.Bt + (size_t)nxt.pn * tstep : cB;
;         for (int t = 0; t < nt; t += 2) {
;             const bool last = (t == nt - 2);
;             const char* a1 = cA + (size_t)(t + 1) * kstep;
;             const char* a2 = last ? nA : cA + (size_t)(t + 2) * kstep; const char* b2 = last ? nB : cB + (size_t)(t + 2) * kstep;
;             const char* a3 = a2 + kstep; const char* b3 = b2 + kstep;
;             if (last && has_next) S.a_ready(nxt);
;             if constexpr (SP2) {
;             PG8_LDB(B0, 0, 0); PG8_LDB(B1, 0, 1); PG8_SCHED; PG8_LDA(At, 0, 0); PG8_STAGE(PG8_SA(1, 1), a1 + hstep, voffA);
;             PG8_WAIT_V(8); PG8_WAIT_L(0); PG8_BAR; PG8_MMA(0, 0, At, B0); PG8_MMA(0, 1, At, B1); PG8_BAR; PG8_SCHED;
;             PG8_LDA(At, 0, 1); PG8_STAGE(PG8_SB(0, 0), b2, voffB); PG8_STAGE(PG8_SB(0, 1), b2 + hstep, voffB); PG8_STAGE(PG8_SA(0, 0), a2, voffA);
;             PG8_WAIT_V(8); PG8_WAIT_L(0); PG8_BAR; PG8_MMA(1, 0, At, B0); PG8_MMA(1, 1, At, B1); PG8_BAR; PG8_SCHED;
.LBB0_552:
	s_ashr_i32 s35, s34, 31
	s_lshl_b64 s[36:37], s[34:35], 19
	s_add_u32 s36, s13, s36
	s_addc_u32 s37, s47, s37
	s_and_b64 s[40:41], s[38:39], exec
	s_cselect_b32 s35, s37, s51
	s_cselect_b32 s72, s36, s50
	s_ashr_i32 s31, s30, 31
	s_lshl_b64 s[40:41], s[30:31], 19
	s_add_u32 s40, s60, s40
	s_addc_u32 s41, s61, s41
	s_and_b64 s[54:55], s[38:39], exec
	s_cselect_b32 s31, s41, s53
	s_cselect_b32 s73, s40, s52
	s_add_u32 s50, s50, 0x40080
	s_addc_u32 s51, s51, 0
	s_add_u32 s74, s52, 0x100
	s_addc_u32 s75, s53, 0
	s_mov_b32 s76, -2
	s_waitcnt vmcnt(0)
	ds_read_b128 v[128:131], v181
	ds_read_b128 v[132:135], v181 offset:1024
	ds_read_b128 v[136:139], v181 offset:2048
	ds_read_b128 v[140:143], v181 offset:3072
	ds_read_b128 v[144:147], v182
	ds_read_b128 v[148:151], v182 offset:1024
	ds_read_b128 v[168:171], v182 offset:2048
	ds_read_b128 v[172:175], v182 offset:3072
	s_add_u32 s52, s50, 0xfffc0080
	s_addc_u32 s53, s51, -1
	s_cmp_eq_u32 s76, 12
	s_cselect_b32 s55, s35, s53
	s_cselect_b32 s54, s72, s52
	s_cselect_b32 s53, s31, s75
	s_cselect_b32 s52, s73, s74
	v_lshl_add_u64 v[176:177], s[50:51], 0, v[160:161]
	s_add_i32 m0, s63, 0xc000
	ds_read_b128 v[184:187], v183
	ds_read_b128 v[188:191], v183 offset:1024
	ds_read_b128 v[194:197], v183 offset:2048
	ds_read_b128 v[198:201], v183 offset:3072
	ds_read_b128 v[202:205], v183 offset:4096
	ds_read_b128 v[206:209], v183 offset:5120
	ds_read_b128 v[210:213], v183 offset:6144
	ds_read_b128 v[218:221], v183 offset:7168
	global_load_lds_dwordx4 v[176:177], off
	v_lshl_add_u64 v[176:177], s[50:51], 0, v[162:163]
	s_add_i32 m0, s63, 0xe000
	s_nop 0
	global_load_lds_dwordx4 v[176:177], off
	s_waitcnt vmcnt(8)
	s_waitcnt lgkmcnt(0)
	s_barrier
	s_setprio 1
	s_waitcnt lgkmcnt(0)
	v_mfma_f32_16x16x32_bf16 v[124:127], v[128:131], v[184:187], 0
	v_mfma_f32_16x16x32_bf16 v[120:123], v[136:139], v[184:187], 0
	v_mfma_f32_16x16x32_bf16 v[108:111], v[128:131], v[194:197], 0
	v_mfma_f32_16x16x32_bf16 v[104:107], v[136:139], v[194:197], 0
	v_mfma_f32_16x16x32_bf16 v[96:99], v[128:131], v[202:205], 0
	v_mfma_f32_16x16x32_bf16 v[88:91], v[136:139], v[202:205], 0
	v_mfma_f32_16x16x32_bf16 v[80:83], v[128:131], v[210:213], 0
	v_mfma_f32_16x16x32_bf16 v[72:75], v[136:139], v[210:213], 0
	v_mfma_f32_16x16x32_bf16 v[124:127], v[132:135], v[188:191], v[124:127]
	v_mfma_f32_16x16x32_bf16 v[120:123], v[140:143], v[188:191], v[120:123]
	v_mfma_f32_16x16x32_bf16 v[108:111], v[132:135], v[198:201], v[108:111]
	v_mfma_f32_16x16x32_bf16 v[104:107], v[140:143], v[198:201], v[104:107]
	v_mfma_f32_16x16x32_bf16 v[96:99], v[132:135], v[206:209], v[96:99]
	v_mfma_f32_16x16x32_bf16 v[88:91], v[140:143], v[206:209], v[88:91]
	v_mfma_f32_16x16x32_bf16 v[80:83], v[132:135], v[218:221], v[80:83]
	v_mfma_f32_16x16x32_bf16 v[72:75], v[140:143], v[218:221], v[72:75]
	v_mfma_f32_16x16x32_bf16 v[116:119], v[144:147], v[184:187], 0
	v_mfma_f32_16x16x32_bf16 v[112:115], v[168:171], v[184:187], 0
	v_mfma_f32_16x16x32_bf16 v[100:103], v[144:147], v[194:197], 0
	v_mfma_f32_16x16x32_bf16 v[92:95], v[168:171], v[194:197], 0
	v_mfma_f32_16x16x32_bf16 v[84:87], v[144:147], v[202:205], 0
	v_mfma_f32_16x16x32_bf16 v[76:79], v[168:171], v[202:205], 0
	v_mfma_f32_16x16x32_bf16 v[68:71], v[144:147], v[210:213], 0
	v_mfma_f32_16x16x32_bf16 v[64:67], v[168:171], v[210:213], 0
	v_mfma_f32_16x16x32_bf16 v[116:119], v[148:151], v[188:191], v[116:119]
	v_mfma_f32_16x16x32_bf16 v[112:115], v[172:175], v[188:191], v[112:115]
	v_mfma_f32_16x16x32_bf16 v[100:103], v[148:151], v[198:201], v[100:103]
	v_mfma_f32_16x16x32_bf16 v[92:95], v[172:175], v[198:201], v[92:95]
	v_mfma_f32_16x16x32_bf16 v[84:87], v[148:151], v[206:209], v[84:87]
	v_mfma_f32_16x16x32_bf16 v[76:79], v[172:175], v[206:209], v[76:79]
	v_mfma_f32_16x16x32_bf16 v[68:71], v[148:151], v[218:221], v[68:71]
	v_mfma_f32_16x16x32_bf16 v[64:67], v[172:175], v[218:221], v[64:67]
	s_setprio 0
	s_barrier
	s_add_i32 s77, s70, s62
	v_lshl_add_u64 v[176:177], s[52:53], 0, v[156:157]
	s_mov_b32 m0, s77
	ds_read_b128 v[184:187], v183 offset:16384
	ds_read_b128 v[188:191], v183 offset:17408
	ds_read_b128 v[194:197], v183 offset:18432
	ds_read_b128 v[198:201], v183 offset:19456
	ds_read_b128 v[202:205], v183 offset:20480
	ds_read_b128 v[206:209], v183 offset:21504
	ds_read_b128 v[210:213], v183 offset:22528
	ds_read_b128 v[218:221], v183 offset:23552
	global_load_lds_dwordx4 v[176:177], off
	s_add_i32 m0, s77, 0x2000
	s_add_u32 s78, s52, 0x40000
	v_lshl_add_u64 v[214:215], s[52:53], 0, v[152:153]
	s_addc_u32 s79, s53, 0
	s_add_i32 s77, s71, s62
	global_load_lds_dwordx4 v[214:215], off
	v_lshl_add_u64 v[222:223], s[78:79], 0, v[156:157]
	s_mov_b32 m0, s77
	v_lshl_add_u64 v[224:225], s[54:55], 0, v[154:155]
	global_load_lds_dwordx4 v[222:223], off
	v_lshl_add_u64 v[222:223], s[78:79], 0, v[152:153]
	s_add_i32 m0, s77, 0x2000
	s_nop 0
	global_load_lds_dwordx4 v[222:223], off
	v_lshl_add_u64 v[222:223], s[54:55], 0, v[158:159]
	s_mov_b32 m0, s63
	s_nop 0
	global_load_lds_dwordx4 v[222:223], off
	s_mov_b32 m0, s64
	s_nop 0
	global_load_lds_dwordx4 v[224:225], off
	s_waitcnt vmcnt(8)
	s_waitcnt lgkmcnt(0)
	s_barrier
; #define PG8_STAGE(bufoff, gbase, voff) do { _Pragma("unroll") for (int _i = 0; _i < 2; ++_i) \
;         __builtin_amdgcn_global_load_lds((const unsigned*)((const char*)(gbase) + (voff)[_i]), (PG8_LAS unsigned*)(lds + (bufoff) + ldsw + _i * 8192), 16, 0, 0); } while (0)
; #define PG8_LDA(dst, b, h) do { _Pragma("unroll") for (int m = 0; m < 4; ++m) _Pragma("unroll") for (int k = 0; k < 2; ++k) dst[m][k] = *(const PG8_LAS bf16x8*)(lds + PG8_SA(b, h) + aoff + m * 2048 + k * 1024); } while (0)
; #define PG8_LDB(dst, b, h) do { _Pragma("unroll") for (int n = 0; n < 2; ++n) _Pragma("unroll") for (int k = 0; k < 2; ++k) dst[n][k] = *(const PG8_LAS bf16x8*)(lds + PG8_SB(b, h) + boff + n * 2048 + k * 1024); } while (0)
; #define PG8_MMA(ai, bj, At, Bt) do { __builtin_amdgcn_s_setprio(1); _Pragma("unroll") for (int m = 0; m < 4; ++m) _Pragma("unroll") for (int n = 0; n < 2; ++n) _Pragma("unroll") for (int k = 0; k < 2; ++k) \
;         acc[ai][bj][m][n] = __builtin_amdgcn_mfma_f32_16x16x32_bf16(Bt[n][k], At[m][k], acc[ai][bj][m][n], 0, 0, 0); __builtin_amdgcn_s_setprio(0); } while (0)
; #define PG8_WAIT_V(n) asm volatile("s_waitcnt vmcnt(" #n ")" ::: "memory")
; #define PG8_WAIT_L(n) asm volatile("s_waitcnt lgkmcnt(" #n ")" ::: "memory")
; #define PG8_BAR __builtin_amdgcn_s_barrier()
; #define PG8_SCHED __builtin_amdgcn_sched_barrier(0)
; template <class Epi, class Sched, bool ALIGN_EPI = false, bool SP2 = false>
; __device__ __forceinline__ void gemm_phase(PG8_LAS unsigned char* lds, const Gemm g, const Sched& S, const Epi& E) {
;     ...
;             PG8_WAIT_V(8); PG8_WAIT_L(0); PG8_BAR; PG8_MMA(1, 0, At, B0); PG8_MMA(1, 1, At, B1); PG8_BAR; PG8_SCHED;
;             PG8_LDB(B0, 1, 0); PG8_LDB(B1, 1, 1); PG8_SCHED; PG8_LDA(At, 1, 0); PG8_STAGE(PG8_SA(0, 1), a2 + hstep, voffA);
;             PG8_WAIT_V(8); PG8_WAIT_L(0); PG8_BAR; PG8_MMA(0, 0, At, B0); PG8_MMA(0, 1, At, B1); PG8_BAR; PG8_SCHED;
	s_setprio 1
	s_waitcnt lgkmcnt(0)
	v_mfma_f32_16x16x32_bf16 v[60:63], v[128:131], v[184:187], 0
	v_mfma_f32_16x16x32_bf16 v[56:59], v[136:139], v[184:187], 0
	v_mfma_f32_16x16x32_bf16 v[48:51], v[128:131], v[194:197], 0
	v_mfma_f32_16x16x32_bf16 v[40:43], v[136:139], v[194:197], 0
	v_mfma_f32_16x16x32_bf16 v[32:35], v[128:131], v[202:205], 0
	v_mfma_f32_16x16x32_bf16 v[24:27], v[136:139], v[202:205], 0
	v_mfma_f32_16x16x32_bf16 v[16:19], v[128:131], v[210:213], 0
	v_mfma_f32_16x16x32_bf16 v[8:11], v[136:139], v[210:213], 0
	v_mfma_f32_16x16x32_bf16 v[60:63], v[132:135], v[188:191], v[60:63]
	v_mfma_f32_16x16x32_bf16 v[56:59], v[140:143], v[188:191], v[56:59]
	v_mfma_f32_16x16x32_bf16 v[48:51], v[132:135], v[198:201], v[48:51]
	v_mfma_f32_16x16x32_bf16 v[40:43], v[140:143], v[198:201], v[40:43]
	v_mfma_f32_16x16x32_bf16 v[32:35], v[132:135], v[206:209], v[32:35]
	v_mfma_f32_16x16x32_bf16 v[24:27], v[140:143], v[206:209], v[24:27]
	v_mfma_f32_16x16x32_bf16 v[16:19], v[132:135], v[218:221], v[16:19]
	v_mfma_f32_16x16x32_bf16 v[8:11], v[140:143], v[218:221], v[8:11]
	v_mfma_f32_16x16x32_bf16 v[52:55], v[144:147], v[184:187], 0
	v_mfma_f32_16x16x32_bf16 v[44:47], v[168:171], v[184:187], 0
	v_mfma_f32_16x16x32_bf16 v[36:39], v[144:147], v[194:197], 0
	v_mfma_f32_16x16x32_bf16 v[28:31], v[168:171], v[194:197], 0
	v_mfma_f32_16x16x32_bf16 v[20:23], v[144:147], v[202:205], 0
	v_mfma_f32_16x16x32_bf16 v[12:15], v[168:171], v[202:205], 0
	v_mfma_f32_16x16x32_bf16 v[4:7], v[144:147], v[210:213], 0
	v_mfma_f32_16x16x32_bf16 v[0:3], v[168:171], v[210:213], 0
	v_mfma_f32_16x16x32_bf16 v[52:55], v[148:151], v[188:191], v[52:55]
	v_mfma_f32_16x16x32_bf16 v[44:47], v[172:175], v[188:191], v[44:47]
	v_mfma_f32_16x16x32_bf16 v[36:39], v[148:151], v[198:201], v[36:39]
	v_mfma_f32_16x16x32_bf16 v[28:31], v[172:175], v[198:201], v[28:31]
	v_mfma_f32_16x16x32_bf16 v[20:23], v[148:151], v[206:209], v[20:23]
	v_mfma_f32_16x16x32_bf16 v[12:15], v[172:175], v[206:209], v[12:15]
	v_mfma_f32_16x16x32_bf16 v[4:7], v[148:151], v[218:221], v[4:7]
	v_mfma_f32_16x16x32_bf16 v[0:3], v[172:175], v[218:221], v[0:3]
	s_setprio 0
	s_barrier
	s_add_i32 s77, 0, 0x18000
	s_add_i32 s78, 0, 0x1c000
	v_add_u32_e32 v140, s77, v179
	v_add_u32_e32 v172, s78, v179
	ds_read_b128 v[128:131], v140
	ds_read_b128 v[132:135], v140 offset:1024
	ds_read_b128 v[136:139], v140 offset:2048
	ds_read_b128 v[140:143], v140 offset:3072
	ds_read_b128 v[144:147], v172
	ds_read_b128 v[148:151], v172 offset:1024
	ds_read_b128 v[168:171], v172 offset:2048
	ds_read_b128 v[172:175], v172 offset:3072
	s_add_u32 s54, s54, 0x40000
	s_addc_u32 s55, s55, 0
	s_mov_b32 m0, s65
	v_lshl_add_u64 v[226:227], s[54:55], 0, v[158:159]
	ds_read_b128 v[184:187], v183 offset:32768
	ds_read_b128 v[188:191], v183 offset:33792
	ds_read_b128 v[194:197], v183 offset:34816
	ds_read_b128 v[198:201], v183 offset:35840
	ds_read_b128 v[202:205], v183 offset:36864
	ds_read_b128 v[206:209], v183 offset:37888
	ds_read_b128 v[210:213], v183 offset:38912
	ds_read_b128 v[218:221], v183 offset:39936
	global_load_lds_dwordx4 v[226:227], off
	v_lshl_add_u64 v[226:227], s[54:55], 0, v[154:155]
	s_mov_b32 m0, s66
	s_nop 0
	global_load_lds_dwordx4 v[226:227], off
	s_waitcnt vmcnt(8)
	s_waitcnt lgkmcnt(0)
	s_barrier
	s_setprio 1
	s_waitcnt lgkmcnt(0)
	v_mfma_f32_16x16x32_bf16 v[124:127], v[128:131], v[184:187], v[124:127]
	v_mfma_f32_16x16x32_bf16 v[120:123], v[136:139], v[184:187], v[120:123]
	v_mfma_f32_16x16x32_bf16 v[108:111], v[128:131], v[194:197], v[108:111]
	v_mfma_f32_16x16x32_bf16 v[104:107], v[136:139], v[194:197], v[104:107]
	v_mfma_f32_16x16x32_bf16 v[96:99], v[128:131], v[202:205], v[96:99]
	v_mfma_f32_16x16x32_bf16 v[88:91], v[136:139], v[202:205], v[88:91]
	v_mfma_f32_16x16x32_bf16 v[80:83], v[128:131], v[210:213], v[80:83]
	v_mfma_f32_16x16x32_bf16 v[72:75], v[136:139], v[210:213], v[72:75]
	v_mfma_f32_16x16x32_bf16 v[124:127], v[132:135], v[188:191], v[124:127]
	v_mfma_f32_16x16x32_bf16 v[120:123], v[140:143], v[188:191], v[120:123]
	v_mfma_f32_16x16x32_bf16 v[108:111], v[132:135], v[198:201], v[108:111]
	v_mfma_f32_16x16x32_bf16 v[104:107], v[140:143], v[198:201], v[104:107]
	v_mfma_f32_16x16x32_bf16 v[96:99], v[132:135], v[206:209], v[96:99]
	v_mfma_f32_16x16x32_bf16 v[88:91], v[140:143], v[206:209], v[88:91]
	v_mfma_f32_16x16x32_bf16 v[80:83], v[132:135], v[218:221], v[80:83]
	v_mfma_f32_16x16x32_bf16 v[72:75], v[140:143], v[218:221], v[72:75]
	v_mfma_f32_16x16x32_bf16 v[116:119], v[144:147], v[184:187], v[116:119]
	v_mfma_f32_16x16x32_bf16 v[112:115], v[168:171], v[184:187], v[112:115]
	v_mfma_f32_16x16x32_bf16 v[100:103], v[144:147], v[194:197], v[100:103]
	v_mfma_f32_16x16x32_bf16 v[92:95], v[168:171], v[194:197], v[92:95]
	v_mfma_f32_16x16x32_bf16 v[84:87], v[144:147], v[202:205], v[84:87]
	v_mfma_f32_16x16x32_bf16 v[76:79], v[168:171], v[202:205], v[76:79]
	v_mfma_f32_16x16x32_bf16 v[68:71], v[144:147], v[210:213], v[68:71]
	v_mfma_f32_16x16x32_bf16 v[64:67], v[168:171], v[210:213], v[64:67]
	v_mfma_f32_16x16x32_bf16 v[116:119], v[148:151], v[188:191], v[116:119]
	v_mfma_f32_16x16x32_bf16 v[112:115], v[172:175], v[188:191], v[112:115]
	v_mfma_f32_16x16x32_bf16 v[100:103], v[148:151], v[198:201], v[100:103]
	v_mfma_f32_16x16x32_bf16 v[92:95], v[172:175], v[198:201], v[92:95]
	v_mfma_f32_16x16x32_bf16 v[84:87], v[148:151], v[206:209], v[84:87]
	v_mfma_f32_16x16x32_bf16 v[76:79], v[172:175], v[206:209], v[76:79]
	v_mfma_f32_16x16x32_bf16 v[68:71], v[148:151], v[218:221], v[68:71]
	v_mfma_f32_16x16x32_bf16 v[64:67], v[172:175], v[218:221], v[64:67]
	s_setprio 0
	s_barrier
; #define PG8_STAGE(bufoff, gbase, voff) do { _Pragma("unroll") for (int _i = 0; _i < 2; ++_i) \
;         __builtin_amdgcn_global_load_lds((const unsigned*)((const char*)(gbase) + (voff)[_i]), (PG8_LAS unsigned*)(lds + (bufoff) + ldsw + _i * 8192), 16, 0, 0); } while (0)
; #define PG8_LDA(dst, b, h) do { _Pragma("unroll") for (int m = 0; m < 4; ++m) _Pragma("unroll") for (int k = 0; k < 2; ++k) dst[m][k] = *(const PG8_LAS bf16x8*)(lds + PG8_SA(b, h) + aoff + m * 2048 + k * 1024); } while (0)
; #define PG8_LDB(dst, b, h) do { _Pragma("unroll") for (int n = 0; n < 2; ++n) _Pragma("unroll") for (int k = 0; k < 2; ++k) dst[n][k] = *(const PG8_LAS bf16x8*)(lds + PG8_SB(b, h) + boff + n * 2048 + k * 1024); } while (0)
; #define PG8_MMA(ai, bj, At, Bt) do { __builtin_amdgcn_s_setprio(1); _Pragma("unroll") for (int m = 0; m < 4; ++m) _Pragma("unroll") for (int n = 0; n < 2; ++n) _Pragma("unroll") for (int k = 0; k < 2; ++k) \
;         acc[ai][bj][m][n] = __builtin_amdgcn_mfma_f32_16x16x32_bf16(Bt[n][k], At[m][k], acc[ai][bj][m][n], 0, 0, 0); __builtin_amdgcn_s_setprio(0); } while (0)
; #define PG8_WAIT_V(n) asm volatile("s_waitcnt vmcnt(" #n ")" ::: "memory")
; template <class Epi, class Sched, bool ALIGN_EPI = false, bool SP2 = false>
; __device__ __forceinline__ void gemm_phase(PG8_LAS unsigned char* lds, const Gemm g, const Sched& S, const Epi& E) {
;     ...
;             PG8_LDB(B0, 0, 0); PG8_LDB(B1, 0, 1); PG8_SCHED; PG8_LDA(At, 0, 0); PG8_STAGE(PG8_SA(1, 1), a1 + hstep, voffA);
;             PG8_WAIT_V(8); PG8_WAIT_L(0); PG8_BAR; PG8_MMA(0, 0, At, B0); PG8_MMA(0, 1, At, B1); PG8_BAR; PG8_SCHED;
;             PG8_LDA(At, 0, 1); PG8_STAGE(PG8_SB(0, 0), b2, voffB); PG8_STAGE(PG8_SB(0, 1), b2 + hstep, voffB); PG8_STAGE(PG8_SA(0, 0), a2, voffA);
;             PG8_WAIT_V(8); PG8_WAIT_L(0); PG8_BAR; PG8_MMA(1, 0, At, B0); PG8_MMA(1, 1, At, B1); PG8_BAR; PG8_SCHED;
;             PG8_LDB(B0, 1, 0); PG8_LDB(B1, 1, 1); PG8_SCHED; PG8_LDA(At, 1, 0); PG8_STAGE(PG8_SA(0, 1), a2 + hstep, voffA);
;             PG8_WAIT_V(8); PG8_WAIT_L(0); PG8_BAR; PG8_MMA(0, 0, At, B0); PG8_MMA(0, 1, At, B1); PG8_BAR; PG8_SCHED;
;             PG8_LDA(At, 1, 1); PG8_STAGE(PG8_SB(1, 0), b3, voffB); PG8_STAGE(PG8_SB(1, 1), b3 + hstep, voffB); PG8_STAGE(PG8_SA(1, 0), a3, voffA);
;             PG8_WAIT_V(8); PG8_WAIT_L(0); PG8_BAR; PG8_MMA(1, 0, At, B0); PG8_MMA(1, 1, At, B1); PG8_BAR; PG8_SCHED;
	s_add_i32 s54, s77, s62
	v_lshl_add_u64 v[176:177], v[176:177], 0, s[26:27]
	s_mov_b32 m0, s54
	ds_read_b128 v[184:187], v183 offset:49152
	ds_read_b128 v[188:191], v183 offset:50176
	ds_read_b128 v[194:197], v183 offset:51200
	ds_read_b128 v[198:201], v183 offset:52224
	ds_read_b128 v[202:205], v183 offset:53248
	ds_read_b128 v[206:209], v183 offset:54272
	ds_read_b128 v[210:213], v183 offset:55296
	ds_read_b128 v[218:221], v183 offset:56320
	global_load_lds_dwordx4 v[176:177], off
	s_add_i32 m0, s54, 0x2000
	s_add_u32 s52, s52, 0x40080
	v_lshl_add_u64 v[176:177], v[214:215], 0, s[26:27]
	s_addc_u32 s53, s53, 0
	s_add_i32 s54, s78, s62
	global_load_lds_dwordx4 v[176:177], off
	v_lshl_add_u64 v[176:177], s[52:53], 0, v[156:157]
	s_mov_b32 m0, s54
	s_nop 0
	global_load_lds_dwordx4 v[176:177], off
	v_lshl_add_u64 v[176:177], s[52:53], 0, v[152:153]
	s_add_i32 m0, s54, 0x2000
	s_nop 0
	global_load_lds_dwordx4 v[176:177], off
	v_lshl_add_u64 v[176:177], v[222:223], 0, s[26:27]
	s_mov_b32 m0, s68
	s_nop 0
	global_load_lds_dwordx4 v[176:177], off
	v_lshl_add_u64 v[176:177], v[224:225], 0, s[26:27]
	s_mov_b32 m0, s69
	s_nop 0
	global_load_lds_dwordx4 v[176:177], off
	s_waitcnt vmcnt(8)
	s_waitcnt lgkmcnt(0)
	s_barrier
	s_setprio 1
	s_waitcnt lgkmcnt(0)
	v_mfma_f32_16x16x32_bf16 v[60:63], v[128:131], v[184:187], v[60:63]
	v_mfma_f32_16x16x32_bf16 v[56:59], v[136:139], v[184:187], v[56:59]
	v_mfma_f32_16x16x32_bf16 v[48:51], v[128:131], v[194:197], v[48:51]
	v_mfma_f32_16x16x32_bf16 v[40:43], v[136:139], v[194:197], v[40:43]
	v_mfma_f32_16x16x32_bf16 v[32:35], v[128:131], v[202:205], v[32:35]
	v_mfma_f32_16x16x32_bf16 v[24:27], v[136:139], v[202:205], v[24:27]
	v_mfma_f32_16x16x32_bf16 v[16:19], v[128:131], v[210:213], v[16:19]
	v_mfma_f32_16x16x32_bf16 v[8:11], v[136:139], v[210:213], v[8:11]
	v_mfma_f32_16x16x32_bf16 v[60:63], v[132:135], v[188:191], v[60:63]
	v_mfma_f32_16x16x32_bf16 v[56:59], v[140:143], v[188:191], v[56:59]
	v_mfma_f32_16x16x32_bf16 v[48:51], v[132:135], v[198:201], v[48:51]
	v_mfma_f32_16x16x32_bf16 v[40:43], v[140:143], v[198:201], v[40:43]
	v_mfma_f32_16x16x32_bf16 v[32:35], v[132:135], v[206:209], v[32:35]
	v_mfma_f32_16x16x32_bf16 v[24:27], v[140:143], v[206:209], v[24:27]
	v_mfma_f32_16x16x32_bf16 v[16:19], v[132:135], v[218:221], v[16:19]
	v_mfma_f32_16x16x32_bf16 v[8:11], v[140:143], v[218:221], v[8:11]
	v_mfma_f32_16x16x32_bf16 v[52:55], v[144:147], v[184:187], v[52:55]
	v_mfma_f32_16x16x32_bf16 v[44:47], v[168:171], v[184:187], v[44:47]
	v_mfma_f32_16x16x32_bf16 v[36:39], v[144:147], v[194:197], v[36:39]
	v_mfma_f32_16x16x32_bf16 v[28:31], v[168:171], v[194:197], v[28:31]
	v_mfma_f32_16x16x32_bf16 v[20:23], v[144:147], v[202:205], v[20:23]
	v_mfma_f32_16x16x32_bf16 v[12:15], v[168:171], v[202:205], v[12:15]
	v_mfma_f32_16x16x32_bf16 v[4:7], v[144:147], v[210:213], v[4:7]
	v_mfma_f32_16x16x32_bf16 v[0:3], v[168:171], v[210:213], v[0:3]
	v_mfma_f32_16x16x32_bf16 v[52:55], v[148:151], v[188:191], v[52:55]
	v_mfma_f32_16x16x32_bf16 v[44:47], v[172:175], v[188:191], v[44:47]
	v_mfma_f32_16x16x32_bf16 v[36:39], v[148:151], v[198:201], v[36:39]
	v_mfma_f32_16x16x32_bf16 v[28:31], v[172:175], v[198:201], v[28:31]
	v_mfma_f32_16x16x32_bf16 v[20:23], v[148:151], v[206:209], v[20:23]
	v_mfma_f32_16x16x32_bf16 v[12:15], v[172:175], v[206:209], v[12:15]
	v_mfma_f32_16x16x32_bf16 v[4:7], v[148:151], v[218:221], v[4:7]
	v_mfma_f32_16x16x32_bf16 v[0:3], v[172:175], v[218:221], v[0:3]
	s_setprio 0
	s_barrier
	s_add_i32 s76, s76, 2
	s_add_u32 s50, s50, 0x100
	s_addc_u32 s51, s51, 0
	s_add_u32 s74, s74, 0x100
	s_addc_u32 s75, s75, 0
	s_cmp_gt_u32 s76, 13
.LBB0_553:
	ds_read_b128 v[128:131], v181
	ds_read_b128 v[132:135], v181 offset:1024
	ds_read_b128 v[136:139], v181 offset:2048
	ds_read_b128 v[140:143], v181 offset:3072
	ds_read_b128 v[144:147], v182
	ds_read_b128 v[148:151], v182 offset:1024
	ds_read_b128 v[168:171], v182 offset:2048
	ds_read_b128 v[172:175], v182 offset:3072
	s_add_u32 s52, s50, 0xfffc0080
	s_addc_u32 s53, s51, -1
	s_cmp_eq_u32 s76, 12
	s_cselect_b32 s55, s35, s53
	s_cselect_b32 s54, s72, s52
	s_cselect_b32 s53, s31, s75
	s_cselect_b32 s52, s73, s74
	v_lshl_add_u64 v[176:177], s[50:51], 0, v[160:161]
	s_add_i32 m0, s63, 0xc000
	ds_read_b128 v[184:187], v183
	ds_read_b128 v[188:191], v183 offset:1024
	ds_read_b128 v[194:197], v183 offset:2048
	ds_read_b128 v[198:201], v183 offset:3072
	ds_read_b128 v[202:205], v183 offset:4096
	ds_read_b128 v[206:209], v183 offset:5120
	ds_read_b128 v[210:213], v183 offset:6144
	ds_read_b128 v[218:221], v183 offset:7168
	global_load_lds_dwordx4 v[176:177], off
	v_lshl_add_u64 v[176:177], s[50:51], 0, v[162:163]
	s_add_i32 m0, s63, 0xe000
	s_nop 0
	global_load_lds_dwordx4 v[176:177], off
	s_waitcnt vmcnt(8)
	s_waitcnt lgkmcnt(0)
	s_barrier
; #define PG8_STAGE(bufoff, gbase, voff) do { _Pragma("unroll") for (int _i = 0; _i < 2; ++_i) \
;         __builtin_amdgcn_global_load_lds((const unsigned*)((const char*)(gbase) + (voff)[_i]), (PG8_LAS unsigned*)(lds + (bufoff) + ldsw + _i * 8192), 16, 0, 0); } while (0)
; #define PG8_LDA(dst, b, h) do { _Pragma("unroll") for (int m = 0; m < 4; ++m) _Pragma("unroll") for (int k = 0; k < 2; ++k) dst[m][k] = *(const PG8_LAS bf16x8*)(lds + PG8_SA(b, h) + aoff + m * 2048 + k * 1024); } while (0)
; #define PG8_MMA(ai, bj, At, Bt) do { __builtin_amdgcn_s_setprio(1); _Pragma("unroll") for (int m = 0; m < 4; ++m) _Pragma("unroll") for (int n = 0; n < 2; ++n) _Pragma("unroll") for (int k = 0; k < 2; ++k) \
;         acc[ai][bj][m][n] = __builtin_amdgcn_mfma_f32_16x16x32_bf16(Bt[n][k], At[m][k], acc[ai][bj][m][n], 0, 0, 0); __builtin_amdgcn_s_setprio(0); } while (0)
; #define PG8_WAIT_V(n) asm volatile("s_waitcnt vmcnt(" #n ")" ::: "memory")
; #define PG8_WAIT_L(n) asm volatile("s_waitcnt lgkmcnt(" #n ")" ::: "memory")
; #define PG8_BAR __builtin_amdgcn_s_barrier()
; #define PG8_SCHED __builtin_amdgcn_sched_barrier(0)
; template <class Epi, class Sched, bool ALIGN_EPI = false, bool SP2 = false>
; __device__ __forceinline__ void gemm_phase(PG8_LAS unsigned char* lds, const Gemm g, const Sched& S, const Epi& E) {
;     ...
;             PG8_WAIT_V(8); PG8_WAIT_L(0); PG8_BAR; PG8_MMA(0, 0, At, B0); PG8_MMA(0, 1, At, B1); PG8_BAR; PG8_SCHED;
;             PG8_LDA(At, 0, 1); PG8_STAGE(PG8_SB(0, 0), b2, voffB); PG8_STAGE(PG8_SB(0, 1), b2 + hstep, voffB); PG8_STAGE(PG8_SA(0, 0), a2, voffA);
;             PG8_WAIT_V(8); PG8_WAIT_L(0); PG8_BAR; PG8_MMA(1, 0, At, B0); PG8_MMA(1, 1, At, B1); PG8_BAR; PG8_SCHED;
	s_setprio 1
	s_waitcnt lgkmcnt(0)
	v_mfma_f32_16x16x32_bf16 v[124:127], v[128:131], v[184:187], v[124:127]
	v_mfma_f32_16x16x32_bf16 v[120:123], v[136:139], v[184:187], v[120:123]
	v_mfma_f32_16x16x32_bf16 v[108:111], v[128:131], v[194:197], v[108:111]
	v_mfma_f32_16x16x32_bf16 v[104:107], v[136:139], v[194:197], v[104:107]
	v_mfma_f32_16x16x32_bf16 v[96:99], v[128:131], v[202:205], v[96:99]
	v_mfma_f32_16x16x32_bf16 v[88:91], v[136:139], v[202:205], v[88:91]
	v_mfma_f32_16x16x32_bf16 v[80:83], v[128:131], v[210:213], v[80:83]
	v_mfma_f32_16x16x32_bf16 v[72:75], v[136:139], v[210:213], v[72:75]
	v_mfma_f32_16x16x32_bf16 v[124:127], v[132:135], v[188:191], v[124:127]
	v_mfma_f32_16x16x32_bf16 v[120:123], v[140:143], v[188:191], v[120:123]
	v_mfma_f32_16x16x32_bf16 v[108:111], v[132:135], v[198:201], v[108:111]
	v_mfma_f32_16x16x32_bf16 v[104:107], v[140:143], v[198:201], v[104:107]
	v_mfma_f32_16x16x32_bf16 v[96:99], v[132:135], v[206:209], v[96:99]
	v_mfma_f32_16x16x32_bf16 v[88:91], v[140:143], v[206:209], v[88:91]
	v_mfma_f32_16x16x32_bf16 v[80:83], v[132:135], v[218:221], v[80:83]
	v_mfma_f32_16x16x32_bf16 v[72:75], v[140:143], v[218:221], v[72:75]
	v_mfma_f32_16x16x32_bf16 v[116:119], v[144:147], v[184:187], v[116:119]
	v_mfma_f32_16x16x32_bf16 v[112:115], v[168:171], v[184:187], v[112:115]
	v_mfma_f32_16x16x32_bf16 v[100:103], v[144:147], v[194:197], v[100:103]
	v_mfma_f32_16x16x32_bf16 v[92:95], v[168:171], v[194:197], v[92:95]
	v_mfma_f32_16x16x32_bf16 v[84:87], v[144:147], v[202:205], v[84:87]
	v_mfma_f32_16x16x32_bf16 v[76:79], v[168:171], v[202:205], v[76:79]
	v_mfma_f32_16x16x32_bf16 v[68:71], v[144:147], v[210:213], v[68:71]
	v_mfma_f32_16x16x32_bf16 v[64:67], v[168:171], v[210:213], v[64:67]
	v_mfma_f32_16x16x32_bf16 v[116:119], v[148:151], v[188:191], v[116:119]
	v_mfma_f32_16x16x32_bf16 v[112:115], v[172:175], v[188:191], v[112:115]
	v_mfma_f32_16x16x32_bf16 v[100:103], v[148:151], v[198:201], v[100:103]
	v_mfma_f32_16x16x32_bf16 v[92:95], v[172:175], v[198:201], v[92:95]
	v_mfma_f32_16x16x32_bf16 v[84:87], v[148:151], v[206:209], v[84:87]
	v_mfma_f32_16x16x32_bf16 v[76:79], v[172:175], v[206:209], v[76:79]
	v_mfma_f32_16x16x32_bf16 v[68:71], v[148:151], v[218:221], v[68:71]
	v_mfma_f32_16x16x32_bf16 v[64:67], v[172:175], v[218:221], v[64:67]
	s_setprio 0
	s_barrier
	s_add_i32 s77, s70, s62
	v_lshl_add_u64 v[176:177], s[52:53], 0, v[156:157]
	s_mov_b32 m0, s77
	ds_read_b128 v[184:187], v183 offset:16384
	ds_read_b128 v[188:191], v183 offset:17408
	ds_read_b128 v[194:197], v183 offset:18432
	ds_read_b128 v[198:201], v183 offset:19456
	ds_read_b128 v[202:205], v183 offset:20480
	ds_read_b128 v[206:209], v183 offset:21504
	ds_read_b128 v[210:213], v183 offset:22528
	ds_read_b128 v[218:221], v183 offset:23552
	global_load_lds_dwordx4 v[176:177], off
	s_add_i32 m0, s77, 0x2000
	s_add_u32 s78, s52, 0x40000
	v_lshl_add_u64 v[214:215], s[52:53], 0, v[152:153]
	s_addc_u32 s79, s53, 0
	s_add_i32 s77, s71, s62
	global_load_lds_dwordx4 v[214:215], off
	v_lshl_add_u64 v[222:223], s[78:79], 0, v[156:157]
	s_mov_b32 m0, s77
	v_lshl_add_u64 v[224:225], s[54:55], 0, v[154:155]
	global_load_lds_dwordx4 v[222:223], off
	v_lshl_add_u64 v[222:223], s[78:79], 0, v[152:153]
	s_add_i32 m0, s77, 0x2000
	s_nop 0
	global_load_lds_dwordx4 v[222:223], off
	v_lshl_add_u64 v[222:223], s[54:55], 0, v[158:159]
	s_mov_b32 m0, s63
	s_nop 0
	global_load_lds_dwordx4 v[222:223], off
	s_mov_b32 m0, s64
	s_nop 0
	global_load_lds_dwordx4 v[224:225], off
	s_waitcnt vmcnt(8)
	s_waitcnt lgkmcnt(0)
	s_barrier
	s_setprio 1
	s_waitcnt lgkmcnt(0)
	v_mfma_f32_16x16x32_bf16 v[60:63], v[128:131], v[184:187], v[60:63]
	v_mfma_f32_16x16x32_bf16 v[56:59], v[136:139], v[184:187], v[56:59]
	v_mfma_f32_16x16x32_bf16 v[48:51], v[128:131], v[194:197], v[48:51]
	v_mfma_f32_16x16x32_bf16 v[40:43], v[136:139], v[194:197], v[40:43]
	v_mfma_f32_16x16x32_bf16 v[32:35], v[128:131], v[202:205], v[32:35]
	v_mfma_f32_16x16x32_bf16 v[24:27], v[136:139], v[202:205], v[24:27]
	v_mfma_f32_16x16x32_bf16 v[16:19], v[128:131], v[210:213], v[16:19]
	v_mfma_f32_16x16x32_bf16 v[8:11], v[136:139], v[210:213], v[8:11]
	v_mfma_f32_16x16x32_bf16 v[60:63], v[132:135], v[188:191], v[60:63]
	v_mfma_f32_16x16x32_bf16 v[56:59], v[140:143], v[188:191], v[56:59]
	v_mfma_f32_16x16x32_bf16 v[48:51], v[132:135], v[198:201], v[48:51]
	v_mfma_f32_16x16x32_bf16 v[40:43], v[140:143], v[198:201], v[40:43]
	v_mfma_f32_16x16x32_bf16 v[32:35], v[132:135], v[206:209], v[32:35]
	v_mfma_f32_16x16x32_bf16 v[24:27], v[140:143], v[206:209], v[24:27]
	v_mfma_f32_16x16x32_bf16 v[16:19], v[132:135], v[218:221], v[16:19]
	v_mfma_f32_16x16x32_bf16 v[8:11], v[140:143], v[218:221], v[8:11]
	v_mfma_f32_16x16x32_bf16 v[52:55], v[144:147], v[184:187], v[52:55]
	v_mfma_f32_16x16x32_bf16 v[44:47], v[168:171], v[184:187], v[44:47]
	v_mfma_f32_16x16x32_bf16 v[36:39], v[144:147], v[194:197], v[36:39]
	v_mfma_f32_16x16x32_bf16 v[28:31], v[168:171], v[194:197], v[28:31]
	v_mfma_f32_16x16x32_bf16 v[20:23], v[144:147], v[202:205], v[20:23]
	v_mfma_f32_16x16x32_bf16 v[12:15], v[168:171], v[202:205], v[12:15]
	v_mfma_f32_16x16x32_bf16 v[4:7], v[144:147], v[210:213], v[4:7]
	v_mfma_f32_16x16x32_bf16 v[0:3], v[168:171], v[210:213], v[0:3]
	v_mfma_f32_16x16x32_bf16 v[52:55], v[148:151], v[188:191], v[52:55]
	v_mfma_f32_16x16x32_bf16 v[44:47], v[172:175], v[188:191], v[44:47]
	v_mfma_f32_16x16x32_bf16 v[36:39], v[148:151], v[198:201], v[36:39]
	v_mfma_f32_16x16x32_bf16 v[28:31], v[172:175], v[198:201], v[28:31]
	v_mfma_f32_16x16x32_bf16 v[20:23], v[148:151], v[206:209], v[20:23]
	v_mfma_f32_16x16x32_bf16 v[12:15], v[172:175], v[206:209], v[12:15]
	v_mfma_f32_16x16x32_bf16 v[4:7], v[148:151], v[218:221], v[4:7]
	v_mfma_f32_16x16x32_bf16 v[0:3], v[172:175], v[218:221], v[0:3]
	s_setprio 0
	s_barrier
; #define PG8_STAGE(bufoff, gbase, voff) do { _Pragma("unroll") for (int _i = 0; _i < 2; ++_i) \
;         __builtin_amdgcn_global_load_lds((const unsigned*)((const char*)(gbase) + (voff)[_i]), (PG8_LAS unsigned*)(lds + (bufoff) + ldsw + _i * 8192), 16, 0, 0); } while (0)
; #define PG8_LDA(dst, b, h) do { _Pragma("unroll") for (int m = 0; m < 4; ++m) _Pragma("unroll") for (int k = 0; k < 2; ++k) dst[m][k] = *(const PG8_LAS bf16x8*)(lds + PG8_SA(b, h) + aoff + m * 2048 + k * 1024); } while (0)
; #define PG8_LDB(dst, b, h) do { _Pragma("unroll") for (int n = 0; n < 2; ++n) _Pragma("unroll") for (int k = 0; k < 2; ++k) dst[n][k] = *(const PG8_LAS bf16x8*)(lds + PG8_SB(b, h) + boff + n * 2048 + k * 1024); } while (0)
; #define PG8_MMA(ai, bj, At, Bt) do { __builtin_amdgcn_s_setprio(1); _Pragma("unroll") for (int m = 0; m < 4; ++m) _Pragma("unroll") for (int n = 0; n < 2; ++n) _Pragma("unroll") for (int k = 0; k < 2; ++k) \
;         acc[ai][bj][m][n] = __builtin_amdgcn_mfma_f32_16x16x32_bf16(Bt[n][k], At[m][k], acc[ai][bj][m][n], 0, 0, 0); __builtin_amdgcn_s_setprio(0); } while (0)
; #define PG8_WAIT_V(n) asm volatile("s_waitcnt vmcnt(" #n ")" ::: "memory")
; #define PG8_WAIT_L(n) asm volatile("s_waitcnt lgkmcnt(" #n ")" ::: "memory")
; #define PG8_BAR __builtin_amdgcn_s_barrier()
; #define PG8_SCHED __builtin_amdgcn_sched_barrier(0)
; template <class Epi, class Sched, bool ALIGN_EPI = false, bool SP2 = false>
; __device__ __forceinline__ void gemm_phase(PG8_LAS unsigned char* lds, const Gemm g, const Sched& S, const Epi& E) {
;     ...
;             PG8_LDB(B0, 1, 0); PG8_LDB(B1, 1, 1); PG8_SCHED; PG8_LDA(At, 1, 0); PG8_STAGE(PG8_SA(0, 1), a2 + hstep, voffA);
;             PG8_WAIT_V(8); PG8_WAIT_L(0); PG8_BAR; PG8_MMA(0, 0, At, B0); PG8_MMA(0, 1, At, B1); PG8_BAR; PG8_SCHED;
	s_add_i32 s77, 0, 0x18000
	s_add_i32 s78, 0, 0x1c000
	v_add_u32_e32 v140, s77, v179
	v_add_u32_e32 v172, s78, v179
	ds_read_b128 v[128:131], v140
	ds_read_b128 v[132:135], v140 offset:1024
	ds_read_b128 v[136:139], v140 offset:2048
	ds_read_b128 v[140:143], v140 offset:3072
	ds_read_b128 v[144:147], v172
	ds_read_b128 v[148:151], v172 offset:1024
	ds_read_b128 v[168:171], v172 offset:2048
	ds_read_b128 v[172:175], v172 offset:3072
	s_add_u32 s54, s54, 0x40000
	s_addc_u32 s55, s55, 0
	s_mov_b32 m0, s65
	v_lshl_add_u64 v[226:227], s[54:55], 0, v[158:159]
	ds_read_b128 v[184:187], v183 offset:32768
	ds_read_b128 v[188:191], v183 offset:33792
	ds_read_b128 v[194:197], v183 offset:34816
	ds_read_b128 v[198:201], v183 offset:35840
	ds_read_b128 v[202:205], v183 offset:36864
	ds_read_b128 v[206:209], v183 offset:37888
	ds_read_b128 v[210:213], v183 offset:38912
	ds_read_b128 v[218:221], v183 offset:39936
	global_load_lds_dwordx4 v[226:227], off
	v_lshl_add_u64 v[226:227], s[54:55], 0, v[154:155]
	s_mov_b32 m0, s66
	s_nop 0
	global_load_lds_dwordx4 v[226:227], off
	s_waitcnt vmcnt(8)
	s_waitcnt lgkmcnt(0)
	s_barrier
	s_setprio 1
	s_waitcnt lgkmcnt(0)
	v_mfma_f32_16x16x32_bf16 v[124:127], v[128:131], v[184:187], v[124:127]
	v_mfma_f32_16x16x32_bf16 v[120:123], v[136:139], v[184:187], v[120:123]
	v_mfma_f32_16x16x32_bf16 v[108:111], v[128:131], v[194:197], v[108:111]
	v_mfma_f32_16x16x32_bf16 v[104:107], v[136:139], v[194:197], v[104:107]
	v_mfma_f32_16x16x32_bf16 v[96:99], v[128:131], v[202:205], v[96:99]
	v_mfma_f32_16x16x32_bf16 v[88:91], v[136:139], v[202:205], v[88:91]
	v_mfma_f32_16x16x32_bf16 v[80:83], v[128:131], v[210:213], v[80:83]
	v_mfma_f32_16x16x32_bf16 v[72:75], v[136:139], v[210:213], v[72:75]
	v_mfma_f32_16x16x32_bf16 v[124:127], v[132:135], v[188:191], v[124:127]
	v_mfma_f32_16x16x32_bf16 v[120:123], v[140:143], v[188:191], v[120:123]
	v_mfma_f32_16x16x32_bf16 v[108:111], v[132:135], v[198:201], v[108:111]
	v_mfma_f32_16x16x32_bf16 v[104:107], v[140:143], v[198:201], v[104:107]
	v_mfma_f32_16x16x32_bf16 v[96:99], v[132:135], v[206:209], v[96:99]
	v_mfma_f32_16x16x32_bf16 v[88:91], v[140:143], v[206:209], v[88:91]
	v_mfma_f32_16x16x32_bf16 v[80:83], v[132:135], v[218:221], v[80:83]
	v_mfma_f32_16x16x32_bf16 v[72:75], v[140:143], v[218:221], v[72:75]
	v_mfma_f32_16x16x32_bf16 v[116:119], v[144:147], v[184:187], v[116:119]
	v_mfma_f32_16x16x32_bf16 v[112:115], v[168:171], v[184:187], v[112:115]
	v_mfma_f32_16x16x32_bf16 v[100:103], v[144:147], v[194:197], v[100:103]
	v_mfma_f32_16x16x32_bf16 v[92:95], v[168:171], v[194:197], v[92:95]
	v_mfma_f32_16x16x32_bf16 v[84:87], v[144:147], v[202:205], v[84:87]
	v_mfma_f32_16x16x32_bf16 v[76:79], v[168:171], v[202:205], v[76:79]
	v_mfma_f32_16x16x32_bf16 v[68:71], v[144:147], v[210:213], v[68:71]
	v_mfma_f32_16x16x32_bf16 v[64:67], v[168:171], v[210:213], v[64:67]
	v_mfma_f32_16x16x32_bf16 v[116:119], v[148:151], v[188:191], v[116:119]
	v_mfma_f32_16x16x32_bf16 v[112:115], v[172:175], v[188:191], v[112:115]
	v_mfma_f32_16x16x32_bf16 v[100:103], v[148:151], v[198:201], v[100:103]
	v_mfma_f32_16x16x32_bf16 v[92:95], v[172:175], v[198:201], v[92:95]
	v_mfma_f32_16x16x32_bf16 v[84:87], v[148:151], v[206:209], v[84:87]
	v_mfma_f32_16x16x32_bf16 v[76:79], v[172:175], v[206:209], v[76:79]
	v_mfma_f32_16x16x32_bf16 v[68:71], v[148:151], v[218:221], v[68:71]
	v_mfma_f32_16x16x32_bf16 v[64:67], v[172:175], v[218:221], v[64:67]
	s_setprio 0
	s_barrier
; #define PG8_STAGE(bufoff, gbase, voff) do { _Pragma("unroll") for (int _i = 0; _i < 2; ++_i) \
;         __builtin_amdgcn_global_load_lds((const unsigned*)((const char*)(gbase) + (voff)[_i]), (PG8_LAS unsigned*)(lds + (bufoff) + ldsw + _i * 8192), 16, 0, 0); } while (0)
; #define PG8_LDA(dst, b, h) do { _Pragma("unroll") for (int m = 0; m < 4; ++m) _Pragma("unroll") for (int k = 0; k < 2; ++k) dst[m][k] = *(const PG8_LAS bf16x8*)(lds + PG8_SA(b, h) + aoff + m * 2048 + k * 1024); } while (0)
; #define PG8_MMA(ai, bj, At, Bt) do { __builtin_amdgcn_s_setprio(1); _Pragma("unroll") for (int m = 0; m < 4; ++m) _Pragma("unroll") for (int n = 0; n < 2; ++n) _Pragma("unroll") for (int k = 0; k < 2; ++k) \
;         acc[ai][bj][m][n] = __builtin_amdgcn_mfma_f32_16x16x32_bf16(Bt[n][k], At[m][k], acc[ai][bj][m][n], 0, 0, 0); __builtin_amdgcn_s_setprio(0); } while (0)
; #define PG8_WAIT_V(n) asm volatile("s_waitcnt vmcnt(" #n ")" ::: "memory")
; #define PG8_WAIT_L(n) asm volatile("s_waitcnt lgkmcnt(" #n ")" ::: "memory")
; #define PG8_BAR __builtin_amdgcn_s_barrier()
; #define PG8_SCHED __builtin_amdgcn_sched_barrier(0)
; template <class Epi, class Sched, bool ALIGN_EPI = false, bool SP2 = false>
; __device__ __forceinline__ void gemm_phase(PG8_LAS unsigned char* lds, const Gemm g, const Sched& S, const Epi& E) {
;     ...
;             PG8_LDA(At, 1, 1); PG8_STAGE(PG8_SB(1, 0), b3, voffB); PG8_STAGE(PG8_SB(1, 1), b3 + hstep, voffB); PG8_STAGE(PG8_SA(1, 0), a3, voffA);
;             PG8_WAIT_V(8); PG8_WAIT_L(0); PG8_BAR; PG8_MMA(1, 0, At, B0); PG8_MMA(1, 1, At, B1); PG8_BAR; PG8_SCHED;
;     ...
;         if constexpr (ALIGN_EPI) { if (wr == 0) PG8_BAR; }
	s_add_i32 s54, s77, s62
	v_lshl_add_u64 v[176:177], v[176:177], 0, s[26:27]
	s_mov_b32 m0, s54
	ds_read_b128 v[184:187], v183 offset:49152
	ds_read_b128 v[188:191], v183 offset:50176
	ds_read_b128 v[194:197], v183 offset:51200
	ds_read_b128 v[198:201], v183 offset:52224
	ds_read_b128 v[202:205], v183 offset:53248
	ds_read_b128 v[206:209], v183 offset:54272
	ds_read_b128 v[210:213], v183 offset:55296
	ds_read_b128 v[218:221], v183 offset:56320
	global_load_lds_dwordx4 v[176:177], off
	s_add_i32 m0, s54, 0x2000
	s_add_u32 s52, s52, 0x40080
	v_lshl_add_u64 v[176:177], v[214:215], 0, s[26:27]
	s_addc_u32 s53, s53, 0
	s_add_i32 s54, s78, s62
	global_load_lds_dwordx4 v[176:177], off
	v_lshl_add_u64 v[176:177], s[52:53], 0, v[156:157]
	s_mov_b32 m0, s54
	s_nop 0
	global_load_lds_dwordx4 v[176:177], off
	v_lshl_add_u64 v[176:177], s[52:53], 0, v[152:153]
	s_add_i32 m0, s54, 0x2000
	s_nop 0
	global_load_lds_dwordx4 v[176:177], off
	v_lshl_add_u64 v[176:177], v[222:223], 0, s[26:27]
	s_mov_b32 m0, s68
	s_nop 0
	global_load_lds_dwordx4 v[176:177], off
	v_lshl_add_u64 v[176:177], v[224:225], 0, s[26:27]
	s_mov_b32 m0, s69
	s_nop 0
	global_load_lds_dwordx4 v[176:177], off
	s_waitcnt vmcnt(8)
	s_waitcnt lgkmcnt(0)
	s_barrier
	s_setprio 1
	s_waitcnt lgkmcnt(0)
	v_mfma_f32_16x16x32_bf16 v[60:63], v[128:131], v[184:187], v[60:63]
	v_mfma_f32_16x16x32_bf16 v[56:59], v[136:139], v[184:187], v[56:59]
	v_mfma_f32_16x16x32_bf16 v[48:51], v[128:131], v[194:197], v[48:51]
	v_mfma_f32_16x16x32_bf16 v[40:43], v[136:139], v[194:197], v[40:43]
	v_mfma_f32_16x16x32_bf16 v[32:35], v[128:131], v[202:205], v[32:35]
	v_mfma_f32_16x16x32_bf16 v[24:27], v[136:139], v[202:205], v[24:27]
	v_mfma_f32_16x16x32_bf16 v[16:19], v[128:131], v[210:213], v[16:19]
	v_mfma_f32_16x16x32_bf16 v[8:11], v[136:139], v[210:213], v[8:11]
	v_mfma_f32_16x16x32_bf16 v[60:63], v[132:135], v[188:191], v[60:63]
	v_mfma_f32_16x16x32_bf16 v[56:59], v[140:143], v[188:191], v[56:59]
	v_mfma_f32_16x16x32_bf16 v[48:51], v[132:135], v[198:201], v[48:51]
	v_mfma_f32_16x16x32_bf16 v[40:43], v[140:143], v[198:201], v[40:43]
	v_mfma_f32_16x16x32_bf16 v[32:35], v[132:135], v[206:209], v[32:35]
	v_mfma_f32_16x16x32_bf16 v[24:27], v[140:143], v[206:209], v[24:27]
	v_mfma_f32_16x16x32_bf16 v[16:19], v[132:135], v[218:221], v[16:19]
	v_mfma_f32_16x16x32_bf16 v[8:11], v[140:143], v[218:221], v[8:11]
	v_mfma_f32_16x16x32_bf16 v[52:55], v[144:147], v[184:187], v[52:55]
	v_mfma_f32_16x16x32_bf16 v[44:47], v[168:171], v[184:187], v[44:47]
	v_mfma_f32_16x16x32_bf16 v[36:39], v[144:147], v[194:197], v[36:39]
	v_mfma_f32_16x16x32_bf16 v[28:31], v[168:171], v[194:197], v[28:31]
	v_mfma_f32_16x16x32_bf16 v[20:23], v[144:147], v[202:205], v[20:23]
	v_mfma_f32_16x16x32_bf16 v[12:15], v[168:171], v[202:205], v[12:15]
	v_mfma_f32_16x16x32_bf16 v[4:7], v[144:147], v[210:213], v[4:7]
	v_mfma_f32_16x16x32_bf16 v[0:3], v[168:171], v[210:213], v[0:3]
	v_mfma_f32_16x16x32_bf16 v[52:55], v[148:151], v[188:191], v[52:55]
	v_mfma_f32_16x16x32_bf16 v[44:47], v[172:175], v[188:191], v[44:47]
	v_mfma_f32_16x16x32_bf16 v[36:39], v[148:151], v[198:201], v[36:39]
	v_mfma_f32_16x16x32_bf16 v[28:31], v[172:175], v[198:201], v[28:31]
	v_mfma_f32_16x16x32_bf16 v[20:23], v[148:151], v[206:209], v[20:23]
	v_mfma_f32_16x16x32_bf16 v[12:15], v[172:175], v[206:209], v[12:15]
	v_mfma_f32_16x16x32_bf16 v[4:7], v[148:151], v[218:221], v[4:7]
	v_mfma_f32_16x16x32_bf16 v[0:3], v[172:175], v[218:221], v[0:3]
	s_setprio 0
	s_barrier
	s_add_i32 s76, s76, 2
	s_add_u32 s50, s50, 0x100
	s_addc_u32 s51, s51, 0
	s_add_u32 s74, s74, 0x100
	s_addc_u32 s75, s75, 0
	s_cmp_gt_u32 s76, 13
	s_cbranch_scc0 .LBB0_553
	s_and_b64 vcc, exec, s[28:29]
	s_cbranch_vccz .LBB0_556
	s_barrier

; #define PG8_STAGE(bufoff, gbase, voff) do { _Pragma("unroll") for (int _i = 0; _i < 2; ++_i) \
;         __builtin_amdgcn_global_load_lds((const unsigned*)((const char*)(gbase) + (voff)[_i]), (PG8_LAS unsigned*)(lds + (bufoff) + ldsw + _i * 8192), 16, 0, 0); } while (0)
; #define PG8_LDA(dst, b, h) do { _Pragma("unroll") for (int m = 0; m < 4; ++m) _Pragma("unroll") for (int k = 0; k < 2; ++k) dst[m][k] = *(const PG8_LAS bf16x8*)(lds + PG8_SA(b, h) + aoff + m * 2048 + k * 1024); } while (0)
; #define PG8_LDB(dst, b, h) do { _Pragma("unroll") for (int n = 0; n < 2; ++n) _Pragma("unroll") for (int k = 0; k < 2; ++k) dst[n][k] = *(const PG8_LAS bf16x8*)(lds + PG8_SB(b, h) + boff + n * 2048 + k * 1024); } while (0)
; #define PG8_WAIT_V(n) asm volatile("s_waitcnt vmcnt(" #n ")" ::: "memory")
; #define PG8_WAIT_L(n) asm volatile("s_waitcnt lgkmcnt(" #n ")" ::: "memory")
; #define PG8_BAR __builtin_amdgcn_s_barrier()
; #define PG8_SCHED __builtin_amdgcn_sched_barrier(0)
; template <class Epi, class Sched, bool ALIGN_EPI = false, bool SP2 = false>
; __device__ __forceinline__ void gemm_phase(PG8_LAS unsigned char* lds, const Gemm g, const Sched& S, const Epi& E) {
;     ...
;         const bool has_next = S.next(ui + 1, nxt);
;         const char* nA = has_next ? (const char*)g.A + (size_t)nxt.pm * tstep : cA; const char* nB = has_next ? (const char*)g.Bt + (size_t)nxt.pn * tstep : cB;
;         for (int t = 0; t < nt; t += 2) {
;             const bool last = (t == nt - 2);
;             const char* a1 = cA + (size_t)(t + 1) * kstep;
;             const char* a2 = last ? nA : cA + (size_t)(t + 2) * kstep; const char* b2 = last ? nB : cB + (size_t)(t + 2) * kstep;
;             const char* a3 = a2 + kstep; const char* b3 = b2 + kstep;
;             if (last && has_next) S.a_ready(nxt);
;             if constexpr (SP2) {
;             PG8_LDB(B0, 0, 0); PG8_LDB(B1, 0, 1); PG8_SCHED; PG8_LDA(At, 0, 0); PG8_STAGE(PG8_SA(1, 1), a1 + hstep, voffA);
;             PG8_WAIT_V(8); PG8_WAIT_L(0); PG8_BAR; PG8_MMA(0, 0, At, B0); PG8_MMA(0, 1, At, B1); PG8_BAR; PG8_SCHED;
;             PG8_LDA(At, 0, 1); PG8_STAGE(PG8_SB(0, 0), b2, voffB); PG8_STAGE(PG8_SB(0, 1), b2 + hstep, voffB); PG8_STAGE(PG8_SA(0, 0), a2, voffA);
;             PG8_WAIT_V(8); PG8_WAIT_L(0); PG8_BAR; PG8_MMA(1, 0, At, B0); PG8_MMA(1, 1, At, B1); PG8_BAR; PG8_SCHED;
.LBB0_572:
	s_ashr_i32 s27, s26, 31
	s_lshl_b64 s[28:29], s[26:27], 19
	s_add_u32 s28, s47, s28
	s_addc_u32 s29, s52, s29
	s_and_b64 s[30:31], s[40:41], exec
	s_cselect_b32 s27, s29, s37
	s_cselect_b32 s68, s28, s36
	s_ashr_i32 s25, s24, 31
	s_lshl_b64 s[30:31], s[24:25], 19
	s_add_u32 s30, s53, s30
	s_addc_u32 s31, s54, s31
	s_and_b64 s[50:51], s[40:41], exec
	s_cselect_b32 s25, s31, s45
	s_cselect_b32 s69, s30, s44
	s_add_u32 s36, s36, 0x40080
	s_addc_u32 s37, s37, 0
	s_add_u32 s70, s44, 0x100
	s_addc_u32 s71, s45, 0
	s_mov_b32 s72, -2
	ds_read_b128 v[128:131], v220
	ds_read_b128 v[132:135], v220 offset:1024
	ds_read_b128 v[136:139], v220 offset:2048
	ds_read_b128 v[140:143], v220 offset:3072
	ds_read_b128 v[144:147], v221
	ds_read_b128 v[148:151], v221 offset:1024
	ds_read_b128 v[152:155], v221 offset:2048
	ds_read_b128 v[156:159], v221 offset:3072
	s_add_u32 s44, s36, 0xfffc0080
	s_addc_u32 s45, s37, -1
	s_cmp_eq_u32 s72, 12
	s_cselect_b32 s51, s27, s45
	s_cselect_b32 s50, s68, s44
	s_cselect_b32 s45, s25, s71
	s_cselect_b32 s44, s69, s70
	v_lshl_add_u64 v[210:211], s[36:37], 0, v[194:195]
	s_add_i32 m0, s55, 0xc000
	ds_read_b128 v[160:163], v222
	ds_read_b128 v[164:167], v222 offset:1024
	ds_read_b128 v[168:171], v222 offset:2048
	ds_read_b128 v[172:175], v222 offset:3072
	ds_read_b128 v[176:179], v222 offset:4096
	ds_read_b128 v[180:183], v222 offset:5120
	ds_read_b128 v[202:205], v222 offset:6144
	ds_read_b128 v[206:209], v222 offset:7168
	global_load_lds_dwordx4 v[210:211], off
	v_lshl_add_u64 v[210:211], s[36:37], 0, v[196:197]
	s_add_i32 m0, s55, 0xe000
	s_nop 0
	global_load_lds_dwordx4 v[210:211], off
	s_waitcnt vmcnt(8)
	s_waitcnt lgkmcnt(0)
	s_barrier
	s_setprio 1
	s_waitcnt lgkmcnt(0)
	v_mfma_f32_16x16x32_bf16 v[124:127], v[128:131], v[160:163], 0
	v_mfma_f32_16x16x32_bf16 v[120:123], v[136:139], v[160:163], 0
	v_mfma_f32_16x16x32_bf16 v[108:111], v[128:131], v[168:171], 0
	v_mfma_f32_16x16x32_bf16 v[104:107], v[136:139], v[168:171], 0
	v_mfma_f32_16x16x32_bf16 v[92:95], v[128:131], v[176:179], 0
	v_mfma_f32_16x16x32_bf16 v[88:91], v[136:139], v[176:179], 0
	v_mfma_f32_16x16x32_bf16 v[76:79], v[128:131], v[202:205], 0
	v_mfma_f32_16x16x32_bf16 v[72:75], v[136:139], v[202:205], 0
	v_mfma_f32_16x16x32_bf16 v[124:127], v[132:135], v[164:167], v[124:127]
	v_mfma_f32_16x16x32_bf16 v[120:123], v[140:143], v[164:167], v[120:123]
	v_mfma_f32_16x16x32_bf16 v[108:111], v[132:135], v[172:175], v[108:111]
	v_mfma_f32_16x16x32_bf16 v[104:107], v[140:143], v[172:175], v[104:107]
	v_mfma_f32_16x16x32_bf16 v[92:95], v[132:135], v[180:183], v[92:95]
	v_mfma_f32_16x16x32_bf16 v[88:91], v[140:143], v[180:183], v[88:91]
	v_mfma_f32_16x16x32_bf16 v[76:79], v[132:135], v[206:209], v[76:79]
	v_mfma_f32_16x16x32_bf16 v[72:75], v[140:143], v[206:209], v[72:75]
	v_mfma_f32_16x16x32_bf16 v[116:119], v[144:147], v[160:163], 0
	v_mfma_f32_16x16x32_bf16 v[112:115], v[152:155], v[160:163], 0
	v_mfma_f32_16x16x32_bf16 v[100:103], v[144:147], v[168:171], 0
	v_mfma_f32_16x16x32_bf16 v[96:99], v[152:155], v[168:171], 0
	v_mfma_f32_16x16x32_bf16 v[84:87], v[144:147], v[176:179], 0
	v_mfma_f32_16x16x32_bf16 v[80:83], v[152:155], v[176:179], 0
	v_mfma_f32_16x16x32_bf16 v[68:71], v[144:147], v[202:205], 0
	v_mfma_f32_16x16x32_bf16 v[64:67], v[152:155], v[202:205], 0
	v_mfma_f32_16x16x32_bf16 v[116:119], v[148:151], v[164:167], v[116:119]
	v_mfma_f32_16x16x32_bf16 v[112:115], v[156:159], v[164:167], v[112:115]
	v_mfma_f32_16x16x32_bf16 v[100:103], v[148:151], v[172:175], v[100:103]
	v_mfma_f32_16x16x32_bf16 v[96:99], v[156:159], v[172:175], v[96:99]
	v_mfma_f32_16x16x32_bf16 v[84:87], v[148:151], v[180:183], v[84:87]
	v_mfma_f32_16x16x32_bf16 v[80:83], v[156:159], v[180:183], v[80:83]
	v_mfma_f32_16x16x32_bf16 v[68:71], v[148:151], v[206:209], v[68:71]
	v_mfma_f32_16x16x32_bf16 v[64:67], v[156:159], v[206:209], v[64:67]
	s_setprio 0
	s_barrier
	s_add_i32 s73, s66, s13
	v_lshl_add_u64 v[210:211], s[44:45], 0, v[188:189]
	s_mov_b32 m0, s73
	ds_read_b128 v[160:163], v222 offset:16384
	ds_read_b128 v[164:167], v222 offset:17408
	ds_read_b128 v[168:171], v222 offset:18432
	ds_read_b128 v[172:175], v222 offset:19456
	ds_read_b128 v[176:179], v222 offset:20480
	ds_read_b128 v[180:183], v222 offset:21504
	ds_read_b128 v[202:205], v222 offset:22528
	ds_read_b128 v[206:209], v222 offset:23552
	global_load_lds_dwordx4 v[210:211], off
	s_add_i32 m0, s73, 0x2000
	s_add_u32 s74, s44, 0x40000
	v_lshl_add_u64 v[212:213], s[44:45], 0, v[184:185]
	s_addc_u32 s75, s45, 0
	s_add_i32 s73, s67, s13
	global_load_lds_dwordx4 v[212:213], off
	v_lshl_add_u64 v[214:215], s[74:75], 0, v[188:189]
	s_mov_b32 m0, s73
	v_lshl_add_u64 v[224:225], s[50:51], 0, v[186:187]
	global_load_lds_dwordx4 v[214:215], off
	v_lshl_add_u64 v[214:215], s[74:75], 0, v[184:185]
	s_add_i32 m0, s73, 0x2000
	s_nop 0
	global_load_lds_dwordx4 v[214:215], off
	v_lshl_add_u64 v[214:215], s[50:51], 0, v[190:191]
	s_mov_b32 m0, s55
	s_nop 0
	global_load_lds_dwordx4 v[214:215], off
	s_mov_b32 m0, s60
	s_nop 0
	global_load_lds_dwordx4 v[224:225], off
	s_waitcnt vmcnt(8)
	s_waitcnt lgkmcnt(0)
	s_barrier
; #define PG8_STAGE(bufoff, gbase, voff) do { _Pragma("unroll") for (int _i = 0; _i < 2; ++_i) \
;         __builtin_amdgcn_global_load_lds((const unsigned*)((const char*)(gbase) + (voff)[_i]), (PG8_LAS unsigned*)(lds + (bufoff) + ldsw + _i * 8192), 16, 0, 0); } while (0)
; #define PG8_LDA(dst, b, h) do { _Pragma("unroll") for (int m = 0; m < 4; ++m) _Pragma("unroll") for (int k = 0; k < 2; ++k) dst[m][k] = *(const PG8_LAS bf16x8*)(lds + PG8_SA(b, h) + aoff + m * 2048 + k * 1024); } while (0)
; #define PG8_LDB(dst, b, h) do { _Pragma("unroll") for (int n = 0; n < 2; ++n) _Pragma("unroll") for (int k = 0; k < 2; ++k) dst[n][k] = *(const PG8_LAS bf16x8*)(lds + PG8_SB(b, h) + boff + n * 2048 + k * 1024); } while (0)
; #define PG8_MMA(ai, bj, At, Bt) do { __builtin_amdgcn_s_setprio(1); _Pragma("unroll") for (int m = 0; m < 4; ++m) _Pragma("unroll") for (int n = 0; n < 2; ++n) _Pragma("unroll") for (int k = 0; k < 2; ++k) \
;         acc[ai][bj][m][n] = __builtin_amdgcn_mfma_f32_16x16x32_bf16(Bt[n][k], At[m][k], acc[ai][bj][m][n], 0, 0, 0); __builtin_amdgcn_s_setprio(0); } while (0)
; #define PG8_WAIT_V(n) asm volatile("s_waitcnt vmcnt(" #n ")" ::: "memory")
; #define PG8_WAIT_L(n) asm volatile("s_waitcnt lgkmcnt(" #n ")" ::: "memory")
; #define PG8_BAR __builtin_amdgcn_s_barrier()
; #define PG8_SCHED __builtin_amdgcn_sched_barrier(0)
; template <class Epi, class Sched, bool ALIGN_EPI = false, bool SP2 = false>
; __device__ __forceinline__ void gemm_phase(PG8_LAS unsigned char* lds, const Gemm g, const Sched& S, const Epi& E) {
;     ...
;             PG8_WAIT_V(8); PG8_WAIT_L(0); PG8_BAR; PG8_MMA(1, 0, At, B0); PG8_MMA(1, 1, At, B1); PG8_BAR; PG8_SCHED;
;             PG8_LDB(B0, 1, 0); PG8_LDB(B1, 1, 1); PG8_SCHED; PG8_LDA(At, 1, 0); PG8_STAGE(PG8_SA(0, 1), a2 + hstep, voffA);
;             PG8_WAIT_V(8); PG8_WAIT_L(0); PG8_BAR; PG8_MMA(0, 0, At, B0); PG8_MMA(0, 1, At, B1); PG8_BAR; PG8_SCHED;
	s_setprio 1
	s_waitcnt lgkmcnt(0)
	v_mfma_f32_16x16x32_bf16 v[60:63], v[128:131], v[160:163], 0
	v_mfma_f32_16x16x32_bf16 v[56:59], v[136:139], v[160:163], 0
	v_mfma_f32_16x16x32_bf16 v[44:47], v[128:131], v[168:171], 0
	v_mfma_f32_16x16x32_bf16 v[40:43], v[136:139], v[168:171], 0
	v_mfma_f32_16x16x32_bf16 v[28:31], v[128:131], v[176:179], 0
	v_mfma_f32_16x16x32_bf16 v[24:27], v[136:139], v[176:179], 0
	v_mfma_f32_16x16x32_bf16 v[12:15], v[128:131], v[202:205], 0
	v_mfma_f32_16x16x32_bf16 v[8:11], v[136:139], v[202:205], 0
	v_mfma_f32_16x16x32_bf16 v[60:63], v[132:135], v[164:167], v[60:63]
	v_mfma_f32_16x16x32_bf16 v[56:59], v[140:143], v[164:167], v[56:59]
	v_mfma_f32_16x16x32_bf16 v[44:47], v[132:135], v[172:175], v[44:47]
	v_mfma_f32_16x16x32_bf16 v[40:43], v[140:143], v[172:175], v[40:43]
	v_mfma_f32_16x16x32_bf16 v[28:31], v[132:135], v[180:183], v[28:31]
	v_mfma_f32_16x16x32_bf16 v[24:27], v[140:143], v[180:183], v[24:27]
	v_mfma_f32_16x16x32_bf16 v[12:15], v[132:135], v[206:209], v[12:15]
	v_mfma_f32_16x16x32_bf16 v[8:11], v[140:143], v[206:209], v[8:11]
	v_mfma_f32_16x16x32_bf16 v[52:55], v[144:147], v[160:163], 0
	v_mfma_f32_16x16x32_bf16 v[48:51], v[152:155], v[160:163], 0
	v_mfma_f32_16x16x32_bf16 v[36:39], v[144:147], v[168:171], 0
	v_mfma_f32_16x16x32_bf16 v[32:35], v[152:155], v[168:171], 0
	v_mfma_f32_16x16x32_bf16 v[20:23], v[144:147], v[176:179], 0
	v_mfma_f32_16x16x32_bf16 v[16:19], v[152:155], v[176:179], 0
	v_mfma_f32_16x16x32_bf16 v[4:7], v[144:147], v[202:205], 0
	v_mfma_f32_16x16x32_bf16 v[0:3], v[152:155], v[202:205], 0
	v_mfma_f32_16x16x32_bf16 v[52:55], v[148:151], v[164:167], v[52:55]
	v_mfma_f32_16x16x32_bf16 v[48:51], v[156:159], v[164:167], v[48:51]
	v_mfma_f32_16x16x32_bf16 v[36:39], v[148:151], v[172:175], v[36:39]
	v_mfma_f32_16x16x32_bf16 v[32:35], v[156:159], v[172:175], v[32:35]
	v_mfma_f32_16x16x32_bf16 v[20:23], v[148:151], v[180:183], v[20:23]
	v_mfma_f32_16x16x32_bf16 v[16:19], v[156:159], v[180:183], v[16:19]
	v_mfma_f32_16x16x32_bf16 v[4:7], v[148:151], v[206:209], v[4:7]
	v_mfma_f32_16x16x32_bf16 v[0:3], v[156:159], v[206:209], v[0:3]
	s_setprio 0
	s_barrier
	s_add_i32 s73, 0, 0x18000
	s_add_i32 s74, 0, 0x1c000
	v_add_u32_e32 v140, s73, v218
	v_add_u32_e32 v156, s74, v218
	ds_read_b128 v[128:131], v140
	ds_read_b128 v[132:135], v140 offset:1024
	ds_read_b128 v[136:139], v140 offset:2048
	ds_read_b128 v[140:143], v140 offset:3072
	ds_read_b128 v[144:147], v156
	ds_read_b128 v[148:151], v156 offset:1024
	ds_read_b128 v[152:155], v156 offset:2048
	ds_read_b128 v[156:159], v156 offset:3072
	s_add_u32 s50, s50, 0x40000
	s_addc_u32 s51, s51, 0
	s_mov_b32 m0, s61
	v_lshl_add_u64 v[226:227], s[50:51], 0, v[190:191]
	ds_read_b128 v[160:163], v222 offset:32768
	ds_read_b128 v[164:167], v222 offset:33792
	ds_read_b128 v[168:171], v222 offset:34816
	ds_read_b128 v[172:175], v222 offset:35840
	ds_read_b128 v[176:179], v222 offset:36864
	ds_read_b128 v[180:183], v222 offset:37888
	ds_read_b128 v[202:205], v222 offset:38912
	ds_read_b128 v[206:209], v222 offset:39936
	global_load_lds_dwordx4 v[226:227], off
	v_lshl_add_u64 v[226:227], s[50:51], 0, v[186:187]
	s_mov_b32 m0, s62
	s_nop 0
	global_load_lds_dwordx4 v[226:227], off
	s_waitcnt vmcnt(8)
	s_waitcnt lgkmcnt(0)
	s_barrier
	s_setprio 1
	s_waitcnt lgkmcnt(0)
	v_mfma_f32_16x16x32_bf16 v[124:127], v[128:131], v[160:163], v[124:127]
	v_mfma_f32_16x16x32_bf16 v[120:123], v[136:139], v[160:163], v[120:123]
	v_mfma_f32_16x16x32_bf16 v[108:111], v[128:131], v[168:171], v[108:111]
	v_mfma_f32_16x16x32_bf16 v[104:107], v[136:139], v[168:171], v[104:107]
	v_mfma_f32_16x16x32_bf16 v[92:95], v[128:131], v[176:179], v[92:95]
	v_mfma_f32_16x16x32_bf16 v[88:91], v[136:139], v[176:179], v[88:91]
	v_mfma_f32_16x16x32_bf16 v[76:79], v[128:131], v[202:205], v[76:79]
	v_mfma_f32_16x16x32_bf16 v[72:75], v[136:139], v[202:205], v[72:75]
	v_mfma_f32_16x16x32_bf16 v[124:127], v[132:135], v[164:167], v[124:127]
	v_mfma_f32_16x16x32_bf16 v[120:123], v[140:143], v[164:167], v[120:123]
	v_mfma_f32_16x16x32_bf16 v[108:111], v[132:135], v[172:175], v[108:111]
	v_mfma_f32_16x16x32_bf16 v[104:107], v[140:143], v[172:175], v[104:107]
	v_mfma_f32_16x16x32_bf16 v[92:95], v[132:135], v[180:183], v[92:95]
	v_mfma_f32_16x16x32_bf16 v[88:91], v[140:143], v[180:183], v[88:91]
	v_mfma_f32_16x16x32_bf16 v[76:79], v[132:135], v[206:209], v[76:79]
	v_mfma_f32_16x16x32_bf16 v[72:75], v[140:143], v[206:209], v[72:75]
	v_mfma_f32_16x16x32_bf16 v[116:119], v[144:147], v[160:163], v[116:119]
	v_mfma_f32_16x16x32_bf16 v[112:115], v[152:155], v[160:163], v[112:115]
	v_mfma_f32_16x16x32_bf16 v[100:103], v[144:147], v[168:171], v[100:103]
	v_mfma_f32_16x16x32_bf16 v[96:99], v[152:155], v[168:171], v[96:99]
	v_mfma_f32_16x16x32_bf16 v[84:87], v[144:147], v[176:179], v[84:87]
	v_mfma_f32_16x16x32_bf16 v[80:83], v[152:155], v[176:179], v[80:83]
	v_mfma_f32_16x16x32_bf16 v[68:71], v[144:147], v[202:205], v[68:71]
	v_mfma_f32_16x16x32_bf16 v[64:67], v[152:155], v[202:205], v[64:67]
	v_mfma_f32_16x16x32_bf16 v[116:119], v[148:151], v[164:167], v[116:119]
	v_mfma_f32_16x16x32_bf16 v[112:115], v[156:159], v[164:167], v[112:115]
	v_mfma_f32_16x16x32_bf16 v[100:103], v[148:151], v[172:175], v[100:103]
	v_mfma_f32_16x16x32_bf16 v[96:99], v[156:159], v[172:175], v[96:99]
	v_mfma_f32_16x16x32_bf16 v[84:87], v[148:151], v[180:183], v[84:87]
	v_mfma_f32_16x16x32_bf16 v[80:83], v[156:159], v[180:183], v[80:83]
	v_mfma_f32_16x16x32_bf16 v[68:71], v[148:151], v[206:209], v[68:71]
	v_mfma_f32_16x16x32_bf16 v[64:67], v[156:159], v[206:209], v[64:67]
	s_setprio 0
	s_barrier
; #define PG8_STAGE(bufoff, gbase, voff) do { _Pragma("unroll") for (int _i = 0; _i < 2; ++_i) \
;         __builtin_amdgcn_global_load_lds((const unsigned*)((const char*)(gbase) + (voff)[_i]), (PG8_LAS unsigned*)(lds + (bufoff) + ldsw + _i * 8192), 16, 0, 0); } while (0)
; #define PG8_LDA(dst, b, h) do { _Pragma("unroll") for (int m = 0; m < 4; ++m) _Pragma("unroll") for (int k = 0; k < 2; ++k) dst[m][k] = *(const PG8_LAS bf16x8*)(lds + PG8_SA(b, h) + aoff + m * 2048 + k * 1024); } while (0)
; #define PG8_LDB(dst, b, h) do { _Pragma("unroll") for (int n = 0; n < 2; ++n) _Pragma("unroll") for (int k = 0; k < 2; ++k) dst[n][k] = *(const PG8_LAS bf16x8*)(lds + PG8_SB(b, h) + boff + n * 2048 + k * 1024); } while (0)
; #define PG8_MMA(ai, bj, At, Bt) do { __builtin_amdgcn_s_setprio(1); _Pragma("unroll") for (int m = 0; m < 4; ++m) _Pragma("unroll") for (int n = 0; n < 2; ++n) _Pragma("unroll") for (int k = 0; k < 2; ++k) \
;         acc[ai][bj][m][n] = __builtin_amdgcn_mfma_f32_16x16x32_bf16(Bt[n][k], At[m][k], acc[ai][bj][m][n], 0, 0, 0); __builtin_amdgcn_s_setprio(0); } while (0)
; #define PG8_WAIT_V(n) asm volatile("s_waitcnt vmcnt(" #n ")" ::: "memory")
; template <class Epi, class Sched, bool ALIGN_EPI = false, bool SP2 = false>
; __device__ __forceinline__ void gemm_phase(PG8_LAS unsigned char* lds, const Gemm g, const Sched& S, const Epi& E) {
;     ...
;             PG8_LDB(B0, 0, 0); PG8_LDB(B1, 0, 1); PG8_SCHED; PG8_LDA(At, 0, 0); PG8_STAGE(PG8_SA(1, 1), a1 + hstep, voffA);
;             PG8_WAIT_V(8); PG8_WAIT_L(0); PG8_BAR; PG8_MMA(0, 0, At, B0); PG8_MMA(0, 1, At, B1); PG8_BAR; PG8_SCHED;
;             PG8_LDA(At, 0, 1); PG8_STAGE(PG8_SB(0, 0), b2, voffB); PG8_STAGE(PG8_SB(0, 1), b2 + hstep, voffB); PG8_STAGE(PG8_SA(0, 0), a2, voffA);
;             PG8_WAIT_V(8); PG8_WAIT_L(0); PG8_BAR; PG8_MMA(1, 0, At, B0); PG8_MMA(1, 1, At, B1); PG8_BAR; PG8_SCHED;
;             PG8_LDB(B0, 1, 0); PG8_LDB(B1, 1, 1); PG8_SCHED; PG8_LDA(At, 1, 0); PG8_STAGE(PG8_SA(0, 1), a2 + hstep, voffA);
;             PG8_WAIT_V(8); PG8_WAIT_L(0); PG8_BAR; PG8_MMA(0, 0, At, B0); PG8_MMA(0, 1, At, B1); PG8_BAR; PG8_SCHED;
;             PG8_LDA(At, 1, 1); PG8_STAGE(PG8_SB(1, 0), b3, voffB); PG8_STAGE(PG8_SB(1, 1), b3 + hstep, voffB); PG8_STAGE(PG8_SA(1, 0), a3, voffA);
;             PG8_WAIT_V(8); PG8_WAIT_L(0); PG8_BAR; PG8_MMA(1, 0, At, B0); PG8_MMA(1, 1, At, B1); PG8_BAR; PG8_SCHED;
	s_add_i32 s50, s73, s13
	v_lshl_add_u64 v[210:211], v[210:211], 0, s[20:21]
	s_mov_b32 m0, s50
	ds_read_b128 v[160:163], v222 offset:49152
	ds_read_b128 v[164:167], v222 offset:50176
	ds_read_b128 v[168:171], v222 offset:51200
	ds_read_b128 v[172:175], v222 offset:52224
	ds_read_b128 v[176:179], v222 offset:53248
	ds_read_b128 v[180:183], v222 offset:54272
	ds_read_b128 v[202:205], v222 offset:55296
	ds_read_b128 v[206:209], v222 offset:56320
	global_load_lds_dwordx4 v[210:211], off
	s_add_i32 m0, s50, 0x2000
	s_add_u32 s44, s44, 0x40080
	v_lshl_add_u64 v[210:211], v[212:213], 0, s[20:21]
	s_addc_u32 s45, s45, 0
	s_add_i32 s50, s74, s13
	global_load_lds_dwordx4 v[210:211], off
	v_lshl_add_u64 v[210:211], s[44:45], 0, v[188:189]
	s_mov_b32 m0, s50
	s_nop 0
	global_load_lds_dwordx4 v[210:211], off
	v_lshl_add_u64 v[210:211], s[44:45], 0, v[184:185]
	s_add_i32 m0, s50, 0x2000
	s_nop 0
	global_load_lds_dwordx4 v[210:211], off
	v_lshl_add_u64 v[210:211], v[214:215], 0, s[20:21]
	s_mov_b32 m0, s64
	s_nop 0
	global_load_lds_dwordx4 v[210:211], off
	v_lshl_add_u64 v[210:211], v[224:225], 0, s[20:21]
	s_mov_b32 m0, s65
	s_nop 0
	global_load_lds_dwordx4 v[210:211], off
	s_waitcnt vmcnt(8)
	s_waitcnt lgkmcnt(0)
	s_barrier
	s_setprio 1
	s_waitcnt lgkmcnt(0)
	v_mfma_f32_16x16x32_bf16 v[60:63], v[128:131], v[160:163], v[60:63]
	v_mfma_f32_16x16x32_bf16 v[56:59], v[136:139], v[160:163], v[56:59]
	v_mfma_f32_16x16x32_bf16 v[44:47], v[128:131], v[168:171], v[44:47]
	v_mfma_f32_16x16x32_bf16 v[40:43], v[136:139], v[168:171], v[40:43]
	v_mfma_f32_16x16x32_bf16 v[28:31], v[128:131], v[176:179], v[28:31]
	v_mfma_f32_16x16x32_bf16 v[24:27], v[136:139], v[176:179], v[24:27]
	v_mfma_f32_16x16x32_bf16 v[12:15], v[128:131], v[202:205], v[12:15]
	v_mfma_f32_16x16x32_bf16 v[8:11], v[136:139], v[202:205], v[8:11]
	v_mfma_f32_16x16x32_bf16 v[60:63], v[132:135], v[164:167], v[60:63]
	v_mfma_f32_16x16x32_bf16 v[56:59], v[140:143], v[164:167], v[56:59]
	v_mfma_f32_16x16x32_bf16 v[44:47], v[132:135], v[172:175], v[44:47]
	v_mfma_f32_16x16x32_bf16 v[40:43], v[140:143], v[172:175], v[40:43]
	v_mfma_f32_16x16x32_bf16 v[28:31], v[132:135], v[180:183], v[28:31]
	v_mfma_f32_16x16x32_bf16 v[24:27], v[140:143], v[180:183], v[24:27]
	v_mfma_f32_16x16x32_bf16 v[12:15], v[132:135], v[206:209], v[12:15]
	v_mfma_f32_16x16x32_bf16 v[8:11], v[140:143], v[206:209], v[8:11]
	v_mfma_f32_16x16x32_bf16 v[52:55], v[144:147], v[160:163], v[52:55]
	v_mfma_f32_16x16x32_bf16 v[48:51], v[152:155], v[160:163], v[48:51]
	v_mfma_f32_16x16x32_bf16 v[36:39], v[144:147], v[168:171], v[36:39]
	v_mfma_f32_16x16x32_bf16 v[32:35], v[152:155], v[168:171], v[32:35]
	v_mfma_f32_16x16x32_bf16 v[20:23], v[144:147], v[176:179], v[20:23]
	v_mfma_f32_16x16x32_bf16 v[16:19], v[152:155], v[176:179], v[16:19]
	v_mfma_f32_16x16x32_bf16 v[4:7], v[144:147], v[202:205], v[4:7]
	v_mfma_f32_16x16x32_bf16 v[0:3], v[152:155], v[202:205], v[0:3]
	v_mfma_f32_16x16x32_bf16 v[52:55], v[148:151], v[164:167], v[52:55]
	v_mfma_f32_16x16x32_bf16 v[48:51], v[156:159], v[164:167], v[48:51]
	v_mfma_f32_16x16x32_bf16 v[36:39], v[148:151], v[172:175], v[36:39]
	v_mfma_f32_16x16x32_bf16 v[32:35], v[156:159], v[172:175], v[32:35]
	v_mfma_f32_16x16x32_bf16 v[20:23], v[148:151], v[180:183], v[20:23]
	v_mfma_f32_16x16x32_bf16 v[16:19], v[156:159], v[180:183], v[16:19]
	v_mfma_f32_16x16x32_bf16 v[4:7], v[148:151], v[206:209], v[4:7]
	v_mfma_f32_16x16x32_bf16 v[0:3], v[156:159], v[206:209], v[0:3]
	s_setprio 0
	s_barrier
	s_add_i32 s72, s72, 2
	s_add_u32 s36, s36, 0x100
	s_addc_u32 s37, s37, 0
	s_add_u32 s70, s70, 0x100
	s_addc_u32 s71, s71, 0
	s_cmp_gt_u32 s72, 13
.LBB0_573:
	ds_read_b128 v[128:131], v220
	ds_read_b128 v[132:135], v220 offset:1024
	ds_read_b128 v[136:139], v220 offset:2048
	ds_read_b128 v[140:143], v220 offset:3072
	ds_read_b128 v[144:147], v221
	ds_read_b128 v[148:151], v221 offset:1024
	ds_read_b128 v[152:155], v221 offset:2048
	ds_read_b128 v[156:159], v221 offset:3072
	s_add_u32 s44, s36, 0xfffc0080
	s_addc_u32 s45, s37, -1
	s_cmp_eq_u32 s72, 12
	s_cselect_b32 s51, s27, s45
	s_cselect_b32 s50, s68, s44
	s_cselect_b32 s45, s25, s71
	s_cselect_b32 s44, s69, s70
	v_lshl_add_u64 v[210:211], s[36:37], 0, v[194:195]
	s_add_i32 m0, s55, 0xc000
	ds_read_b128 v[160:163], v222
	ds_read_b128 v[164:167], v222 offset:1024
	ds_read_b128 v[168:171], v222 offset:2048
	ds_read_b128 v[172:175], v222 offset:3072
	ds_read_b128 v[176:179], v222 offset:4096
	ds_read_b128 v[180:183], v222 offset:5120
	ds_read_b128 v[202:205], v222 offset:6144
	ds_read_b128 v[206:209], v222 offset:7168
	global_load_lds_dwordx4 v[210:211], off
	v_lshl_add_u64 v[210:211], s[36:37], 0, v[196:197]
	s_add_i32 m0, s55, 0xe000
	s_nop 0
	global_load_lds_dwordx4 v[210:211], off
	s_waitcnt vmcnt(8)
	s_waitcnt lgkmcnt(0)
	s_barrier
; #define PG8_STAGE(bufoff, gbase, voff) do { _Pragma("unroll") for (int _i = 0; _i < 2; ++_i) \
;         __builtin_amdgcn_global_load_lds((const unsigned*)((const char*)(gbase) + (voff)[_i]), (PG8_LAS unsigned*)(lds + (bufoff) + ldsw + _i * 8192), 16, 0, 0); } while (0)
; #define PG8_LDA(dst, b, h) do { _Pragma("unroll") for (int m = 0; m < 4; ++m) _Pragma("unroll") for (int k = 0; k < 2; ++k) dst[m][k] = *(const PG8_LAS bf16x8*)(lds + PG8_SA(b, h) + aoff + m * 2048 + k * 1024); } while (0)
; #define PG8_MMA(ai, bj, At, Bt) do { __builtin_amdgcn_s_setprio(1); _Pragma("unroll") for (int m = 0; m < 4; ++m) _Pragma("unroll") for (int n = 0; n < 2; ++n) _Pragma("unroll") for (int k = 0; k < 2; ++k) \
;         acc[ai][bj][m][n] = __builtin_amdgcn_mfma_f32_16x16x32_bf16(Bt[n][k], At[m][k], acc[ai][bj][m][n], 0, 0, 0); __builtin_amdgcn_s_setprio(0); } while (0)
; #define PG8_WAIT_V(n) asm volatile("s_waitcnt vmcnt(" #n ")" ::: "memory")
; #define PG8_WAIT_L(n) asm volatile("s_waitcnt lgkmcnt(" #n ")" ::: "memory")
; #define PG8_BAR __builtin_amdgcn_s_barrier()
; #define PG8_SCHED __builtin_amdgcn_sched_barrier(0)
; template <class Epi, class Sched, bool ALIGN_EPI = false, bool SP2 = false>
; __device__ __forceinline__ void gemm_phase(PG8_LAS unsigned char* lds, const Gemm g, const Sched& S, const Epi& E) {
;     ...
;             PG8_WAIT_V(8); PG8_WAIT_L(0); PG8_BAR; PG8_MMA(0, 0, At, B0); PG8_MMA(0, 1, At, B1); PG8_BAR; PG8_SCHED;
;             PG8_LDA(At, 0, 1); PG8_STAGE(PG8_SB(0, 0), b2, voffB); PG8_STAGE(PG8_SB(0, 1), b2 + hstep, voffB); PG8_STAGE(PG8_SA(0, 0), a2, voffA);
;             PG8_WAIT_V(8); PG8_WAIT_L(0); PG8_BAR; PG8_MMA(1, 0, At, B0); PG8_MMA(1, 1, At, B1); PG8_BAR; PG8_SCHED;
	s_setprio 1
	s_waitcnt lgkmcnt(0)
	v_mfma_f32_16x16x32_bf16 v[124:127], v[128:131], v[160:163], v[124:127]
	v_mfma_f32_16x16x32_bf16 v[120:123], v[136:139], v[160:163], v[120:123]
	v_mfma_f32_16x16x32_bf16 v[108:111], v[128:131], v[168:171], v[108:111]
	v_mfma_f32_16x16x32_bf16 v[104:107], v[136:139], v[168:171], v[104:107]
	v_mfma_f32_16x16x32_bf16 v[92:95], v[128:131], v[176:179], v[92:95]
	v_mfma_f32_16x16x32_bf16 v[88:91], v[136:139], v[176:179], v[88:91]
	v_mfma_f32_16x16x32_bf16 v[76:79], v[128:131], v[202:205], v[76:79]
	v_mfma_f32_16x16x32_bf16 v[72:75], v[136:139], v[202:205], v[72:75]
	v_mfma_f32_16x16x32_bf16 v[124:127], v[132:135], v[164:167], v[124:127]
	v_mfma_f32_16x16x32_bf16 v[120:123], v[140:143], v[164:167], v[120:123]
	v_mfma_f32_16x16x32_bf16 v[108:111], v[132:135], v[172:175], v[108:111]
	v_mfma_f32_16x16x32_bf16 v[104:107], v[140:143], v[172:175], v[104:107]
	v_mfma_f32_16x16x32_bf16 v[92:95], v[132:135], v[180:183], v[92:95]
	v_mfma_f32_16x16x32_bf16 v[88:91], v[140:143], v[180:183], v[88:91]
	v_mfma_f32_16x16x32_bf16 v[76:79], v[132:135], v[206:209], v[76:79]
	v_mfma_f32_16x16x32_bf16 v[72:75], v[140:143], v[206:209], v[72:75]
	v_mfma_f32_16x16x32_bf16 v[116:119], v[144:147], v[160:163], v[116:119]
	v_mfma_f32_16x16x32_bf16 v[112:115], v[152:155], v[160:163], v[112:115]
	v_mfma_f32_16x16x32_bf16 v[100:103], v[144:147], v[168:171], v[100:103]
	v_mfma_f32_16x16x32_bf16 v[96:99], v[152:155], v[168:171], v[96:99]
	v_mfma_f32_16x16x32_bf16 v[84:87], v[144:147], v[176:179], v[84:87]
	v_mfma_f32_16x16x32_bf16 v[80:83], v[152:155], v[176:179], v[80:83]
	v_mfma_f32_16x16x32_bf16 v[68:71], v[144:147], v[202:205], v[68:71]
	v_mfma_f32_16x16x32_bf16 v[64:67], v[152:155], v[202:205], v[64:67]
	v_mfma_f32_16x16x32_bf16 v[116:119], v[148:151], v[164:167], v[116:119]
	v_mfma_f32_16x16x32_bf16 v[112:115], v[156:159], v[164:167], v[112:115]
	v_mfma_f32_16x16x32_bf16 v[100:103], v[148:151], v[172:175], v[100:103]
	v_mfma_f32_16x16x32_bf16 v[96:99], v[156:159], v[172:175], v[96:99]
	v_mfma_f32_16x16x32_bf16 v[84:87], v[148:151], v[180:183], v[84:87]
	v_mfma_f32_16x16x32_bf16 v[80:83], v[156:159], v[180:183], v[80:83]
	v_mfma_f32_16x16x32_bf16 v[68:71], v[148:151], v[206:209], v[68:71]
	v_mfma_f32_16x16x32_bf16 v[64:67], v[156:159], v[206:209], v[64:67]
	s_setprio 0
	s_barrier
	s_add_i32 s73, s66, s13
	v_lshl_add_u64 v[210:211], s[44:45], 0, v[188:189]
	s_mov_b32 m0, s73
	ds_read_b128 v[160:163], v222 offset:16384
	ds_read_b128 v[164:167], v222 offset:17408
	ds_read_b128 v[168:171], v222 offset:18432
	ds_read_b128 v[172:175], v222 offset:19456
	ds_read_b128 v[176:179], v222 offset:20480
	ds_read_b128 v[180:183], v222 offset:21504
	ds_read_b128 v[202:205], v222 offset:22528
	ds_read_b128 v[206:209], v222 offset:23552
	global_load_lds_dwordx4 v[210:211], off
	s_add_i32 m0, s73, 0x2000
	s_add_u32 s74, s44, 0x40000
	v_lshl_add_u64 v[212:213], s[44:45], 0, v[184:185]
	s_addc_u32 s75, s45, 0
	s_add_i32 s73, s67, s13
	global_load_lds_dwordx4 v[212:213], off
	v_lshl_add_u64 v[214:215], s[74:75], 0, v[188:189]
	s_mov_b32 m0, s73
	v_lshl_add_u64 v[224:225], s[50:51], 0, v[186:187]
	global_load_lds_dwordx4 v[214:215], off
	v_lshl_add_u64 v[214:215], s[74:75], 0, v[184:185]
	s_add_i32 m0, s73, 0x2000
	s_nop 0
	global_load_lds_dwordx4 v[214:215], off
	v_lshl_add_u64 v[214:215], s[50:51], 0, v[190:191]
	s_mov_b32 m0, s55
	s_nop 0
	global_load_lds_dwordx4 v[214:215], off
	s_mov_b32 m0, s60
	s_nop 0
	global_load_lds_dwordx4 v[224:225], off
	s_waitcnt vmcnt(8)
	s_waitcnt lgkmcnt(0)
	s_barrier
	s_setprio 1
	s_waitcnt lgkmcnt(0)
	v_mfma_f32_16x16x32_bf16 v[60:63], v[128:131], v[160:163], v[60:63]
	v_mfma_f32_16x16x32_bf16 v[56:59], v[136:139], v[160:163], v[56:59]
	v_mfma_f32_16x16x32_bf16 v[44:47], v[128:131], v[168:171], v[44:47]
	v_mfma_f32_16x16x32_bf16 v[40:43], v[136:139], v[168:171], v[40:43]
	v_mfma_f32_16x16x32_bf16 v[28:31], v[128:131], v[176:179], v[28:31]
	v_mfma_f32_16x16x32_bf16 v[24:27], v[136:139], v[176:179], v[24:27]
	v_mfma_f32_16x16x32_bf16 v[12:15], v[128:131], v[202:205], v[12:15]
	v_mfma_f32_16x16x32_bf16 v[8:11], v[136:139], v[202:205], v[8:11]
	v_mfma_f32_16x16x32_bf16 v[60:63], v[132:135], v[164:167], v[60:63]
	v_mfma_f32_16x16x32_bf16 v[56:59], v[140:143], v[164:167], v[56:59]
	v_mfma_f32_16x16x32_bf16 v[44:47], v[132:135], v[172:175], v[44:47]
	v_mfma_f32_16x16x32_bf16 v[40:43], v[140:143], v[172:175], v[40:43]
	v_mfma_f32_16x16x32_bf16 v[28:31], v[132:135], v[180:183], v[28:31]
	v_mfma_f32_16x16x32_bf16 v[24:27], v[140:143], v[180:183], v[24:27]
	v_mfma_f32_16x16x32_bf16 v[12:15], v[132:135], v[206:209], v[12:15]
	v_mfma_f32_16x16x32_bf16 v[8:11], v[140:143], v[206:209], v[8:11]
	v_mfma_f32_16x16x32_bf16 v[52:55], v[144:147], v[160:163], v[52:55]
	v_mfma_f32_16x16x32_bf16 v[48:51], v[152:155], v[160:163], v[48:51]
	v_mfma_f32_16x16x32_bf16 v[36:39], v[144:147], v[168:171], v[36:39]
	v_mfma_f32_16x16x32_bf16 v[32:35], v[152:155], v[168:171], v[32:35]
	v_mfma_f32_16x16x32_bf16 v[20:23], v[144:147], v[176:179], v[20:23]
	v_mfma_f32_16x16x32_bf16 v[16:19], v[152:155], v[176:179], v[16:19]
	v_mfma_f32_16x16x32_bf16 v[4:7], v[144:147], v[202:205], v[4:7]
	v_mfma_f32_16x16x32_bf16 v[0:3], v[152:155], v[202:205], v[0:3]
	v_mfma_f32_16x16x32_bf16 v[52:55], v[148:151], v[164:167], v[52:55]
	v_mfma_f32_16x16x32_bf16 v[48:51], v[156:159], v[164:167], v[48:51]
	v_mfma_f32_16x16x32_bf16 v[36:39], v[148:151], v[172:175], v[36:39]
	v_mfma_f32_16x16x32_bf16 v[32:35], v[156:159], v[172:175], v[32:35]
	v_mfma_f32_16x16x32_bf16 v[20:23], v[148:151], v[180:183], v[20:23]
	v_mfma_f32_16x16x32_bf16 v[16:19], v[156:159], v[180:183], v[16:19]
	v_mfma_f32_16x16x32_bf16 v[4:7], v[148:151], v[206:209], v[4:7]
	v_mfma_f32_16x16x32_bf16 v[0:3], v[156:159], v[206:209], v[0:3]
	s_setprio 0
	s_barrier
; #define PG8_STAGE(bufoff, gbase, voff) do { _Pragma("unroll") for (int _i = 0; _i < 2; ++_i) \
;         __builtin_amdgcn_global_load_lds((const unsigned*)((const char*)(gbase) + (voff)[_i]), (PG8_LAS unsigned*)(lds + (bufoff) + ldsw + _i * 8192), 16, 0, 0); } while (0)
; #define PG8_LDA(dst, b, h) do { _Pragma("unroll") for (int m = 0; m < 4; ++m) _Pragma("unroll") for (int k = 0; k < 2; ++k) dst[m][k] = *(const PG8_LAS bf16x8*)(lds + PG8_SA(b, h) + aoff + m * 2048 + k * 1024); } while (0)
; #define PG8_LDB(dst, b, h) do { _Pragma("unroll") for (int n = 0; n < 2; ++n) _Pragma("unroll") for (int k = 0; k < 2; ++k) dst[n][k] = *(const PG8_LAS bf16x8*)(lds + PG8_SB(b, h) + boff + n * 2048 + k * 1024); } while (0)
; #define PG8_MMA(ai, bj, At, Bt) do { __builtin_amdgcn_s_setprio(1); _Pragma("unroll") for (int m = 0; m < 4; ++m) _Pragma("unroll") for (int n = 0; n < 2; ++n) _Pragma("unroll") for (int k = 0; k < 2; ++k) \
;         acc[ai][bj][m][n] = __builtin_amdgcn_mfma_f32_16x16x32_bf16(Bt[n][k], At[m][k], acc[ai][bj][m][n], 0, 0, 0); __builtin_amdgcn_s_setprio(0); } while (0)
; #define PG8_WAIT_V(n) asm volatile("s_waitcnt vmcnt(" #n ")" ::: "memory")
; #define PG8_WAIT_L(n) asm volatile("s_waitcnt lgkmcnt(" #n ")" ::: "memory")
; #define PG8_BAR __builtin_amdgcn_s_barrier()
; #define PG8_SCHED __builtin_amdgcn_sched_barrier(0)
; template <class Epi, class Sched, bool ALIGN_EPI = false, bool SP2 = false>
; __device__ __forceinline__ void gemm_phase(PG8_LAS unsigned char* lds, const Gemm g, const Sched& S, const Epi& E) {
;     ...
;             PG8_LDB(B0, 1, 0); PG8_LDB(B1, 1, 1); PG8_SCHED; PG8_LDA(At, 1, 0); PG8_STAGE(PG8_SA(0, 1), a2 + hstep, voffA);
;             PG8_WAIT_V(8); PG8_WAIT_L(0); PG8_BAR; PG8_MMA(0, 0, At, B0); PG8_MMA(0, 1, At, B1); PG8_BAR; PG8_SCHED;
	s_add_i32 s73, 0, 0x18000
	s_add_i32 s74, 0, 0x1c000
	v_add_u32_e32 v140, s73, v218
	v_add_u32_e32 v156, s74, v218
	ds_read_b128 v[128:131], v140
	ds_read_b128 v[132:135], v140 offset:1024
	ds_read_b128 v[136:139], v140 offset:2048
	ds_read_b128 v[140:143], v140 offset:3072
	ds_read_b128 v[144:147], v156
	ds_read_b128 v[148:151], v156 offset:1024
	ds_read_b128 v[152:155], v156 offset:2048
	ds_read_b128 v[156:159], v156 offset:3072
	s_add_u32 s50, s50, 0x40000
	s_addc_u32 s51, s51, 0
	s_mov_b32 m0, s61
	v_lshl_add_u64 v[226:227], s[50:51], 0, v[190:191]
	ds_read_b128 v[160:163], v222 offset:32768
	ds_read_b128 v[164:167], v222 offset:33792
	ds_read_b128 v[168:171], v222 offset:34816
	ds_read_b128 v[172:175], v222 offset:35840
	ds_read_b128 v[176:179], v222 offset:36864
	ds_read_b128 v[180:183], v222 offset:37888
	ds_read_b128 v[202:205], v222 offset:38912
	ds_read_b128 v[206:209], v222 offset:39936
	global_load_lds_dwordx4 v[226:227], off
	v_lshl_add_u64 v[226:227], s[50:51], 0, v[186:187]
	s_mov_b32 m0, s62
	s_nop 0
	global_load_lds_dwordx4 v[226:227], off
	s_waitcnt vmcnt(8)
	s_waitcnt lgkmcnt(0)
	s_barrier
	s_setprio 1
	s_waitcnt lgkmcnt(0)
	v_mfma_f32_16x16x32_bf16 v[124:127], v[128:131], v[160:163], v[124:127]
	v_mfma_f32_16x16x32_bf16 v[120:123], v[136:139], v[160:163], v[120:123]
	v_mfma_f32_16x16x32_bf16 v[108:111], v[128:131], v[168:171], v[108:111]
	v_mfma_f32_16x16x32_bf16 v[104:107], v[136:139], v[168:171], v[104:107]
	v_mfma_f32_16x16x32_bf16 v[92:95], v[128:131], v[176:179], v[92:95]
	v_mfma_f32_16x16x32_bf16 v[88:91], v[136:139], v[176:179], v[88:91]
	v_mfma_f32_16x16x32_bf16 v[76:79], v[128:131], v[202:205], v[76:79]
	v_mfma_f32_16x16x32_bf16 v[72:75], v[136:139], v[202:205], v[72:75]
	v_mfma_f32_16x16x32_bf16 v[124:127], v[132:135], v[164:167], v[124:127]
	v_mfma_f32_16x16x32_bf16 v[120:123], v[140:143], v[164:167], v[120:123]
	v_mfma_f32_16x16x32_bf16 v[108:111], v[132:135], v[172:175], v[108:111]
	v_mfma_f32_16x16x32_bf16 v[104:107], v[140:143], v[172:175], v[104:107]
	v_mfma_f32_16x16x32_bf16 v[92:95], v[132:135], v[180:183], v[92:95]
	v_mfma_f32_16x16x32_bf16 v[88:91], v[140:143], v[180:183], v[88:91]
	v_mfma_f32_16x16x32_bf16 v[76:79], v[132:135], v[206:209], v[76:79]
	v_mfma_f32_16x16x32_bf16 v[72:75], v[140:143], v[206:209], v[72:75]
	v_mfma_f32_16x16x32_bf16 v[116:119], v[144:147], v[160:163], v[116:119]
	v_mfma_f32_16x16x32_bf16 v[112:115], v[152:155], v[160:163], v[112:115]
	v_mfma_f32_16x16x32_bf16 v[100:103], v[144:147], v[168:171], v[100:103]
	v_mfma_f32_16x16x32_bf16 v[96:99], v[152:155], v[168:171], v[96:99]
	v_mfma_f32_16x16x32_bf16 v[84:87], v[144:147], v[176:179], v[84:87]
	v_mfma_f32_16x16x32_bf16 v[80:83], v[152:155], v[176:179], v[80:83]
	v_mfma_f32_16x16x32_bf16 v[68:71], v[144:147], v[202:205], v[68:71]
	v_mfma_f32_16x16x32_bf16 v[64:67], v[152:155], v[202:205], v[64:67]
	v_mfma_f32_16x16x32_bf16 v[116:119], v[148:151], v[164:167], v[116:119]
	v_mfma_f32_16x16x32_bf16 v[112:115], v[156:159], v[164:167], v[112:115]
	v_mfma_f32_16x16x32_bf16 v[100:103], v[148:151], v[172:175], v[100:103]
	v_mfma_f32_16x16x32_bf16 v[96:99], v[156:159], v[172:175], v[96:99]
	v_mfma_f32_16x16x32_bf16 v[84:87], v[148:151], v[180:183], v[84:87]
	v_mfma_f32_16x16x32_bf16 v[80:83], v[156:159], v[180:183], v[80:83]
	v_mfma_f32_16x16x32_bf16 v[68:71], v[148:151], v[206:209], v[68:71]
	v_mfma_f32_16x16x32_bf16 v[64:67], v[156:159], v[206:209], v[64:67]
	s_setprio 0
	s_barrier
; #define PG8_STAGE(bufoff, gbase, voff) do { _Pragma("unroll") for (int _i = 0; _i < 2; ++_i) \
;         __builtin_amdgcn_global_load_lds((const unsigned*)((const char*)(gbase) + (voff)[_i]), (PG8_LAS unsigned*)(lds + (bufoff) + ldsw + _i * 8192), 16, 0, 0); } while (0)
; #define PG8_LDA(dst, b, h) do { _Pragma("unroll") for (int m = 0; m < 4; ++m) _Pragma("unroll") for (int k = 0; k < 2; ++k) dst[m][k] = *(const PG8_LAS bf16x8*)(lds + PG8_SA(b, h) + aoff + m * 2048 + k * 1024); } while (0)
; #define PG8_MMA(ai, bj, At, Bt) do { __builtin_amdgcn_s_setprio(1); _Pragma("unroll") for (int m = 0; m < 4; ++m) _Pragma("unroll") for (int n = 0; n < 2; ++n) _Pragma("unroll") for (int k = 0; k < 2; ++k) \
;         acc[ai][bj][m][n] = __builtin_amdgcn_mfma_f32_16x16x32_bf16(Bt[n][k], At[m][k], acc[ai][bj][m][n], 0, 0, 0); __builtin_amdgcn_s_setprio(0); } while (0)
; #define PG8_WAIT_V(n) asm volatile("s_waitcnt vmcnt(" #n ")" ::: "memory")
; #define PG8_WAIT_L(n) asm volatile("s_waitcnt lgkmcnt(" #n ")" ::: "memory")
; #define PG8_BAR __builtin_amdgcn_s_barrier()
; #define PG8_SCHED __builtin_amdgcn_sched_barrier(0)
; template <class Epi, class Sched, bool ALIGN_EPI = false, bool SP2 = false>
; __device__ __forceinline__ void gemm_phase(PG8_LAS unsigned char* lds, const Gemm g, const Sched& S, const Epi& E) {
;     ...
;             PG8_LDA(At, 1, 1); PG8_STAGE(PG8_SB(1, 0), b3, voffB); PG8_STAGE(PG8_SB(1, 1), b3 + hstep, voffB); PG8_STAGE(PG8_SA(1, 0), a3, voffA);
;             PG8_WAIT_V(8); PG8_WAIT_L(0); PG8_BAR; PG8_MMA(1, 0, At, B0); PG8_MMA(1, 1, At, B1); PG8_BAR; PG8_SCHED;
;     ...
;         if constexpr (ALIGN_EPI) { if (wr == 0) PG8_BAR; }
	s_add_i32 s50, s73, s13
	v_lshl_add_u64 v[210:211], v[210:211], 0, s[20:21]
	s_mov_b32 m0, s50
	ds_read_b128 v[160:163], v222 offset:49152
	ds_read_b128 v[164:167], v222 offset:50176
	ds_read_b128 v[168:171], v222 offset:51200
	ds_read_b128 v[172:175], v222 offset:52224
	ds_read_b128 v[176:179], v222 offset:53248
	ds_read_b128 v[180:183], v222 offset:54272
	ds_read_b128 v[202:205], v222 offset:55296
	ds_read_b128 v[206:209], v222 offset:56320
	global_load_lds_dwordx4 v[210:211], off
	s_add_i32 m0, s50, 0x2000
	s_add_u32 s44, s44, 0x40080
	v_lshl_add_u64 v[210:211], v[212:213], 0, s[20:21]
	s_addc_u32 s45, s45, 0
	s_add_i32 s50, s74, s13
	global_load_lds_dwordx4 v[210:211], off
	v_lshl_add_u64 v[210:211], s[44:45], 0, v[188:189]
	s_mov_b32 m0, s50
	s_nop 0
	global_load_lds_dwordx4 v[210:211], off
	v_lshl_add_u64 v[210:211], s[44:45], 0, v[184:185]
	s_add_i32 m0, s50, 0x2000
	s_nop 0
	global_load_lds_dwordx4 v[210:211], off
	v_lshl_add_u64 v[210:211], v[214:215], 0, s[20:21]
	s_mov_b32 m0, s64
	s_nop 0
	global_load_lds_dwordx4 v[210:211], off
	v_lshl_add_u64 v[210:211], v[224:225], 0, s[20:21]
	s_mov_b32 m0, s65
	s_nop 0
	global_load_lds_dwordx4 v[210:211], off
	s_waitcnt vmcnt(8)
	s_waitcnt lgkmcnt(0)
	s_barrier
	s_setprio 1
	s_waitcnt lgkmcnt(0)
	v_mfma_f32_16x16x32_bf16 v[60:63], v[128:131], v[160:163], v[60:63]
	v_mfma_f32_16x16x32_bf16 v[56:59], v[136:139], v[160:163], v[56:59]
	v_mfma_f32_16x16x32_bf16 v[44:47], v[128:131], v[168:171], v[44:47]
	v_mfma_f32_16x16x32_bf16 v[40:43], v[136:139], v[168:171], v[40:43]
	v_mfma_f32_16x16x32_bf16 v[28:31], v[128:131], v[176:179], v[28:31]
	v_mfma_f32_16x16x32_bf16 v[24:27], v[136:139], v[176:179], v[24:27]
	v_mfma_f32_16x16x32_bf16 v[12:15], v[128:131], v[202:205], v[12:15]
	v_mfma_f32_16x16x32_bf16 v[8:11], v[136:139], v[202:205], v[8:11]
	v_mfma_f32_16x16x32_bf16 v[60:63], v[132:135], v[164:167], v[60:63]
	v_mfma_f32_16x16x32_bf16 v[56:59], v[140:143], v[164:167], v[56:59]
	v_mfma_f32_16x16x32_bf16 v[44:47], v[132:135], v[172:175], v[44:47]
	v_mfma_f32_16x16x32_bf16 v[40:43], v[140:143], v[172:175], v[40:43]
	v_mfma_f32_16x16x32_bf16 v[28:31], v[132:135], v[180:183], v[28:31]
	v_mfma_f32_16x16x32_bf16 v[24:27], v[140:143], v[180:183], v[24:27]
	v_mfma_f32_16x16x32_bf16 v[12:15], v[132:135], v[206:209], v[12:15]
	v_mfma_f32_16x16x32_bf16 v[8:11], v[140:143], v[206:209], v[8:11]
	v_mfma_f32_16x16x32_bf16 v[52:55], v[144:147], v[160:163], v[52:55]
	v_mfma_f32_16x16x32_bf16 v[48:51], v[152:155], v[160:163], v[48:51]
	v_mfma_f32_16x16x32_bf16 v[36:39], v[144:147], v[168:171], v[36:39]
	v_mfma_f32_16x16x32_bf16 v[32:35], v[152:155], v[168:171], v[32:35]
	v_mfma_f32_16x16x32_bf16 v[20:23], v[144:147], v[176:179], v[20:23]
	v_mfma_f32_16x16x32_bf16 v[16:19], v[152:155], v[176:179], v[16:19]
	v_mfma_f32_16x16x32_bf16 v[4:7], v[144:147], v[202:205], v[4:7]
	v_mfma_f32_16x16x32_bf16 v[0:3], v[152:155], v[202:205], v[0:3]
	v_mfma_f32_16x16x32_bf16 v[52:55], v[148:151], v[164:167], v[52:55]
	v_mfma_f32_16x16x32_bf16 v[48:51], v[156:159], v[164:167], v[48:51]
	v_mfma_f32_16x16x32_bf16 v[36:39], v[148:151], v[172:175], v[36:39]
	v_mfma_f32_16x16x32_bf16 v[32:35], v[156:159], v[172:175], v[32:35]
	v_mfma_f32_16x16x32_bf16 v[20:23], v[148:151], v[180:183], v[20:23]
	v_mfma_f32_16x16x32_bf16 v[16:19], v[156:159], v[180:183], v[16:19]
	v_mfma_f32_16x16x32_bf16 v[4:7], v[148:151], v[206:209], v[4:7]
	v_mfma_f32_16x16x32_bf16 v[0:3], v[156:159], v[206:209], v[0:3]
	s_setprio 0
	s_barrier
	s_add_i32 s72, s72, 2
	s_add_u32 s36, s36, 0x100
	s_addc_u32 s37, s37, 0
	s_add_u32 s70, s70, 0x100
	s_addc_u32 s71, s71, 0
	s_cmp_gt_u32 s72, 13
	s_cbranch_scc0 .LBB0_573
	s_and_b64 vcc, exec, s[22:23]
	s_cbranch_vccz .LBB0_576
	s_barrier

; #define PG8_STAGE(bufoff, gbase, voff) do { _Pragma("unroll") for (int _i = 0; _i < 2; ++_i) \
;         __builtin_amdgcn_global_load_lds((const unsigned*)((const char*)(gbase) + (voff)[_i]), (PG8_LAS unsigned*)(lds + (bufoff) + ldsw + _i * 8192), 16, 0, 0); } while (0)
; #define PG8_LDA(dst, b, h) do { _Pragma("unroll") for (int m = 0; m < 4; ++m) _Pragma("unroll") for (int k = 0; k < 2; ++k) dst[m][k] = *(const PG8_LAS bf16x8*)(lds + PG8_SA(b, h) + aoff + m * 2048 + k * 1024); } while (0)
; #define PG8_LDB(dst, b, h) do { _Pragma("unroll") for (int n = 0; n < 2; ++n) _Pragma("unroll") for (int k = 0; k < 2; ++k) dst[n][k] = *(const PG8_LAS bf16x8*)(lds + PG8_SB(b, h) + boff + n * 2048 + k * 1024); } while (0)
; #define PG8_WAIT_V(n) asm volatile("s_waitcnt vmcnt(" #n ")" ::: "memory")
; #define PG8_WAIT_L(n) asm volatile("s_waitcnt lgkmcnt(" #n ")" ::: "memory")
; #define PG8_BAR __builtin_amdgcn_s_barrier()
; #define PG8_SCHED __builtin_amdgcn_sched_barrier(0)
; template <class Epi, class Sched, bool ALIGN_EPI = false, bool SP2 = false>
; __device__ __forceinline__ void gemm_phase(PG8_LAS unsigned char* lds, const Gemm g, const Sched& S, const Epi& E) {
;     ...
;         const bool has_next = S.next(ui + 1, nxt);
;         const char* nA = has_next ? (const char*)g.A + (size_t)nxt.pm * tstep : cA; const char* nB = has_next ? (const char*)g.Bt + (size_t)nxt.pn * tstep : cB;
;         for (int t = 0; t < nt; t += 2) {
;             const bool last = (t == nt - 2);
;             const char* a1 = cA + (size_t)(t + 1) * kstep;
;             const char* a2 = last ? nA : cA + (size_t)(t + 2) * kstep; const char* b2 = last ? nB : cB + (size_t)(t + 2) * kstep;
;             const char* a3 = a2 + kstep; const char* b3 = b2 + kstep;
;             if (last && has_next) S.a_ready(nxt);
;             if constexpr (SP2) {
;             PG8_LDB(B0, 0, 0); PG8_LDB(B1, 0, 1); PG8_SCHED; PG8_LDA(At, 0, 0); PG8_STAGE(PG8_SA(1, 1), a1 + hstep, voffA);
;             PG8_WAIT_V(8); PG8_WAIT_L(0); PG8_BAR; PG8_MMA(0, 0, At, B0); PG8_MMA(0, 1, At, B1); PG8_BAR; PG8_SCHED;
;             PG8_LDA(At, 0, 1); PG8_STAGE(PG8_SB(0, 0), b2, voffB); PG8_STAGE(PG8_SB(0, 1), b2 + hstep, voffB); PG8_STAGE(PG8_SA(0, 0), a2, voffA);
;             PG8_WAIT_V(8); PG8_WAIT_L(0); PG8_BAR; PG8_MMA(1, 0, At, B0); PG8_MMA(1, 1, At, B1); PG8_BAR; PG8_SCHED;
.LBB0_644:
	s_ashr_i32 s27, s26, 31
	s_lshl_b64 s[28:29], s[26:27], 20
	s_add_u32 s28, s13, s28
	s_addc_u32 s29, s47, s29
	s_and_b64 s[30:31], s[38:39], exec
	s_cselect_b32 s27, s29, s37
	s_cselect_b32 s70, s28, s36
	s_ashr_i32 s25, s24, 31
	s_lshl_b64 s[30:31], s[24:25], 20
	s_add_u32 s30, s52, s30
	s_addc_u32 s31, s53, s31
	s_and_b64 s[44:45], s[38:39], exec
	s_cselect_b32 s25, s31, s41
	s_cselect_b32 s71, s30, s40
	s_add_u32 s72, s40, 0x100
	s_addc_u32 s73, s41, 0
	s_mov_b32 s74, -2
	ds_read_b128 v[92:95], v196
	ds_read_b128 v[100:103], v196 offset:1024
	ds_read_b128 v[108:111], v196 offset:2048
	ds_read_b128 v[116:119], v196 offset:3072
	ds_read_b128 v[144:147], v197
	ds_read_b128 v[148:151], v197 offset:1024
	ds_read_b128 v[152:155], v197 offset:2048
	ds_read_b128 v[156:159], v197 offset:3072
	s_add_u32 s40, s36, 0x100
	s_addc_u32 s41, s37, 0
	s_cmp_eq_u32 s74, 28
	s_cselect_b32 s51, s27, s41
	s_cselect_b32 s50, s70, s40
	s_cselect_b32 s45, s25, s73
	s_cselect_b32 s44, s71, s72
	v_lshl_add_u64 v[212:213], s[36:37], 0, v[176:177]
	s_add_i32 m0, s55, 0xc000
	ds_read_b128 v[160:163], v198
	ds_read_b128 v[164:167], v198 offset:1024
	ds_read_b128 v[168:171], v198 offset:2048
	ds_read_b128 v[184:187], v198 offset:3072
	ds_read_b128 v[188:191], v198 offset:4096
	ds_read_b128 v[200:203], v198 offset:5120
	ds_read_b128 v[204:207], v198 offset:6144
	ds_read_b128 v[208:211], v198 offset:7168
	global_load_lds_dwordx4 v[212:213], off
	v_lshl_add_u64 v[212:213], s[36:37], 0, v[178:179]
	s_add_i32 m0, s55, 0xe000
	s_nop 0
	global_load_lds_dwordx4 v[212:213], off
	s_waitcnt vmcnt(8)
	s_waitcnt lgkmcnt(0)
	s_barrier
	s_setprio 1
	s_waitcnt lgkmcnt(0)
	v_mfma_f32_16x16x32_bf16 v[140:143], v[92:95], v[160:163], 0
	v_mfma_f32_16x16x32_bf16 v[136:139], v[108:111], v[160:163], 0
	v_mfma_f32_16x16x32_bf16 v[132:135], v[92:95], v[168:171], 0
	v_mfma_f32_16x16x32_bf16 v[120:123], v[108:111], v[168:171], 0
	v_mfma_f32_16x16x32_bf16 v[112:115], v[92:95], v[188:191], 0
	v_mfma_f32_16x16x32_bf16 v[88:91], v[108:111], v[188:191], 0
	v_mfma_f32_16x16x32_bf16 v[76:79], v[92:95], v[204:207], 0
	v_mfma_f32_16x16x32_bf16 v[72:75], v[108:111], v[204:207], 0
	v_mfma_f32_16x16x32_bf16 v[140:143], v[100:103], v[164:167], v[140:143]
	v_mfma_f32_16x16x32_bf16 v[136:139], v[116:119], v[164:167], v[136:139]
	v_mfma_f32_16x16x32_bf16 v[132:135], v[100:103], v[184:187], v[132:135]
	v_mfma_f32_16x16x32_bf16 v[120:123], v[116:119], v[184:187], v[120:123]
	v_mfma_f32_16x16x32_bf16 v[112:115], v[100:103], v[200:203], v[112:115]
	v_mfma_f32_16x16x32_bf16 v[88:91], v[116:119], v[200:203], v[88:91]
	v_mfma_f32_16x16x32_bf16 v[76:79], v[100:103], v[208:211], v[76:79]
	v_mfma_f32_16x16x32_bf16 v[72:75], v[116:119], v[208:211], v[72:75]
	v_mfma_f32_16x16x32_bf16 v[128:131], v[144:147], v[160:163], 0
	v_mfma_f32_16x16x32_bf16 v[124:127], v[152:155], v[160:163], 0
	v_mfma_f32_16x16x32_bf16 v[104:107], v[144:147], v[168:171], 0
	v_mfma_f32_16x16x32_bf16 v[96:99], v[152:155], v[168:171], 0
	v_mfma_f32_16x16x32_bf16 v[84:87], v[144:147], v[188:191], 0
	v_mfma_f32_16x16x32_bf16 v[80:83], v[152:155], v[188:191], 0
	v_mfma_f32_16x16x32_bf16 v[68:71], v[144:147], v[204:207], 0
	v_mfma_f32_16x16x32_bf16 v[64:67], v[152:155], v[204:207], 0
	v_mfma_f32_16x16x32_bf16 v[128:131], v[148:151], v[164:167], v[128:131]
	v_mfma_f32_16x16x32_bf16 v[124:127], v[156:159], v[164:167], v[124:127]
	v_mfma_f32_16x16x32_bf16 v[104:107], v[148:151], v[184:187], v[104:107]
	v_mfma_f32_16x16x32_bf16 v[96:99], v[156:159], v[184:187], v[96:99]
	v_mfma_f32_16x16x32_bf16 v[84:87], v[148:151], v[200:203], v[84:87]
	v_mfma_f32_16x16x32_bf16 v[80:83], v[156:159], v[200:203], v[80:83]
	v_mfma_f32_16x16x32_bf16 v[68:71], v[148:151], v[208:211], v[68:71]
	v_mfma_f32_16x16x32_bf16 v[64:67], v[156:159], v[208:211], v[64:67]
	s_setprio 0
	s_barrier
	s_add_i32 s36, s68, s54
	v_lshl_add_u64 v[212:213], s[44:45], 0, v[174:175]
	s_mov_b32 m0, s36
	ds_read_b128 v[160:163], v198 offset:16384
	ds_read_b128 v[164:167], v198 offset:17408
	ds_read_b128 v[168:171], v198 offset:18432
	ds_read_b128 v[184:187], v198 offset:19456
	ds_read_b128 v[188:191], v198 offset:20480
	ds_read_b128 v[200:203], v198 offset:21504
	ds_read_b128 v[204:207], v198 offset:22528
	ds_read_b128 v[208:211], v198 offset:23552
	global_load_lds_dwordx4 v[212:213], off
	s_add_i32 m0, s36, 0x2000
	s_add_u32 s36, s44, 0x80000
	v_lshl_add_u64 v[214:215], s[44:45], 0, v[172:173]
	s_addc_u32 s37, s45, 0
	s_add_i32 s75, s69, s54
	global_load_lds_dwordx4 v[214:215], off
	v_lshl_add_u64 v[218:219], s[36:37], 0, v[174:175]
	s_mov_b32 m0, s75
	v_lshl_add_u64 v[220:221], s[50:51], 0, v[172:173]
	global_load_lds_dwordx4 v[218:219], off
	v_lshl_add_u64 v[218:219], s[36:37], 0, v[172:173]
	s_add_i32 m0, s75, 0x2000
	s_nop 0
	global_load_lds_dwordx4 v[218:219], off
	v_lshl_add_u64 v[218:219], s[50:51], 0, v[174:175]
	s_mov_b32 m0, s55
	s_nop 0
	global_load_lds_dwordx4 v[218:219], off
	s_mov_b32 m0, s60
	s_nop 0
	global_load_lds_dwordx4 v[220:221], off
	s_waitcnt vmcnt(8)
	s_waitcnt lgkmcnt(0)
	s_barrier
; #define PG8_STAGE(bufoff, gbase, voff) do { _Pragma("unroll") for (int _i = 0; _i < 2; ++_i) \
;         __builtin_amdgcn_global_load_lds((const unsigned*)((const char*)(gbase) + (voff)[_i]), (PG8_LAS unsigned*)(lds + (bufoff) + ldsw + _i * 8192), 16, 0, 0); } while (0)
; #define PG8_LDA(dst, b, h) do { _Pragma("unroll") for (int m = 0; m < 4; ++m) _Pragma("unroll") for (int k = 0; k < 2; ++k) dst[m][k] = *(const PG8_LAS bf16x8*)(lds + PG8_SA(b, h) + aoff + m * 2048 + k * 1024); } while (0)
; #define PG8_LDB(dst, b, h) do { _Pragma("unroll") for (int n = 0; n < 2; ++n) _Pragma("unroll") for (int k = 0; k < 2; ++k) dst[n][k] = *(const PG8_LAS bf16x8*)(lds + PG8_SB(b, h) + boff + n * 2048 + k * 1024); } while (0)
; #define PG8_MMA(ai, bj, At, Bt) do { __builtin_amdgcn_s_setprio(1); _Pragma("unroll") for (int m = 0; m < 4; ++m) _Pragma("unroll") for (int n = 0; n < 2; ++n) _Pragma("unroll") for (int k = 0; k < 2; ++k) \
;         acc[ai][bj][m][n] = __builtin_amdgcn_mfma_f32_16x16x32_bf16(Bt[n][k], At[m][k], acc[ai][bj][m][n], 0, 0, 0); __builtin_amdgcn_s_setprio(0); } while (0)
; #define PG8_WAIT_V(n) asm volatile("s_waitcnt vmcnt(" #n ")" ::: "memory")
; #define PG8_WAIT_L(n) asm volatile("s_waitcnt lgkmcnt(" #n ")" ::: "memory")
; #define PG8_BAR __builtin_amdgcn_s_barrier()
; #define PG8_SCHED __builtin_amdgcn_sched_barrier(0)
; template <class Epi, class Sched, bool ALIGN_EPI = false, bool SP2 = false>
; __device__ __forceinline__ void gemm_phase(PG8_LAS unsigned char* lds, const Gemm g, const Sched& S, const Epi& E) {
;     ...
;             PG8_WAIT_V(8); PG8_WAIT_L(0); PG8_BAR; PG8_MMA(1, 0, At, B0); PG8_MMA(1, 1, At, B1); PG8_BAR; PG8_SCHED;
;             PG8_LDB(B0, 1, 0); PG8_LDB(B1, 1, 1); PG8_SCHED; PG8_LDA(At, 1, 0); PG8_STAGE(PG8_SA(0, 1), a2 + hstep, voffA);
;             PG8_WAIT_V(8); PG8_WAIT_L(0); PG8_BAR; PG8_MMA(0, 0, At, B0); PG8_MMA(0, 1, At, B1); PG8_BAR; PG8_SCHED;
	s_setprio 1
	s_waitcnt lgkmcnt(0)
	v_mfma_f32_16x16x32_bf16 v[60:63], v[92:95], v[160:163], 0
	v_mfma_f32_16x16x32_bf16 v[56:59], v[108:111], v[160:163], 0
	v_mfma_f32_16x16x32_bf16 v[52:55], v[92:95], v[168:171], 0
	v_mfma_f32_16x16x32_bf16 v[40:43], v[108:111], v[168:171], 0
	v_mfma_f32_16x16x32_bf16 v[36:39], v[92:95], v[188:191], 0
	v_mfma_f32_16x16x32_bf16 v[24:27], v[108:111], v[188:191], 0
	v_mfma_f32_16x16x32_bf16 v[12:15], v[92:95], v[204:207], 0
	v_mfma_f32_16x16x32_bf16 v[8:11], v[108:111], v[204:207], 0
	v_mfma_f32_16x16x32_bf16 v[60:63], v[100:103], v[164:167], v[60:63]
	v_mfma_f32_16x16x32_bf16 v[56:59], v[116:119], v[164:167], v[56:59]
	v_mfma_f32_16x16x32_bf16 v[52:55], v[100:103], v[184:187], v[52:55]
	v_mfma_f32_16x16x32_bf16 v[40:43], v[116:119], v[184:187], v[40:43]
	v_mfma_f32_16x16x32_bf16 v[36:39], v[100:103], v[200:203], v[36:39]
	v_mfma_f32_16x16x32_bf16 v[24:27], v[116:119], v[200:203], v[24:27]
	v_mfma_f32_16x16x32_bf16 v[12:15], v[100:103], v[208:211], v[12:15]
	v_mfma_f32_16x16x32_bf16 v[8:11], v[116:119], v[208:211], v[8:11]
	v_mfma_f32_16x16x32_bf16 v[48:51], v[144:147], v[160:163], 0
	v_mfma_f32_16x16x32_bf16 v[44:47], v[152:155], v[160:163], 0
	v_mfma_f32_16x16x32_bf16 v[32:35], v[144:147], v[168:171], 0
	v_mfma_f32_16x16x32_bf16 v[28:31], v[152:155], v[168:171], 0
	v_mfma_f32_16x16x32_bf16 v[20:23], v[144:147], v[188:191], 0
	v_mfma_f32_16x16x32_bf16 v[16:19], v[152:155], v[188:191], 0
	v_mfma_f32_16x16x32_bf16 v[4:7], v[144:147], v[204:207], 0
	v_mfma_f32_16x16x32_bf16 v[0:3], v[152:155], v[204:207], 0
	v_mfma_f32_16x16x32_bf16 v[48:51], v[148:151], v[164:167], v[48:51]
	v_mfma_f32_16x16x32_bf16 v[44:47], v[156:159], v[164:167], v[44:47]
	v_mfma_f32_16x16x32_bf16 v[32:35], v[148:151], v[184:187], v[32:35]
	v_mfma_f32_16x16x32_bf16 v[28:31], v[156:159], v[184:187], v[28:31]
	v_mfma_f32_16x16x32_bf16 v[20:23], v[148:151], v[200:203], v[20:23]
	v_mfma_f32_16x16x32_bf16 v[16:19], v[156:159], v[200:203], v[16:19]
	v_mfma_f32_16x16x32_bf16 v[4:7], v[148:151], v[208:211], v[4:7]
	v_mfma_f32_16x16x32_bf16 v[0:3], v[156:159], v[208:211], v[0:3]
	s_setprio 0
	s_barrier
	s_add_i32 s75, 0, 0x18000
	s_add_i32 s76, 0, 0x1c000
	v_add_u32_e32 v116, s75, v194
	v_add_u32_e32 v156, s76, v194
	ds_read_b128 v[92:95], v116
	ds_read_b128 v[100:103], v116 offset:1024
	ds_read_b128 v[108:111], v116 offset:2048
	ds_read_b128 v[116:119], v116 offset:3072
	ds_read_b128 v[144:147], v156
	ds_read_b128 v[148:151], v156 offset:1024
	ds_read_b128 v[152:155], v156 offset:2048
	ds_read_b128 v[156:159], v156 offset:3072
	s_add_u32 s36, s50, 0x80000
	s_addc_u32 s37, s51, 0
	s_mov_b32 m0, s61
	v_lshl_add_u64 v[222:223], s[36:37], 0, v[174:175]
	ds_read_b128 v[160:163], v198 offset:32768
	ds_read_b128 v[164:167], v198 offset:33792
	ds_read_b128 v[168:171], v198 offset:34816
	ds_read_b128 v[184:187], v198 offset:35840
	ds_read_b128 v[188:191], v198 offset:36864
	ds_read_b128 v[200:203], v198 offset:37888
	ds_read_b128 v[204:207], v198 offset:38912
	ds_read_b128 v[208:211], v198 offset:39936
	global_load_lds_dwordx4 v[222:223], off
	v_lshl_add_u64 v[222:223], s[36:37], 0, v[172:173]
	s_mov_b32 m0, s62
	s_nop 0
	global_load_lds_dwordx4 v[222:223], off
	s_waitcnt vmcnt(8)
	s_waitcnt lgkmcnt(0)
	s_barrier
	s_setprio 1
	s_waitcnt lgkmcnt(0)
	v_mfma_f32_16x16x32_bf16 v[140:143], v[92:95], v[160:163], v[140:143]
	v_mfma_f32_16x16x32_bf16 v[136:139], v[108:111], v[160:163], v[136:139]
	v_mfma_f32_16x16x32_bf16 v[132:135], v[92:95], v[168:171], v[132:135]
	v_mfma_f32_16x16x32_bf16 v[120:123], v[108:111], v[168:171], v[120:123]
	v_mfma_f32_16x16x32_bf16 v[112:115], v[92:95], v[188:191], v[112:115]
	v_mfma_f32_16x16x32_bf16 v[88:91], v[108:111], v[188:191], v[88:91]
	v_mfma_f32_16x16x32_bf16 v[76:79], v[92:95], v[204:207], v[76:79]
	v_mfma_f32_16x16x32_bf16 v[72:75], v[108:111], v[204:207], v[72:75]
	v_mfma_f32_16x16x32_bf16 v[140:143], v[100:103], v[164:167], v[140:143]
	v_mfma_f32_16x16x32_bf16 v[136:139], v[116:119], v[164:167], v[136:139]
	v_mfma_f32_16x16x32_bf16 v[132:135], v[100:103], v[184:187], v[132:135]
	v_mfma_f32_16x16x32_bf16 v[120:123], v[116:119], v[184:187], v[120:123]
	v_mfma_f32_16x16x32_bf16 v[112:115], v[100:103], v[200:203], v[112:115]
	v_mfma_f32_16x16x32_bf16 v[88:91], v[116:119], v[200:203], v[88:91]
	v_mfma_f32_16x16x32_bf16 v[76:79], v[100:103], v[208:211], v[76:79]
	v_mfma_f32_16x16x32_bf16 v[72:75], v[116:119], v[208:211], v[72:75]
	v_mfma_f32_16x16x32_bf16 v[128:131], v[144:147], v[160:163], v[128:131]
	v_mfma_f32_16x16x32_bf16 v[124:127], v[152:155], v[160:163], v[124:127]
	v_mfma_f32_16x16x32_bf16 v[104:107], v[144:147], v[168:171], v[104:107]
	v_mfma_f32_16x16x32_bf16 v[96:99], v[152:155], v[168:171], v[96:99]
	v_mfma_f32_16x16x32_bf16 v[84:87], v[144:147], v[188:191], v[84:87]
	v_mfma_f32_16x16x32_bf16 v[80:83], v[152:155], v[188:191], v[80:83]
	v_mfma_f32_16x16x32_bf16 v[68:71], v[144:147], v[204:207], v[68:71]
	v_mfma_f32_16x16x32_bf16 v[64:67], v[152:155], v[204:207], v[64:67]
	v_mfma_f32_16x16x32_bf16 v[128:131], v[148:151], v[164:167], v[128:131]
	v_mfma_f32_16x16x32_bf16 v[124:127], v[156:159], v[164:167], v[124:127]
	v_mfma_f32_16x16x32_bf16 v[104:107], v[148:151], v[184:187], v[104:107]
	v_mfma_f32_16x16x32_bf16 v[96:99], v[156:159], v[184:187], v[96:99]
	v_mfma_f32_16x16x32_bf16 v[84:87], v[148:151], v[200:203], v[84:87]
	v_mfma_f32_16x16x32_bf16 v[80:83], v[156:159], v[200:203], v[80:83]
	v_mfma_f32_16x16x32_bf16 v[68:71], v[148:151], v[208:211], v[68:71]
	v_mfma_f32_16x16x32_bf16 v[64:67], v[156:159], v[208:211], v[64:67]
	s_setprio 0
	s_barrier
; #define PG8_STAGE(bufoff, gbase, voff) do { _Pragma("unroll") for (int _i = 0; _i < 2; ++_i) \
;         __builtin_amdgcn_global_load_lds((const unsigned*)((const char*)(gbase) + (voff)[_i]), (PG8_LAS unsigned*)(lds + (bufoff) + ldsw + _i * 8192), 16, 0, 0); } while (0)
; #define PG8_LDA(dst, b, h) do { _Pragma("unroll") for (int m = 0; m < 4; ++m) _Pragma("unroll") for (int k = 0; k < 2; ++k) dst[m][k] = *(const PG8_LAS bf16x8*)(lds + PG8_SA(b, h) + aoff + m * 2048 + k * 1024); } while (0)
; #define PG8_LDB(dst, b, h) do { _Pragma("unroll") for (int n = 0; n < 2; ++n) _Pragma("unroll") for (int k = 0; k < 2; ++k) dst[n][k] = *(const PG8_LAS bf16x8*)(lds + PG8_SB(b, h) + boff + n * 2048 + k * 1024); } while (0)
; #define PG8_MMA(ai, bj, At, Bt) do { __builtin_amdgcn_s_setprio(1); _Pragma("unroll") for (int m = 0; m < 4; ++m) _Pragma("unroll") for (int n = 0; n < 2; ++n) _Pragma("unroll") for (int k = 0; k < 2; ++k) \
;         acc[ai][bj][m][n] = __builtin_amdgcn_mfma_f32_16x16x32_bf16(Bt[n][k], At[m][k], acc[ai][bj][m][n], 0, 0, 0); __builtin_amdgcn_s_setprio(0); } while (0)
; #define PG8_WAIT_V(n) asm volatile("s_waitcnt vmcnt(" #n ")" ::: "memory")
; #define PG8_BAR __builtin_amdgcn_s_barrier()
; template <class Epi, class Sched, bool ALIGN_EPI = false, bool SP2 = false>
; __device__ __forceinline__ void gemm_phase(PG8_LAS unsigned char* lds, const Gemm g, const Sched& S, const Epi& E) {
;     ...
;         for (int t = 0; t < nt; t += 2) {
;             const bool last = (t == nt - 2);
;             const char* a1 = cA + (size_t)(t + 1) * kstep;
;             const char* a2 = last ? nA : cA + (size_t)(t + 2) * kstep; const char* b2 = last ? nB : cB + (size_t)(t + 2) * kstep;
;             const char* a3 = a2 + kstep; const char* b3 = b2 + kstep;
;             if (last && has_next) S.a_ready(nxt);
;             if constexpr (SP2) {
;             PG8_LDB(B0, 0, 0); PG8_LDB(B1, 0, 1); PG8_SCHED; PG8_LDA(At, 0, 0); PG8_STAGE(PG8_SA(1, 1), a1 + hstep, voffA);
;             PG8_WAIT_V(8); PG8_WAIT_L(0); PG8_BAR; PG8_MMA(0, 0, At, B0); PG8_MMA(0, 1, At, B1); PG8_BAR; PG8_SCHED;
;     ...
;             PG8_LDA(At, 1, 1); PG8_STAGE(PG8_SB(1, 0), b3, voffB); PG8_STAGE(PG8_SB(1, 1), b3 + hstep, voffB); PG8_STAGE(PG8_SA(1, 0), a3, voffA);
;             PG8_WAIT_V(8); PG8_WAIT_L(0); PG8_BAR; PG8_MMA(1, 0, At, B0); PG8_MMA(1, 1, At, B1); PG8_BAR; PG8_SCHED;
	s_add_i32 s36, s75, s54
	v_lshl_add_u64 v[212:213], v[212:213], 0, s[20:21]
	s_mov_b32 m0, s36
	ds_read_b128 v[160:163], v198 offset:49152
	ds_read_b128 v[164:167], v198 offset:50176
	ds_read_b128 v[168:171], v198 offset:51200
	ds_read_b128 v[184:187], v198 offset:52224
	ds_read_b128 v[188:191], v198 offset:53248
	ds_read_b128 v[200:203], v198 offset:54272
	ds_read_b128 v[204:207], v198 offset:55296
	ds_read_b128 v[208:211], v198 offset:56320
	global_load_lds_dwordx4 v[212:213], off
	s_add_i32 m0, s36, 0x2000
	s_add_u32 s36, s44, 0x80080
	v_lshl_add_u64 v[212:213], v[214:215], 0, s[20:21]
	s_addc_u32 s37, s45, 0
	s_add_i32 s44, s76, s54
	global_load_lds_dwordx4 v[212:213], off
	v_lshl_add_u64 v[212:213], s[36:37], 0, v[174:175]
	s_mov_b32 m0, s44
	s_nop 0
	global_load_lds_dwordx4 v[212:213], off
	v_lshl_add_u64 v[212:213], s[36:37], 0, v[172:173]
	s_add_i32 m0, s44, 0x2000
	s_nop 0
	global_load_lds_dwordx4 v[212:213], off
	v_lshl_add_u64 v[212:213], v[218:219], 0, s[20:21]
	s_mov_b32 m0, s66
	s_nop 0
	global_load_lds_dwordx4 v[212:213], off
	v_lshl_add_u64 v[212:213], v[220:221], 0, s[20:21]
	s_mov_b32 m0, s67
	s_nop 0
	global_load_lds_dwordx4 v[212:213], off
	s_waitcnt vmcnt(8)
	s_waitcnt lgkmcnt(0)
	s_barrier
	s_setprio 1
	s_waitcnt lgkmcnt(0)
	v_mfma_f32_16x16x32_bf16 v[60:63], v[92:95], v[160:163], v[60:63]
	v_mfma_f32_16x16x32_bf16 v[56:59], v[108:111], v[160:163], v[56:59]
	v_mfma_f32_16x16x32_bf16 v[52:55], v[92:95], v[168:171], v[52:55]
	v_mfma_f32_16x16x32_bf16 v[40:43], v[108:111], v[168:171], v[40:43]
	v_mfma_f32_16x16x32_bf16 v[36:39], v[92:95], v[188:191], v[36:39]
	v_mfma_f32_16x16x32_bf16 v[24:27], v[108:111], v[188:191], v[24:27]
	v_mfma_f32_16x16x32_bf16 v[12:15], v[92:95], v[204:207], v[12:15]
	v_mfma_f32_16x16x32_bf16 v[8:11], v[108:111], v[204:207], v[8:11]
	v_mfma_f32_16x16x32_bf16 v[60:63], v[100:103], v[164:167], v[60:63]
	v_mfma_f32_16x16x32_bf16 v[56:59], v[116:119], v[164:167], v[56:59]
	v_mfma_f32_16x16x32_bf16 v[52:55], v[100:103], v[184:187], v[52:55]
	v_mfma_f32_16x16x32_bf16 v[40:43], v[116:119], v[184:187], v[40:43]
	v_mfma_f32_16x16x32_bf16 v[36:39], v[100:103], v[200:203], v[36:39]
	v_mfma_f32_16x16x32_bf16 v[24:27], v[116:119], v[200:203], v[24:27]
	v_mfma_f32_16x16x32_bf16 v[12:15], v[100:103], v[208:211], v[12:15]
	v_mfma_f32_16x16x32_bf16 v[8:11], v[116:119], v[208:211], v[8:11]
	v_mfma_f32_16x16x32_bf16 v[48:51], v[144:147], v[160:163], v[48:51]
	v_mfma_f32_16x16x32_bf16 v[44:47], v[152:155], v[160:163], v[44:47]
	v_mfma_f32_16x16x32_bf16 v[32:35], v[144:147], v[168:171], v[32:35]
	v_mfma_f32_16x16x32_bf16 v[28:31], v[152:155], v[168:171], v[28:31]
	v_mfma_f32_16x16x32_bf16 v[20:23], v[144:147], v[188:191], v[20:23]
	v_mfma_f32_16x16x32_bf16 v[16:19], v[152:155], v[188:191], v[16:19]
	v_mfma_f32_16x16x32_bf16 v[4:7], v[144:147], v[204:207], v[4:7]
	v_mfma_f32_16x16x32_bf16 v[0:3], v[152:155], v[204:207], v[0:3]
	v_mfma_f32_16x16x32_bf16 v[48:51], v[148:151], v[164:167], v[48:51]
	v_mfma_f32_16x16x32_bf16 v[44:47], v[156:159], v[164:167], v[44:47]
	v_mfma_f32_16x16x32_bf16 v[32:35], v[148:151], v[184:187], v[32:35]
	v_mfma_f32_16x16x32_bf16 v[28:31], v[156:159], v[184:187], v[28:31]
	v_mfma_f32_16x16x32_bf16 v[20:23], v[148:151], v[200:203], v[20:23]
	v_mfma_f32_16x16x32_bf16 v[16:19], v[156:159], v[200:203], v[16:19]
	v_mfma_f32_16x16x32_bf16 v[4:7], v[148:151], v[208:211], v[4:7]
	v_mfma_f32_16x16x32_bf16 v[0:3], v[156:159], v[208:211], v[0:3]
	s_setprio 0
	s_barrier
	s_add_i32 s74, s74, 2
	s_add_u32 s72, s72, 0x100
	s_addc_u32 s73, s73, 0
	s_cmp_gt_u32 s74, 29
	s_mov_b64 s[36:37], s[40:41]
.LBB0_645:
	ds_read_b128 v[92:95], v196
	ds_read_b128 v[100:103], v196 offset:1024
	ds_read_b128 v[108:111], v196 offset:2048
	ds_read_b128 v[116:119], v196 offset:3072
	ds_read_b128 v[144:147], v197
	ds_read_b128 v[148:151], v197 offset:1024
	ds_read_b128 v[152:155], v197 offset:2048
	ds_read_b128 v[156:159], v197 offset:3072
	s_add_u32 s40, s36, 0x100
	s_addc_u32 s41, s37, 0
	s_cmp_eq_u32 s74, 28
	s_cselect_b32 s51, s27, s41
	s_cselect_b32 s50, s70, s40
	s_cselect_b32 s45, s25, s73
	s_cselect_b32 s44, s71, s72
	v_lshl_add_u64 v[212:213], s[36:37], 0, v[176:177]
	s_add_i32 m0, s55, 0xc000
	ds_read_b128 v[160:163], v198
	ds_read_b128 v[164:167], v198 offset:1024
	ds_read_b128 v[168:171], v198 offset:2048
	ds_read_b128 v[184:187], v198 offset:3072
	ds_read_b128 v[188:191], v198 offset:4096
	ds_read_b128 v[200:203], v198 offset:5120
	ds_read_b128 v[204:207], v198 offset:6144
	ds_read_b128 v[208:211], v198 offset:7168
	global_load_lds_dwordx4 v[212:213], off
	v_lshl_add_u64 v[212:213], s[36:37], 0, v[178:179]
	s_add_i32 m0, s55, 0xe000
	s_nop 0
	global_load_lds_dwordx4 v[212:213], off
	s_waitcnt vmcnt(8)
	s_waitcnt lgkmcnt(0)
	s_barrier
; #define PG8_STAGE(bufoff, gbase, voff) do { _Pragma("unroll") for (int _i = 0; _i < 2; ++_i) \
;         __builtin_amdgcn_global_load_lds((const unsigned*)((const char*)(gbase) + (voff)[_i]), (PG8_LAS unsigned*)(lds + (bufoff) + ldsw + _i * 8192), 16, 0, 0); } while (0)
; #define PG8_LDA(dst, b, h) do { _Pragma("unroll") for (int m = 0; m < 4; ++m) _Pragma("unroll") for (int k = 0; k < 2; ++k) dst[m][k] = *(const PG8_LAS bf16x8*)(lds + PG8_SA(b, h) + aoff + m * 2048 + k * 1024); } while (0)
; #define PG8_MMA(ai, bj, At, Bt) do { __builtin_amdgcn_s_setprio(1); _Pragma("unroll") for (int m = 0; m < 4; ++m) _Pragma("unroll") for (int n = 0; n < 2; ++n) _Pragma("unroll") for (int k = 0; k < 2; ++k) \
;         acc[ai][bj][m][n] = __builtin_amdgcn_mfma_f32_16x16x32_bf16(Bt[n][k], At[m][k], acc[ai][bj][m][n], 0, 0, 0); __builtin_amdgcn_s_setprio(0); } while (0)
; #define PG8_WAIT_V(n) asm volatile("s_waitcnt vmcnt(" #n ")" ::: "memory")
; #define PG8_WAIT_L(n) asm volatile("s_waitcnt lgkmcnt(" #n ")" ::: "memory")
; #define PG8_BAR __builtin_amdgcn_s_barrier()
; #define PG8_SCHED __builtin_amdgcn_sched_barrier(0)
; template <class Epi, class Sched, bool ALIGN_EPI = false, bool SP2 = false>
; __device__ __forceinline__ void gemm_phase(PG8_LAS unsigned char* lds, const Gemm g, const Sched& S, const Epi& E) {
;     ...
;             PG8_WAIT_V(8); PG8_WAIT_L(0); PG8_BAR; PG8_MMA(0, 0, At, B0); PG8_MMA(0, 1, At, B1); PG8_BAR; PG8_SCHED;
;             PG8_LDA(At, 0, 1); PG8_STAGE(PG8_SB(0, 0), b2, voffB); PG8_STAGE(PG8_SB(0, 1), b2 + hstep, voffB); PG8_STAGE(PG8_SA(0, 0), a2, voffA);
;             PG8_WAIT_V(8); PG8_WAIT_L(0); PG8_BAR; PG8_MMA(1, 0, At, B0); PG8_MMA(1, 1, At, B1); PG8_BAR; PG8_SCHED;
	s_setprio 1
	s_waitcnt lgkmcnt(0)
	v_mfma_f32_16x16x32_bf16 v[140:143], v[92:95], v[160:163], v[140:143]
	v_mfma_f32_16x16x32_bf16 v[136:139], v[108:111], v[160:163], v[136:139]
	v_mfma_f32_16x16x32_bf16 v[132:135], v[92:95], v[168:171], v[132:135]
	v_mfma_f32_16x16x32_bf16 v[120:123], v[108:111], v[168:171], v[120:123]
	v_mfma_f32_16x16x32_bf16 v[112:115], v[92:95], v[188:191], v[112:115]
	v_mfma_f32_16x16x32_bf16 v[88:91], v[108:111], v[188:191], v[88:91]
	v_mfma_f32_16x16x32_bf16 v[76:79], v[92:95], v[204:207], v[76:79]
	v_mfma_f32_16x16x32_bf16 v[72:75], v[108:111], v[204:207], v[72:75]
	v_mfma_f32_16x16x32_bf16 v[140:143], v[100:103], v[164:167], v[140:143]
	v_mfma_f32_16x16x32_bf16 v[136:139], v[116:119], v[164:167], v[136:139]
	v_mfma_f32_16x16x32_bf16 v[132:135], v[100:103], v[184:187], v[132:135]
	v_mfma_f32_16x16x32_bf16 v[120:123], v[116:119], v[184:187], v[120:123]
	v_mfma_f32_16x16x32_bf16 v[112:115], v[100:103], v[200:203], v[112:115]
	v_mfma_f32_16x16x32_bf16 v[88:91], v[116:119], v[200:203], v[88:91]
	v_mfma_f32_16x16x32_bf16 v[76:79], v[100:103], v[208:211], v[76:79]
	v_mfma_f32_16x16x32_bf16 v[72:75], v[116:119], v[208:211], v[72:75]
	v_mfma_f32_16x16x32_bf16 v[128:131], v[144:147], v[160:163], v[128:131]
	v_mfma_f32_16x16x32_bf16 v[124:127], v[152:155], v[160:163], v[124:127]
	v_mfma_f32_16x16x32_bf16 v[104:107], v[144:147], v[168:171], v[104:107]
	v_mfma_f32_16x16x32_bf16 v[96:99], v[152:155], v[168:171], v[96:99]
	v_mfma_f32_16x16x32_bf16 v[84:87], v[144:147], v[188:191], v[84:87]
	v_mfma_f32_16x16x32_bf16 v[80:83], v[152:155], v[188:191], v[80:83]
	v_mfma_f32_16x16x32_bf16 v[68:71], v[144:147], v[204:207], v[68:71]
	v_mfma_f32_16x16x32_bf16 v[64:67], v[152:155], v[204:207], v[64:67]
	v_mfma_f32_16x16x32_bf16 v[128:131], v[148:151], v[164:167], v[128:131]
	v_mfma_f32_16x16x32_bf16 v[124:127], v[156:159], v[164:167], v[124:127]
	v_mfma_f32_16x16x32_bf16 v[104:107], v[148:151], v[184:187], v[104:107]
	v_mfma_f32_16x16x32_bf16 v[96:99], v[156:159], v[184:187], v[96:99]
	v_mfma_f32_16x16x32_bf16 v[84:87], v[148:151], v[200:203], v[84:87]
	v_mfma_f32_16x16x32_bf16 v[80:83], v[156:159], v[200:203], v[80:83]
	v_mfma_f32_16x16x32_bf16 v[68:71], v[148:151], v[208:211], v[68:71]
	v_mfma_f32_16x16x32_bf16 v[64:67], v[156:159], v[208:211], v[64:67]
	s_setprio 0
	s_barrier
	s_add_i32 s36, s68, s54
	v_lshl_add_u64 v[212:213], s[44:45], 0, v[174:175]
	s_mov_b32 m0, s36
	ds_read_b128 v[160:163], v198 offset:16384
	ds_read_b128 v[164:167], v198 offset:17408
	ds_read_b128 v[168:171], v198 offset:18432
	ds_read_b128 v[184:187], v198 offset:19456
	ds_read_b128 v[188:191], v198 offset:20480
	ds_read_b128 v[200:203], v198 offset:21504
	ds_read_b128 v[204:207], v198 offset:22528
	ds_read_b128 v[208:211], v198 offset:23552
	global_load_lds_dwordx4 v[212:213], off
	s_add_i32 m0, s36, 0x2000
	s_add_u32 s36, s44, 0x80000
	v_lshl_add_u64 v[214:215], s[44:45], 0, v[172:173]
	s_addc_u32 s37, s45, 0
	s_add_i32 s75, s69, s54
	global_load_lds_dwordx4 v[214:215], off
	v_lshl_add_u64 v[218:219], s[36:37], 0, v[174:175]
	s_mov_b32 m0, s75
	v_lshl_add_u64 v[220:221], s[50:51], 0, v[172:173]
	global_load_lds_dwordx4 v[218:219], off
	v_lshl_add_u64 v[218:219], s[36:37], 0, v[172:173]
	s_add_i32 m0, s75, 0x2000
	s_nop 0
	global_load_lds_dwordx4 v[218:219], off
	v_lshl_add_u64 v[218:219], s[50:51], 0, v[174:175]
	s_mov_b32 m0, s55
	s_nop 0
	global_load_lds_dwordx4 v[218:219], off
	s_mov_b32 m0, s60
	s_nop 0
	global_load_lds_dwordx4 v[220:221], off
	s_waitcnt vmcnt(8)
	s_waitcnt lgkmcnt(0)
	s_barrier
	s_setprio 1
	s_waitcnt lgkmcnt(0)
	v_mfma_f32_16x16x32_bf16 v[60:63], v[92:95], v[160:163], v[60:63]
	v_mfma_f32_16x16x32_bf16 v[56:59], v[108:111], v[160:163], v[56:59]
	v_mfma_f32_16x16x32_bf16 v[52:55], v[92:95], v[168:171], v[52:55]
	v_mfma_f32_16x16x32_bf16 v[40:43], v[108:111], v[168:171], v[40:43]
	v_mfma_f32_16x16x32_bf16 v[36:39], v[92:95], v[188:191], v[36:39]
	v_mfma_f32_16x16x32_bf16 v[24:27], v[108:111], v[188:191], v[24:27]
	v_mfma_f32_16x16x32_bf16 v[12:15], v[92:95], v[204:207], v[12:15]
	v_mfma_f32_16x16x32_bf16 v[8:11], v[108:111], v[204:207], v[8:11]
	v_mfma_f32_16x16x32_bf16 v[60:63], v[100:103], v[164:167], v[60:63]
	v_mfma_f32_16x16x32_bf16 v[56:59], v[116:119], v[164:167], v[56:59]
	v_mfma_f32_16x16x32_bf16 v[52:55], v[100:103], v[184:187], v[52:55]
	v_mfma_f32_16x16x32_bf16 v[40:43], v[116:119], v[184:187], v[40:43]
	v_mfma_f32_16x16x32_bf16 v[36:39], v[100:103], v[200:203], v[36:39]
	v_mfma_f32_16x16x32_bf16 v[24:27], v[116:119], v[200:203], v[24:27]
	v_mfma_f32_16x16x32_bf16 v[12:15], v[100:103], v[208:211], v[12:15]
	v_mfma_f32_16x16x32_bf16 v[8:11], v[116:119], v[208:211], v[8:11]
	v_mfma_f32_16x16x32_bf16 v[48:51], v[144:147], v[160:163], v[48:51]
	v_mfma_f32_16x16x32_bf16 v[44:47], v[152:155], v[160:163], v[44:47]
	v_mfma_f32_16x16x32_bf16 v[32:35], v[144:147], v[168:171], v[32:35]
	v_mfma_f32_16x16x32_bf16 v[28:31], v[152:155], v[168:171], v[28:31]
	v_mfma_f32_16x16x32_bf16 v[20:23], v[144:147], v[188:191], v[20:23]
	v_mfma_f32_16x16x32_bf16 v[16:19], v[152:155], v[188:191], v[16:19]
	v_mfma_f32_16x16x32_bf16 v[4:7], v[144:147], v[204:207], v[4:7]
	v_mfma_f32_16x16x32_bf16 v[0:3], v[152:155], v[204:207], v[0:3]
	v_mfma_f32_16x16x32_bf16 v[48:51], v[148:151], v[164:167], v[48:51]
	v_mfma_f32_16x16x32_bf16 v[44:47], v[156:159], v[164:167], v[44:47]
	v_mfma_f32_16x16x32_bf16 v[32:35], v[148:151], v[184:187], v[32:35]
	v_mfma_f32_16x16x32_bf16 v[28:31], v[156:159], v[184:187], v[28:31]
	v_mfma_f32_16x16x32_bf16 v[20:23], v[148:151], v[200:203], v[20:23]
	v_mfma_f32_16x16x32_bf16 v[16:19], v[156:159], v[200:203], v[16:19]
	v_mfma_f32_16x16x32_bf16 v[4:7], v[148:151], v[208:211], v[4:7]
	v_mfma_f32_16x16x32_bf16 v[0:3], v[156:159], v[208:211], v[0:3]
	s_setprio 0
	s_barrier
; #define PG8_STAGE(bufoff, gbase, voff) do { _Pragma("unroll") for (int _i = 0; _i < 2; ++_i) \
;         __builtin_amdgcn_global_load_lds((const unsigned*)((const char*)(gbase) + (voff)[_i]), (PG8_LAS unsigned*)(lds + (bufoff) + ldsw + _i * 8192), 16, 0, 0); } while (0)
; #define PG8_LDA(dst, b, h) do { _Pragma("unroll") for (int m = 0; m < 4; ++m) _Pragma("unroll") for (int k = 0; k < 2; ++k) dst[m][k] = *(const PG8_LAS bf16x8*)(lds + PG8_SA(b, h) + aoff + m * 2048 + k * 1024); } while (0)
; #define PG8_LDB(dst, b, h) do { _Pragma("unroll") for (int n = 0; n < 2; ++n) _Pragma("unroll") for (int k = 0; k < 2; ++k) dst[n][k] = *(const PG8_LAS bf16x8*)(lds + PG8_SB(b, h) + boff + n * 2048 + k * 1024); } while (0)
; #define PG8_MMA(ai, bj, At, Bt) do { __builtin_amdgcn_s_setprio(1); _Pragma("unroll") for (int m = 0; m < 4; ++m) _Pragma("unroll") for (int n = 0; n < 2; ++n) _Pragma("unroll") for (int k = 0; k < 2; ++k) \
;         acc[ai][bj][m][n] = __builtin_amdgcn_mfma_f32_16x16x32_bf16(Bt[n][k], At[m][k], acc[ai][bj][m][n], 0, 0, 0); __builtin_amdgcn_s_setprio(0); } while (0)
; #define PG8_WAIT_V(n) asm volatile("s_waitcnt vmcnt(" #n ")" ::: "memory")
; #define PG8_WAIT_L(n) asm volatile("s_waitcnt lgkmcnt(" #n ")" ::: "memory")
; #define PG8_BAR __builtin_amdgcn_s_barrier()
; #define PG8_SCHED __builtin_amdgcn_sched_barrier(0)
; template <class Epi, class Sched, bool ALIGN_EPI = false, bool SP2 = false>
; __device__ __forceinline__ void gemm_phase(PG8_LAS unsigned char* lds, const Gemm g, const Sched& S, const Epi& E) {
;     ...
;             PG8_LDB(B0, 1, 0); PG8_LDB(B1, 1, 1); PG8_SCHED; PG8_LDA(At, 1, 0); PG8_STAGE(PG8_SA(0, 1), a2 + hstep, voffA);
;             PG8_WAIT_V(8); PG8_WAIT_L(0); PG8_BAR; PG8_MMA(0, 0, At, B0); PG8_MMA(0, 1, At, B1); PG8_BAR; PG8_SCHED;
	s_add_i32 s75, 0, 0x18000
	s_add_i32 s76, 0, 0x1c000
	v_add_u32_e32 v116, s75, v194
	v_add_u32_e32 v156, s76, v194
	ds_read_b128 v[92:95], v116
	ds_read_b128 v[100:103], v116 offset:1024
	ds_read_b128 v[108:111], v116 offset:2048
	ds_read_b128 v[116:119], v116 offset:3072
	ds_read_b128 v[144:147], v156
	ds_read_b128 v[148:151], v156 offset:1024
	ds_read_b128 v[152:155], v156 offset:2048
	ds_read_b128 v[156:159], v156 offset:3072
	s_add_u32 s36, s50, 0x80000
	s_addc_u32 s37, s51, 0
	s_mov_b32 m0, s61
	v_lshl_add_u64 v[222:223], s[36:37], 0, v[174:175]
	ds_read_b128 v[160:163], v198 offset:32768
	ds_read_b128 v[164:167], v198 offset:33792
	ds_read_b128 v[168:171], v198 offset:34816
	ds_read_b128 v[184:187], v198 offset:35840
	ds_read_b128 v[188:191], v198 offset:36864
	ds_read_b128 v[200:203], v198 offset:37888
	ds_read_b128 v[204:207], v198 offset:38912
	ds_read_b128 v[208:211], v198 offset:39936
	global_load_lds_dwordx4 v[222:223], off
	v_lshl_add_u64 v[222:223], s[36:37], 0, v[172:173]
	s_mov_b32 m0, s62
	s_nop 0
	global_load_lds_dwordx4 v[222:223], off
	s_waitcnt vmcnt(8)
	s_waitcnt lgkmcnt(0)
	s_barrier
	s_setprio 1
	s_waitcnt lgkmcnt(0)
	v_mfma_f32_16x16x32_bf16 v[140:143], v[92:95], v[160:163], v[140:143]
	v_mfma_f32_16x16x32_bf16 v[136:139], v[108:111], v[160:163], v[136:139]
	v_mfma_f32_16x16x32_bf16 v[132:135], v[92:95], v[168:171], v[132:135]
	v_mfma_f32_16x16x32_bf16 v[120:123], v[108:111], v[168:171], v[120:123]
	v_mfma_f32_16x16x32_bf16 v[112:115], v[92:95], v[188:191], v[112:115]
	v_mfma_f32_16x16x32_bf16 v[88:91], v[108:111], v[188:191], v[88:91]
	v_mfma_f32_16x16x32_bf16 v[76:79], v[92:95], v[204:207], v[76:79]
	v_mfma_f32_16x16x32_bf16 v[72:75], v[108:111], v[204:207], v[72:75]
	v_mfma_f32_16x16x32_bf16 v[140:143], v[100:103], v[164:167], v[140:143]
	v_mfma_f32_16x16x32_bf16 v[136:139], v[116:119], v[164:167], v[136:139]
	v_mfma_f32_16x16x32_bf16 v[132:135], v[100:103], v[184:187], v[132:135]
	v_mfma_f32_16x16x32_bf16 v[120:123], v[116:119], v[184:187], v[120:123]
	v_mfma_f32_16x16x32_bf16 v[112:115], v[100:103], v[200:203], v[112:115]
	v_mfma_f32_16x16x32_bf16 v[88:91], v[116:119], v[200:203], v[88:91]
	v_mfma_f32_16x16x32_bf16 v[76:79], v[100:103], v[208:211], v[76:79]
	v_mfma_f32_16x16x32_bf16 v[72:75], v[116:119], v[208:211], v[72:75]
	v_mfma_f32_16x16x32_bf16 v[128:131], v[144:147], v[160:163], v[128:131]
	v_mfma_f32_16x16x32_bf16 v[124:127], v[152:155], v[160:163], v[124:127]
	v_mfma_f32_16x16x32_bf16 v[104:107], v[144:147], v[168:171], v[104:107]
	v_mfma_f32_16x16x32_bf16 v[96:99], v[152:155], v[168:171], v[96:99]
	v_mfma_f32_16x16x32_bf16 v[84:87], v[144:147], v[188:191], v[84:87]
	v_mfma_f32_16x16x32_bf16 v[80:83], v[152:155], v[188:191], v[80:83]
	v_mfma_f32_16x16x32_bf16 v[68:71], v[144:147], v[204:207], v[68:71]
	v_mfma_f32_16x16x32_bf16 v[64:67], v[152:155], v[204:207], v[64:67]
	v_mfma_f32_16x16x32_bf16 v[128:131], v[148:151], v[164:167], v[128:131]
	v_mfma_f32_16x16x32_bf16 v[124:127], v[156:159], v[164:167], v[124:127]
	v_mfma_f32_16x16x32_bf16 v[104:107], v[148:151], v[184:187], v[104:107]
	v_mfma_f32_16x16x32_bf16 v[96:99], v[156:159], v[184:187], v[96:99]
	v_mfma_f32_16x16x32_bf16 v[84:87], v[148:151], v[200:203], v[84:87]
	v_mfma_f32_16x16x32_bf16 v[80:83], v[156:159], v[200:203], v[80:83]
	v_mfma_f32_16x16x32_bf16 v[68:71], v[148:151], v[208:211], v[68:71]
	v_mfma_f32_16x16x32_bf16 v[64:67], v[156:159], v[208:211], v[64:67]
	s_setprio 0
	s_barrier
; #define PG8_STAGE(bufoff, gbase, voff) do { _Pragma("unroll") for (int _i = 0; _i < 2; ++_i) \
;         __builtin_amdgcn_global_load_lds((const unsigned*)((const char*)(gbase) + (voff)[_i]), (PG8_LAS unsigned*)(lds + (bufoff) + ldsw + _i * 8192), 16, 0, 0); } while (0)
; #define PG8_LDA(dst, b, h) do { _Pragma("unroll") for (int m = 0; m < 4; ++m) _Pragma("unroll") for (int k = 0; k < 2; ++k) dst[m][k] = *(const PG8_LAS bf16x8*)(lds + PG8_SA(b, h) + aoff + m * 2048 + k * 1024); } while (0)
; #define PG8_MMA(ai, bj, At, Bt) do { __builtin_amdgcn_s_setprio(1); _Pragma("unroll") for (int m = 0; m < 4; ++m) _Pragma("unroll") for (int n = 0; n < 2; ++n) _Pragma("unroll") for (int k = 0; k < 2; ++k) \
;         acc[ai][bj][m][n] = __builtin_amdgcn_mfma_f32_16x16x32_bf16(Bt[n][k], At[m][k], acc[ai][bj][m][n], 0, 0, 0); __builtin_amdgcn_s_setprio(0); } while (0)
; #define PG8_WAIT_V(n) asm volatile("s_waitcnt vmcnt(" #n ")" ::: "memory")
; #define PG8_WAIT_L(n) asm volatile("s_waitcnt lgkmcnt(" #n ")" ::: "memory")
; #define PG8_BAR __builtin_amdgcn_s_barrier()
; #define PG8_SCHED __builtin_amdgcn_sched_barrier(0)
; template <class Epi, class Sched, bool ALIGN_EPI = false, bool SP2 = false>
; __device__ __forceinline__ void gemm_phase(PG8_LAS unsigned char* lds, const Gemm g, const Sched& S, const Epi& E) {
;     ...
;             PG8_LDA(At, 1, 1); PG8_STAGE(PG8_SB(1, 0), b3, voffB); PG8_STAGE(PG8_SB(1, 1), b3 + hstep, voffB); PG8_STAGE(PG8_SA(1, 0), a3, voffA);
;             PG8_WAIT_V(8); PG8_WAIT_L(0); PG8_BAR; PG8_MMA(1, 0, At, B0); PG8_MMA(1, 1, At, B1); PG8_BAR; PG8_SCHED;
;     ...
;         }
;         if constexpr (ALIGN_EPI) { if (wr == 0) PG8_BAR; }
	s_add_i32 s36, s75, s54
	v_lshl_add_u64 v[212:213], v[212:213], 0, s[20:21]
	s_mov_b32 m0, s36
	ds_read_b128 v[160:163], v198 offset:49152
	ds_read_b128 v[164:167], v198 offset:50176
	ds_read_b128 v[168:171], v198 offset:51200
	ds_read_b128 v[184:187], v198 offset:52224
	ds_read_b128 v[188:191], v198 offset:53248
	ds_read_b128 v[200:203], v198 offset:54272
	ds_read_b128 v[204:207], v198 offset:55296
	ds_read_b128 v[208:211], v198 offset:56320
	global_load_lds_dwordx4 v[212:213], off
	s_add_i32 m0, s36, 0x2000
	s_add_u32 s36, s44, 0x80080
	v_lshl_add_u64 v[212:213], v[214:215], 0, s[20:21]
	s_addc_u32 s37, s45, 0
	s_add_i32 s44, s76, s54
	global_load_lds_dwordx4 v[212:213], off
	v_lshl_add_u64 v[212:213], s[36:37], 0, v[174:175]
	s_mov_b32 m0, s44
	s_nop 0
	global_load_lds_dwordx4 v[212:213], off
	v_lshl_add_u64 v[212:213], s[36:37], 0, v[172:173]
	s_add_i32 m0, s44, 0x2000
	s_nop 0
	global_load_lds_dwordx4 v[212:213], off
	v_lshl_add_u64 v[212:213], v[218:219], 0, s[20:21]
	s_mov_b32 m0, s66
	s_nop 0
	global_load_lds_dwordx4 v[212:213], off
	v_lshl_add_u64 v[212:213], v[220:221], 0, s[20:21]
	s_mov_b32 m0, s67
	s_nop 0
	global_load_lds_dwordx4 v[212:213], off
	s_waitcnt vmcnt(8)
	s_waitcnt lgkmcnt(0)
	s_barrier
	s_setprio 1
	s_waitcnt lgkmcnt(0)
	v_mfma_f32_16x16x32_bf16 v[60:63], v[92:95], v[160:163], v[60:63]
	v_mfma_f32_16x16x32_bf16 v[56:59], v[108:111], v[160:163], v[56:59]
	v_mfma_f32_16x16x32_bf16 v[52:55], v[92:95], v[168:171], v[52:55]
	v_mfma_f32_16x16x32_bf16 v[40:43], v[108:111], v[168:171], v[40:43]
	v_mfma_f32_16x16x32_bf16 v[36:39], v[92:95], v[188:191], v[36:39]
	v_mfma_f32_16x16x32_bf16 v[24:27], v[108:111], v[188:191], v[24:27]
	v_mfma_f32_16x16x32_bf16 v[12:15], v[92:95], v[204:207], v[12:15]
	v_mfma_f32_16x16x32_bf16 v[8:11], v[108:111], v[204:207], v[8:11]
	v_mfma_f32_16x16x32_bf16 v[60:63], v[100:103], v[164:167], v[60:63]
	v_mfma_f32_16x16x32_bf16 v[56:59], v[116:119], v[164:167], v[56:59]
	v_mfma_f32_16x16x32_bf16 v[52:55], v[100:103], v[184:187], v[52:55]
	v_mfma_f32_16x16x32_bf16 v[40:43], v[116:119], v[184:187], v[40:43]
	v_mfma_f32_16x16x32_bf16 v[36:39], v[100:103], v[200:203], v[36:39]
	v_mfma_f32_16x16x32_bf16 v[24:27], v[116:119], v[200:203], v[24:27]
	v_mfma_f32_16x16x32_bf16 v[12:15], v[100:103], v[208:211], v[12:15]
	v_mfma_f32_16x16x32_bf16 v[8:11], v[116:119], v[208:211], v[8:11]
	v_mfma_f32_16x16x32_bf16 v[48:51], v[144:147], v[160:163], v[48:51]
	v_mfma_f32_16x16x32_bf16 v[44:47], v[152:155], v[160:163], v[44:47]
	v_mfma_f32_16x16x32_bf16 v[32:35], v[144:147], v[168:171], v[32:35]
	v_mfma_f32_16x16x32_bf16 v[28:31], v[152:155], v[168:171], v[28:31]
	v_mfma_f32_16x16x32_bf16 v[20:23], v[144:147], v[188:191], v[20:23]
	v_mfma_f32_16x16x32_bf16 v[16:19], v[152:155], v[188:191], v[16:19]
	v_mfma_f32_16x16x32_bf16 v[4:7], v[144:147], v[204:207], v[4:7]
	v_mfma_f32_16x16x32_bf16 v[0:3], v[152:155], v[204:207], v[0:3]
	v_mfma_f32_16x16x32_bf16 v[48:51], v[148:151], v[164:167], v[48:51]
	v_mfma_f32_16x16x32_bf16 v[44:47], v[156:159], v[164:167], v[44:47]
	v_mfma_f32_16x16x32_bf16 v[32:35], v[148:151], v[184:187], v[32:35]
	v_mfma_f32_16x16x32_bf16 v[28:31], v[156:159], v[184:187], v[28:31]
	v_mfma_f32_16x16x32_bf16 v[20:23], v[148:151], v[200:203], v[20:23]
	v_mfma_f32_16x16x32_bf16 v[16:19], v[156:159], v[200:203], v[16:19]
	v_mfma_f32_16x16x32_bf16 v[4:7], v[148:151], v[208:211], v[4:7]
	v_mfma_f32_16x16x32_bf16 v[0:3], v[156:159], v[208:211], v[0:3]
	s_setprio 0
	s_barrier
	s_add_i32 s74, s74, 2
	s_add_u32 s72, s72, 0x100
	s_addc_u32 s73, s73, 0
	s_cmp_gt_u32 s74, 29
	s_mov_b64 s[36:37], s[40:41]
	s_cbranch_scc0 .LBB0_645
	s_and_b64 vcc, exec, s[22:23]
	s_cbranch_vccz .LBB0_648
	s_barrier

; #define PG8_STAGE(bufoff, gbase, voff) do { _Pragma("unroll") for (int _i = 0; _i < 2; ++_i) \
;         __builtin_amdgcn_global_load_lds((const unsigned*)((const char*)(gbase) + (voff)[_i]), (PG8_LAS unsigned*)(lds + (bufoff) + ldsw + _i * 8192), 16, 0, 0); } while (0)
; #define PG8_WAIT_V(n) asm volatile("s_waitcnt vmcnt(" #n ")" ::: "memory")
; #define PG8_BAR __builtin_amdgcn_s_barrier()
; template <class Epi, class Sched, bool ALIGN_EPI = false, bool SP2 = false>
; __device__ __forceinline__ void gemm_phase(PG8_LAS unsigned char* lds, const Gemm g, const Sched& S, const Epi& E) {
;     int tid_ = threadIdx.x; asm volatile("" : "+v"(tid_));
;     const int tid = tid_, wid = __builtin_amdgcn_readfirstlane(tid >> 6), lane = tid & 63, wr = wid >> 2, wc = wid & 3, fr = lane & 15, fq = lane >> 4;
;     const int K = g.K, nt = K / BK;
;     unsigned voffA[2], voffB[2];
; #pragma unroll
;     for (int i = 0; i < 2; ++i) { int R, C; stage_rc(tid * 16 + i * 8192, R, C); const int Rb = Epi::PERM ? ((R & ~31) + perm32(R & 31)) : R;
;         voffA[i] = (unsigned)(R * K + C) * 2u; voffB[i] = (unsigned)(Rb * K + C) * 2u; }
;     ...
;     const char* cA = (const char*)g.A + (size_t)cur.pm * tstep; const char* cB = (const char*)g.Bt + (size_t)cur.pn * tstep;
;     S.a_ready(cur);
;     if constexpr (SP2) {
;         PG8_STAGE(PG8_SB(0, 0), cB, voffB); PG8_STAGE(PG8_SB(0, 1), cB + hstep, voffB); PG8_STAGE(PG8_SA(0, 0), cA, voffA); PG8_STAGE(PG8_SA(0, 1), cA + hstep, voffA);
;         if (wr == 1) PG8_BAR;
;         PG8_WAIT_V(2); PG8_BAR;
.LBB0_762:
	s_or_b64 exec, exec, s[12:13]
	s_nop 0
	s_nop 0
	s_nop 0
	s_nop 0
	s_mov_b64 s[14:15], s[0:1]
	s_mov_b64 s[16:17], s[0:1]
	s_mov_b64 s[12:13], s[0:1]
	v_mov_b32_e32 v14, v216
	s_waitcnt lgkmcnt(0)
	s_barrier
	s_cmpk_lt_i32 s2, 0x1000
	s_nop 0
	v_readfirstlane_b32 s18, v14
	s_cbranch_scc0 .LBB0_782
	v_lshlrev_b32_e32 v0, 4, v14
	v_add_u32_e32 v1, 0x2000, v0
	v_ashrrev_i32_e32 v2, 31, v1
	v_lshrrev_b32_e32 v2, 22, v2
	v_add_u32_e32 v2, v1, v2
	v_ashrrev_i32_e32 v8, 10, v2
	v_mul_i32_i24_e32 v2, 0x400, v8
	v_sub_u32_e32 v1, v1, v2
	v_lshrrev_b32_e32 v2, 4, v1
	v_bitop3_b32 v1, v2, v1, 32 bitop3:0x6c
	v_ashrrev_i32_e32 v2, 31, v1
	s_load_dwordx2 s[14:15], s[14:15], 0xc8
	s_nop 0
	s_load_dwordx2 s[16:17], s[16:17], 0xc8
	v_lshrrev_b32_e32 v2, 26, v2
	v_add_u32_e32 v2, v1, v2
	v_lshlrev_b32_e32 v3, 3, v8
	v_ashrrev_i32_e32 v9, 6, v2
	v_and_b32_e32 v3, -16, v3
	v_add_u32_e32 v3, v9, v3
	s_waitcnt lgkmcnt(0)
	s_add_u32 s40, s14, 0x7800000
	v_and_b32_e32 v4, 3, v9
	s_mov_b32 s14, 0xfffe0
	v_lshrrev_b32_e32 v5, 2, v3
	v_lshlrev_b32_e32 v6, 1, v3
	v_and_b32_e32 v2, 0xc0, v2
	v_and_or_b32 v4, v3, s14, v4
	v_and_b32_e32 v5, 4, v5
	v_and_b32_e32 v6, 24, v6
	v_sub_u32_e32 v1, v1, v2
	v_mov_b32_e32 v2, 1
	v_or3_b32 v4, v4, v5, v6
	v_lshlrev_b32_e32 v5, 5, v8
	v_ashrrev_i16_sdwa v1, v2, sext(v1) dst_sel:DWORD dst_unused:UNUSED_PAD src0_sel:DWORD src1_sel:BYTE_0
	v_and_b32_e32 v5, 32, v5
	v_bfe_i32 v10, v1, 0, 16
	v_add_lshl_u32 v1, v5, v10, 1
	s_waitcnt vmcnt(0)
	v_lshl_add_u32 v128, v4, 12, v1
	v_lshl_add_u32 v130, v3, 12, v1
	v_bfe_i32 v1, v14, 27, 1
	v_lshrrev_b32_e32 v1, 22, v1
	v_add_u32_e32 v1, v0, v1
	v_and_b32_e32 v1, 0xfffffc00, v1
	v_sub_u32_e32 v0, v0, v1
	v_lshrrev_b32_e32 v1, 4, v0
	v_ashrrev_i32_e32 v3, 31, v14
	v_bitop3_b32 v0, v1, v0, 32 bitop3:0x6c
	v_lshrrev_b32_e32 v3, 26, v3
	v_ashrrev_i32_e32 v1, 31, v0
	v_add_u32_e32 v3, v14, v3
	s_addc_u32 s41, s15, 0
	v_lshrrev_b32_e32 v1, 26, v1
	v_ashrrev_i32_e32 v12, 6, v3
	s_add_u32 s44, s16, 0x3600000
	v_add_u32_e32 v1, v0, v1
	v_lshlrev_b32_e32 v3, 3, v12
	s_addc_u32 s45, s17, 0
	s_ashr_i32 s19, s18, 6
	v_ashrrev_i32_e32 v11, 6, v1
	v_and_b32_e32 v3, -16, v3
	s_ashr_i32 s20, s18, 8
	s_lshl_b32 s47, s19, 10
	v_add_u32_e32 v3, v11, v3
	v_and_b32_e32 v4, 3, v11
	s_lshl_b32 s17, s59, 9
	v_and_or_b32 v4, v3, s14, v4
	s_mul_i32 s16, s59, 0x201
	s_and_b64 s[14:15], s[42:43], exec
	s_cselect_b32 s14, s16, s17
	s_add_i32 s14, s14, s56
	s_ashr_i32 s15, s14, 31
	s_lshr_b32 s15, s15, 24
	s_add_i32 s15, s14, s15
	s_ashr_i32 s16, s15, 8
	s_and_b32 s15, s15, 0xff00
	s_sub_i32 s15, s14, s15
	s_sext_i32_i16 s14, s15
	s_bfe_u32 s14, s14, 0x3001c
	s_add_i32 s17, s15, s14
	s_sext_i32_i16 s14, s17
	s_and_b32 s17, s17, 0xfff8
	s_sub_i32 s15, s15, s17
	s_lshl_b32 s16, s16, 3
	s_sext_i32_i16 s15, s15
	v_lshrrev_b32_e32 v5, 2, v3
	v_lshlrev_b32_e32 v6, 1, v3
	v_and_b32_e32 v1, 0xc0, v1
	s_lshr_b32 s14, s14, 3
	s_add_i32 s28, s16, s15
	v_and_b32_e32 v5, 4, v5
	v_and_b32_e32 v6, 24, v6
	v_sub_u32_e32 v0, v0, v1
	s_ashr_i32 s29, s28, 31
	s_bfe_i64 s[22:23], s[14:15], 0x100000
	v_or3_b32 v4, v4, v5, v6
	v_lshlrev_b32_e32 v5, 5, v12
	v_ashrrev_i16_sdwa v0, v2, sext(v0) dst_sel:DWORD dst_unused:UNUSED_PAD src0_sel:DWORD src1_sel:BYTE_0
	s_lshl_b64 s[16:17], s[28:29], 20
	s_lshl_b64 s[22:23], s[22:23], 20
	v_and_b32_e32 v5, 32, v5
	v_bfe_i32 v13, v0, 0, 16
	s_add_u32 s34, s44, s22
	v_add_lshl_u32 v0, v5, v13, 1
	s_addc_u32 s35, s45, s23
	s_add_i32 s50, s47, 0
	v_lshl_add_u32 v132, v4, 12, v0
	s_add_i32 m0, s50, 0x10000
	v_lshl_add_u32 v134, v3, 12, v0
	global_load_lds_dwordx4 v132, s[34:35]
	s_add_i32 m0, s50, 0x12000
	s_add_u32 s22, s34, 0x80000
	global_load_lds_dwordx4 v128, s[34:35]
	s_addc_u32 s23, s35, 0
	s_add_i32 m0, s50, 0x14000
	v_mov_b32_e32 v133, 0
	global_load_lds_dwordx4 v132, s[22:23]
	s_add_i32 m0, s50, 0x16000
	s_add_u32 s30, s40, s16
	s_addc_u32 s31, s41, s17
	s_add_i32 s51, s50, 0x2000
	global_load_lds_dwordx4 v128, s[22:23]
	s_mov_b32 m0, s50
	s_add_u32 s16, s30, 0x80000
	global_load_lds_dwordx4 v134, s[30:31]
	s_mov_b32 m0, s51
	s_addc_u32 s17, s31, 0
	s_add_i32 s52, s50, 0x4000
	global_load_lds_dwordx4 v130, s[30:31]
	s_mov_b32 m0, s52
	s_add_i32 s53, s50, 0x6000
	global_load_lds_dwordx4 v134, s[16:17]
	s_mov_b32 m0, s53
	v_mov_b32_e32 v129, v133
	global_load_lds_dwordx4 v130, s[16:17]
	s_load_dwordx2 s[16:17], s[12:13], 0xc8
	v_mov_b32_e32 v135, v133
	v_mov_b32_e32 v131, v133
	s_cmp_eq_u32 s20, 1
	s_mov_b32 s54, 0
	v_lshl_add_u64 v[6:7], s[34:35], 0, v[132:133]
	v_lshl_add_u64 v[4:5], s[34:35], 0, v[128:129]
	v_lshl_add_u64 v[0:1], s[30:31], 0, v[134:135]
	s_cselect_b64 s[12:13], -1, 0
	s_cmp_lg_u32 s20, 1
	v_lshl_add_u64 v[2:3], s[30:31], 0, v[130:131]
	s_cbranch_scc1 .LBB0_765
	s_barrier

; #define PG8_STAGE(bufoff, gbase, voff) do { _Pragma("unroll") for (int _i = 0; _i < 2; ++_i) \
;         __builtin_amdgcn_global_load_lds((const unsigned*)((const char*)(gbase) + (voff)[_i]), (PG8_LAS unsigned*)(lds + (bufoff) + ldsw + _i * 8192), 16, 0, 0); } while (0)
; #define PG8_LDA(dst, b, h) do { _Pragma("unroll") for (int m = 0; m < 4; ++m) _Pragma("unroll") for (int k = 0; k < 2; ++k) dst[m][k] = *(const PG8_LAS bf16x8*)(lds + PG8_SA(b, h) + aoff + m * 2048 + k * 1024); } while (0)
; #define PG8_LDB(dst, b, h) do { _Pragma("unroll") for (int n = 0; n < 2; ++n) _Pragma("unroll") for (int k = 0; k < 2; ++k) dst[n][k] = *(const PG8_LAS bf16x8*)(lds + PG8_SB(b, h) + boff + n * 2048 + k * 1024); } while (0)
; #define PG8_WAIT_V(n) asm volatile("s_waitcnt vmcnt(" #n ")" ::: "memory")
; #define PG8_WAIT_L(n) asm volatile("s_waitcnt lgkmcnt(" #n ")" ::: "memory")
; #define PG8_BAR __builtin_amdgcn_s_barrier()
; #define PG8_SCHED __builtin_amdgcn_sched_barrier(0)
; template <class Epi, class Sched, bool ALIGN_EPI = false, bool SP2 = false>
; __device__ __forceinline__ void gemm_phase(PG8_LAS unsigned char* lds, const Gemm g, const Sched& S, const Epi& E) {
;     ...
;         const bool has_next = S.next(ui + 1, nxt);
;         const char* nA = has_next ? (const char*)g.A + (size_t)nxt.pm * tstep : cA; const char* nB = has_next ? (const char*)g.Bt + (size_t)nxt.pn * tstep : cB;
;         for (int t = 0; t < nt; t += 2) {
;             const bool last = (t == nt - 2);
;             const char* a1 = cA + (size_t)(t + 1) * kstep;
;             const char* a2 = last ? nA : cA + (size_t)(t + 2) * kstep; const char* b2 = last ? nB : cB + (size_t)(t + 2) * kstep;
;             const char* a3 = a2 + kstep; const char* b3 = b2 + kstep;
;             if (last && has_next) S.a_ready(nxt);
;             if constexpr (SP2) {
;             PG8_LDB(B0, 0, 0); PG8_LDB(B1, 0, 1); PG8_SCHED; PG8_LDA(At, 0, 0); PG8_STAGE(PG8_SA(1, 1), a1 + hstep, voffA);
;             PG8_WAIT_V(8); PG8_WAIT_L(0); PG8_BAR; PG8_MMA(0, 0, At, B0); PG8_MMA(0, 1, At, B1); PG8_BAR; PG8_SCHED;
;             PG8_LDA(At, 0, 1); PG8_STAGE(PG8_SB(0, 0), b2, voffB); PG8_STAGE(PG8_SB(0, 1), b2 + hstep, voffB); PG8_STAGE(PG8_SA(0, 0), a2, voffA);
;             PG8_WAIT_V(8); PG8_WAIT_L(0); PG8_BAR; PG8_MMA(1, 0, At, B0); PG8_MMA(1, 1, At, B1); PG8_BAR; PG8_SCHED;
.LBB0_774:
	s_ashr_i32 s23, s22, 31
	s_lshl_b64 s[24:25], s[22:23], 20
	s_add_u32 s24, s40, s24
	s_addc_u32 s25, s41, s25
	s_and_b64 s[26:27], s[38:39], exec
	s_cselect_b32 s23, s25, s31
	s_cselect_b32 s62, s24, s30
	s_ashr_i32 s21, s20, 31
	s_lshl_b64 s[26:27], s[20:21], 20
	s_add_u32 s26, s44, s26
	s_addc_u32 s27, s45, s27
	s_and_b64 s[36:37], s[38:39], exec
	s_cselect_b32 s21, s27, s35
	s_cselect_b32 s63, s26, s34
	s_add_u32 s30, s30, 0x80080
	s_addc_u32 s31, s31, 0
	s_add_u32 s64, s34, 0x100
	s_addc_u32 s65, s35, 0
	s_mov_b32 s66, -2
	ds_read_b128 v[152:155], v149
	ds_read_b128 v[156:159], v149 offset:1024
	ds_read_b128 v[160:163], v149 offset:2048
	ds_read_b128 v[164:167], v149 offset:3072
	ds_read_b128 v[168:171], v150
	ds_read_b128 v[172:175], v150 offset:1024
	ds_read_b128 v[176:179], v150 offset:2048
	ds_read_b128 v[180:183], v150 offset:3072
	s_add_u32 s34, s30, 0xfff80080
	s_addc_u32 s35, s31, -1
	s_cmp_eq_u32 s66, 28
	s_cselect_b32 s37, s23, s35
	s_cselect_b32 s36, s62, s34
	s_cselect_b32 s35, s21, s65
	s_cselect_b32 s34, s63, s64
	v_lshl_add_u64 v[144:145], s[30:31], 0, v[136:137]
	s_add_i32 m0, s50, 0xc000
	ds_read_b128 v[184:187], v151
	ds_read_b128 v[188:191], v151 offset:1024
	ds_read_b128 v[192:195], v151 offset:2048
	ds_read_b128 v[196:199], v151 offset:3072
	ds_read_b128 v[200:203], v151 offset:4096
	ds_read_b128 v[204:207], v151 offset:5120
	ds_read_b128 v[208:211], v151 offset:6144
	ds_read_b128 v[212:215], v151 offset:7168
	global_load_lds_dwordx4 v[144:145], off
	v_lshl_add_u64 v[144:145], s[30:31], 0, v[138:139]
	s_add_i32 m0, s50, 0xe000
	s_nop 0
	global_load_lds_dwordx4 v[144:145], off
	s_waitcnt vmcnt(8)
	s_waitcnt lgkmcnt(0)
	s_barrier
	s_setprio 1
	s_waitcnt lgkmcnt(0)
	v_mfma_f32_16x16x32_bf16 v[124:127], v[152:155], v[184:187], 0
	v_mfma_f32_16x16x32_bf16 v[120:123], v[160:163], v[184:187], 0
	v_mfma_f32_16x16x32_bf16 v[108:111], v[152:155], v[192:195], 0
	v_mfma_f32_16x16x32_bf16 v[104:107], v[160:163], v[192:195], 0
	v_mfma_f32_16x16x32_bf16 v[92:95], v[152:155], v[200:203], 0
	v_mfma_f32_16x16x32_bf16 v[88:91], v[160:163], v[200:203], 0
	v_mfma_f32_16x16x32_bf16 v[76:79], v[152:155], v[208:211], 0
	v_mfma_f32_16x16x32_bf16 v[72:75], v[160:163], v[208:211], 0
	v_mfma_f32_16x16x32_bf16 v[124:127], v[156:159], v[188:191], v[124:127]
	v_mfma_f32_16x16x32_bf16 v[120:123], v[164:167], v[188:191], v[120:123]
	v_mfma_f32_16x16x32_bf16 v[108:111], v[156:159], v[196:199], v[108:111]
	v_mfma_f32_16x16x32_bf16 v[104:107], v[164:167], v[196:199], v[104:107]
	v_mfma_f32_16x16x32_bf16 v[92:95], v[156:159], v[204:207], v[92:95]
	v_mfma_f32_16x16x32_bf16 v[88:91], v[164:167], v[204:207], v[88:91]
	v_mfma_f32_16x16x32_bf16 v[76:79], v[156:159], v[212:215], v[76:79]
	v_mfma_f32_16x16x32_bf16 v[72:75], v[164:167], v[212:215], v[72:75]
	v_mfma_f32_16x16x32_bf16 v[116:119], v[168:171], v[184:187], 0
	v_mfma_f32_16x16x32_bf16 v[112:115], v[176:179], v[184:187], 0
	v_mfma_f32_16x16x32_bf16 v[100:103], v[168:171], v[192:195], 0
	v_mfma_f32_16x16x32_bf16 v[96:99], v[176:179], v[192:195], 0
	v_mfma_f32_16x16x32_bf16 v[84:87], v[168:171], v[200:203], 0
	v_mfma_f32_16x16x32_bf16 v[80:83], v[176:179], v[200:203], 0
	v_mfma_f32_16x16x32_bf16 v[68:71], v[168:171], v[208:211], 0
	v_mfma_f32_16x16x32_bf16 v[64:67], v[176:179], v[208:211], 0
	v_mfma_f32_16x16x32_bf16 v[116:119], v[172:175], v[188:191], v[116:119]
	v_mfma_f32_16x16x32_bf16 v[112:115], v[180:183], v[188:191], v[112:115]
	v_mfma_f32_16x16x32_bf16 v[100:103], v[172:175], v[196:199], v[100:103]
	v_mfma_f32_16x16x32_bf16 v[96:99], v[180:183], v[196:199], v[96:99]
	v_mfma_f32_16x16x32_bf16 v[84:87], v[172:175], v[204:207], v[84:87]
	v_mfma_f32_16x16x32_bf16 v[80:83], v[180:183], v[204:207], v[80:83]
	v_mfma_f32_16x16x32_bf16 v[68:71], v[172:175], v[212:215], v[68:71]
	v_mfma_f32_16x16x32_bf16 v[64:67], v[180:183], v[212:215], v[64:67]
	s_setprio 0
	s_barrier
	s_add_i32 s67, s60, s47
	v_lshl_add_u64 v[144:145], s[34:35], 0, v[132:133]
	s_mov_b32 m0, s67
	ds_read_b128 v[184:187], v151 offset:16384
	ds_read_b128 v[188:191], v151 offset:17408
	ds_read_b128 v[192:195], v151 offset:18432
	ds_read_b128 v[196:199], v151 offset:19456
	ds_read_b128 v[200:203], v151 offset:20480
	ds_read_b128 v[204:207], v151 offset:21504
	ds_read_b128 v[208:211], v151 offset:22528
	ds_read_b128 v[212:215], v151 offset:23552
	global_load_lds_dwordx4 v[144:145], off
	s_add_i32 m0, s67, 0x2000
	s_add_u32 s68, s34, 0x80000
	v_lshl_add_u64 v[218:219], s[34:35], 0, v[128:129]
	s_addc_u32 s69, s35, 0
	s_add_i32 s67, s61, s47
	global_load_lds_dwordx4 v[218:219], off
	v_lshl_add_u64 v[220:221], s[68:69], 0, v[132:133]
	s_mov_b32 m0, s67
	v_lshl_add_u64 v[222:223], s[36:37], 0, v[130:131]
	global_load_lds_dwordx4 v[220:221], off
	v_lshl_add_u64 v[220:221], s[68:69], 0, v[128:129]
	s_add_i32 m0, s67, 0x2000
	s_nop 0
	global_load_lds_dwordx4 v[220:221], off
	v_lshl_add_u64 v[220:221], s[36:37], 0, v[134:135]
	s_mov_b32 m0, s50
	s_nop 0
	global_load_lds_dwordx4 v[220:221], off
	s_mov_b32 m0, s51
	s_nop 0
	global_load_lds_dwordx4 v[222:223], off
	s_waitcnt vmcnt(8)
	s_waitcnt lgkmcnt(0)
	s_barrier
; #define PG8_STAGE(bufoff, gbase, voff) do { _Pragma("unroll") for (int _i = 0; _i < 2; ++_i) \
;         __builtin_amdgcn_global_load_lds((const unsigned*)((const char*)(gbase) + (voff)[_i]), (PG8_LAS unsigned*)(lds + (bufoff) + ldsw + _i * 8192), 16, 0, 0); } while (0)
; #define PG8_LDA(dst, b, h) do { _Pragma("unroll") for (int m = 0; m < 4; ++m) _Pragma("unroll") for (int k = 0; k < 2; ++k) dst[m][k] = *(const PG8_LAS bf16x8*)(lds + PG8_SA(b, h) + aoff + m * 2048 + k * 1024); } while (0)
; #define PG8_LDB(dst, b, h) do { _Pragma("unroll") for (int n = 0; n < 2; ++n) _Pragma("unroll") for (int k = 0; k < 2; ++k) dst[n][k] = *(const PG8_LAS bf16x8*)(lds + PG8_SB(b, h) + boff + n * 2048 + k * 1024); } while (0)
; #define PG8_MMA(ai, bj, At, Bt) do { __builtin_amdgcn_s_setprio(1); _Pragma("unroll") for (int m = 0; m < 4; ++m) _Pragma("unroll") for (int n = 0; n < 2; ++n) _Pragma("unroll") for (int k = 0; k < 2; ++k) \
;         acc[ai][bj][m][n] = __builtin_amdgcn_mfma_f32_16x16x32_bf16(Bt[n][k], At[m][k], acc[ai][bj][m][n], 0, 0, 0); __builtin_amdgcn_s_setprio(0); } while (0)
; #define PG8_WAIT_V(n) asm volatile("s_waitcnt vmcnt(" #n ")" ::: "memory")
; #define PG8_WAIT_L(n) asm volatile("s_waitcnt lgkmcnt(" #n ")" ::: "memory")
; #define PG8_BAR __builtin_amdgcn_s_barrier()
; #define PG8_SCHED __builtin_amdgcn_sched_barrier(0)
; template <class Epi, class Sched, bool ALIGN_EPI = false, bool SP2 = false>
; __device__ __forceinline__ void gemm_phase(PG8_LAS unsigned char* lds, const Gemm g, const Sched& S, const Epi& E) {
;     ...
;             PG8_WAIT_V(8); PG8_WAIT_L(0); PG8_BAR; PG8_MMA(1, 0, At, B0); PG8_MMA(1, 1, At, B1); PG8_BAR; PG8_SCHED;
;             PG8_LDB(B0, 1, 0); PG8_LDB(B1, 1, 1); PG8_SCHED; PG8_LDA(At, 1, 0); PG8_STAGE(PG8_SA(0, 1), a2 + hstep, voffA);
;             PG8_WAIT_V(8); PG8_WAIT_L(0); PG8_BAR; PG8_MMA(0, 0, At, B0); PG8_MMA(0, 1, At, B1); PG8_BAR; PG8_SCHED;
	s_setprio 1
	s_waitcnt lgkmcnt(0)
	v_mfma_f32_16x16x32_bf16 v[60:63], v[152:155], v[184:187], 0
	v_mfma_f32_16x16x32_bf16 v[56:59], v[160:163], v[184:187], 0
	v_mfma_f32_16x16x32_bf16 v[44:47], v[152:155], v[192:195], 0
	v_mfma_f32_16x16x32_bf16 v[40:43], v[160:163], v[192:195], 0
	v_mfma_f32_16x16x32_bf16 v[28:31], v[152:155], v[200:203], 0
	v_mfma_f32_16x16x32_bf16 v[24:27], v[160:163], v[200:203], 0
	v_mfma_f32_16x16x32_bf16 v[12:15], v[152:155], v[208:211], 0
	v_mfma_f32_16x16x32_bf16 v[8:11], v[160:163], v[208:211], 0
	v_mfma_f32_16x16x32_bf16 v[60:63], v[156:159], v[188:191], v[60:63]
	v_mfma_f32_16x16x32_bf16 v[56:59], v[164:167], v[188:191], v[56:59]
	v_mfma_f32_16x16x32_bf16 v[44:47], v[156:159], v[196:199], v[44:47]
	v_mfma_f32_16x16x32_bf16 v[40:43], v[164:167], v[196:199], v[40:43]
	v_mfma_f32_16x16x32_bf16 v[28:31], v[156:159], v[204:207], v[28:31]
	v_mfma_f32_16x16x32_bf16 v[24:27], v[164:167], v[204:207], v[24:27]
	v_mfma_f32_16x16x32_bf16 v[12:15], v[156:159], v[212:215], v[12:15]
	v_mfma_f32_16x16x32_bf16 v[8:11], v[164:167], v[212:215], v[8:11]
	v_mfma_f32_16x16x32_bf16 v[52:55], v[168:171], v[184:187], 0
	v_mfma_f32_16x16x32_bf16 v[48:51], v[176:179], v[184:187], 0
	v_mfma_f32_16x16x32_bf16 v[36:39], v[168:171], v[192:195], 0
	v_mfma_f32_16x16x32_bf16 v[32:35], v[176:179], v[192:195], 0
	v_mfma_f32_16x16x32_bf16 v[20:23], v[168:171], v[200:203], 0
	v_mfma_f32_16x16x32_bf16 v[16:19], v[176:179], v[200:203], 0
	v_mfma_f32_16x16x32_bf16 v[4:7], v[168:171], v[208:211], 0
	v_mfma_f32_16x16x32_bf16 v[0:3], v[176:179], v[208:211], 0
	v_mfma_f32_16x16x32_bf16 v[52:55], v[172:175], v[188:191], v[52:55]
	v_mfma_f32_16x16x32_bf16 v[48:51], v[180:183], v[188:191], v[48:51]
	v_mfma_f32_16x16x32_bf16 v[36:39], v[172:175], v[196:199], v[36:39]
	v_mfma_f32_16x16x32_bf16 v[32:35], v[180:183], v[196:199], v[32:35]
	v_mfma_f32_16x16x32_bf16 v[20:23], v[172:175], v[204:207], v[20:23]
	v_mfma_f32_16x16x32_bf16 v[16:19], v[180:183], v[204:207], v[16:19]
	v_mfma_f32_16x16x32_bf16 v[4:7], v[172:175], v[212:215], v[4:7]
	v_mfma_f32_16x16x32_bf16 v[0:3], v[180:183], v[212:215], v[0:3]
	s_setprio 0
	s_barrier
	s_add_i32 s67, 0, 0x18000
	s_add_i32 s68, 0, 0x1c000
	v_add_u32_e32 v164, s67, v147
	v_add_u32_e32 v180, s68, v147
	ds_read_b128 v[152:155], v164
	ds_read_b128 v[156:159], v164 offset:1024
	ds_read_b128 v[160:163], v164 offset:2048
	ds_read_b128 v[164:167], v164 offset:3072
	ds_read_b128 v[168:171], v180
	ds_read_b128 v[172:175], v180 offset:1024
	ds_read_b128 v[176:179], v180 offset:2048
	ds_read_b128 v[180:183], v180 offset:3072
	s_add_u32 s36, s36, 0x80000
	s_addc_u32 s37, s37, 0
	s_mov_b32 m0, s52
	v_lshl_add_u64 v[224:225], s[36:37], 0, v[134:135]
	ds_read_b128 v[184:187], v151 offset:32768
	ds_read_b128 v[188:191], v151 offset:33792
	ds_read_b128 v[192:195], v151 offset:34816
	ds_read_b128 v[196:199], v151 offset:35840
	ds_read_b128 v[200:203], v151 offset:36864
	ds_read_b128 v[204:207], v151 offset:37888
	ds_read_b128 v[208:211], v151 offset:38912
	ds_read_b128 v[212:215], v151 offset:39936
	global_load_lds_dwordx4 v[224:225], off
	v_lshl_add_u64 v[224:225], s[36:37], 0, v[130:131]
	s_mov_b32 m0, s53
	s_nop 0
	global_load_lds_dwordx4 v[224:225], off
	s_waitcnt vmcnt(8)
	s_waitcnt lgkmcnt(0)
	s_barrier
	s_setprio 1
	s_waitcnt lgkmcnt(0)
	v_mfma_f32_16x16x32_bf16 v[124:127], v[152:155], v[184:187], v[124:127]
	v_mfma_f32_16x16x32_bf16 v[120:123], v[160:163], v[184:187], v[120:123]
	v_mfma_f32_16x16x32_bf16 v[108:111], v[152:155], v[192:195], v[108:111]
	v_mfma_f32_16x16x32_bf16 v[104:107], v[160:163], v[192:195], v[104:107]
	v_mfma_f32_16x16x32_bf16 v[92:95], v[152:155], v[200:203], v[92:95]
	v_mfma_f32_16x16x32_bf16 v[88:91], v[160:163], v[200:203], v[88:91]
	v_mfma_f32_16x16x32_bf16 v[76:79], v[152:155], v[208:211], v[76:79]
	v_mfma_f32_16x16x32_bf16 v[72:75], v[160:163], v[208:211], v[72:75]
	v_mfma_f32_16x16x32_bf16 v[124:127], v[156:159], v[188:191], v[124:127]
	v_mfma_f32_16x16x32_bf16 v[120:123], v[164:167], v[188:191], v[120:123]
	v_mfma_f32_16x16x32_bf16 v[108:111], v[156:159], v[196:199], v[108:111]
	v_mfma_f32_16x16x32_bf16 v[104:107], v[164:167], v[196:199], v[104:107]
	v_mfma_f32_16x16x32_bf16 v[92:95], v[156:159], v[204:207], v[92:95]
	v_mfma_f32_16x16x32_bf16 v[88:91], v[164:167], v[204:207], v[88:91]
	v_mfma_f32_16x16x32_bf16 v[76:79], v[156:159], v[212:215], v[76:79]
	v_mfma_f32_16x16x32_bf16 v[72:75], v[164:167], v[212:215], v[72:75]
	v_mfma_f32_16x16x32_bf16 v[116:119], v[168:171], v[184:187], v[116:119]
	v_mfma_f32_16x16x32_bf16 v[112:115], v[176:179], v[184:187], v[112:115]
	v_mfma_f32_16x16x32_bf16 v[100:103], v[168:171], v[192:195], v[100:103]
	v_mfma_f32_16x16x32_bf16 v[96:99], v[176:179], v[192:195], v[96:99]
	v_mfma_f32_16x16x32_bf16 v[84:87], v[168:171], v[200:203], v[84:87]
	v_mfma_f32_16x16x32_bf16 v[80:83], v[176:179], v[200:203], v[80:83]
	v_mfma_f32_16x16x32_bf16 v[68:71], v[168:171], v[208:211], v[68:71]
	v_mfma_f32_16x16x32_bf16 v[64:67], v[176:179], v[208:211], v[64:67]
	v_mfma_f32_16x16x32_bf16 v[116:119], v[172:175], v[188:191], v[116:119]
	v_mfma_f32_16x16x32_bf16 v[112:115], v[180:183], v[188:191], v[112:115]
	v_mfma_f32_16x16x32_bf16 v[100:103], v[172:175], v[196:199], v[100:103]
	v_mfma_f32_16x16x32_bf16 v[96:99], v[180:183], v[196:199], v[96:99]
	v_mfma_f32_16x16x32_bf16 v[84:87], v[172:175], v[204:207], v[84:87]
	v_mfma_f32_16x16x32_bf16 v[80:83], v[180:183], v[204:207], v[80:83]
	v_mfma_f32_16x16x32_bf16 v[68:71], v[172:175], v[212:215], v[68:71]
	v_mfma_f32_16x16x32_bf16 v[64:67], v[180:183], v[212:215], v[64:67]
	s_setprio 0
	s_barrier
; #define PG8_STAGE(bufoff, gbase, voff) do { _Pragma("unroll") for (int _i = 0; _i < 2; ++_i) \
;         __builtin_amdgcn_global_load_lds((const unsigned*)((const char*)(gbase) + (voff)[_i]), (PG8_LAS unsigned*)(lds + (bufoff) + ldsw + _i * 8192), 16, 0, 0); } while (0)
; #define PG8_LDA(dst, b, h) do { _Pragma("unroll") for (int m = 0; m < 4; ++m) _Pragma("unroll") for (int k = 0; k < 2; ++k) dst[m][k] = *(const PG8_LAS bf16x8*)(lds + PG8_SA(b, h) + aoff + m * 2048 + k * 1024); } while (0)
; #define PG8_LDB(dst, b, h) do { _Pragma("unroll") for (int n = 0; n < 2; ++n) _Pragma("unroll") for (int k = 0; k < 2; ++k) dst[n][k] = *(const PG8_LAS bf16x8*)(lds + PG8_SB(b, h) + boff + n * 2048 + k * 1024); } while (0)
; #define PG8_MMA(ai, bj, At, Bt) do { __builtin_amdgcn_s_setprio(1); _Pragma("unroll") for (int m = 0; m < 4; ++m) _Pragma("unroll") for (int n = 0; n < 2; ++n) _Pragma("unroll") for (int k = 0; k < 2; ++k) \
;         acc[ai][bj][m][n] = __builtin_amdgcn_mfma_f32_16x16x32_bf16(Bt[n][k], At[m][k], acc[ai][bj][m][n], 0, 0, 0); __builtin_amdgcn_s_setprio(0); } while (0)
; #define PG8_WAIT_V(n) asm volatile("s_waitcnt vmcnt(" #n ")" ::: "memory")
; #define PG8_BAR __builtin_amdgcn_s_barrier()
; template <class Epi, class Sched, bool ALIGN_EPI = false, bool SP2 = false>
; __device__ __forceinline__ void gemm_phase(PG8_LAS unsigned char* lds, const Gemm g, const Sched& S, const Epi& E) {
;     ...
;         for (int t = 0; t < nt; t += 2) {
;             const bool last = (t == nt - 2);
;             const char* a1 = cA + (size_t)(t + 1) * kstep;
;             const char* a2 = last ? nA : cA + (size_t)(t + 2) * kstep; const char* b2 = last ? nB : cB + (size_t)(t + 2) * kstep;
;             const char* a3 = a2 + kstep; const char* b3 = b2 + kstep;
;             if (last && has_next) S.a_ready(nxt);
;             if constexpr (SP2) {
;             PG8_LDB(B0, 0, 0); PG8_LDB(B1, 0, 1); PG8_SCHED; PG8_LDA(At, 0, 0); PG8_STAGE(PG8_SA(1, 1), a1 + hstep, voffA);
;             PG8_WAIT_V(8); PG8_WAIT_L(0); PG8_BAR; PG8_MMA(0, 0, At, B0); PG8_MMA(0, 1, At, B1); PG8_BAR; PG8_SCHED;
;     ...
;             PG8_LDA(At, 1, 1); PG8_STAGE(PG8_SB(1, 0), b3, voffB); PG8_STAGE(PG8_SB(1, 1), b3 + hstep, voffB); PG8_STAGE(PG8_SA(1, 0), a3, voffA);
;             PG8_WAIT_V(8); PG8_WAIT_L(0); PG8_BAR; PG8_MMA(1, 0, At, B0); PG8_MMA(1, 1, At, B1); PG8_BAR; PG8_SCHED;
	s_add_i32 s36, s67, s47
	v_lshl_add_u64 v[144:145], v[144:145], 0, s[16:17]
	s_mov_b32 m0, s36
	ds_read_b128 v[184:187], v151 offset:49152
	ds_read_b128 v[188:191], v151 offset:50176
	ds_read_b128 v[192:195], v151 offset:51200
	ds_read_b128 v[196:199], v151 offset:52224
	ds_read_b128 v[200:203], v151 offset:53248
	ds_read_b128 v[204:207], v151 offset:54272
	ds_read_b128 v[208:211], v151 offset:55296
	ds_read_b128 v[212:215], v151 offset:56320
	global_load_lds_dwordx4 v[144:145], off
	s_add_i32 m0, s36, 0x2000
	s_add_u32 s34, s34, 0x80080
	v_lshl_add_u64 v[144:145], v[218:219], 0, s[16:17]
	s_addc_u32 s35, s35, 0
	s_add_i32 s36, s68, s47
	global_load_lds_dwordx4 v[144:145], off
	v_lshl_add_u64 v[144:145], s[34:35], 0, v[132:133]
	s_mov_b32 m0, s36
	s_nop 0
	global_load_lds_dwordx4 v[144:145], off
	v_lshl_add_u64 v[144:145], s[34:35], 0, v[128:129]
	s_add_i32 m0, s36, 0x2000
	s_nop 0
	global_load_lds_dwordx4 v[144:145], off
	v_lshl_add_u64 v[144:145], v[220:221], 0, s[16:17]
	s_mov_b32 m0, s55
	s_nop 0
	global_load_lds_dwordx4 v[144:145], off
	v_lshl_add_u64 v[144:145], v[222:223], 0, s[16:17]
	s_mov_b32 m0, s59
	s_nop 0
	global_load_lds_dwordx4 v[144:145], off
	s_waitcnt vmcnt(8)
	s_waitcnt lgkmcnt(0)
	s_barrier
	s_setprio 1
	s_waitcnt lgkmcnt(0)
	v_mfma_f32_16x16x32_bf16 v[60:63], v[152:155], v[184:187], v[60:63]
	v_mfma_f32_16x16x32_bf16 v[56:59], v[160:163], v[184:187], v[56:59]
	v_mfma_f32_16x16x32_bf16 v[44:47], v[152:155], v[192:195], v[44:47]
	v_mfma_f32_16x16x32_bf16 v[40:43], v[160:163], v[192:195], v[40:43]
	v_mfma_f32_16x16x32_bf16 v[28:31], v[152:155], v[200:203], v[28:31]
	v_mfma_f32_16x16x32_bf16 v[24:27], v[160:163], v[200:203], v[24:27]
	v_mfma_f32_16x16x32_bf16 v[12:15], v[152:155], v[208:211], v[12:15]
	v_mfma_f32_16x16x32_bf16 v[8:11], v[160:163], v[208:211], v[8:11]
	v_mfma_f32_16x16x32_bf16 v[60:63], v[156:159], v[188:191], v[60:63]
	v_mfma_f32_16x16x32_bf16 v[56:59], v[164:167], v[188:191], v[56:59]
	v_mfma_f32_16x16x32_bf16 v[44:47], v[156:159], v[196:199], v[44:47]
	v_mfma_f32_16x16x32_bf16 v[40:43], v[164:167], v[196:199], v[40:43]
	v_mfma_f32_16x16x32_bf16 v[28:31], v[156:159], v[204:207], v[28:31]
	v_mfma_f32_16x16x32_bf16 v[24:27], v[164:167], v[204:207], v[24:27]
	v_mfma_f32_16x16x32_bf16 v[12:15], v[156:159], v[212:215], v[12:15]
	v_mfma_f32_16x16x32_bf16 v[8:11], v[164:167], v[212:215], v[8:11]
	v_mfma_f32_16x16x32_bf16 v[52:55], v[168:171], v[184:187], v[52:55]
	v_mfma_f32_16x16x32_bf16 v[48:51], v[176:179], v[184:187], v[48:51]
	v_mfma_f32_16x16x32_bf16 v[36:39], v[168:171], v[192:195], v[36:39]
	v_mfma_f32_16x16x32_bf16 v[32:35], v[176:179], v[192:195], v[32:35]
	v_mfma_f32_16x16x32_bf16 v[20:23], v[168:171], v[200:203], v[20:23]
	v_mfma_f32_16x16x32_bf16 v[16:19], v[176:179], v[200:203], v[16:19]
	v_mfma_f32_16x16x32_bf16 v[4:7], v[168:171], v[208:211], v[4:7]
	v_mfma_f32_16x16x32_bf16 v[0:3], v[176:179], v[208:211], v[0:3]
	v_mfma_f32_16x16x32_bf16 v[52:55], v[172:175], v[188:191], v[52:55]
	v_mfma_f32_16x16x32_bf16 v[48:51], v[180:183], v[188:191], v[48:51]
	v_mfma_f32_16x16x32_bf16 v[36:39], v[172:175], v[196:199], v[36:39]
	v_mfma_f32_16x16x32_bf16 v[32:35], v[180:183], v[196:199], v[32:35]
	v_mfma_f32_16x16x32_bf16 v[20:23], v[172:175], v[204:207], v[20:23]
	v_mfma_f32_16x16x32_bf16 v[16:19], v[180:183], v[204:207], v[16:19]
	v_mfma_f32_16x16x32_bf16 v[4:7], v[172:175], v[212:215], v[4:7]
	v_mfma_f32_16x16x32_bf16 v[0:3], v[180:183], v[212:215], v[0:3]
	s_setprio 0
	s_barrier
	s_add_i32 s66, s66, 2
	s_add_u32 s30, s30, 0x100
	s_addc_u32 s31, s31, 0
	s_add_u32 s64, s64, 0x100
	s_addc_u32 s65, s65, 0
	s_cmp_gt_u32 s66, 29
.LBB0_775:
	ds_read_b128 v[152:155], v149
	ds_read_b128 v[156:159], v149 offset:1024
	ds_read_b128 v[160:163], v149 offset:2048
	ds_read_b128 v[164:167], v149 offset:3072
	ds_read_b128 v[168:171], v150
	ds_read_b128 v[172:175], v150 offset:1024
	ds_read_b128 v[176:179], v150 offset:2048
	ds_read_b128 v[180:183], v150 offset:3072
	s_add_u32 s34, s30, 0xfff80080
	s_addc_u32 s35, s31, -1
	s_cmp_eq_u32 s66, 28
	s_cselect_b32 s37, s23, s35
	s_cselect_b32 s36, s62, s34
	s_cselect_b32 s35, s21, s65
	s_cselect_b32 s34, s63, s64
	v_lshl_add_u64 v[144:145], s[30:31], 0, v[136:137]
	s_add_i32 m0, s50, 0xc000
	ds_read_b128 v[184:187], v151
	ds_read_b128 v[188:191], v151 offset:1024
	ds_read_b128 v[192:195], v151 offset:2048
	ds_read_b128 v[196:199], v151 offset:3072
	ds_read_b128 v[200:203], v151 offset:4096
	ds_read_b128 v[204:207], v151 offset:5120
	ds_read_b128 v[208:211], v151 offset:6144
	ds_read_b128 v[212:215], v151 offset:7168
	global_load_lds_dwordx4 v[144:145], off
	v_lshl_add_u64 v[144:145], s[30:31], 0, v[138:139]
	s_add_i32 m0, s50, 0xe000
	s_nop 0
	global_load_lds_dwordx4 v[144:145], off
	s_waitcnt vmcnt(8)
	s_waitcnt lgkmcnt(0)
	s_barrier
; #define PG8_STAGE(bufoff, gbase, voff) do { _Pragma("unroll") for (int _i = 0; _i < 2; ++_i) \
;         __builtin_amdgcn_global_load_lds((const unsigned*)((const char*)(gbase) + (voff)[_i]), (PG8_LAS unsigned*)(lds + (bufoff) + ldsw + _i * 8192), 16, 0, 0); } while (0)
; #define PG8_LDA(dst, b, h) do { _Pragma("unroll") for (int m = 0; m < 4; ++m) _Pragma("unroll") for (int k = 0; k < 2; ++k) dst[m][k] = *(const PG8_LAS bf16x8*)(lds + PG8_SA(b, h) + aoff + m * 2048 + k * 1024); } while (0)
; #define PG8_MMA(ai, bj, At, Bt) do { __builtin_amdgcn_s_setprio(1); _Pragma("unroll") for (int m = 0; m < 4; ++m) _Pragma("unroll") for (int n = 0; n < 2; ++n) _Pragma("unroll") for (int k = 0; k < 2; ++k) \
;         acc[ai][bj][m][n] = __builtin_amdgcn_mfma_f32_16x16x32_bf16(Bt[n][k], At[m][k], acc[ai][bj][m][n], 0, 0, 0); __builtin_amdgcn_s_setprio(0); } while (0)
; #define PG8_WAIT_V(n) asm volatile("s_waitcnt vmcnt(" #n ")" ::: "memory")
; #define PG8_WAIT_L(n) asm volatile("s_waitcnt lgkmcnt(" #n ")" ::: "memory")
; #define PG8_BAR __builtin_amdgcn_s_barrier()
; #define PG8_SCHED __builtin_amdgcn_sched_barrier(0)
; template <class Epi, class Sched, bool ALIGN_EPI = false, bool SP2 = false>
; __device__ __forceinline__ void gemm_phase(PG8_LAS unsigned char* lds, const Gemm g, const Sched& S, const Epi& E) {
;     ...
;             PG8_WAIT_V(8); PG8_WAIT_L(0); PG8_BAR; PG8_MMA(0, 0, At, B0); PG8_MMA(0, 1, At, B1); PG8_BAR; PG8_SCHED;
;             PG8_LDA(At, 0, 1); PG8_STAGE(PG8_SB(0, 0), b2, voffB); PG8_STAGE(PG8_SB(0, 1), b2 + hstep, voffB); PG8_STAGE(PG8_SA(0, 0), a2, voffA);
;             PG8_WAIT_V(8); PG8_WAIT_L(0); PG8_BAR; PG8_MMA(1, 0, At, B0); PG8_MMA(1, 1, At, B1); PG8_BAR; PG8_SCHED;
	s_setprio 1
	s_waitcnt lgkmcnt(0)
	v_mfma_f32_16x16x32_bf16 v[124:127], v[152:155], v[184:187], v[124:127]
	v_mfma_f32_16x16x32_bf16 v[120:123], v[160:163], v[184:187], v[120:123]
	v_mfma_f32_16x16x32_bf16 v[108:111], v[152:155], v[192:195], v[108:111]
	v_mfma_f32_16x16x32_bf16 v[104:107], v[160:163], v[192:195], v[104:107]
	v_mfma_f32_16x16x32_bf16 v[92:95], v[152:155], v[200:203], v[92:95]
	v_mfma_f32_16x16x32_bf16 v[88:91], v[160:163], v[200:203], v[88:91]
	v_mfma_f32_16x16x32_bf16 v[76:79], v[152:155], v[208:211], v[76:79]
	v_mfma_f32_16x16x32_bf16 v[72:75], v[160:163], v[208:211], v[72:75]
	v_mfma_f32_16x16x32_bf16 v[124:127], v[156:159], v[188:191], v[124:127]
	v_mfma_f32_16x16x32_bf16 v[120:123], v[164:167], v[188:191], v[120:123]
	v_mfma_f32_16x16x32_bf16 v[108:111], v[156:159], v[196:199], v[108:111]
	v_mfma_f32_16x16x32_bf16 v[104:107], v[164:167], v[196:199], v[104:107]
	v_mfma_f32_16x16x32_bf16 v[92:95], v[156:159], v[204:207], v[92:95]
	v_mfma_f32_16x16x32_bf16 v[88:91], v[164:167], v[204:207], v[88:91]
	v_mfma_f32_16x16x32_bf16 v[76:79], v[156:159], v[212:215], v[76:79]
	v_mfma_f32_16x16x32_bf16 v[72:75], v[164:167], v[212:215], v[72:75]
	v_mfma_f32_16x16x32_bf16 v[116:119], v[168:171], v[184:187], v[116:119]
	v_mfma_f32_16x16x32_bf16 v[112:115], v[176:179], v[184:187], v[112:115]
	v_mfma_f32_16x16x32_bf16 v[100:103], v[168:171], v[192:195], v[100:103]
	v_mfma_f32_16x16x32_bf16 v[96:99], v[176:179], v[192:195], v[96:99]
	v_mfma_f32_16x16x32_bf16 v[84:87], v[168:171], v[200:203], v[84:87]
	v_mfma_f32_16x16x32_bf16 v[80:83], v[176:179], v[200:203], v[80:83]
	v_mfma_f32_16x16x32_bf16 v[68:71], v[168:171], v[208:211], v[68:71]
	v_mfma_f32_16x16x32_bf16 v[64:67], v[176:179], v[208:211], v[64:67]
	v_mfma_f32_16x16x32_bf16 v[116:119], v[172:175], v[188:191], v[116:119]
	v_mfma_f32_16x16x32_bf16 v[112:115], v[180:183], v[188:191], v[112:115]
	v_mfma_f32_16x16x32_bf16 v[100:103], v[172:175], v[196:199], v[100:103]
	v_mfma_f32_16x16x32_bf16 v[96:99], v[180:183], v[196:199], v[96:99]
	v_mfma_f32_16x16x32_bf16 v[84:87], v[172:175], v[204:207], v[84:87]
	v_mfma_f32_16x16x32_bf16 v[80:83], v[180:183], v[204:207], v[80:83]
	v_mfma_f32_16x16x32_bf16 v[68:71], v[172:175], v[212:215], v[68:71]
	v_mfma_f32_16x16x32_bf16 v[64:67], v[180:183], v[212:215], v[64:67]
	s_setprio 0
	s_barrier
	s_add_i32 s67, s60, s47
	v_lshl_add_u64 v[144:145], s[34:35], 0, v[132:133]
	s_mov_b32 m0, s67
	ds_read_b128 v[184:187], v151 offset:16384
	ds_read_b128 v[188:191], v151 offset:17408
	ds_read_b128 v[192:195], v151 offset:18432
	ds_read_b128 v[196:199], v151 offset:19456
	ds_read_b128 v[200:203], v151 offset:20480
	ds_read_b128 v[204:207], v151 offset:21504
	ds_read_b128 v[208:211], v151 offset:22528
	ds_read_b128 v[212:215], v151 offset:23552
	global_load_lds_dwordx4 v[144:145], off
	s_add_i32 m0, s67, 0x2000
	s_add_u32 s68, s34, 0x80000
	v_lshl_add_u64 v[218:219], s[34:35], 0, v[128:129]
	s_addc_u32 s69, s35, 0
	s_add_i32 s67, s61, s47
	global_load_lds_dwordx4 v[218:219], off
	v_lshl_add_u64 v[220:221], s[68:69], 0, v[132:133]
	s_mov_b32 m0, s67
	v_lshl_add_u64 v[222:223], s[36:37], 0, v[130:131]
	global_load_lds_dwordx4 v[220:221], off
	v_lshl_add_u64 v[220:221], s[68:69], 0, v[128:129]
	s_add_i32 m0, s67, 0x2000
	s_nop 0
	global_load_lds_dwordx4 v[220:221], off
	v_lshl_add_u64 v[220:221], s[36:37], 0, v[134:135]
	s_mov_b32 m0, s50
	s_nop 0
	global_load_lds_dwordx4 v[220:221], off
	s_mov_b32 m0, s51
	s_nop 0
	global_load_lds_dwordx4 v[222:223], off
	s_waitcnt vmcnt(8)
	s_waitcnt lgkmcnt(0)
	s_barrier
	s_setprio 1
	s_waitcnt lgkmcnt(0)
	v_mfma_f32_16x16x32_bf16 v[60:63], v[152:155], v[184:187], v[60:63]
	v_mfma_f32_16x16x32_bf16 v[56:59], v[160:163], v[184:187], v[56:59]
	v_mfma_f32_16x16x32_bf16 v[44:47], v[152:155], v[192:195], v[44:47]
	v_mfma_f32_16x16x32_bf16 v[40:43], v[160:163], v[192:195], v[40:43]
	v_mfma_f32_16x16x32_bf16 v[28:31], v[152:155], v[200:203], v[28:31]
	v_mfma_f32_16x16x32_bf16 v[24:27], v[160:163], v[200:203], v[24:27]
	v_mfma_f32_16x16x32_bf16 v[12:15], v[152:155], v[208:211], v[12:15]
	v_mfma_f32_16x16x32_bf16 v[8:11], v[160:163], v[208:211], v[8:11]
	v_mfma_f32_16x16x32_bf16 v[60:63], v[156:159], v[188:191], v[60:63]
	v_mfma_f32_16x16x32_bf16 v[56:59], v[164:167], v[188:191], v[56:59]
	v_mfma_f32_16x16x32_bf16 v[44:47], v[156:159], v[196:199], v[44:47]
	v_mfma_f32_16x16x32_bf16 v[40:43], v[164:167], v[196:199], v[40:43]
	v_mfma_f32_16x16x32_bf16 v[28:31], v[156:159], v[204:207], v[28:31]
	v_mfma_f32_16x16x32_bf16 v[24:27], v[164:167], v[204:207], v[24:27]
	v_mfma_f32_16x16x32_bf16 v[12:15], v[156:159], v[212:215], v[12:15]
	v_mfma_f32_16x16x32_bf16 v[8:11], v[164:167], v[212:215], v[8:11]
	v_mfma_f32_16x16x32_bf16 v[52:55], v[168:171], v[184:187], v[52:55]
	v_mfma_f32_16x16x32_bf16 v[48:51], v[176:179], v[184:187], v[48:51]
	v_mfma_f32_16x16x32_bf16 v[36:39], v[168:171], v[192:195], v[36:39]
	v_mfma_f32_16x16x32_bf16 v[32:35], v[176:179], v[192:195], v[32:35]
	v_mfma_f32_16x16x32_bf16 v[20:23], v[168:171], v[200:203], v[20:23]
	v_mfma_f32_16x16x32_bf16 v[16:19], v[176:179], v[200:203], v[16:19]
	v_mfma_f32_16x16x32_bf16 v[4:7], v[168:171], v[208:211], v[4:7]
	v_mfma_f32_16x16x32_bf16 v[0:3], v[176:179], v[208:211], v[0:3]
	v_mfma_f32_16x16x32_bf16 v[52:55], v[172:175], v[188:191], v[52:55]
	v_mfma_f32_16x16x32_bf16 v[48:51], v[180:183], v[188:191], v[48:51]
	v_mfma_f32_16x16x32_bf16 v[36:39], v[172:175], v[196:199], v[36:39]
	v_mfma_f32_16x16x32_bf16 v[32:35], v[180:183], v[196:199], v[32:35]
	v_mfma_f32_16x16x32_bf16 v[20:23], v[172:175], v[204:207], v[20:23]
	v_mfma_f32_16x16x32_bf16 v[16:19], v[180:183], v[204:207], v[16:19]
	v_mfma_f32_16x16x32_bf16 v[4:7], v[172:175], v[212:215], v[4:7]
	v_mfma_f32_16x16x32_bf16 v[0:3], v[180:183], v[212:215], v[0:3]
	s_setprio 0
	s_barrier
; #define PG8_STAGE(bufoff, gbase, voff) do { _Pragma("unroll") for (int _i = 0; _i < 2; ++_i) \
;         __builtin_amdgcn_global_load_lds((const unsigned*)((const char*)(gbase) + (voff)[_i]), (PG8_LAS unsigned*)(lds + (bufoff) + ldsw + _i * 8192), 16, 0, 0); } while (0)
; #define PG8_LDA(dst, b, h) do { _Pragma("unroll") for (int m = 0; m < 4; ++m) _Pragma("unroll") for (int k = 0; k < 2; ++k) dst[m][k] = *(const PG8_LAS bf16x8*)(lds + PG8_SA(b, h) + aoff + m * 2048 + k * 1024); } while (0)
; #define PG8_LDB(dst, b, h) do { _Pragma("unroll") for (int n = 0; n < 2; ++n) _Pragma("unroll") for (int k = 0; k < 2; ++k) dst[n][k] = *(const PG8_LAS bf16x8*)(lds + PG8_SB(b, h) + boff + n * 2048 + k * 1024); } while (0)
; #define PG8_MMA(ai, bj, At, Bt) do { __builtin_amdgcn_s_setprio(1); _Pragma("unroll") for (int m = 0; m < 4; ++m) _Pragma("unroll") for (int n = 0; n < 2; ++n) _Pragma("unroll") for (int k = 0; k < 2; ++k) \
;         acc[ai][bj][m][n] = __builtin_amdgcn_mfma_f32_16x16x32_bf16(Bt[n][k], At[m][k], acc[ai][bj][m][n], 0, 0, 0); __builtin_amdgcn_s_setprio(0); } while (0)
; #define PG8_WAIT_V(n) asm volatile("s_waitcnt vmcnt(" #n ")" ::: "memory")
; #define PG8_WAIT_L(n) asm volatile("s_waitcnt lgkmcnt(" #n ")" ::: "memory")
; #define PG8_BAR __builtin_amdgcn_s_barrier()
; #define PG8_SCHED __builtin_amdgcn_sched_barrier(0)
; template <class Epi, class Sched, bool ALIGN_EPI = false, bool SP2 = false>
; __device__ __forceinline__ void gemm_phase(PG8_LAS unsigned char* lds, const Gemm g, const Sched& S, const Epi& E) {
;     ...
;             PG8_LDB(B0, 1, 0); PG8_LDB(B1, 1, 1); PG8_SCHED; PG8_LDA(At, 1, 0); PG8_STAGE(PG8_SA(0, 1), a2 + hstep, voffA);
;             PG8_WAIT_V(8); PG8_WAIT_L(0); PG8_BAR; PG8_MMA(0, 0, At, B0); PG8_MMA(0, 1, At, B1); PG8_BAR; PG8_SCHED;
	s_add_i32 s67, 0, 0x18000
	s_add_i32 s68, 0, 0x1c000
	v_add_u32_e32 v164, s67, v147
	v_add_u32_e32 v180, s68, v147
	ds_read_b128 v[152:155], v164
	ds_read_b128 v[156:159], v164 offset:1024
	ds_read_b128 v[160:163], v164 offset:2048
	ds_read_b128 v[164:167], v164 offset:3072
	ds_read_b128 v[168:171], v180
	ds_read_b128 v[172:175], v180 offset:1024
	ds_read_b128 v[176:179], v180 offset:2048
	ds_read_b128 v[180:183], v180 offset:3072
	s_add_u32 s36, s36, 0x80000
	s_addc_u32 s37, s37, 0
	s_mov_b32 m0, s52
	v_lshl_add_u64 v[224:225], s[36:37], 0, v[134:135]
	ds_read_b128 v[184:187], v151 offset:32768
	ds_read_b128 v[188:191], v151 offset:33792
	ds_read_b128 v[192:195], v151 offset:34816
	ds_read_b128 v[196:199], v151 offset:35840
	ds_read_b128 v[200:203], v151 offset:36864
	ds_read_b128 v[204:207], v151 offset:37888
	ds_read_b128 v[208:211], v151 offset:38912
	ds_read_b128 v[212:215], v151 offset:39936
	global_load_lds_dwordx4 v[224:225], off
	v_lshl_add_u64 v[224:225], s[36:37], 0, v[130:131]
	s_mov_b32 m0, s53
	s_nop 0
	global_load_lds_dwordx4 v[224:225], off
	s_waitcnt vmcnt(8)
	s_waitcnt lgkmcnt(0)
	s_barrier
	s_setprio 1
	s_waitcnt lgkmcnt(0)
	v_mfma_f32_16x16x32_bf16 v[124:127], v[152:155], v[184:187], v[124:127]
	v_mfma_f32_16x16x32_bf16 v[120:123], v[160:163], v[184:187], v[120:123]
	v_mfma_f32_16x16x32_bf16 v[108:111], v[152:155], v[192:195], v[108:111]
	v_mfma_f32_16x16x32_bf16 v[104:107], v[160:163], v[192:195], v[104:107]
	v_mfma_f32_16x16x32_bf16 v[92:95], v[152:155], v[200:203], v[92:95]
	v_mfma_f32_16x16x32_bf16 v[88:91], v[160:163], v[200:203], v[88:91]
	v_mfma_f32_16x16x32_bf16 v[76:79], v[152:155], v[208:211], v[76:79]
	v_mfma_f32_16x16x32_bf16 v[72:75], v[160:163], v[208:211], v[72:75]
	v_mfma_f32_16x16x32_bf16 v[124:127], v[156:159], v[188:191], v[124:127]
	v_mfma_f32_16x16x32_bf16 v[120:123], v[164:167], v[188:191], v[120:123]
	v_mfma_f32_16x16x32_bf16 v[108:111], v[156:159], v[196:199], v[108:111]
	v_mfma_f32_16x16x32_bf16 v[104:107], v[164:167], v[196:199], v[104:107]
	v_mfma_f32_16x16x32_bf16 v[92:95], v[156:159], v[204:207], v[92:95]
	v_mfma_f32_16x16x32_bf16 v[88:91], v[164:167], v[204:207], v[88:91]
	v_mfma_f32_16x16x32_bf16 v[76:79], v[156:159], v[212:215], v[76:79]
	v_mfma_f32_16x16x32_bf16 v[72:75], v[164:167], v[212:215], v[72:75]
	v_mfma_f32_16x16x32_bf16 v[116:119], v[168:171], v[184:187], v[116:119]
	v_mfma_f32_16x16x32_bf16 v[112:115], v[176:179], v[184:187], v[112:115]
	v_mfma_f32_16x16x32_bf16 v[100:103], v[168:171], v[192:195], v[100:103]
	v_mfma_f32_16x16x32_bf16 v[96:99], v[176:179], v[192:195], v[96:99]
	v_mfma_f32_16x16x32_bf16 v[84:87], v[168:171], v[200:203], v[84:87]
	v_mfma_f32_16x16x32_bf16 v[80:83], v[176:179], v[200:203], v[80:83]
	v_mfma_f32_16x16x32_bf16 v[68:71], v[168:171], v[208:211], v[68:71]
	v_mfma_f32_16x16x32_bf16 v[64:67], v[176:179], v[208:211], v[64:67]
	v_mfma_f32_16x16x32_bf16 v[116:119], v[172:175], v[188:191], v[116:119]
	v_mfma_f32_16x16x32_bf16 v[112:115], v[180:183], v[188:191], v[112:115]
	v_mfma_f32_16x16x32_bf16 v[100:103], v[172:175], v[196:199], v[100:103]
	v_mfma_f32_16x16x32_bf16 v[96:99], v[180:183], v[196:199], v[96:99]
	v_mfma_f32_16x16x32_bf16 v[84:87], v[172:175], v[204:207], v[84:87]
	v_mfma_f32_16x16x32_bf16 v[80:83], v[180:183], v[204:207], v[80:83]
	v_mfma_f32_16x16x32_bf16 v[68:71], v[172:175], v[212:215], v[68:71]
	v_mfma_f32_16x16x32_bf16 v[64:67], v[180:183], v[212:215], v[64:67]
	s_setprio 0
	s_barrier
; #define PG8_STAGE(bufoff, gbase, voff) do { _Pragma("unroll") for (int _i = 0; _i < 2; ++_i) \
;         __builtin_amdgcn_global_load_lds((const unsigned*)((const char*)(gbase) + (voff)[_i]), (PG8_LAS unsigned*)(lds + (bufoff) + ldsw + _i * 8192), 16, 0, 0); } while (0)
; #define PG8_LDA(dst, b, h) do { _Pragma("unroll") for (int m = 0; m < 4; ++m) _Pragma("unroll") for (int k = 0; k < 2; ++k) dst[m][k] = *(const PG8_LAS bf16x8*)(lds + PG8_SA(b, h) + aoff + m * 2048 + k * 1024); } while (0)
; #define PG8_MMA(ai, bj, At, Bt) do { __builtin_amdgcn_s_setprio(1); _Pragma("unroll") for (int m = 0; m < 4; ++m) _Pragma("unroll") for (int n = 0; n < 2; ++n) _Pragma("unroll") for (int k = 0; k < 2; ++k) \
;         acc[ai][bj][m][n] = __builtin_amdgcn_mfma_f32_16x16x32_bf16(Bt[n][k], At[m][k], acc[ai][bj][m][n], 0, 0, 0); __builtin_amdgcn_s_setprio(0); } while (0)
; #define PG8_WAIT_V(n) asm volatile("s_waitcnt vmcnt(" #n ")" ::: "memory")
; #define PG8_WAIT_L(n) asm volatile("s_waitcnt lgkmcnt(" #n ")" ::: "memory")
; #define PG8_BAR __builtin_amdgcn_s_barrier()
; #define PG8_SCHED __builtin_amdgcn_sched_barrier(0)
; template <class Epi, class Sched, bool ALIGN_EPI = false, bool SP2 = false>
; __device__ __forceinline__ void gemm_phase(PG8_LAS unsigned char* lds, const Gemm g, const Sched& S, const Epi& E) {
;     ...
;             PG8_LDA(At, 1, 1); PG8_STAGE(PG8_SB(1, 0), b3, voffB); PG8_STAGE(PG8_SB(1, 1), b3 + hstep, voffB); PG8_STAGE(PG8_SA(1, 0), a3, voffA);
;             PG8_WAIT_V(8); PG8_WAIT_L(0); PG8_BAR; PG8_MMA(1, 0, At, B0); PG8_MMA(1, 1, At, B1); PG8_BAR; PG8_SCHED;
;     ...
;         }
;         if constexpr (ALIGN_EPI) { if (wr == 0) PG8_BAR; }
	s_add_i32 s36, s67, s47
	v_lshl_add_u64 v[144:145], v[144:145], 0, s[16:17]
	s_mov_b32 m0, s36
	ds_read_b128 v[184:187], v151 offset:49152
	ds_read_b128 v[188:191], v151 offset:50176
	ds_read_b128 v[192:195], v151 offset:51200
	ds_read_b128 v[196:199], v151 offset:52224
	ds_read_b128 v[200:203], v151 offset:53248
	ds_read_b128 v[204:207], v151 offset:54272
	ds_read_b128 v[208:211], v151 offset:55296
	ds_read_b128 v[212:215], v151 offset:56320
	global_load_lds_dwordx4 v[144:145], off
	s_add_i32 m0, s36, 0x2000
	s_add_u32 s34, s34, 0x80080
	v_lshl_add_u64 v[144:145], v[218:219], 0, s[16:17]
	s_addc_u32 s35, s35, 0
	s_add_i32 s36, s68, s47
	global_load_lds_dwordx4 v[144:145], off
	v_lshl_add_u64 v[144:145], s[34:35], 0, v[132:133]
	s_mov_b32 m0, s36
	s_nop 0
	global_load_lds_dwordx4 v[144:145], off
	v_lshl_add_u64 v[144:145], s[34:35], 0, v[128:129]
	s_add_i32 m0, s36, 0x2000
	s_nop 0
	global_load_lds_dwordx4 v[144:145], off
	v_lshl_add_u64 v[144:145], v[220:221], 0, s[16:17]
	s_mov_b32 m0, s55
	s_nop 0
	global_load_lds_dwordx4 v[144:145], off
	v_lshl_add_u64 v[144:145], v[222:223], 0, s[16:17]
	s_mov_b32 m0, s59
	s_nop 0
	global_load_lds_dwordx4 v[144:145], off
	s_waitcnt vmcnt(8)
	s_waitcnt lgkmcnt(0)
	s_barrier
	s_setprio 1
	s_waitcnt lgkmcnt(0)
	v_mfma_f32_16x16x32_bf16 v[60:63], v[152:155], v[184:187], v[60:63]
	v_mfma_f32_16x16x32_bf16 v[56:59], v[160:163], v[184:187], v[56:59]
	v_mfma_f32_16x16x32_bf16 v[44:47], v[152:155], v[192:195], v[44:47]
	v_mfma_f32_16x16x32_bf16 v[40:43], v[160:163], v[192:195], v[40:43]
	v_mfma_f32_16x16x32_bf16 v[28:31], v[152:155], v[200:203], v[28:31]
	v_mfma_f32_16x16x32_bf16 v[24:27], v[160:163], v[200:203], v[24:27]
	v_mfma_f32_16x16x32_bf16 v[12:15], v[152:155], v[208:211], v[12:15]
	v_mfma_f32_16x16x32_bf16 v[8:11], v[160:163], v[208:211], v[8:11]
	v_mfma_f32_16x16x32_bf16 v[60:63], v[156:159], v[188:191], v[60:63]
	v_mfma_f32_16x16x32_bf16 v[56:59], v[164:167], v[188:191], v[56:59]
	v_mfma_f32_16x16x32_bf16 v[44:47], v[156:159], v[196:199], v[44:47]
	v_mfma_f32_16x16x32_bf16 v[40:43], v[164:167], v[196:199], v[40:43]
	v_mfma_f32_16x16x32_bf16 v[28:31], v[156:159], v[204:207], v[28:31]
	v_mfma_f32_16x16x32_bf16 v[24:27], v[164:167], v[204:207], v[24:27]
	v_mfma_f32_16x16x32_bf16 v[12:15], v[156:159], v[212:215], v[12:15]
	v_mfma_f32_16x16x32_bf16 v[8:11], v[164:167], v[212:215], v[8:11]
	v_mfma_f32_16x16x32_bf16 v[52:55], v[168:171], v[184:187], v[52:55]
	v_mfma_f32_16x16x32_bf16 v[48:51], v[176:179], v[184:187], v[48:51]
	v_mfma_f32_16x16x32_bf16 v[36:39], v[168:171], v[192:195], v[36:39]
	v_mfma_f32_16x16x32_bf16 v[32:35], v[176:179], v[192:195], v[32:35]
	v_mfma_f32_16x16x32_bf16 v[20:23], v[168:171], v[200:203], v[20:23]
	v_mfma_f32_16x16x32_bf16 v[16:19], v[176:179], v[200:203], v[16:19]
	v_mfma_f32_16x16x32_bf16 v[4:7], v[168:171], v[208:211], v[4:7]
	v_mfma_f32_16x16x32_bf16 v[0:3], v[176:179], v[208:211], v[0:3]
	v_mfma_f32_16x16x32_bf16 v[52:55], v[172:175], v[188:191], v[52:55]
	v_mfma_f32_16x16x32_bf16 v[48:51], v[180:183], v[188:191], v[48:51]
	v_mfma_f32_16x16x32_bf16 v[36:39], v[172:175], v[196:199], v[36:39]
	v_mfma_f32_16x16x32_bf16 v[32:35], v[180:183], v[196:199], v[32:35]
	v_mfma_f32_16x16x32_bf16 v[20:23], v[172:175], v[204:207], v[20:23]
	v_mfma_f32_16x16x32_bf16 v[16:19], v[180:183], v[204:207], v[16:19]
	v_mfma_f32_16x16x32_bf16 v[4:7], v[172:175], v[212:215], v[4:7]
	v_mfma_f32_16x16x32_bf16 v[0:3], v[180:183], v[212:215], v[0:3]
	s_setprio 0
	s_barrier
	s_add_i32 s66, s66, 2
	s_add_u32 s30, s30, 0x100
	s_addc_u32 s31, s31, 0
	s_add_u32 s64, s64, 0x100
	s_addc_u32 s65, s65, 0
	s_cmp_gt_u32 s66, 29
	s_cbranch_scc0 .LBB0_775
	s_and_b64 vcc, exec, s[18:19]
	s_cbranch_vccz .LBB0_778
	s_barrier

; #define PG8_STAGE(bufoff, gbase, voff) do { _Pragma("unroll") for (int _i = 0; _i < 2; ++_i) \
;         __builtin_amdgcn_global_load_lds((const unsigned*)((const char*)(gbase) + (voff)[_i]), (PG8_LAS unsigned*)(lds + (bufoff) + ldsw + _i * 8192), 16, 0, 0); } while (0)
; #define PG8_LDA(dst, b, h) do { _Pragma("unroll") for (int m = 0; m < 4; ++m) _Pragma("unroll") for (int k = 0; k < 2; ++k) dst[m][k] = *(const PG8_LAS bf16x8*)(lds + PG8_SA(b, h) + aoff + m * 2048 + k * 1024); } while (0)
; #define PG8_LDB(dst, b, h) do { _Pragma("unroll") for (int n = 0; n < 2; ++n) _Pragma("unroll") for (int k = 0; k < 2; ++k) dst[n][k] = *(const PG8_LAS bf16x8*)(lds + PG8_SB(b, h) + boff + n * 2048 + k * 1024); } while (0)
; #define PG8_WAIT_V(n) asm volatile("s_waitcnt vmcnt(" #n ")" ::: "memory")
; #define PG8_WAIT_L(n) asm volatile("s_waitcnt lgkmcnt(" #n ")" ::: "memory")
; #define PG8_BAR __builtin_amdgcn_s_barrier()
; #define PG8_SCHED __builtin_amdgcn_sched_barrier(0)
; template <class Epi, class Sched, bool ALIGN_EPI = false, bool SP2 = false>
; __device__ __forceinline__ void gemm_phase(PG8_LAS unsigned char* lds, const Gemm g, const Sched& S, const Epi& E) {
;     ...
;         const bool has_next = S.next(ui + 1, nxt);
;         const char* nA = has_next ? (const char*)g.A + (size_t)nxt.pm * tstep : cA; const char* nB = has_next ? (const char*)g.Bt + (size_t)nxt.pn * tstep : cB;
;         for (int t = 0; t < nt; t += 2) {
;             const bool last = (t == nt - 2);
;             const char* a1 = cA + (size_t)(t + 1) * kstep;
;             const char* a2 = last ? nA : cA + (size_t)(t + 2) * kstep; const char* b2 = last ? nB : cB + (size_t)(t + 2) * kstep;
;             const char* a3 = a2 + kstep; const char* b3 = b2 + kstep;
;             if (last && has_next) S.a_ready(nxt);
;             if constexpr (SP2) {
;             PG8_LDB(B0, 0, 0); PG8_LDB(B1, 0, 1); PG8_SCHED; PG8_LDA(At, 0, 0); PG8_STAGE(PG8_SA(1, 1), a1 + hstep, voffA);
;             PG8_WAIT_V(8); PG8_WAIT_L(0); PG8_BAR; PG8_MMA(0, 0, At, B0); PG8_MMA(0, 1, At, B1); PG8_BAR; PG8_SCHED;
;             PG8_LDA(At, 0, 1); PG8_STAGE(PG8_SB(0, 0), b2, voffB); PG8_STAGE(PG8_SB(0, 1), b2 + hstep, voffB); PG8_STAGE(PG8_SA(0, 0), a2, voffA);
;             PG8_WAIT_V(8); PG8_WAIT_L(0); PG8_BAR; PG8_MMA(1, 0, At, B0); PG8_MMA(1, 1, At, B1); PG8_BAR; PG8_SCHED;
.LBB0_846:
	s_ashr_i32 s23, s22, 31
	s_lshl_b64 s[24:25], s[22:23], 22
	s_add_u32 s24, s40, s24
	s_addc_u32 s25, s41, s25
	s_and_b64 s[26:27], s[0:1], exec
	s_cselect_b32 s23, s25, s31
	s_cselect_b32 s57, s24, s30
	s_ashr_i32 s21, s20, 31
	s_lshl_b64 s[26:27], s[20:21], 22
	s_add_u32 s26, s44, s26
	s_addc_u32 s27, s45, s27
	s_and_b64 s[36:37], s[0:1], exec
	s_cselect_b32 s21, s27, s35
	s_cselect_b32 s58, s26, s34
	s_add_u32 s59, s34, 0x100
	s_addc_u32 s60, s35, 0
	s_mov_b32 s61, -2
	ds_read_b128 v[72:75], v165
	ds_read_b128 v[84:87], v165 offset:1024
	ds_read_b128 v[92:95], v165 offset:2048
	ds_read_b128 v[108:111], v165 offset:3072
	ds_read_b128 v[156:159], v166
	ds_read_b128 v[168:171], v166 offset:1024
	ds_read_b128 v[172:175], v166 offset:2048
	ds_read_b128 v[176:179], v166 offset:3072
	s_add_u32 s34, s30, 0x100
	s_addc_u32 s35, s31, 0
	s_cmpk_eq_i32 s61, 0x7c
	s_cselect_b32 s39, s23, s35
	s_cselect_b32 s38, s57, s34
	s_cselect_b32 s37, s21, s60
	s_cselect_b32 s36, s58, s59
	v_lshl_add_u64 v[160:161], s[30:31], 0, v[148:149]
	s_add_i32 m0, s42, 0xc000
	ds_read_b128 v[180:183], v167
	ds_read_b128 v[184:187], v167 offset:1024
	ds_read_b128 v[188:191], v167 offset:2048
	ds_read_b128 v[192:195], v167 offset:3072
	ds_read_b128 v[196:199], v167 offset:4096
	ds_read_b128 v[200:203], v167 offset:5120
	ds_read_b128 v[204:207], v167 offset:6144
	ds_read_b128 v[208:211], v167 offset:7168
	global_load_lds_dwordx4 v[160:161], off
	v_lshl_add_u64 v[160:161], s[30:31], 0, v[150:151]
	s_add_i32 m0, s42, 0xe000
	s_nop 0
	global_load_lds_dwordx4 v[160:161], off
	s_waitcnt vmcnt(8)
	s_waitcnt lgkmcnt(0)
	s_barrier
	s_setprio 1
	s_waitcnt lgkmcnt(0)
	v_mfma_f32_16x16x32_bf16 v[140:143], v[72:75], v[180:183], 0
	v_mfma_f32_16x16x32_bf16 v[136:139], v[92:95], v[180:183], 0
	v_mfma_f32_16x16x32_bf16 v[132:135], v[72:75], v[188:191], 0
	v_mfma_f32_16x16x32_bf16 v[128:131], v[92:95], v[188:191], 0
	v_mfma_f32_16x16x32_bf16 v[120:123], v[72:75], v[196:199], 0
	v_mfma_f32_16x16x32_bf16 v[112:115], v[92:95], v[196:199], 0
	v_mfma_f32_16x16x32_bf16 v[100:103], v[72:75], v[204:207], 0
	v_mfma_f32_16x16x32_bf16 v[88:91], v[92:95], v[204:207], 0
	v_mfma_f32_16x16x32_bf16 v[140:143], v[84:87], v[184:187], v[140:143]
	v_mfma_f32_16x16x32_bf16 v[136:139], v[108:111], v[184:187], v[136:139]
	v_mfma_f32_16x16x32_bf16 v[132:135], v[84:87], v[192:195], v[132:135]
	v_mfma_f32_16x16x32_bf16 v[128:131], v[108:111], v[192:195], v[128:131]
	v_mfma_f32_16x16x32_bf16 v[120:123], v[84:87], v[200:203], v[120:123]
	v_mfma_f32_16x16x32_bf16 v[112:115], v[108:111], v[200:203], v[112:115]
	v_mfma_f32_16x16x32_bf16 v[100:103], v[84:87], v[208:211], v[100:103]
	v_mfma_f32_16x16x32_bf16 v[88:91], v[108:111], v[208:211], v[88:91]
	v_mfma_f32_16x16x32_bf16 v[124:127], v[156:159], v[180:183], 0
	v_mfma_f32_16x16x32_bf16 v[116:119], v[172:175], v[180:183], 0
	v_mfma_f32_16x16x32_bf16 v[104:107], v[156:159], v[188:191], 0
	v_mfma_f32_16x16x32_bf16 v[96:99], v[172:175], v[188:191], 0
	v_mfma_f32_16x16x32_bf16 v[80:83], v[156:159], v[196:199], 0
	v_mfma_f32_16x16x32_bf16 v[76:79], v[172:175], v[196:199], 0
	v_mfma_f32_16x16x32_bf16 v[68:71], v[156:159], v[204:207], 0
	v_mfma_f32_16x16x32_bf16 v[64:67], v[172:175], v[204:207], 0
	v_mfma_f32_16x16x32_bf16 v[124:127], v[168:171], v[184:187], v[124:127]
	v_mfma_f32_16x16x32_bf16 v[116:119], v[176:179], v[184:187], v[116:119]
	v_mfma_f32_16x16x32_bf16 v[104:107], v[168:171], v[192:195], v[104:107]
	v_mfma_f32_16x16x32_bf16 v[96:99], v[176:179], v[192:195], v[96:99]
	v_mfma_f32_16x16x32_bf16 v[80:83], v[168:171], v[200:203], v[80:83]
	v_mfma_f32_16x16x32_bf16 v[76:79], v[176:179], v[200:203], v[76:79]
	v_mfma_f32_16x16x32_bf16 v[68:71], v[168:171], v[208:211], v[68:71]
	v_mfma_f32_16x16x32_bf16 v[64:67], v[176:179], v[208:211], v[64:67]
	s_setprio 0
	s_barrier
	s_add_i32 s30, s55, s47
	v_lshl_add_u64 v[160:161], s[36:37], 0, v[146:147]
	s_mov_b32 m0, s30
	ds_read_b128 v[180:183], v167 offset:16384
	ds_read_b128 v[184:187], v167 offset:17408
	ds_read_b128 v[188:191], v167 offset:18432
	ds_read_b128 v[192:195], v167 offset:19456
	ds_read_b128 v[196:199], v167 offset:20480
	ds_read_b128 v[200:203], v167 offset:21504
	ds_read_b128 v[204:207], v167 offset:22528
	ds_read_b128 v[208:211], v167 offset:23552
	global_load_lds_dwordx4 v[160:161], off
	s_add_i32 m0, s30, 0x2000
	s_add_u32 s30, s36, 0x200000
	v_lshl_add_u64 v[212:213], s[36:37], 0, v[144:145]
	s_addc_u32 s31, s37, 0
	s_add_i32 s62, s56, s47
	global_load_lds_dwordx4 v[212:213], off
	v_lshl_add_u64 v[214:215], s[30:31], 0, v[146:147]
	s_mov_b32 m0, s62
	v_lshl_add_u64 v[216:217], s[38:39], 0, v[144:145]
	global_load_lds_dwordx4 v[214:215], off
	v_lshl_add_u64 v[214:215], s[30:31], 0, v[144:145]
	s_add_i32 m0, s62, 0x2000
	s_nop 0
	global_load_lds_dwordx4 v[214:215], off
	v_lshl_add_u64 v[214:215], s[38:39], 0, v[146:147]
	s_mov_b32 m0, s42
	s_nop 0
	global_load_lds_dwordx4 v[214:215], off
	s_mov_b32 m0, s43
	s_nop 0
	global_load_lds_dwordx4 v[216:217], off
	s_waitcnt vmcnt(8)
	s_waitcnt lgkmcnt(0)
	s_barrier
; #define PG8_STAGE(bufoff, gbase, voff) do { _Pragma("unroll") for (int _i = 0; _i < 2; ++_i) \
;         __builtin_amdgcn_global_load_lds((const unsigned*)((const char*)(gbase) + (voff)[_i]), (PG8_LAS unsigned*)(lds + (bufoff) + ldsw + _i * 8192), 16, 0, 0); } while (0)
; #define PG8_LDA(dst, b, h) do { _Pragma("unroll") for (int m = 0; m < 4; ++m) _Pragma("unroll") for (int k = 0; k < 2; ++k) dst[m][k] = *(const PG8_LAS bf16x8*)(lds + PG8_SA(b, h) + aoff + m * 2048 + k * 1024); } while (0)
; #define PG8_LDB(dst, b, h) do { _Pragma("unroll") for (int n = 0; n < 2; ++n) _Pragma("unroll") for (int k = 0; k < 2; ++k) dst[n][k] = *(const PG8_LAS bf16x8*)(lds + PG8_SB(b, h) + boff + n * 2048 + k * 1024); } while (0)
; #define PG8_MMA(ai, bj, At, Bt) do { __builtin_amdgcn_s_setprio(1); _Pragma("unroll") for (int m = 0; m < 4; ++m) _Pragma("unroll") for (int n = 0; n < 2; ++n) _Pragma("unroll") for (int k = 0; k < 2; ++k) \
;         acc[ai][bj][m][n] = __builtin_amdgcn_mfma_f32_16x16x32_bf16(Bt[n][k], At[m][k], acc[ai][bj][m][n], 0, 0, 0); __builtin_amdgcn_s_setprio(0); } while (0)
; #define PG8_WAIT_V(n) asm volatile("s_waitcnt vmcnt(" #n ")" ::: "memory")
; #define PG8_WAIT_L(n) asm volatile("s_waitcnt lgkmcnt(" #n ")" ::: "memory")
; #define PG8_BAR __builtin_amdgcn_s_barrier()
; #define PG8_SCHED __builtin_amdgcn_sched_barrier(0)
; template <class Epi, class Sched, bool ALIGN_EPI = false, bool SP2 = false>
; __device__ __forceinline__ void gemm_phase(PG8_LAS unsigned char* lds, const Gemm g, const Sched& S, const Epi& E) {
;     ...
;             PG8_WAIT_V(8); PG8_WAIT_L(0); PG8_BAR; PG8_MMA(1, 0, At, B0); PG8_MMA(1, 1, At, B1); PG8_BAR; PG8_SCHED;
;             PG8_LDB(B0, 1, 0); PG8_LDB(B1, 1, 1); PG8_SCHED; PG8_LDA(At, 1, 0); PG8_STAGE(PG8_SA(0, 1), a2 + hstep, voffA);
;             PG8_WAIT_V(8); PG8_WAIT_L(0); PG8_BAR; PG8_MMA(0, 0, At, B0); PG8_MMA(0, 1, At, B1); PG8_BAR; PG8_SCHED;
	s_setprio 1
	s_waitcnt lgkmcnt(0)
	v_mfma_f32_16x16x32_bf16 v[60:63], v[72:75], v[180:183], 0
	v_mfma_f32_16x16x32_bf16 v[56:59], v[92:95], v[180:183], 0
	v_mfma_f32_16x16x32_bf16 v[52:55], v[72:75], v[188:191], 0
	v_mfma_f32_16x16x32_bf16 v[44:47], v[92:95], v[188:191], 0
	v_mfma_f32_16x16x32_bf16 v[36:39], v[72:75], v[196:199], 0
	v_mfma_f32_16x16x32_bf16 v[28:31], v[92:95], v[196:199], 0
	v_mfma_f32_16x16x32_bf16 v[20:23], v[72:75], v[204:207], 0
	v_mfma_f32_16x16x32_bf16 v[12:15], v[92:95], v[204:207], 0
	v_mfma_f32_16x16x32_bf16 v[60:63], v[84:87], v[184:187], v[60:63]
	v_mfma_f32_16x16x32_bf16 v[56:59], v[108:111], v[184:187], v[56:59]
	v_mfma_f32_16x16x32_bf16 v[52:55], v[84:87], v[192:195], v[52:55]
	v_mfma_f32_16x16x32_bf16 v[44:47], v[108:111], v[192:195], v[44:47]
	v_mfma_f32_16x16x32_bf16 v[36:39], v[84:87], v[200:203], v[36:39]
	v_mfma_f32_16x16x32_bf16 v[28:31], v[108:111], v[200:203], v[28:31]
	v_mfma_f32_16x16x32_bf16 v[20:23], v[84:87], v[208:211], v[20:23]
	v_mfma_f32_16x16x32_bf16 v[12:15], v[108:111], v[208:211], v[12:15]
	v_mfma_f32_16x16x32_bf16 v[48:51], v[156:159], v[180:183], 0
	v_mfma_f32_16x16x32_bf16 v[40:43], v[172:175], v[180:183], 0
	v_mfma_f32_16x16x32_bf16 v[32:35], v[156:159], v[188:191], 0
	v_mfma_f32_16x16x32_bf16 v[24:27], v[172:175], v[188:191], 0
	v_mfma_f32_16x16x32_bf16 v[16:19], v[156:159], v[196:199], 0
	v_mfma_f32_16x16x32_bf16 v[8:11], v[172:175], v[196:199], 0
	v_mfma_f32_16x16x32_bf16 v[4:7], v[156:159], v[204:207], 0
	v_mfma_f32_16x16x32_bf16 v[0:3], v[172:175], v[204:207], 0
	v_mfma_f32_16x16x32_bf16 v[48:51], v[168:171], v[184:187], v[48:51]
	v_mfma_f32_16x16x32_bf16 v[40:43], v[176:179], v[184:187], v[40:43]
	v_mfma_f32_16x16x32_bf16 v[32:35], v[168:171], v[192:195], v[32:35]
	v_mfma_f32_16x16x32_bf16 v[24:27], v[176:179], v[192:195], v[24:27]
	v_mfma_f32_16x16x32_bf16 v[16:19], v[168:171], v[200:203], v[16:19]
	v_mfma_f32_16x16x32_bf16 v[8:11], v[176:179], v[200:203], v[8:11]
	v_mfma_f32_16x16x32_bf16 v[4:7], v[168:171], v[208:211], v[4:7]
	v_mfma_f32_16x16x32_bf16 v[0:3], v[176:179], v[208:211], v[0:3]
	s_setprio 0
	s_barrier
	s_add_i32 s62, 0, 0x18000
	s_add_i32 s63, 0, 0x1c000
	v_add_u32_e32 v108, s62, v163
	v_add_u32_e32 v176, s63, v163
	ds_read_b128 v[72:75], v108
	ds_read_b128 v[84:87], v108 offset:1024
	ds_read_b128 v[92:95], v108 offset:2048
	ds_read_b128 v[108:111], v108 offset:3072
	ds_read_b128 v[156:159], v176
	ds_read_b128 v[168:171], v176 offset:1024
	ds_read_b128 v[172:175], v176 offset:2048
	ds_read_b128 v[176:179], v176 offset:3072
	s_add_u32 s30, s38, 0x200000
	s_addc_u32 s31, s39, 0
	s_mov_b32 m0, s48
	v_lshl_add_u64 v[218:219], s[30:31], 0, v[146:147]
	ds_read_b128 v[180:183], v167 offset:32768
	ds_read_b128 v[184:187], v167 offset:33792
	ds_read_b128 v[188:191], v167 offset:34816
	ds_read_b128 v[192:195], v167 offset:35840
	ds_read_b128 v[196:199], v167 offset:36864
	ds_read_b128 v[200:203], v167 offset:37888
	ds_read_b128 v[204:207], v167 offset:38912
	ds_read_b128 v[208:211], v167 offset:39936
	global_load_lds_dwordx4 v[218:219], off
	v_lshl_add_u64 v[218:219], s[30:31], 0, v[144:145]
	s_mov_b32 m0, s49
	s_nop 0
	global_load_lds_dwordx4 v[218:219], off
	s_waitcnt vmcnt(8)
	s_waitcnt lgkmcnt(0)
	s_barrier
	s_setprio 1
	s_waitcnt lgkmcnt(0)
	v_mfma_f32_16x16x32_bf16 v[140:143], v[72:75], v[180:183], v[140:143]
	v_mfma_f32_16x16x32_bf16 v[136:139], v[92:95], v[180:183], v[136:139]
	v_mfma_f32_16x16x32_bf16 v[132:135], v[72:75], v[188:191], v[132:135]
	v_mfma_f32_16x16x32_bf16 v[128:131], v[92:95], v[188:191], v[128:131]
	v_mfma_f32_16x16x32_bf16 v[120:123], v[72:75], v[196:199], v[120:123]
	v_mfma_f32_16x16x32_bf16 v[112:115], v[92:95], v[196:199], v[112:115]
	v_mfma_f32_16x16x32_bf16 v[100:103], v[72:75], v[204:207], v[100:103]
	v_mfma_f32_16x16x32_bf16 v[88:91], v[92:95], v[204:207], v[88:91]
	v_mfma_f32_16x16x32_bf16 v[140:143], v[84:87], v[184:187], v[140:143]
	v_mfma_f32_16x16x32_bf16 v[136:139], v[108:111], v[184:187], v[136:139]
	v_mfma_f32_16x16x32_bf16 v[132:135], v[84:87], v[192:195], v[132:135]
	v_mfma_f32_16x16x32_bf16 v[128:131], v[108:111], v[192:195], v[128:131]
	v_mfma_f32_16x16x32_bf16 v[120:123], v[84:87], v[200:203], v[120:123]
	v_mfma_f32_16x16x32_bf16 v[112:115], v[108:111], v[200:203], v[112:115]
	v_mfma_f32_16x16x32_bf16 v[100:103], v[84:87], v[208:211], v[100:103]
	v_mfma_f32_16x16x32_bf16 v[88:91], v[108:111], v[208:211], v[88:91]
	v_mfma_f32_16x16x32_bf16 v[124:127], v[156:159], v[180:183], v[124:127]
	v_mfma_f32_16x16x32_bf16 v[116:119], v[172:175], v[180:183], v[116:119]
	v_mfma_f32_16x16x32_bf16 v[104:107], v[156:159], v[188:191], v[104:107]
	v_mfma_f32_16x16x32_bf16 v[96:99], v[172:175], v[188:191], v[96:99]
	v_mfma_f32_16x16x32_bf16 v[80:83], v[156:159], v[196:199], v[80:83]
	v_mfma_f32_16x16x32_bf16 v[76:79], v[172:175], v[196:199], v[76:79]
	v_mfma_f32_16x16x32_bf16 v[68:71], v[156:159], v[204:207], v[68:71]
	v_mfma_f32_16x16x32_bf16 v[64:67], v[172:175], v[204:207], v[64:67]
	v_mfma_f32_16x16x32_bf16 v[124:127], v[168:171], v[184:187], v[124:127]
	v_mfma_f32_16x16x32_bf16 v[116:119], v[176:179], v[184:187], v[116:119]
	v_mfma_f32_16x16x32_bf16 v[104:107], v[168:171], v[192:195], v[104:107]
	v_mfma_f32_16x16x32_bf16 v[96:99], v[176:179], v[192:195], v[96:99]
	v_mfma_f32_16x16x32_bf16 v[80:83], v[168:171], v[200:203], v[80:83]
	v_mfma_f32_16x16x32_bf16 v[76:79], v[176:179], v[200:203], v[76:79]
	v_mfma_f32_16x16x32_bf16 v[68:71], v[168:171], v[208:211], v[68:71]
	v_mfma_f32_16x16x32_bf16 v[64:67], v[176:179], v[208:211], v[64:67]
	s_setprio 0
	s_barrier
; #define PG8_STAGE(bufoff, gbase, voff) do { _Pragma("unroll") for (int _i = 0; _i < 2; ++_i) \
;         __builtin_amdgcn_global_load_lds((const unsigned*)((const char*)(gbase) + (voff)[_i]), (PG8_LAS unsigned*)(lds + (bufoff) + ldsw + _i * 8192), 16, 0, 0); } while (0)
; #define PG8_LDA(dst, b, h) do { _Pragma("unroll") for (int m = 0; m < 4; ++m) _Pragma("unroll") for (int k = 0; k < 2; ++k) dst[m][k] = *(const PG8_LAS bf16x8*)(lds + PG8_SA(b, h) + aoff + m * 2048 + k * 1024); } while (0)
; #define PG8_LDB(dst, b, h) do { _Pragma("unroll") for (int n = 0; n < 2; ++n) _Pragma("unroll") for (int k = 0; k < 2; ++k) dst[n][k] = *(const PG8_LAS bf16x8*)(lds + PG8_SB(b, h) + boff + n * 2048 + k * 1024); } while (0)
; #define PG8_MMA(ai, bj, At, Bt) do { __builtin_amdgcn_s_setprio(1); _Pragma("unroll") for (int m = 0; m < 4; ++m) _Pragma("unroll") for (int n = 0; n < 2; ++n) _Pragma("unroll") for (int k = 0; k < 2; ++k) \
;         acc[ai][bj][m][n] = __builtin_amdgcn_mfma_f32_16x16x32_bf16(Bt[n][k], At[m][k], acc[ai][bj][m][n], 0, 0, 0); __builtin_amdgcn_s_setprio(0); } while (0)
; #define PG8_WAIT_V(n) asm volatile("s_waitcnt vmcnt(" #n ")" ::: "memory")
; #define PG8_BAR __builtin_amdgcn_s_barrier()
; template <class Epi, class Sched, bool ALIGN_EPI = false, bool SP2 = false>
; __device__ __forceinline__ void gemm_phase(PG8_LAS unsigned char* lds, const Gemm g, const Sched& S, const Epi& E) {
;     ...
;         for (int t = 0; t < nt; t += 2) {
;             const bool last = (t == nt - 2);
;             const char* a1 = cA + (size_t)(t + 1) * kstep;
;             const char* a2 = last ? nA : cA + (size_t)(t + 2) * kstep; const char* b2 = last ? nB : cB + (size_t)(t + 2) * kstep;
;             const char* a3 = a2 + kstep; const char* b3 = b2 + kstep;
;             if (last && has_next) S.a_ready(nxt);
;             if constexpr (SP2) {
;             PG8_LDB(B0, 0, 0); PG8_LDB(B1, 0, 1); PG8_SCHED; PG8_LDA(At, 0, 0); PG8_STAGE(PG8_SA(1, 1), a1 + hstep, voffA);
;             PG8_WAIT_V(8); PG8_WAIT_L(0); PG8_BAR; PG8_MMA(0, 0, At, B0); PG8_MMA(0, 1, At, B1); PG8_BAR; PG8_SCHED;
;     ...
;             PG8_LDA(At, 1, 1); PG8_STAGE(PG8_SB(1, 0), b3, voffB); PG8_STAGE(PG8_SB(1, 1), b3 + hstep, voffB); PG8_STAGE(PG8_SA(1, 0), a3, voffA);
;             PG8_WAIT_V(8); PG8_WAIT_L(0); PG8_BAR; PG8_MMA(1, 0, At, B0); PG8_MMA(1, 1, At, B1); PG8_BAR; PG8_SCHED;
	s_add_i32 s30, s62, s47
	v_lshl_add_u64 v[160:161], v[160:161], 0, s[8:9]
	s_mov_b32 m0, s30
	ds_read_b128 v[180:183], v167 offset:49152
	ds_read_b128 v[184:187], v167 offset:50176
	ds_read_b128 v[188:191], v167 offset:51200
	ds_read_b128 v[192:195], v167 offset:52224
	ds_read_b128 v[196:199], v167 offset:53248
	ds_read_b128 v[200:203], v167 offset:54272
	ds_read_b128 v[204:207], v167 offset:55296
	ds_read_b128 v[208:211], v167 offset:56320
	global_load_lds_dwordx4 v[160:161], off
	s_add_i32 m0, s30, 0x2000
	s_add_u32 s30, s36, 0x200080
	v_lshl_add_u64 v[160:161], v[212:213], 0, s[8:9]
	s_addc_u32 s31, s37, 0
	s_add_i32 s36, s63, s47
	global_load_lds_dwordx4 v[160:161], off
	v_lshl_add_u64 v[160:161], s[30:31], 0, v[146:147]
	s_mov_b32 m0, s36
	s_nop 0
	global_load_lds_dwordx4 v[160:161], off
	v_lshl_add_u64 v[160:161], s[30:31], 0, v[144:145]
	s_add_i32 m0, s36, 0x2000
	s_nop 0
	global_load_lds_dwordx4 v[160:161], off
	v_lshl_add_u64 v[160:161], v[214:215], 0, s[8:9]
	s_mov_b32 m0, s53
	s_nop 0
	global_load_lds_dwordx4 v[160:161], off
	v_lshl_add_u64 v[160:161], v[216:217], 0, s[8:9]
	s_mov_b32 m0, s54
	s_nop 0
	global_load_lds_dwordx4 v[160:161], off
	s_waitcnt vmcnt(8)
	s_waitcnt lgkmcnt(0)
	s_barrier
	s_setprio 1
	s_waitcnt lgkmcnt(0)
	v_mfma_f32_16x16x32_bf16 v[60:63], v[72:75], v[180:183], v[60:63]
	v_mfma_f32_16x16x32_bf16 v[56:59], v[92:95], v[180:183], v[56:59]
	v_mfma_f32_16x16x32_bf16 v[52:55], v[72:75], v[188:191], v[52:55]
	v_mfma_f32_16x16x32_bf16 v[44:47], v[92:95], v[188:191], v[44:47]
	v_mfma_f32_16x16x32_bf16 v[36:39], v[72:75], v[196:199], v[36:39]
	v_mfma_f32_16x16x32_bf16 v[28:31], v[92:95], v[196:199], v[28:31]
	v_mfma_f32_16x16x32_bf16 v[20:23], v[72:75], v[204:207], v[20:23]
	v_mfma_f32_16x16x32_bf16 v[12:15], v[92:95], v[204:207], v[12:15]
	v_mfma_f32_16x16x32_bf16 v[60:63], v[84:87], v[184:187], v[60:63]
	v_mfma_f32_16x16x32_bf16 v[56:59], v[108:111], v[184:187], v[56:59]
	v_mfma_f32_16x16x32_bf16 v[52:55], v[84:87], v[192:195], v[52:55]
	v_mfma_f32_16x16x32_bf16 v[44:47], v[108:111], v[192:195], v[44:47]
	v_mfma_f32_16x16x32_bf16 v[36:39], v[84:87], v[200:203], v[36:39]
	v_mfma_f32_16x16x32_bf16 v[28:31], v[108:111], v[200:203], v[28:31]
	v_mfma_f32_16x16x32_bf16 v[20:23], v[84:87], v[208:211], v[20:23]
	v_mfma_f32_16x16x32_bf16 v[12:15], v[108:111], v[208:211], v[12:15]
	v_mfma_f32_16x16x32_bf16 v[48:51], v[156:159], v[180:183], v[48:51]
	v_mfma_f32_16x16x32_bf16 v[40:43], v[172:175], v[180:183], v[40:43]
	v_mfma_f32_16x16x32_bf16 v[32:35], v[156:159], v[188:191], v[32:35]
	v_mfma_f32_16x16x32_bf16 v[24:27], v[172:175], v[188:191], v[24:27]
	v_mfma_f32_16x16x32_bf16 v[16:19], v[156:159], v[196:199], v[16:19]
	v_mfma_f32_16x16x32_bf16 v[8:11], v[172:175], v[196:199], v[8:11]
	v_mfma_f32_16x16x32_bf16 v[4:7], v[156:159], v[204:207], v[4:7]
	v_mfma_f32_16x16x32_bf16 v[0:3], v[172:175], v[204:207], v[0:3]
	v_mfma_f32_16x16x32_bf16 v[48:51], v[168:171], v[184:187], v[48:51]
	v_mfma_f32_16x16x32_bf16 v[40:43], v[176:179], v[184:187], v[40:43]
	v_mfma_f32_16x16x32_bf16 v[32:35], v[168:171], v[192:195], v[32:35]
	v_mfma_f32_16x16x32_bf16 v[24:27], v[176:179], v[192:195], v[24:27]
	v_mfma_f32_16x16x32_bf16 v[16:19], v[168:171], v[200:203], v[16:19]
	v_mfma_f32_16x16x32_bf16 v[8:11], v[176:179], v[200:203], v[8:11]
	v_mfma_f32_16x16x32_bf16 v[4:7], v[168:171], v[208:211], v[4:7]
	v_mfma_f32_16x16x32_bf16 v[0:3], v[176:179], v[208:211], v[0:3]
	s_setprio 0
	s_barrier
	s_add_i32 s61, s61, 2
	s_add_u32 s59, s59, 0x100
	s_addc_u32 s60, s60, 0
	s_cmpk_gt_u32 s61, 0x7d
	s_mov_b64 s[30:31], s[34:35]
.LBB0_847:
	ds_read_b128 v[72:75], v165
	ds_read_b128 v[84:87], v165 offset:1024
	ds_read_b128 v[92:95], v165 offset:2048
	ds_read_b128 v[108:111], v165 offset:3072
	ds_read_b128 v[156:159], v166
	ds_read_b128 v[168:171], v166 offset:1024
	ds_read_b128 v[172:175], v166 offset:2048
	ds_read_b128 v[176:179], v166 offset:3072
	s_add_u32 s34, s30, 0x100
	s_addc_u32 s35, s31, 0
	s_cmpk_eq_i32 s61, 0x7c
	s_cselect_b32 s39, s23, s35
	s_cselect_b32 s38, s57, s34
	s_cselect_b32 s37, s21, s60
	s_cselect_b32 s36, s58, s59
	v_lshl_add_u64 v[160:161], s[30:31], 0, v[148:149]
	s_add_i32 m0, s42, 0xc000
	ds_read_b128 v[180:183], v167
	ds_read_b128 v[184:187], v167 offset:1024
	ds_read_b128 v[188:191], v167 offset:2048
	ds_read_b128 v[192:195], v167 offset:3072
	ds_read_b128 v[196:199], v167 offset:4096
	ds_read_b128 v[200:203], v167 offset:5120
	ds_read_b128 v[204:207], v167 offset:6144
	ds_read_b128 v[208:211], v167 offset:7168
	global_load_lds_dwordx4 v[160:161], off
	v_lshl_add_u64 v[160:161], s[30:31], 0, v[150:151]
	s_add_i32 m0, s42, 0xe000
	s_nop 0
	global_load_lds_dwordx4 v[160:161], off
	s_waitcnt vmcnt(8)
	s_waitcnt lgkmcnt(0)
	s_barrier
; #define PG8_STAGE(bufoff, gbase, voff) do { _Pragma("unroll") for (int _i = 0; _i < 2; ++_i) \
;         __builtin_amdgcn_global_load_lds((const unsigned*)((const char*)(gbase) + (voff)[_i]), (PG8_LAS unsigned*)(lds + (bufoff) + ldsw + _i * 8192), 16, 0, 0); } while (0)
; #define PG8_LDA(dst, b, h) do { _Pragma("unroll") for (int m = 0; m < 4; ++m) _Pragma("unroll") for (int k = 0; k < 2; ++k) dst[m][k] = *(const PG8_LAS bf16x8*)(lds + PG8_SA(b, h) + aoff + m * 2048 + k * 1024); } while (0)
; #define PG8_MMA(ai, bj, At, Bt) do { __builtin_amdgcn_s_setprio(1); _Pragma("unroll") for (int m = 0; m < 4; ++m) _Pragma("unroll") for (int n = 0; n < 2; ++n) _Pragma("unroll") for (int k = 0; k < 2; ++k) \
;         acc[ai][bj][m][n] = __builtin_amdgcn_mfma_f32_16x16x32_bf16(Bt[n][k], At[m][k], acc[ai][bj][m][n], 0, 0, 0); __builtin_amdgcn_s_setprio(0); } while (0)
; #define PG8_WAIT_V(n) asm volatile("s_waitcnt vmcnt(" #n ")" ::: "memory")
; #define PG8_WAIT_L(n) asm volatile("s_waitcnt lgkmcnt(" #n ")" ::: "memory")
; #define PG8_BAR __builtin_amdgcn_s_barrier()
; #define PG8_SCHED __builtin_amdgcn_sched_barrier(0)
; template <class Epi, class Sched, bool ALIGN_EPI = false, bool SP2 = false>
; __device__ __forceinline__ void gemm_phase(PG8_LAS unsigned char* lds, const Gemm g, const Sched& S, const Epi& E) {
;     ...
;             PG8_WAIT_V(8); PG8_WAIT_L(0); PG8_BAR; PG8_MMA(0, 0, At, B0); PG8_MMA(0, 1, At, B1); PG8_BAR; PG8_SCHED;
;             PG8_LDA(At, 0, 1); PG8_STAGE(PG8_SB(0, 0), b2, voffB); PG8_STAGE(PG8_SB(0, 1), b2 + hstep, voffB); PG8_STAGE(PG8_SA(0, 0), a2, voffA);
;             PG8_WAIT_V(8); PG8_WAIT_L(0); PG8_BAR; PG8_MMA(1, 0, At, B0); PG8_MMA(1, 1, At, B1); PG8_BAR; PG8_SCHED;
	s_setprio 1
	s_waitcnt lgkmcnt(0)
	v_mfma_f32_16x16x32_bf16 v[140:143], v[72:75], v[180:183], v[140:143]
	v_mfma_f32_16x16x32_bf16 v[136:139], v[92:95], v[180:183], v[136:139]
	v_mfma_f32_16x16x32_bf16 v[132:135], v[72:75], v[188:191], v[132:135]
	v_mfma_f32_16x16x32_bf16 v[128:131], v[92:95], v[188:191], v[128:131]
	v_mfma_f32_16x16x32_bf16 v[120:123], v[72:75], v[196:199], v[120:123]
	v_mfma_f32_16x16x32_bf16 v[112:115], v[92:95], v[196:199], v[112:115]
	v_mfma_f32_16x16x32_bf16 v[100:103], v[72:75], v[204:207], v[100:103]
	v_mfma_f32_16x16x32_bf16 v[88:91], v[92:95], v[204:207], v[88:91]
	v_mfma_f32_16x16x32_bf16 v[140:143], v[84:87], v[184:187], v[140:143]
	v_mfma_f32_16x16x32_bf16 v[136:139], v[108:111], v[184:187], v[136:139]
	v_mfma_f32_16x16x32_bf16 v[132:135], v[84:87], v[192:195], v[132:135]
	v_mfma_f32_16x16x32_bf16 v[128:131], v[108:111], v[192:195], v[128:131]
	v_mfma_f32_16x16x32_bf16 v[120:123], v[84:87], v[200:203], v[120:123]
	v_mfma_f32_16x16x32_bf16 v[112:115], v[108:111], v[200:203], v[112:115]
	v_mfma_f32_16x16x32_bf16 v[100:103], v[84:87], v[208:211], v[100:103]
	v_mfma_f32_16x16x32_bf16 v[88:91], v[108:111], v[208:211], v[88:91]
	v_mfma_f32_16x16x32_bf16 v[124:127], v[156:159], v[180:183], v[124:127]
	v_mfma_f32_16x16x32_bf16 v[116:119], v[172:175], v[180:183], v[116:119]
	v_mfma_f32_16x16x32_bf16 v[104:107], v[156:159], v[188:191], v[104:107]
	v_mfma_f32_16x16x32_bf16 v[96:99], v[172:175], v[188:191], v[96:99]
	v_mfma_f32_16x16x32_bf16 v[80:83], v[156:159], v[196:199], v[80:83]
	v_mfma_f32_16x16x32_bf16 v[76:79], v[172:175], v[196:199], v[76:79]
	v_mfma_f32_16x16x32_bf16 v[68:71], v[156:159], v[204:207], v[68:71]
	v_mfma_f32_16x16x32_bf16 v[64:67], v[172:175], v[204:207], v[64:67]
	v_mfma_f32_16x16x32_bf16 v[124:127], v[168:171], v[184:187], v[124:127]
	v_mfma_f32_16x16x32_bf16 v[116:119], v[176:179], v[184:187], v[116:119]
	v_mfma_f32_16x16x32_bf16 v[104:107], v[168:171], v[192:195], v[104:107]
	v_mfma_f32_16x16x32_bf16 v[96:99], v[176:179], v[192:195], v[96:99]
	v_mfma_f32_16x16x32_bf16 v[80:83], v[168:171], v[200:203], v[80:83]
	v_mfma_f32_16x16x32_bf16 v[76:79], v[176:179], v[200:203], v[76:79]
	v_mfma_f32_16x16x32_bf16 v[68:71], v[168:171], v[208:211], v[68:71]
	v_mfma_f32_16x16x32_bf16 v[64:67], v[176:179], v[208:211], v[64:67]
	s_setprio 0
	s_barrier
	s_add_i32 s30, s55, s47
	v_lshl_add_u64 v[160:161], s[36:37], 0, v[146:147]
	s_mov_b32 m0, s30
	ds_read_b128 v[180:183], v167 offset:16384
	ds_read_b128 v[184:187], v167 offset:17408
	ds_read_b128 v[188:191], v167 offset:18432
	ds_read_b128 v[192:195], v167 offset:19456
	ds_read_b128 v[196:199], v167 offset:20480
	ds_read_b128 v[200:203], v167 offset:21504
	ds_read_b128 v[204:207], v167 offset:22528
	ds_read_b128 v[208:211], v167 offset:23552
	global_load_lds_dwordx4 v[160:161], off
	s_add_i32 m0, s30, 0x2000
	s_add_u32 s30, s36, 0x200000
	v_lshl_add_u64 v[212:213], s[36:37], 0, v[144:145]
	s_addc_u32 s31, s37, 0
	s_add_i32 s62, s56, s47
	global_load_lds_dwordx4 v[212:213], off
	v_lshl_add_u64 v[214:215], s[30:31], 0, v[146:147]
	s_mov_b32 m0, s62
	v_lshl_add_u64 v[216:217], s[38:39], 0, v[144:145]
	global_load_lds_dwordx4 v[214:215], off
	v_lshl_add_u64 v[214:215], s[30:31], 0, v[144:145]
	s_add_i32 m0, s62, 0x2000
	s_nop 0
	global_load_lds_dwordx4 v[214:215], off
	v_lshl_add_u64 v[214:215], s[38:39], 0, v[146:147]
	s_mov_b32 m0, s42
	s_nop 0
	global_load_lds_dwordx4 v[214:215], off
	s_mov_b32 m0, s43
	s_nop 0
	global_load_lds_dwordx4 v[216:217], off
	s_waitcnt vmcnt(8)
	s_waitcnt lgkmcnt(0)
	s_barrier
	s_setprio 1
	s_waitcnt lgkmcnt(0)
	v_mfma_f32_16x16x32_bf16 v[60:63], v[72:75], v[180:183], v[60:63]
	v_mfma_f32_16x16x32_bf16 v[56:59], v[92:95], v[180:183], v[56:59]
	v_mfma_f32_16x16x32_bf16 v[52:55], v[72:75], v[188:191], v[52:55]
	v_mfma_f32_16x16x32_bf16 v[44:47], v[92:95], v[188:191], v[44:47]
	v_mfma_f32_16x16x32_bf16 v[36:39], v[72:75], v[196:199], v[36:39]
	v_mfma_f32_16x16x32_bf16 v[28:31], v[92:95], v[196:199], v[28:31]
	v_mfma_f32_16x16x32_bf16 v[20:23], v[72:75], v[204:207], v[20:23]
	v_mfma_f32_16x16x32_bf16 v[12:15], v[92:95], v[204:207], v[12:15]
	v_mfma_f32_16x16x32_bf16 v[60:63], v[84:87], v[184:187], v[60:63]
	v_mfma_f32_16x16x32_bf16 v[56:59], v[108:111], v[184:187], v[56:59]
	v_mfma_f32_16x16x32_bf16 v[52:55], v[84:87], v[192:195], v[52:55]
	v_mfma_f32_16x16x32_bf16 v[44:47], v[108:111], v[192:195], v[44:47]
	v_mfma_f32_16x16x32_bf16 v[36:39], v[84:87], v[200:203], v[36:39]
	v_mfma_f32_16x16x32_bf16 v[28:31], v[108:111], v[200:203], v[28:31]
	v_mfma_f32_16x16x32_bf16 v[20:23], v[84:87], v[208:211], v[20:23]
	v_mfma_f32_16x16x32_bf16 v[12:15], v[108:111], v[208:211], v[12:15]
	v_mfma_f32_16x16x32_bf16 v[48:51], v[156:159], v[180:183], v[48:51]
	v_mfma_f32_16x16x32_bf16 v[40:43], v[172:175], v[180:183], v[40:43]
	v_mfma_f32_16x16x32_bf16 v[32:35], v[156:159], v[188:191], v[32:35]
	v_mfma_f32_16x16x32_bf16 v[24:27], v[172:175], v[188:191], v[24:27]
	v_mfma_f32_16x16x32_bf16 v[16:19], v[156:159], v[196:199], v[16:19]
	v_mfma_f32_16x16x32_bf16 v[8:11], v[172:175], v[196:199], v[8:11]
	v_mfma_f32_16x16x32_bf16 v[4:7], v[156:159], v[204:207], v[4:7]
	v_mfma_f32_16x16x32_bf16 v[0:3], v[172:175], v[204:207], v[0:3]
	v_mfma_f32_16x16x32_bf16 v[48:51], v[168:171], v[184:187], v[48:51]
	v_mfma_f32_16x16x32_bf16 v[40:43], v[176:179], v[184:187], v[40:43]
	v_mfma_f32_16x16x32_bf16 v[32:35], v[168:171], v[192:195], v[32:35]
	v_mfma_f32_16x16x32_bf16 v[24:27], v[176:179], v[192:195], v[24:27]
	v_mfma_f32_16x16x32_bf16 v[16:19], v[168:171], v[200:203], v[16:19]
	v_mfma_f32_16x16x32_bf16 v[8:11], v[176:179], v[200:203], v[8:11]
	v_mfma_f32_16x16x32_bf16 v[4:7], v[168:171], v[208:211], v[4:7]
	v_mfma_f32_16x16x32_bf16 v[0:3], v[176:179], v[208:211], v[0:3]
	s_setprio 0
	s_barrier
; #define PG8_STAGE(bufoff, gbase, voff) do { _Pragma("unroll") for (int _i = 0; _i < 2; ++_i) \
;         __builtin_amdgcn_global_load_lds((const unsigned*)((const char*)(gbase) + (voff)[_i]), (PG8_LAS unsigned*)(lds + (bufoff) + ldsw + _i * 8192), 16, 0, 0); } while (0)
; #define PG8_LDA(dst, b, h) do { _Pragma("unroll") for (int m = 0; m < 4; ++m) _Pragma("unroll") for (int k = 0; k < 2; ++k) dst[m][k] = *(const PG8_LAS bf16x8*)(lds + PG8_SA(b, h) + aoff + m * 2048 + k * 1024); } while (0)
; #define PG8_LDB(dst, b, h) do { _Pragma("unroll") for (int n = 0; n < 2; ++n) _Pragma("unroll") for (int k = 0; k < 2; ++k) dst[n][k] = *(const PG8_LAS bf16x8*)(lds + PG8_SB(b, h) + boff + n * 2048 + k * 1024); } while (0)
; #define PG8_MMA(ai, bj, At, Bt) do { __builtin_amdgcn_s_setprio(1); _Pragma("unroll") for (int m = 0; m < 4; ++m) _Pragma("unroll") for (int n = 0; n < 2; ++n) _Pragma("unroll") for (int k = 0; k < 2; ++k) \
;         acc[ai][bj][m][n] = __builtin_amdgcn_mfma_f32_16x16x32_bf16(Bt[n][k], At[m][k], acc[ai][bj][m][n], 0, 0, 0); __builtin_amdgcn_s_setprio(0); } while (0)
; #define PG8_WAIT_V(n) asm volatile("s_waitcnt vmcnt(" #n ")" ::: "memory")
; #define PG8_WAIT_L(n) asm volatile("s_waitcnt lgkmcnt(" #n ")" ::: "memory")
; #define PG8_BAR __builtin_amdgcn_s_barrier()
; #define PG8_SCHED __builtin_amdgcn_sched_barrier(0)
; template <class Epi, class Sched, bool ALIGN_EPI = false, bool SP2 = false>
; __device__ __forceinline__ void gemm_phase(PG8_LAS unsigned char* lds, const Gemm g, const Sched& S, const Epi& E) {
;     ...
;             PG8_LDB(B0, 1, 0); PG8_LDB(B1, 1, 1); PG8_SCHED; PG8_LDA(At, 1, 0); PG8_STAGE(PG8_SA(0, 1), a2 + hstep, voffA);
;             PG8_WAIT_V(8); PG8_WAIT_L(0); PG8_BAR; PG8_MMA(0, 0, At, B0); PG8_MMA(0, 1, At, B1); PG8_BAR; PG8_SCHED;
	s_add_i32 s62, 0, 0x18000
	s_add_i32 s63, 0, 0x1c000
	v_add_u32_e32 v108, s62, v163
	v_add_u32_e32 v176, s63, v163
	ds_read_b128 v[72:75], v108
	ds_read_b128 v[84:87], v108 offset:1024
	ds_read_b128 v[92:95], v108 offset:2048
	ds_read_b128 v[108:111], v108 offset:3072
	ds_read_b128 v[156:159], v176
	ds_read_b128 v[168:171], v176 offset:1024
	ds_read_b128 v[172:175], v176 offset:2048
	ds_read_b128 v[176:179], v176 offset:3072
	s_add_u32 s30, s38, 0x200000
	s_addc_u32 s31, s39, 0
	s_mov_b32 m0, s48
	v_lshl_add_u64 v[218:219], s[30:31], 0, v[146:147]
	ds_read_b128 v[180:183], v167 offset:32768
	ds_read_b128 v[184:187], v167 offset:33792
	ds_read_b128 v[188:191], v167 offset:34816
	ds_read_b128 v[192:195], v167 offset:35840
	ds_read_b128 v[196:199], v167 offset:36864
	ds_read_b128 v[200:203], v167 offset:37888
	ds_read_b128 v[204:207], v167 offset:38912
	ds_read_b128 v[208:211], v167 offset:39936
	global_load_lds_dwordx4 v[218:219], off
	v_lshl_add_u64 v[218:219], s[30:31], 0, v[144:145]
	s_mov_b32 m0, s49
	s_nop 0
	global_load_lds_dwordx4 v[218:219], off
	s_waitcnt vmcnt(8)
	s_waitcnt lgkmcnt(0)
	s_barrier
	s_setprio 1
	s_waitcnt lgkmcnt(0)
	v_mfma_f32_16x16x32_bf16 v[140:143], v[72:75], v[180:183], v[140:143]
	v_mfma_f32_16x16x32_bf16 v[136:139], v[92:95], v[180:183], v[136:139]
	v_mfma_f32_16x16x32_bf16 v[132:135], v[72:75], v[188:191], v[132:135]
	v_mfma_f32_16x16x32_bf16 v[128:131], v[92:95], v[188:191], v[128:131]
	v_mfma_f32_16x16x32_bf16 v[120:123], v[72:75], v[196:199], v[120:123]
	v_mfma_f32_16x16x32_bf16 v[112:115], v[92:95], v[196:199], v[112:115]
	v_mfma_f32_16x16x32_bf16 v[100:103], v[72:75], v[204:207], v[100:103]
	v_mfma_f32_16x16x32_bf16 v[88:91], v[92:95], v[204:207], v[88:91]
	v_mfma_f32_16x16x32_bf16 v[140:143], v[84:87], v[184:187], v[140:143]
	v_mfma_f32_16x16x32_bf16 v[136:139], v[108:111], v[184:187], v[136:139]
	v_mfma_f32_16x16x32_bf16 v[132:135], v[84:87], v[192:195], v[132:135]
	v_mfma_f32_16x16x32_bf16 v[128:131], v[108:111], v[192:195], v[128:131]
	v_mfma_f32_16x16x32_bf16 v[120:123], v[84:87], v[200:203], v[120:123]
	v_mfma_f32_16x16x32_bf16 v[112:115], v[108:111], v[200:203], v[112:115]
	v_mfma_f32_16x16x32_bf16 v[100:103], v[84:87], v[208:211], v[100:103]
	v_mfma_f32_16x16x32_bf16 v[88:91], v[108:111], v[208:211], v[88:91]
	v_mfma_f32_16x16x32_bf16 v[124:127], v[156:159], v[180:183], v[124:127]
	v_mfma_f32_16x16x32_bf16 v[116:119], v[172:175], v[180:183], v[116:119]
	v_mfma_f32_16x16x32_bf16 v[104:107], v[156:159], v[188:191], v[104:107]
	v_mfma_f32_16x16x32_bf16 v[96:99], v[172:175], v[188:191], v[96:99]
	v_mfma_f32_16x16x32_bf16 v[80:83], v[156:159], v[196:199], v[80:83]
	v_mfma_f32_16x16x32_bf16 v[76:79], v[172:175], v[196:199], v[76:79]
	v_mfma_f32_16x16x32_bf16 v[68:71], v[156:159], v[204:207], v[68:71]
	v_mfma_f32_16x16x32_bf16 v[64:67], v[172:175], v[204:207], v[64:67]
	v_mfma_f32_16x16x32_bf16 v[124:127], v[168:171], v[184:187], v[124:127]
	v_mfma_f32_16x16x32_bf16 v[116:119], v[176:179], v[184:187], v[116:119]
	v_mfma_f32_16x16x32_bf16 v[104:107], v[168:171], v[192:195], v[104:107]
	v_mfma_f32_16x16x32_bf16 v[96:99], v[176:179], v[192:195], v[96:99]
	v_mfma_f32_16x16x32_bf16 v[80:83], v[168:171], v[200:203], v[80:83]
	v_mfma_f32_16x16x32_bf16 v[76:79], v[176:179], v[200:203], v[76:79]
	v_mfma_f32_16x16x32_bf16 v[68:71], v[168:171], v[208:211], v[68:71]
	v_mfma_f32_16x16x32_bf16 v[64:67], v[176:179], v[208:211], v[64:67]
	s_setprio 0
	s_barrier
; #define PG8_STAGE(bufoff, gbase, voff) do { _Pragma("unroll") for (int _i = 0; _i < 2; ++_i) \
;         __builtin_amdgcn_global_load_lds((const unsigned*)((const char*)(gbase) + (voff)[_i]), (PG8_LAS unsigned*)(lds + (bufoff) + ldsw + _i * 8192), 16, 0, 0); } while (0)
; #define PG8_LDA(dst, b, h) do { _Pragma("unroll") for (int m = 0; m < 4; ++m) _Pragma("unroll") for (int k = 0; k < 2; ++k) dst[m][k] = *(const PG8_LAS bf16x8*)(lds + PG8_SA(b, h) + aoff + m * 2048 + k * 1024); } while (0)
; #define PG8_MMA(ai, bj, At, Bt) do { __builtin_amdgcn_s_setprio(1); _Pragma("unroll") for (int m = 0; m < 4; ++m) _Pragma("unroll") for (int n = 0; n < 2; ++n) _Pragma("unroll") for (int k = 0; k < 2; ++k) \
;         acc[ai][bj][m][n] = __builtin_amdgcn_mfma_f32_16x16x32_bf16(Bt[n][k], At[m][k], acc[ai][bj][m][n], 0, 0, 0); __builtin_amdgcn_s_setprio(0); } while (0)
; #define PG8_WAIT_V(n) asm volatile("s_waitcnt vmcnt(" #n ")" ::: "memory")
; #define PG8_WAIT_L(n) asm volatile("s_waitcnt lgkmcnt(" #n ")" ::: "memory")
; #define PG8_BAR __builtin_amdgcn_s_barrier()
; #define PG8_SCHED __builtin_amdgcn_sched_barrier(0)
; template <class Epi, class Sched, bool ALIGN_EPI = false, bool SP2 = false>
; __device__ __forceinline__ void gemm_phase(PG8_LAS unsigned char* lds, const Gemm g, const Sched& S, const Epi& E) {
;     ...
;             PG8_LDA(At, 1, 1); PG8_STAGE(PG8_SB(1, 0), b3, voffB); PG8_STAGE(PG8_SB(1, 1), b3 + hstep, voffB); PG8_STAGE(PG8_SA(1, 0), a3, voffA);
;             PG8_WAIT_V(8); PG8_WAIT_L(0); PG8_BAR; PG8_MMA(1, 0, At, B0); PG8_MMA(1, 1, At, B1); PG8_BAR; PG8_SCHED;
;     ...
;         }
;         if constexpr (ALIGN_EPI) { if (wr == 0) PG8_BAR; }
	s_add_i32 s30, s62, s47
	v_lshl_add_u64 v[160:161], v[160:161], 0, s[8:9]
	s_mov_b32 m0, s30
	ds_read_b128 v[180:183], v167 offset:49152
	ds_read_b128 v[184:187], v167 offset:50176
	ds_read_b128 v[188:191], v167 offset:51200
	ds_read_b128 v[192:195], v167 offset:52224
	ds_read_b128 v[196:199], v167 offset:53248
	ds_read_b128 v[200:203], v167 offset:54272
	ds_read_b128 v[204:207], v167 offset:55296
	ds_read_b128 v[208:211], v167 offset:56320
	global_load_lds_dwordx4 v[160:161], off
	s_add_i32 m0, s30, 0x2000
	s_add_u32 s30, s36, 0x200080
	v_lshl_add_u64 v[160:161], v[212:213], 0, s[8:9]
	s_addc_u32 s31, s37, 0
	s_add_i32 s36, s63, s47
	global_load_lds_dwordx4 v[160:161], off
	v_lshl_add_u64 v[160:161], s[30:31], 0, v[146:147]
	s_mov_b32 m0, s36
	s_nop 0
	global_load_lds_dwordx4 v[160:161], off
	v_lshl_add_u64 v[160:161], s[30:31], 0, v[144:145]
	s_add_i32 m0, s36, 0x2000
	s_nop 0
	global_load_lds_dwordx4 v[160:161], off
	v_lshl_add_u64 v[160:161], v[214:215], 0, s[8:9]
	s_mov_b32 m0, s53
	s_nop 0
	global_load_lds_dwordx4 v[160:161], off
	v_lshl_add_u64 v[160:161], v[216:217], 0, s[8:9]
	s_mov_b32 m0, s54
	s_nop 0
	global_load_lds_dwordx4 v[160:161], off
	s_waitcnt vmcnt(8)
	s_waitcnt lgkmcnt(0)
	s_barrier
	s_setprio 1
	s_waitcnt lgkmcnt(0)
	v_mfma_f32_16x16x32_bf16 v[60:63], v[72:75], v[180:183], v[60:63]
	v_mfma_f32_16x16x32_bf16 v[56:59], v[92:95], v[180:183], v[56:59]
	v_mfma_f32_16x16x32_bf16 v[52:55], v[72:75], v[188:191], v[52:55]
	v_mfma_f32_16x16x32_bf16 v[44:47], v[92:95], v[188:191], v[44:47]
	v_mfma_f32_16x16x32_bf16 v[36:39], v[72:75], v[196:199], v[36:39]
	v_mfma_f32_16x16x32_bf16 v[28:31], v[92:95], v[196:199], v[28:31]
	v_mfma_f32_16x16x32_bf16 v[20:23], v[72:75], v[204:207], v[20:23]
	v_mfma_f32_16x16x32_bf16 v[12:15], v[92:95], v[204:207], v[12:15]
	v_mfma_f32_16x16x32_bf16 v[60:63], v[84:87], v[184:187], v[60:63]
	v_mfma_f32_16x16x32_bf16 v[56:59], v[108:111], v[184:187], v[56:59]
	v_mfma_f32_16x16x32_bf16 v[52:55], v[84:87], v[192:195], v[52:55]
	v_mfma_f32_16x16x32_bf16 v[44:47], v[108:111], v[192:195], v[44:47]
	v_mfma_f32_16x16x32_bf16 v[36:39], v[84:87], v[200:203], v[36:39]
	v_mfma_f32_16x16x32_bf16 v[28:31], v[108:111], v[200:203], v[28:31]
	v_mfma_f32_16x16x32_bf16 v[20:23], v[84:87], v[208:211], v[20:23]
	v_mfma_f32_16x16x32_bf16 v[12:15], v[108:111], v[208:211], v[12:15]
	v_mfma_f32_16x16x32_bf16 v[48:51], v[156:159], v[180:183], v[48:51]
	v_mfma_f32_16x16x32_bf16 v[40:43], v[172:175], v[180:183], v[40:43]
	v_mfma_f32_16x16x32_bf16 v[32:35], v[156:159], v[188:191], v[32:35]
	v_mfma_f32_16x16x32_bf16 v[24:27], v[172:175], v[188:191], v[24:27]
	v_mfma_f32_16x16x32_bf16 v[16:19], v[156:159], v[196:199], v[16:19]
	v_mfma_f32_16x16x32_bf16 v[8:11], v[172:175], v[196:199], v[8:11]
	v_mfma_f32_16x16x32_bf16 v[4:7], v[156:159], v[204:207], v[4:7]
	v_mfma_f32_16x16x32_bf16 v[0:3], v[172:175], v[204:207], v[0:3]
	v_mfma_f32_16x16x32_bf16 v[48:51], v[168:171], v[184:187], v[48:51]
	v_mfma_f32_16x16x32_bf16 v[40:43], v[176:179], v[184:187], v[40:43]
	v_mfma_f32_16x16x32_bf16 v[32:35], v[168:171], v[192:195], v[32:35]
	v_mfma_f32_16x16x32_bf16 v[24:27], v[176:179], v[192:195], v[24:27]
	v_mfma_f32_16x16x32_bf16 v[16:19], v[168:171], v[200:203], v[16:19]
	v_mfma_f32_16x16x32_bf16 v[8:11], v[176:179], v[200:203], v[8:11]
	v_mfma_f32_16x16x32_bf16 v[4:7], v[168:171], v[208:211], v[4:7]
	v_mfma_f32_16x16x32_bf16 v[0:3], v[176:179], v[208:211], v[0:3]
	s_setprio 0
	s_barrier
	s_add_i32 s61, s61, 2
	s_add_u32 s59, s59, 0x100
	s_addc_u32 s60, s60, 0
	s_cmpk_gt_u32 s61, 0x7d
	s_mov_b64 s[30:31], s[34:35]
	s_cbranch_scc0 .LBB0_847
	s_and_b64 vcc, exec, s[10:11]
	s_cbranch_vccz .LBB0_850
	s_barrier
